# residual epilogue: x loads as full 128-byte lines (8 rows per instruction, halves exchanged by DPP) instead of 16 half lines
# speedup vs baseline: 1.0025x; 1.0025x over previous
; #define PG8_STAGE(bufoff, gbase, voff) do { _Pragma("unroll") for (int _i = 0; _i < 2; ++_i) \
;         __builtin_amdgcn_global_load_lds((const unsigned*)((const char*)(gbase) + (voff)[_i]), (LAS unsigned*)(lds + (bufoff) + ldsw + _i * 8192), 16, 0, 0); } while (0)
; #define PG8_LDA(dst, b, h) do { _Pragma("unroll") for (int m = 0; m < 4; ++m) _Pragma("unroll") for (int k = 0; k < 2; ++k) dst[m][k] = *(const LAS bf16x8*)(lds + PG8_SA(b, h) + aoff + m * 2048 + k * 1024); } while (0)
; #define PG8_WAIT_V(n) asm volatile("s_waitcnt vmcnt(" #n ")" ::: "memory")
; #define PG8_WAIT_L(n) asm volatile("s_waitcnt lgkmcnt(" #n ")" ::: "memory")
; template <class Epi>
; __device__ __forceinline__ void gemm_phase(LAS unsigned char* lds, const Gemm g, const StaticOrder& S, const Epi& E) {
;     ...
;         for (int t = 0; t < nt; t += 2) {
;             const bool last = (t == nt - 2);
;             const char* a1 = cA + (size_t)(t + 1) * kstep;
;             const char* a2 = last ? nA : cA + (size_t)(t + 2) * kstep; const char* b2 = last ? nB : cB + (size_t)(t + 2) * kstep;
;             const char* a3 = a2 + kstep; const char* b3 = b2 + kstep;
;             PG8_LDB(B0, 0, 0); PG8_SCHED; PG8_LDA(At, 0, 0); PG8_STAGE(PG8_SA(1, 1), a1 + hstepA, voffA);
;             PG8_WAIT_L(8); PG8_BAR; PG8_WAIT_L(0); PG8_MMA(0, 0, At, B0); PG8_BAR; PG8_SCHED;
;             PG8_LDB(B1, 0, 1); PG8_STAGE(PG8_SB(0, 0), b2, voffB);
;             PG8_BAR; PG8_WAIT_L(0); PG8_MMA(0, 1, At, B1); PG8_BAR;
;             PG8_LDA(At, 0, 1); PG8_STAGE(PG8_SA(0, 0), a2, voffA);
;             PG8_BAR; PG8_WAIT_L(0); PG8_MMA(1, 0, At, B0); PG8_BAR; PG8_SCHED;
;             PG8_STAGE(PG8_SB(0, 1), b2 + hstepB, voffB);
;             PG8_WAIT_V(6); PG8_BAR; PG8_MMA(1, 1, At, B1); PG8_BAR;
;             PG8_LDB(B0, 1, 0); PG8_SCHED; PG8_LDA(At, 1, 0); PG8_STAGE(PG8_SA(0, 1), a2 + hstepA, voffA);
;             PG8_WAIT_L(8); PG8_BAR; PG8_WAIT_L(0); PG8_MMA(0, 0, At, B0); PG8_BAR; PG8_SCHED;
;             PG8_LDB(B1, 1, 1); PG8_STAGE(PG8_SB(1, 0), b3, voffB);
;             PG8_BAR; PG8_WAIT_L(0); PG8_MMA(0, 1, At, B1); PG8_BAR;
;             PG8_LDA(At, 1, 1); PG8_STAGE(PG8_SA(1, 0), a3, voffA);
;             PG8_BAR; PG8_WAIT_L(0); PG8_MMA(1, 0, At, B0); PG8_BAR; PG8_SCHED;
;             PG8_STAGE(PG8_SB(1, 1), b3 + hstepB, voffB);
;             PG8_WAIT_V(6); PG8_BAR; PG8_MMA(1, 1, At, B1); PG8_BAR;
.LBB0_411:
	ds_read_b128 v[140:143], v149
	ds_read_b128 v[152:155], v149 offset:1024
	ds_read_b128 v[156:159], v149 offset:2048
	ds_read_b128 v[160:163], v149 offset:3072
	s_add_u32 s28, s26, 0x100
	s_addc_u32 s29, s27, 0
	s_cmp_eq_u32 s68, 40
	s_cselect_b32 s35, s11, s29
	s_cselect_b32 s34, s10, s28
	s_cselect_b32 s31, s13, s63
	s_cselect_b32 s30, s12, s49
	v_lshl_add_u64 v[144:145], s[26:27], 0, v[132:133]
	s_add_i32 m0, s36, 0xc000
	ds_read_b128 v[164:167], v150
	ds_read_b128 v[168:171], v150 offset:1024
	ds_read_b128 v[172:175], v150 offset:2048
	ds_read_b128 v[176:179], v150 offset:3072
	ds_read_b128 v[180:183], v150 offset:4096
	ds_read_b128 v[184:187], v150 offset:5120
	ds_read_b128 v[188:191], v150 offset:6144
	ds_read_b128 v[192:195], v150 offset:7168
	global_load_lds_dwordx4 v[144:145], off
	v_lshl_add_u64 v[144:145], s[26:27], 0, v[134:135]
	s_add_i32 m0, s36, 0xe000
	s_nop 0
	global_load_lds_dwordx4 v[144:145], off
	ds_read_b128 v[196:199], v151
	ds_read_b128 v[200:203], v151 offset:1024
	ds_read_b128 v[204:207], v151 offset:2048
	ds_read_b128 v[208:211], v151 offset:3072
	s_waitcnt lgkmcnt(0)
	s_barrier
	s_setprio 1
	v_mfma_f32_16x16x32_bf16 v[124:127], v[140:143], v[164:167], v[124:127]
	v_mfma_f32_16x16x32_bf16 v[120:123], v[156:159], v[164:167], v[120:123]
	v_mfma_f32_16x16x32_bf16 v[112:115], v[140:143], v[172:175], v[112:115]
	v_mfma_f32_16x16x32_bf16 v[104:107], v[156:159], v[172:175], v[104:107]
	v_mfma_f32_16x16x32_bf16 v[92:95], v[140:143], v[180:183], v[92:95]
	v_mfma_f32_16x16x32_bf16 v[88:91], v[156:159], v[180:183], v[88:91]
	v_mfma_f32_16x16x32_bf16 v[80:83], v[140:143], v[188:191], v[80:83]
	v_mfma_f32_16x16x32_bf16 v[72:75], v[156:159], v[188:191], v[72:75]
	v_mfma_f32_16x16x32_bf16 v[124:127], v[152:155], v[168:171], v[124:127]
	v_mfma_f32_16x16x32_bf16 v[120:123], v[160:163], v[168:171], v[120:123]
	v_mfma_f32_16x16x32_bf16 v[112:115], v[152:155], v[176:179], v[112:115]
	v_mfma_f32_16x16x32_bf16 v[104:107], v[160:163], v[176:179], v[104:107]
	v_mfma_f32_16x16x32_bf16 v[92:95], v[152:155], v[184:187], v[92:95]
	v_mfma_f32_16x16x32_bf16 v[88:91], v[160:163], v[184:187], v[88:91]
	v_mfma_f32_16x16x32_bf16 v[80:83], v[152:155], v[192:195], v[80:83]
	v_mfma_f32_16x16x32_bf16 v[72:75], v[160:163], v[192:195], v[72:75]
	v_mfma_f32_16x16x32_bf16 v[116:119], v[196:199], v[164:167], v[116:119]
	v_mfma_f32_16x16x32_bf16 v[108:111], v[204:207], v[164:167], v[108:111]
	v_mfma_f32_16x16x32_bf16 v[100:103], v[196:199], v[172:175], v[100:103]
	v_mfma_f32_16x16x32_bf16 v[96:99], v[204:207], v[172:175], v[96:99]
	v_mfma_f32_16x16x32_bf16 v[84:87], v[196:199], v[180:183], v[84:87]
	v_mfma_f32_16x16x32_bf16 v[76:79], v[204:207], v[180:183], v[76:79]
	v_mfma_f32_16x16x32_bf16 v[68:71], v[196:199], v[188:191], v[68:71]
	v_mfma_f32_16x16x32_bf16 v[64:67], v[204:207], v[188:191], v[64:67]
	v_mfma_f32_16x16x32_bf16 v[116:119], v[200:203], v[168:171], v[116:119]
	v_mfma_f32_16x16x32_bf16 v[108:111], v[208:211], v[168:171], v[108:111]
	v_mfma_f32_16x16x32_bf16 v[100:103], v[200:203], v[176:179], v[100:103]
	v_mfma_f32_16x16x32_bf16 v[96:99], v[208:211], v[176:179], v[96:99]
	v_mfma_f32_16x16x32_bf16 v[84:87], v[200:203], v[184:187], v[84:87]
	v_mfma_f32_16x16x32_bf16 v[76:79], v[208:211], v[184:187], v[76:79]
	v_mfma_f32_16x16x32_bf16 v[68:71], v[200:203], v[192:195], v[68:71]
	v_mfma_f32_16x16x32_bf16 v[64:67], v[208:211], v[192:195], v[64:67]
	s_setprio 0
	s_barrier
	s_nop 1
	ds_read_b128 v[164:167], v150 offset:16384
	ds_read_b128 v[168:171], v150 offset:17408
	ds_read_b128 v[172:175], v150 offset:18432
	ds_read_b128 v[176:179], v150 offset:19456
	ds_read_b128 v[180:183], v150 offset:20480
	ds_read_b128 v[184:187], v150 offset:21504
	ds_read_b128 v[188:191], v150 offset:22528
	ds_read_b128 v[192:195], v150 offset:23552
	s_add_i32 s26, s43, s7
	v_lshl_add_u64 v[144:145], s[30:31], 0, v[128:129]
	s_mov_b32 m0, s26
	s_nop 0
	global_load_lds_dwordx4 v[144:145], off
	v_lshl_add_u64 v[212:213], s[30:31], 0, v[130:131]
	s_add_i32 m0, s26, 0x2000
	s_nop 0
	global_load_lds_dwordx4 v[212:213], off
	s_mov_b32 m0, s36
	v_lshl_add_u64 v[214:215], s[34:35], 0, v[128:129]
	global_load_lds_dwordx4 v[214:215], off
	v_lshl_add_u64 v[216:217], s[34:35], 0, v[130:131]
	s_mov_b32 m0, s37
	s_nop 0
	global_load_lds_dwordx4 v[216:217], off
	s_add_u32 s26, s30, 0xb0000
	s_addc_u32 s27, s31, 0
	s_add_i32 s69, s44, s7
	v_lshl_add_u64 v[254:255], s[26:27], 0, v[128:129]
	s_mov_b32 m0, s69
	s_nop 0
	global_load_lds_dwordx4 v[254:255], off
	v_lshl_add_u64 v[254:255], s[26:27], 0, v[130:131]
	s_add_i32 m0, s69, 0x2000
	s_nop 0
	global_load_lds_dwordx4 v[254:255], off
	s_waitcnt vmcnt(6)
	s_waitcnt lgkmcnt(0)
	s_barrier
; #define PG8_STAGE(bufoff, gbase, voff) do { _Pragma("unroll") for (int _i = 0; _i < 2; ++_i) \
;         __builtin_amdgcn_global_load_lds((const unsigned*)((const char*)(gbase) + (voff)[_i]), (LAS unsigned*)(lds + (bufoff) + ldsw + _i * 8192), 16, 0, 0); } while (0)
; #define PG8_LDA(dst, b, h) do { _Pragma("unroll") for (int m = 0; m < 4; ++m) _Pragma("unroll") for (int k = 0; k < 2; ++k) dst[m][k] = *(const LAS bf16x8*)(lds + PG8_SA(b, h) + aoff + m * 2048 + k * 1024); } while (0)
; #define PG8_WAIT_V(n) asm volatile("s_waitcnt vmcnt(" #n ")" ::: "memory")
; #define PG8_WAIT_L(n) asm volatile("s_waitcnt lgkmcnt(" #n ")" ::: "memory")
; template <class Epi>
; __device__ __forceinline__ void gemm_phase(LAS unsigned char* lds, const Gemm g, const StaticOrder& S, const Epi& E) {
;     ...
;         for (int t = 0; t < nt; t += 2) {
;             const bool last = (t == nt - 2);
;             const char* a1 = cA + (size_t)(t + 1) * kstep;
;             const char* a2 = last ? nA : cA + (size_t)(t + 2) * kstep; const char* b2 = last ? nB : cB + (size_t)(t + 2) * kstep;
;             const char* a3 = a2 + kstep; const char* b3 = b2 + kstep;
;             PG8_LDB(B0, 0, 0); PG8_SCHED; PG8_LDA(At, 0, 0); PG8_STAGE(PG8_SA(1, 1), a1 + hstepA, voffA);
;             PG8_WAIT_L(8); PG8_BAR; PG8_WAIT_L(0); PG8_MMA(0, 0, At, B0); PG8_BAR; PG8_SCHED;
;             PG8_LDB(B1, 0, 1); PG8_STAGE(PG8_SB(0, 0), b2, voffB);
;             PG8_BAR; PG8_WAIT_L(0); PG8_MMA(0, 1, At, B1); PG8_BAR;
;             PG8_LDA(At, 0, 1); PG8_STAGE(PG8_SA(0, 0), a2, voffA);
;             PG8_BAR; PG8_WAIT_L(0); PG8_MMA(1, 0, At, B0); PG8_BAR; PG8_SCHED;
;             PG8_STAGE(PG8_SB(0, 1), b2 + hstepB, voffB);
;             PG8_WAIT_V(6); PG8_BAR; PG8_MMA(1, 1, At, B1); PG8_BAR;
;             PG8_LDB(B0, 1, 0); PG8_SCHED; PG8_LDA(At, 1, 0); PG8_STAGE(PG8_SA(0, 1), a2 + hstepA, voffA);
;             PG8_WAIT_L(8); PG8_BAR; PG8_WAIT_L(0); PG8_MMA(0, 0, At, B0); PG8_BAR; PG8_SCHED;
;             PG8_LDB(B1, 1, 1); PG8_STAGE(PG8_SB(1, 0), b3, voffB);
;             PG8_BAR; PG8_WAIT_L(0); PG8_MMA(0, 1, At, B1); PG8_BAR;
;             PG8_LDA(At, 1, 1); PG8_STAGE(PG8_SA(1, 0), a3, voffA);
;             PG8_BAR; PG8_WAIT_L(0); PG8_MMA(1, 0, At, B0); PG8_BAR; PG8_SCHED;
;             PG8_STAGE(PG8_SB(1, 1), b3 + hstepB, voffB);
;             PG8_WAIT_V(6); PG8_BAR; PG8_MMA(1, 1, At, B1); PG8_BAR;
	s_setprio 1
	v_mfma_f32_16x16x32_bf16 v[60:63], v[140:143], v[164:167], v[60:63]
	v_mfma_f32_16x16x32_bf16 v[56:59], v[156:159], v[164:167], v[56:59]
	v_mfma_f32_16x16x32_bf16 v[48:51], v[140:143], v[172:175], v[48:51]
	v_mfma_f32_16x16x32_bf16 v[40:43], v[156:159], v[172:175], v[40:43]
	v_mfma_f32_16x16x32_bf16 v[28:31], v[140:143], v[180:183], v[28:31]
	v_mfma_f32_16x16x32_bf16 v[24:27], v[156:159], v[180:183], v[24:27]
	v_mfma_f32_16x16x32_bf16 v[16:19], v[140:143], v[188:191], v[16:19]
	v_mfma_f32_16x16x32_bf16 v[8:11], v[156:159], v[188:191], v[8:11]
	v_mfma_f32_16x16x32_bf16 v[60:63], v[152:155], v[168:171], v[60:63]
	v_mfma_f32_16x16x32_bf16 v[56:59], v[160:163], v[168:171], v[56:59]
	v_mfma_f32_16x16x32_bf16 v[48:51], v[152:155], v[176:179], v[48:51]
	v_mfma_f32_16x16x32_bf16 v[40:43], v[160:163], v[176:179], v[40:43]
	v_mfma_f32_16x16x32_bf16 v[28:31], v[152:155], v[184:187], v[28:31]
	v_mfma_f32_16x16x32_bf16 v[24:27], v[160:163], v[184:187], v[24:27]
	v_mfma_f32_16x16x32_bf16 v[16:19], v[152:155], v[192:195], v[16:19]
	v_mfma_f32_16x16x32_bf16 v[8:11], v[160:163], v[192:195], v[8:11]
	v_mfma_f32_16x16x32_bf16 v[52:55], v[196:199], v[164:167], v[52:55]
	v_mfma_f32_16x16x32_bf16 v[44:47], v[204:207], v[164:167], v[44:47]
	v_mfma_f32_16x16x32_bf16 v[36:39], v[196:199], v[172:175], v[36:39]
	v_mfma_f32_16x16x32_bf16 v[32:35], v[204:207], v[172:175], v[32:35]
	v_mfma_f32_16x16x32_bf16 v[20:23], v[196:199], v[180:183], v[20:23]
	v_mfma_f32_16x16x32_bf16 v[12:15], v[204:207], v[180:183], v[12:15]
	v_mfma_f32_16x16x32_bf16 v[4:7], v[196:199], v[188:191], v[4:7]
	v_mfma_f32_16x16x32_bf16 v[0:3], v[204:207], v[188:191], v[0:3]
	v_mfma_f32_16x16x32_bf16 v[52:55], v[200:203], v[168:171], v[52:55]
	v_mfma_f32_16x16x32_bf16 v[44:47], v[208:211], v[168:171], v[44:47]
	v_mfma_f32_16x16x32_bf16 v[36:39], v[200:203], v[176:179], v[36:39]
	v_mfma_f32_16x16x32_bf16 v[32:35], v[208:211], v[176:179], v[32:35]
	v_mfma_f32_16x16x32_bf16 v[20:23], v[200:203], v[184:187], v[20:23]
	v_mfma_f32_16x16x32_bf16 v[12:15], v[208:211], v[184:187], v[12:15]
	v_mfma_f32_16x16x32_bf16 v[4:7], v[200:203], v[192:195], v[4:7]
	v_mfma_f32_16x16x32_bf16 v[0:3], v[208:211], v[192:195], v[0:3]
	s_setprio 0
	s_add_i32 s69, 0, 0x18000
	v_add_u32_e32 v160, s69, v147
	s_barrier
	ds_read_b128 v[140:143], v160
	ds_read_b128 v[152:155], v160 offset:1024
	ds_read_b128 v[156:159], v160 offset:2048
	ds_read_b128 v[160:163], v160 offset:3072
	s_add_u32 s26, s34, 0xb0000
	s_addc_u32 s27, s35, 0
	s_mov_b32 m0, s38
	v_lshl_add_u64 v[196:197], s[26:27], 0, v[128:129]
	ds_read_b128 v[164:167], v150 offset:32768
	ds_read_b128 v[168:171], v150 offset:33792
	ds_read_b128 v[172:175], v150 offset:34816
	ds_read_b128 v[176:179], v150 offset:35840
	ds_read_b128 v[180:183], v150 offset:36864
	ds_read_b128 v[184:187], v150 offset:37888
	ds_read_b128 v[188:191], v150 offset:38912
	ds_read_b128 v[192:195], v150 offset:39936
	global_load_lds_dwordx4 v[196:197], off
	v_lshl_add_u64 v[196:197], s[26:27], 0, v[130:131]
	s_mov_b32 m0, s39
	s_nop 0
	global_load_lds_dwordx4 v[196:197], off
	s_add_i32 s34, 0, 0x1c000
	v_add_u32_e32 v208, s34, v147
	ds_read_b128 v[196:199], v208
	ds_read_b128 v[200:203], v208 offset:1024
	ds_read_b128 v[204:207], v208 offset:2048
	ds_read_b128 v[208:211], v208 offset:3072
	s_waitcnt lgkmcnt(0)
	s_barrier
	s_setprio 1
	v_mfma_f32_16x16x32_bf16 v[124:127], v[140:143], v[164:167], v[124:127]
	v_mfma_f32_16x16x32_bf16 v[120:123], v[156:159], v[164:167], v[120:123]
	v_mfma_f32_16x16x32_bf16 v[112:115], v[140:143], v[172:175], v[112:115]
	v_mfma_f32_16x16x32_bf16 v[104:107], v[156:159], v[172:175], v[104:107]
	v_mfma_f32_16x16x32_bf16 v[92:95], v[140:143], v[180:183], v[92:95]
	v_mfma_f32_16x16x32_bf16 v[88:91], v[156:159], v[180:183], v[88:91]
	v_mfma_f32_16x16x32_bf16 v[80:83], v[140:143], v[188:191], v[80:83]
	v_mfma_f32_16x16x32_bf16 v[72:75], v[156:159], v[188:191], v[72:75]
	v_mfma_f32_16x16x32_bf16 v[124:127], v[152:155], v[168:171], v[124:127]
	v_mfma_f32_16x16x32_bf16 v[120:123], v[160:163], v[168:171], v[120:123]
	v_mfma_f32_16x16x32_bf16 v[112:115], v[152:155], v[176:179], v[112:115]
	v_mfma_f32_16x16x32_bf16 v[104:107], v[160:163], v[176:179], v[104:107]
	v_mfma_f32_16x16x32_bf16 v[92:95], v[152:155], v[184:187], v[92:95]
	v_mfma_f32_16x16x32_bf16 v[88:91], v[160:163], v[184:187], v[88:91]
	v_mfma_f32_16x16x32_bf16 v[80:83], v[152:155], v[192:195], v[80:83]
	v_mfma_f32_16x16x32_bf16 v[72:75], v[160:163], v[192:195], v[72:75]
	v_mfma_f32_16x16x32_bf16 v[116:119], v[196:199], v[164:167], v[116:119]
	v_mfma_f32_16x16x32_bf16 v[108:111], v[204:207], v[164:167], v[108:111]
	v_mfma_f32_16x16x32_bf16 v[100:103], v[196:199], v[172:175], v[100:103]
	v_mfma_f32_16x16x32_bf16 v[96:99], v[204:207], v[172:175], v[96:99]
	v_mfma_f32_16x16x32_bf16 v[84:87], v[196:199], v[180:183], v[84:87]
	v_mfma_f32_16x16x32_bf16 v[76:79], v[204:207], v[180:183], v[76:79]
	v_mfma_f32_16x16x32_bf16 v[68:71], v[196:199], v[188:191], v[68:71]
	v_mfma_f32_16x16x32_bf16 v[64:67], v[204:207], v[188:191], v[64:67]
	v_mfma_f32_16x16x32_bf16 v[116:119], v[200:203], v[168:171], v[116:119]
	v_mfma_f32_16x16x32_bf16 v[108:111], v[208:211], v[168:171], v[108:111]
	v_mfma_f32_16x16x32_bf16 v[100:103], v[200:203], v[176:179], v[100:103]
	v_mfma_f32_16x16x32_bf16 v[96:99], v[208:211], v[176:179], v[96:99]
	v_mfma_f32_16x16x32_bf16 v[84:87], v[200:203], v[184:187], v[84:87]
	v_mfma_f32_16x16x32_bf16 v[76:79], v[208:211], v[184:187], v[76:79]
	v_mfma_f32_16x16x32_bf16 v[68:71], v[200:203], v[192:195], v[68:71]
	v_mfma_f32_16x16x32_bf16 v[64:67], v[208:211], v[192:195], v[64:67]
	s_setprio 0
	s_barrier
; template <class Epi>
; __device__ __forceinline__ void gemm_phase(LAS unsigned char* lds, const Gemm g, const StaticOrder& S, const Epi& E) {
;     ...
;         for (int t = 0; t < nt; t += 2) {
;             const bool last = (t == nt - 2);
;             const char* a1 = cA + (size_t)(t + 1) * kstep;
;             const char* a2 = last ? nA : cA + (size_t)(t + 2) * kstep; const char* b2 = last ? nB : cB + (size_t)(t + 2) * kstep;
;             const char* a3 = a2 + kstep; const char* b3 = b2 + kstep;
;             PG8_LDB(B0, 0, 0); PG8_SCHED; PG8_LDA(At, 0, 0); PG8_STAGE(PG8_SA(1, 1), a1 + hstepA, voffA);
;             PG8_WAIT_L(8); PG8_BAR; PG8_WAIT_L(0); PG8_MMA(0, 0, At, B0); PG8_BAR; PG8_SCHED;
;             PG8_LDB(B1, 0, 1); PG8_STAGE(PG8_SB(0, 0), b2, voffB);
;             PG8_BAR; PG8_WAIT_L(0); PG8_MMA(0, 1, At, B1); PG8_BAR;
;             PG8_LDA(At, 0, 1); PG8_STAGE(PG8_SA(0, 0), a2, voffA);
;             PG8_BAR; PG8_WAIT_L(0); PG8_MMA(1, 0, At, B0); PG8_BAR; PG8_SCHED;
;             PG8_STAGE(PG8_SB(0, 1), b2 + hstepB, voffB);
;             PG8_WAIT_V(6); PG8_BAR; PG8_MMA(1, 1, At, B1); PG8_BAR;
;             PG8_LDB(B0, 1, 0); PG8_SCHED; PG8_LDA(At, 1, 0); PG8_STAGE(PG8_SA(0, 1), a2 + hstepA, voffA);
;             PG8_WAIT_L(8); PG8_BAR; PG8_WAIT_L(0); PG8_MMA(0, 0, At, B0); PG8_BAR; PG8_SCHED;
;             PG8_LDB(B1, 1, 1); PG8_STAGE(PG8_SB(1, 0), b3, voffB);
;             PG8_BAR; PG8_WAIT_L(0); PG8_MMA(0, 1, At, B1); PG8_BAR;
;             PG8_LDA(At, 1, 1); PG8_STAGE(PG8_SA(1, 0), a3, voffA);
;             PG8_BAR; PG8_WAIT_L(0); PG8_MMA(1, 0, At, B0); PG8_BAR; PG8_SCHED;
;             PG8_STAGE(PG8_SB(1, 1), b3 + hstepB, voffB);
;             PG8_WAIT_V(6); PG8_BAR; PG8_MMA(1, 1, At, B1); PG8_BAR;
;         }
;     __device__ __forceinline__ void operator()(AccRef acc, const Unit& u, int wr, int wc, int fr, int fq) const {
;         const int row0 = u.pm * 256 + wr * 64 + fr, col0 = u.pn * 256 + wc * 32 + 4 * fq;
;         f32x4 sv[2][2], bv[2][2];
; #pragma unroll
;         for (int bj = 0; bj < 2; ++bj)
; #pragma unroll
;             for (int n = 0; n < 2; ++n) {
;                 sv[bj][n] = scale ? *(const f32x4*)(scale + col0 + bj * 128 + n * 16) : (f32x4){1.f, 1.f, 1.f, 1.f};
;                 bv[bj][n] = bias ? *(const f32x4*)(bias + col0 + bj * 128 + n * 16) : (f32x4){0.f, 0.f, 0.f, 0.f}; }
; #pragma unroll
	s_nop 1
	ds_read_b128 v[164:167], v150 offset:49152
	ds_read_b128 v[168:171], v150 offset:50176
	ds_read_b128 v[172:175], v150 offset:51200
	ds_read_b128 v[176:179], v150 offset:52224
	ds_read_b128 v[180:183], v150 offset:53248
	ds_read_b128 v[184:187], v150 offset:54272
	ds_read_b128 v[188:191], v150 offset:55296
	ds_read_b128 v[192:195], v150 offset:56320
	s_add_i32 s26, s69, s7
	v_lshl_add_u64 v[254:255], v[144:145], 0, s[16:17]
	s_mov_b32 m0, s26
	s_nop 0
	global_load_lds_dwordx4 v[254:255], off
	v_lshl_add_u64 v[254:255], v[212:213], 0, s[16:17]
	s_add_i32 m0, s26, 0x2000
	s_nop 0
	global_load_lds_dwordx4 v[254:255], off
	s_mov_b32 m0, s41
	v_lshl_add_u64 v[254:255], v[214:215], 0, s[16:17]
	global_load_lds_dwordx4 v[254:255], off
	v_lshl_add_u64 v[144:145], v[216:217], 0, s[16:17]
	s_mov_b32 m0, s42
	s_nop 0
	global_load_lds_dwordx4 v[144:145], off
	s_add_u32 s26, s30, 0xb0080
	s_addc_u32 s27, s31, 0
	s_add_i32 s30, s34, s7
	v_lshl_add_u64 v[254:255], s[26:27], 0, v[128:129]
	s_mov_b32 m0, s30
	s_nop 0
	global_load_lds_dwordx4 v[254:255], off
	v_lshl_add_u64 v[254:255], s[26:27], 0, v[130:131]
	s_add_i32 m0, s30, 0x2000
	s_nop 0
	global_load_lds_dwordx4 v[254:255], off
	s_waitcnt vmcnt(6)
	s_waitcnt lgkmcnt(0)
	s_barrier
	s_setprio 1
	v_mfma_f32_16x16x32_bf16 v[60:63], v[140:143], v[164:167], v[60:63]
	v_mfma_f32_16x16x32_bf16 v[56:59], v[156:159], v[164:167], v[56:59]
	v_mfma_f32_16x16x32_bf16 v[48:51], v[140:143], v[172:175], v[48:51]
	v_mfma_f32_16x16x32_bf16 v[40:43], v[156:159], v[172:175], v[40:43]
	v_mfma_f32_16x16x32_bf16 v[28:31], v[140:143], v[180:183], v[28:31]
	v_mfma_f32_16x16x32_bf16 v[24:27], v[156:159], v[180:183], v[24:27]
	v_mfma_f32_16x16x32_bf16 v[16:19], v[140:143], v[188:191], v[16:19]
	v_mfma_f32_16x16x32_bf16 v[8:11], v[156:159], v[188:191], v[8:11]
	v_mfma_f32_16x16x32_bf16 v[60:63], v[152:155], v[168:171], v[60:63]
	v_mfma_f32_16x16x32_bf16 v[56:59], v[160:163], v[168:171], v[56:59]
	v_mfma_f32_16x16x32_bf16 v[48:51], v[152:155], v[176:179], v[48:51]
	v_mfma_f32_16x16x32_bf16 v[40:43], v[160:163], v[176:179], v[40:43]
	v_mfma_f32_16x16x32_bf16 v[28:31], v[152:155], v[184:187], v[28:31]
	v_mfma_f32_16x16x32_bf16 v[24:27], v[160:163], v[184:187], v[24:27]
	v_mfma_f32_16x16x32_bf16 v[16:19], v[152:155], v[192:195], v[16:19]
	v_mfma_f32_16x16x32_bf16 v[8:11], v[160:163], v[192:195], v[8:11]
	v_mfma_f32_16x16x32_bf16 v[52:55], v[196:199], v[164:167], v[52:55]
	v_mfma_f32_16x16x32_bf16 v[44:47], v[204:207], v[164:167], v[44:47]
	v_mfma_f32_16x16x32_bf16 v[36:39], v[196:199], v[172:175], v[36:39]
	v_mfma_f32_16x16x32_bf16 v[32:35], v[204:207], v[172:175], v[32:35]
	v_mfma_f32_16x16x32_bf16 v[20:23], v[196:199], v[180:183], v[20:23]
	v_mfma_f32_16x16x32_bf16 v[12:15], v[204:207], v[180:183], v[12:15]
	v_mfma_f32_16x16x32_bf16 v[4:7], v[196:199], v[188:191], v[4:7]
	v_mfma_f32_16x16x32_bf16 v[0:3], v[204:207], v[188:191], v[0:3]
	v_mfma_f32_16x16x32_bf16 v[52:55], v[200:203], v[168:171], v[52:55]
	v_mfma_f32_16x16x32_bf16 v[44:47], v[208:211], v[168:171], v[44:47]
	v_mfma_f32_16x16x32_bf16 v[36:39], v[200:203], v[176:179], v[36:39]
	v_mfma_f32_16x16x32_bf16 v[32:35], v[208:211], v[176:179], v[32:35]
	v_mfma_f32_16x16x32_bf16 v[20:23], v[200:203], v[184:187], v[20:23]
	v_mfma_f32_16x16x32_bf16 v[12:15], v[208:211], v[184:187], v[12:15]
	v_mfma_f32_16x16x32_bf16 v[4:7], v[200:203], v[192:195], v[4:7]
	v_mfma_f32_16x16x32_bf16 v[0:3], v[208:211], v[192:195], v[0:3]
	s_setprio 0
	s_add_i32 s68, s68, 2
	s_add_u32 s49, s49, 0x100
	s_addc_u32 s63, s63, 0
	s_cmp_gt_u32 s68, 41
	s_mov_b64 s[26:27], s[28:29]
	s_barrier
	s_cbranch_scc0 .LBB0_411
	v_lshl_or_b32 v144, s47, 8, v148
	v_lshl_add_u32 v145, s48, 8, v146
	v_lshlrev_b32_e32 v144, 2, v144
	v_lshl_add_u32 v145, v145, 12, v144
	v_add_u32_e32 v216, 0x10000, v145
	v_add_u32_e32 v217, 0x20000, v145
	v_add_u32_e32 v218, 0x30000, v145
	v_add_u32_e32 v220, 0x80000, v145
	v_add_u32_e32 v221, 0x90000, v145
	v_add_u32_e32 v222, 0xa0000, v145
	v_add_u32_e32 v223, 0xb0000, v145
	v_and_b32_e32 v235, 8, v146
	v_cmp_ne_u32_e32 vcc, 0, v235
	v_mov_b32_e32 v232, 0xffff8040
	s_nop 0
	v_cndmask_b32_e32 v232, 0, v232, vcc
	v_mov_b32_e32 v233, 64
	v_mov_b32_e32 v235, 0x8000
	v_cndmask_b32_e32 v233, v235, v233, vcc
	v_add_u32_e32 v224, v145, v232
	v_add_u32_e32 v225, v216, v232
	v_add_u32_e32 v226, v217, v232
	v_add_u32_e32 v227, v218, v232
	v_add_u32_e32 v228, v220, v232
	v_add_u32_e32 v229, v221, v232
	v_add_u32_e32 v230, v222, v232
	v_add_u32_e32 v231, v223, v232
	s_and_b64 vcc, exec, s[8:9]
	s_mov_b32 s47, s45
	s_mov_b32 s48, s46
	s_mov_b64 s[28:29], s[12:13]
	s_mov_b64 s[26:27], s[10:11]
	global_load_dwordx4 v[140:143], v224, s[52:53]
	v_add_u32_e32 v144, v145, v233
	global_load_dwordx4 v[152:155], v144, s[52:53]
	global_load_dwordx4 v[156:159], v224, s[52:53] offset:512
	v_add_u32_e32 v144, v145, v233
	global_load_dwordx4 v[160:163], v144, s[52:53] offset:512
	global_load_dwordx4 v[164:167], v225, s[52:53]
	v_add_u32_e32 v144, v216, v233
	global_load_dwordx4 v[168:171], v144, s[52:53]
	global_load_dwordx4 v[172:175], v225, s[52:53] offset:512
	v_add_u32_e32 v144, v216, v233
	global_load_dwordx4 v[176:179], v144, s[52:53] offset:512
	global_load_dwordx4 v[180:183], v226, s[52:53]
	v_add_u32_e32 v144, v217, v233
	global_load_dwordx4 v[184:187], v144, s[52:53]
	global_load_dwordx4 v[188:191], v226, s[52:53] offset:512
	v_add_u32_e32 v144, v217, v233
	global_load_dwordx4 v[192:195], v144, s[52:53] offset:512
	global_load_dwordx4 v[196:199], v227, s[52:53]
	v_add_u32_e32 v144, v218, v233
	global_load_dwordx4 v[200:203], v144, s[52:53]
	global_load_dwordx4 v[204:207], v227, s[52:53] offset:512
;     __device__ __forceinline__ void operator()(AccRef acc, const Unit& u, int wr, int wc, int fr, int fq) const {
;     ...
;         for (int ai = 0; ai < 2; ++ai)
; #pragma unroll
;             for (int mh = 0; mh < 2; ++mh) {
;                 f32x4 bs[2][2][2];
; #pragma unroll
;                 for (int m = 0; m < 2; ++m)
; #pragma unroll
;                     for (int bj = 0; bj < 2; ++bj)
; #pragma unroll
;                         for (int n = 0; n < 2; ++n) bs[m][bj][n] = *(const f32x4*)(base + (size_t)(row0 + ai * 128 + (2 * mh + m) * 16) * D + col0 + bj * 128 + n * 16);
; #pragma unroll
;                 for (int m = 0; m < 2; ++m)
; #pragma unroll
;                     for (int bj = 0; bj < 2; ++bj)
; #pragma unroll
;                         for (int n = 0; n < 2; ++n) *(f32x4*)(out + (size_t)(row0 + ai * 128 + (2 * mh + m) * 16) * D + col0 + bj * 128 + n * 16) = bs[m][bj][n] + sv[bj][n] * (acc[ai][bj][2 * mh + m][n] + bv[bj][n]);
	v_add_u32_e32 v144, v218, v233
	global_load_dwordx4 v[208:211], v144, s[52:53] offset:512
	v_pk_add_f32 v[124:125], v[124:125], 0 op_sel_hi:[1,0]
	v_pk_add_f32 v[126:127], v[126:127], 0 op_sel_hi:[1,0]
	v_pk_add_f32 v[120:121], v[120:121], 0 op_sel_hi:[1,0]
	v_pk_add_f32 v[122:123], v[122:123], 0 op_sel_hi:[1,0]
	v_pk_add_f32 v[116:117], v[116:117], 0 op_sel_hi:[1,0]
	v_pk_add_f32 v[118:119], v[118:119], 0 op_sel_hi:[1,0]
	v_pk_add_f32 v[108:109], v[108:109], 0 op_sel_hi:[1,0]
	v_pk_add_f32 v[110:111], v[110:111], 0 op_sel_hi:[1,0]
	v_pk_add_f32 v[112:113], v[112:113], 0 op_sel_hi:[1,0]
	v_pk_add_f32 v[114:115], v[114:115], 0 op_sel_hi:[1,0]
	v_pk_add_f32 v[104:105], v[104:105], 0 op_sel_hi:[1,0]
	v_pk_add_f32 v[106:107], v[106:107], 0 op_sel_hi:[1,0]
	v_pk_add_f32 v[100:101], v[100:101], 0 op_sel_hi:[1,0]
	v_pk_add_f32 v[102:103], v[102:103], 0 op_sel_hi:[1,0]
	v_pk_add_f32 v[96:97], v[96:97], 0 op_sel_hi:[1,0]
	v_pk_add_f32 v[98:99], v[98:99], 0 op_sel_hi:[1,0]
	v_pk_add_f32 v[92:93], v[92:93], 0 op_sel_hi:[1,0]
	v_pk_add_f32 v[94:95], v[94:95], 0 op_sel_hi:[1,0]
	v_pk_add_f32 v[88:89], v[88:89], 0 op_sel_hi:[1,0]
	v_pk_add_f32 v[90:91], v[90:91], 0 op_sel_hi:[1,0]
	v_pk_add_f32 v[84:85], v[84:85], 0 op_sel_hi:[1,0]
	v_pk_add_f32 v[86:87], v[86:87], 0 op_sel_hi:[1,0]
	v_pk_add_f32 v[76:77], v[76:77], 0 op_sel_hi:[1,0]
	v_pk_add_f32 v[78:79], v[78:79], 0 op_sel_hi:[1,0]
	v_pk_add_f32 v[80:81], v[80:81], 0 op_sel_hi:[1,0]
	v_pk_add_f32 v[82:83], v[82:83], 0 op_sel_hi:[1,0]
	v_pk_add_f32 v[72:73], v[72:73], 0 op_sel_hi:[1,0]
	v_pk_add_f32 v[74:75], v[74:75], 0 op_sel_hi:[1,0]
	v_pk_add_f32 v[68:69], v[68:69], 0 op_sel_hi:[1,0]
	v_pk_add_f32 v[70:71], v[70:71], 0 op_sel_hi:[1,0]
	v_pk_add_f32 v[64:65], v[64:65], 0 op_sel_hi:[1,0]
	v_pk_add_f32 v[66:67], v[66:67], 0 op_sel_hi:[1,0]
	v_pk_add_f32 v[60:61], v[60:61], 0 op_sel_hi:[1,0]
	v_pk_add_f32 v[62:63], v[62:63], 0 op_sel_hi:[1,0]
	v_pk_add_f32 v[56:57], v[56:57], 0 op_sel_hi:[1,0]
	v_pk_add_f32 v[58:59], v[58:59], 0 op_sel_hi:[1,0]
	v_pk_add_f32 v[52:53], v[52:53], 0 op_sel_hi:[1,0]
	v_pk_add_f32 v[54:55], v[54:55], 0 op_sel_hi:[1,0]
	v_pk_add_f32 v[44:45], v[44:45], 0 op_sel_hi:[1,0]
	v_pk_add_f32 v[46:47], v[46:47], 0 op_sel_hi:[1,0]
	v_pk_add_f32 v[48:49], v[48:49], 0 op_sel_hi:[1,0]
	v_pk_add_f32 v[50:51], v[50:51], 0 op_sel_hi:[1,0]
	v_pk_add_f32 v[40:41], v[40:41], 0 op_sel_hi:[1,0]
	v_pk_add_f32 v[42:43], v[42:43], 0 op_sel_hi:[1,0]
	v_pk_add_f32 v[36:37], v[36:37], 0 op_sel_hi:[1,0]
	v_pk_add_f32 v[38:39], v[38:39], 0 op_sel_hi:[1,0]
	v_pk_add_f32 v[32:33], v[32:33], 0 op_sel_hi:[1,0]
	v_pk_add_f32 v[34:35], v[34:35], 0 op_sel_hi:[1,0]
	v_pk_add_f32 v[28:29], v[28:29], 0 op_sel_hi:[1,0]
	v_pk_add_f32 v[30:31], v[30:31], 0 op_sel_hi:[1,0]
	v_pk_add_f32 v[24:25], v[24:25], 0 op_sel_hi:[1,0]
	v_pk_add_f32 v[26:27], v[26:27], 0 op_sel_hi:[1,0]
	v_pk_add_f32 v[20:21], v[20:21], 0 op_sel_hi:[1,0]
	v_pk_add_f32 v[22:23], v[22:23], 0 op_sel_hi:[1,0]
	v_pk_add_f32 v[12:13], v[12:13], 0 op_sel_hi:[1,0]
	v_pk_add_f32 v[14:15], v[14:15], 0 op_sel_hi:[1,0]
	v_pk_add_f32 v[16:17], v[16:17], 0 op_sel_hi:[1,0]
	v_pk_add_f32 v[18:19], v[18:19], 0 op_sel_hi:[1,0]
	v_pk_add_f32 v[8:9], v[8:9], 0 op_sel_hi:[1,0]
	v_pk_add_f32 v[10:11], v[10:11], 0 op_sel_hi:[1,0]
	v_pk_add_f32 v[4:5], v[4:5], 0 op_sel_hi:[1,0]
	v_pk_add_f32 v[6:7], v[6:7], 0 op_sel_hi:[1,0]
	v_pk_add_f32 v[0:1], v[0:1], 0 op_sel_hi:[1,0]
	v_pk_add_f32 v[2:3], v[2:3], 0 op_sel_hi:[1,0]
	s_waitcnt vmcnt(8)
	v_mov_b32_e32 v212, v152
	v_mov_b32_e32 v213, v153
	v_mov_b32_e32 v214, v154
	v_mov_b32_e32 v215, v155
	s_nop 0
	v_mov_b32_dpp v152, v140 row_shl:8 row_mask:0xf bank_mask:0x3
	v_mov_b32_dpp v153, v141 row_shl:8 row_mask:0xf bank_mask:0x3
	v_mov_b32_dpp v154, v142 row_shl:8 row_mask:0xf bank_mask:0x3
	v_mov_b32_dpp v155, v143 row_shl:8 row_mask:0xf bank_mask:0x3
	v_mov_b32_dpp v140, v212 row_shr:8 row_mask:0xf bank_mask:0xc
	v_mov_b32_dpp v141, v213 row_shr:8 row_mask:0xf bank_mask:0xc
	v_mov_b32_dpp v142, v214 row_shr:8 row_mask:0xf bank_mask:0xc
	v_mov_b32_dpp v143, v215 row_shr:8 row_mask:0xf bank_mask:0xc
	v_mov_b32_e32 v212, v160
	v_mov_b32_e32 v213, v161
	v_mov_b32_e32 v214, v162
	v_mov_b32_e32 v215, v163
	s_nop 0
	v_mov_b32_dpp v160, v156 row_shl:8 row_mask:0xf bank_mask:0x3
	v_mov_b32_dpp v161, v157 row_shl:8 row_mask:0xf bank_mask:0x3
	v_mov_b32_dpp v162, v158 row_shl:8 row_mask:0xf bank_mask:0x3
	v_mov_b32_dpp v163, v159 row_shl:8 row_mask:0xf bank_mask:0x3
	v_mov_b32_dpp v156, v212 row_shr:8 row_mask:0xf bank_mask:0xc
	v_mov_b32_dpp v157, v213 row_shr:8 row_mask:0xf bank_mask:0xc
	v_mov_b32_dpp v158, v214 row_shr:8 row_mask:0xf bank_mask:0xc
	v_mov_b32_dpp v159, v215 row_shr:8 row_mask:0xf bank_mask:0xc
	v_mov_b32_e32 v212, v168
	v_mov_b32_e32 v213, v169
	v_mov_b32_e32 v214, v170
	v_mov_b32_e32 v215, v171
	s_nop 0
	v_mov_b32_dpp v168, v164 row_shl:8 row_mask:0xf bank_mask:0x3
	v_mov_b32_dpp v169, v165 row_shl:8 row_mask:0xf bank_mask:0x3
	v_mov_b32_dpp v170, v166 row_shl:8 row_mask:0xf bank_mask:0x3
	v_mov_b32_dpp v171, v167 row_shl:8 row_mask:0xf bank_mask:0x3
	v_mov_b32_dpp v164, v212 row_shr:8 row_mask:0xf bank_mask:0xc
	v_mov_b32_dpp v165, v213 row_shr:8 row_mask:0xf bank_mask:0xc
	v_mov_b32_dpp v166, v214 row_shr:8 row_mask:0xf bank_mask:0xc
	v_mov_b32_dpp v167, v215 row_shr:8 row_mask:0xf bank_mask:0xc
	v_mov_b32_e32 v212, v176
	v_mov_b32_e32 v213, v177
	v_mov_b32_e32 v214, v178
	v_mov_b32_e32 v215, v179
	s_nop 0
	v_mov_b32_dpp v176, v172 row_shl:8 row_mask:0xf bank_mask:0x3
	v_mov_b32_dpp v177, v173 row_shl:8 row_mask:0xf bank_mask:0x3
	v_mov_b32_dpp v178, v174 row_shl:8 row_mask:0xf bank_mask:0x3
;     __device__ __forceinline__ void operator()(AccRef acc, const Unit& u, int wr, int wc, int fr, int fq) const {
;     ...
;         for (int ai = 0; ai < 2; ++ai)
; #pragma unroll
;             for (int mh = 0; mh < 2; ++mh) {
;                 f32x4 bs[2][2][2];
; #pragma unroll
;                 for (int m = 0; m < 2; ++m)
; #pragma unroll
;                     for (int bj = 0; bj < 2; ++bj)
; #pragma unroll
;                         for (int n = 0; n < 2; ++n) bs[m][bj][n] = *(const f32x4*)(base + (size_t)(row0 + ai * 128 + (2 * mh + m) * 16) * D + col0 + bj * 128 + n * 16);
; #pragma unroll
;                 for (int m = 0; m < 2; ++m)
; #pragma unroll
;                     for (int bj = 0; bj < 2; ++bj)
; #pragma unroll
;                         for (int n = 0; n < 2; ++n) *(f32x4*)(out + (size_t)(row0 + ai * 128 + (2 * mh + m) * 16) * D + col0 + bj * 128 + n * 16) = bs[m][bj][n] + sv[bj][n] * (acc[ai][bj][2 * mh + m][n] + bv[bj][n]);
;                 asm volatile("" ::: "memory"); }
	v_mov_b32_dpp v179, v175 row_shl:8 row_mask:0xf bank_mask:0x3
	v_mov_b32_dpp v172, v212 row_shr:8 row_mask:0xf bank_mask:0xc
	v_mov_b32_dpp v173, v213 row_shr:8 row_mask:0xf bank_mask:0xc
	v_mov_b32_dpp v174, v214 row_shr:8 row_mask:0xf bank_mask:0xc
	v_mov_b32_dpp v175, v215 row_shr:8 row_mask:0xf bank_mask:0xc
	v_pk_add_f32 v[124:125], v[124:125], v[140:141]
	v_pk_add_f32 v[126:127], v[126:127], v[142:143]
	v_pk_add_f32 v[120:121], v[120:121], v[152:153]
	v_pk_add_f32 v[122:123], v[122:123], v[154:155]
	v_pk_add_f32 v[116:117], v[116:117], v[156:157]
	v_pk_add_f32 v[118:119], v[118:119], v[158:159]
	v_pk_add_f32 v[108:109], v[108:109], v[160:161]
	v_pk_add_f32 v[110:111], v[110:111], v[162:163]
	v_pk_add_f32 v[112:113], v[112:113], v[164:165]
	v_pk_add_f32 v[114:115], v[114:115], v[166:167]
	v_pk_add_f32 v[104:105], v[104:105], v[168:169]
	v_pk_add_f32 v[106:107], v[106:107], v[170:171]
	v_pk_add_f32 v[100:101], v[100:101], v[172:173]
	v_pk_add_f32 v[102:103], v[102:103], v[174:175]
	v_pk_add_f32 v[96:97], v[96:97], v[176:177]
	v_pk_add_f32 v[98:99], v[98:99], v[178:179]
	global_store_dwordx4 v145, v[124:127], s[52:53]
	global_store_dwordx4 v145, v[120:123], s[52:53] offset:64
	global_store_dwordx4 v145, v[116:119], s[52:53] offset:512
	global_store_dwordx4 v145, v[108:111], s[52:53] offset:576
	global_store_dwordx4 v216, v[112:115], s[52:53]
	global_store_dwordx4 v216, v[104:107], s[52:53] offset:64
	global_store_dwordx4 v216, v[100:103], s[52:53] offset:512
	global_store_dwordx4 v216, v[96:99], s[52:53] offset:576
	global_load_dwordx4 v[140:143], v228, s[52:53]
	v_add_u32_e32 v144, v220, v233
	global_load_dwordx4 v[152:155], v144, s[52:53]
	global_load_dwordx4 v[156:159], v228, s[52:53] offset:512
	v_add_u32_e32 v144, v220, v233
	global_load_dwordx4 v[160:163], v144, s[52:53] offset:512
	global_load_dwordx4 v[164:167], v229, s[52:53]
	v_add_u32_e32 v144, v221, v233
	global_load_dwordx4 v[168:171], v144, s[52:53]
	global_load_dwordx4 v[172:175], v229, s[52:53] offset:512
	v_add_u32_e32 v144, v221, v233
	global_load_dwordx4 v[176:179], v144, s[52:53] offset:512
	s_waitcnt vmcnt(16)
	v_mov_b32_e32 v212, v184
	v_mov_b32_e32 v213, v185
	v_mov_b32_e32 v214, v186
	v_mov_b32_e32 v215, v187
	s_nop 0
	v_mov_b32_dpp v184, v180 row_shl:8 row_mask:0xf bank_mask:0x3
	v_mov_b32_dpp v185, v181 row_shl:8 row_mask:0xf bank_mask:0x3
	v_mov_b32_dpp v186, v182 row_shl:8 row_mask:0xf bank_mask:0x3
	v_mov_b32_dpp v187, v183 row_shl:8 row_mask:0xf bank_mask:0x3
	v_mov_b32_dpp v180, v212 row_shr:8 row_mask:0xf bank_mask:0xc
	v_mov_b32_dpp v181, v213 row_shr:8 row_mask:0xf bank_mask:0xc
	v_mov_b32_dpp v182, v214 row_shr:8 row_mask:0xf bank_mask:0xc
	v_mov_b32_dpp v183, v215 row_shr:8 row_mask:0xf bank_mask:0xc
	v_mov_b32_e32 v212, v192
	v_mov_b32_e32 v213, v193
	v_mov_b32_e32 v214, v194
	v_mov_b32_e32 v215, v195
	s_nop 0
	v_mov_b32_dpp v192, v188 row_shl:8 row_mask:0xf bank_mask:0x3
	v_mov_b32_dpp v193, v189 row_shl:8 row_mask:0xf bank_mask:0x3
	v_mov_b32_dpp v194, v190 row_shl:8 row_mask:0xf bank_mask:0x3
	v_mov_b32_dpp v195, v191 row_shl:8 row_mask:0xf bank_mask:0x3
	v_mov_b32_dpp v188, v212 row_shr:8 row_mask:0xf bank_mask:0xc
	v_mov_b32_dpp v189, v213 row_shr:8 row_mask:0xf bank_mask:0xc
	v_mov_b32_dpp v190, v214 row_shr:8 row_mask:0xf bank_mask:0xc
	v_mov_b32_dpp v191, v215 row_shr:8 row_mask:0xf bank_mask:0xc
	v_mov_b32_e32 v212, v200
	v_mov_b32_e32 v213, v201
	v_mov_b32_e32 v214, v202
	v_mov_b32_e32 v215, v203
	s_nop 0
	v_mov_b32_dpp v200, v196 row_shl:8 row_mask:0xf bank_mask:0x3
	v_mov_b32_dpp v201, v197 row_shl:8 row_mask:0xf bank_mask:0x3
	v_mov_b32_dpp v202, v198 row_shl:8 row_mask:0xf bank_mask:0x3
	v_mov_b32_dpp v203, v199 row_shl:8 row_mask:0xf bank_mask:0x3
	v_mov_b32_dpp v196, v212 row_shr:8 row_mask:0xf bank_mask:0xc
	v_mov_b32_dpp v197, v213 row_shr:8 row_mask:0xf bank_mask:0xc
	v_mov_b32_dpp v198, v214 row_shr:8 row_mask:0xf bank_mask:0xc
	v_mov_b32_dpp v199, v215 row_shr:8 row_mask:0xf bank_mask:0xc
	v_mov_b32_e32 v212, v208
	v_mov_b32_e32 v213, v209
	v_mov_b32_e32 v214, v210
	v_mov_b32_e32 v215, v211
	s_nop 0
	v_mov_b32_dpp v208, v204 row_shl:8 row_mask:0xf bank_mask:0x3
	v_mov_b32_dpp v209, v205 row_shl:8 row_mask:0xf bank_mask:0x3
	v_mov_b32_dpp v210, v206 row_shl:8 row_mask:0xf bank_mask:0x3
	v_mov_b32_dpp v211, v207 row_shl:8 row_mask:0xf bank_mask:0x3
	v_mov_b32_dpp v204, v212 row_shr:8 row_mask:0xf bank_mask:0xc
	v_mov_b32_dpp v205, v213 row_shr:8 row_mask:0xf bank_mask:0xc
	v_mov_b32_dpp v206, v214 row_shr:8 row_mask:0xf bank_mask:0xc
	v_mov_b32_dpp v207, v215 row_shr:8 row_mask:0xf bank_mask:0xc
	v_pk_add_f32 v[92:93], v[92:93], v[180:181]
	v_pk_add_f32 v[94:95], v[94:95], v[182:183]
	v_pk_add_f32 v[88:89], v[88:89], v[184:185]
	v_pk_add_f32 v[90:91], v[90:91], v[186:187]
	v_pk_add_f32 v[84:85], v[84:85], v[188:189]
	v_pk_add_f32 v[86:87], v[86:87], v[190:191]
	v_pk_add_f32 v[76:77], v[76:77], v[192:193]
	v_pk_add_f32 v[78:79], v[78:79], v[194:195]
	v_pk_add_f32 v[80:81], v[80:81], v[196:197]
	v_pk_add_f32 v[82:83], v[82:83], v[198:199]
	v_pk_add_f32 v[72:73], v[72:73], v[200:201]
	v_pk_add_f32 v[74:75], v[74:75], v[202:203]
	v_pk_add_f32 v[68:69], v[68:69], v[204:205]
	v_pk_add_f32 v[70:71], v[70:71], v[206:207]
	v_pk_add_f32 v[64:65], v[64:65], v[208:209]
	v_pk_add_f32 v[66:67], v[66:67], v[210:211]
	global_store_dwordx4 v217, v[92:95], s[52:53]
	global_store_dwordx4 v217, v[88:91], s[52:53] offset:64
	global_store_dwordx4 v217, v[84:87], s[52:53] offset:512
	global_store_dwordx4 v217, v[76:79], s[52:53] offset:576
	global_store_dwordx4 v218, v[80:83], s[52:53]
	global_store_dwordx4 v218, v[72:75], s[52:53] offset:64
	global_store_dwordx4 v218, v[68:71], s[52:53] offset:512
	global_store_dwordx4 v218, v[64:67], s[52:53] offset:576
	global_load_dwordx4 v[180:183], v230, s[52:53]
	v_add_u32_e32 v144, v222, v233
	global_load_dwordx4 v[184:187], v144, s[52:53]
	global_load_dwordx4 v[188:191], v230, s[52:53] offset:512
	v_add_u32_e32 v144, v222, v233
	global_load_dwordx4 v[192:195], v144, s[52:53] offset:512
	global_load_dwordx4 v[196:199], v231, s[52:53]
	v_add_u32_e32 v144, v223, v233
	global_load_dwordx4 v[200:203], v144, s[52:53]
	global_load_dwordx4 v[204:207], v231, s[52:53] offset:512
	v_add_u32_e32 v144, v223, v233
	global_load_dwordx4 v[208:211], v144, s[52:53] offset:512
	s_waitcnt vmcnt(16)
;     __device__ __forceinline__ void operator()(AccRef acc, const Unit& u, int wr, int wc, int fr, int fq) const {
;     ...
;         for (int ai = 0; ai < 2; ++ai)
; #pragma unroll
;             for (int mh = 0; mh < 2; ++mh) {
;                 f32x4 bs[2][2][2];
; #pragma unroll
;                 for (int m = 0; m < 2; ++m)
; #pragma unroll
;                     for (int bj = 0; bj < 2; ++bj)
; #pragma unroll
;                         for (int n = 0; n < 2; ++n) bs[m][bj][n] = *(const f32x4*)(base + (size_t)(row0 + ai * 128 + (2 * mh + m) * 16) * D + col0 + bj * 128 + n * 16);
; #pragma unroll
;                 for (int m = 0; m < 2; ++m)
; #pragma unroll
;                     for (int bj = 0; bj < 2; ++bj)
; #pragma unroll
;                         for (int n = 0; n < 2; ++n) *(f32x4*)(out + (size_t)(row0 + ai * 128 + (2 * mh + m) * 16) * D + col0 + bj * 128 + n * 16) = bs[m][bj][n] + sv[bj][n] * (acc[ai][bj][2 * mh + m][n] + bv[bj][n]);
;                 asm volatile("" ::: "memory"); }
	v_mov_b32_e32 v212, v152
	v_mov_b32_e32 v213, v153
	v_mov_b32_e32 v214, v154
	v_mov_b32_e32 v215, v155
	s_nop 0
	v_mov_b32_dpp v152, v140 row_shl:8 row_mask:0xf bank_mask:0x3
	v_mov_b32_dpp v153, v141 row_shl:8 row_mask:0xf bank_mask:0x3
	v_mov_b32_dpp v154, v142 row_shl:8 row_mask:0xf bank_mask:0x3
	v_mov_b32_dpp v155, v143 row_shl:8 row_mask:0xf bank_mask:0x3
	v_mov_b32_dpp v140, v212 row_shr:8 row_mask:0xf bank_mask:0xc
	v_mov_b32_dpp v141, v213 row_shr:8 row_mask:0xf bank_mask:0xc
	v_mov_b32_dpp v142, v214 row_shr:8 row_mask:0xf bank_mask:0xc
	v_mov_b32_dpp v143, v215 row_shr:8 row_mask:0xf bank_mask:0xc
	v_mov_b32_e32 v212, v160
	v_mov_b32_e32 v213, v161
	v_mov_b32_e32 v214, v162
	v_mov_b32_e32 v215, v163
	s_nop 0
	v_mov_b32_dpp v160, v156 row_shl:8 row_mask:0xf bank_mask:0x3
	v_mov_b32_dpp v161, v157 row_shl:8 row_mask:0xf bank_mask:0x3
	v_mov_b32_dpp v162, v158 row_shl:8 row_mask:0xf bank_mask:0x3
	v_mov_b32_dpp v163, v159 row_shl:8 row_mask:0xf bank_mask:0x3
	v_mov_b32_dpp v156, v212 row_shr:8 row_mask:0xf bank_mask:0xc
	v_mov_b32_dpp v157, v213 row_shr:8 row_mask:0xf bank_mask:0xc
	v_mov_b32_dpp v158, v214 row_shr:8 row_mask:0xf bank_mask:0xc
	v_mov_b32_dpp v159, v215 row_shr:8 row_mask:0xf bank_mask:0xc
	v_mov_b32_e32 v212, v168
	v_mov_b32_e32 v213, v169
	v_mov_b32_e32 v214, v170
	v_mov_b32_e32 v215, v171
	s_nop 0
	v_mov_b32_dpp v168, v164 row_shl:8 row_mask:0xf bank_mask:0x3
	v_mov_b32_dpp v169, v165 row_shl:8 row_mask:0xf bank_mask:0x3
	v_mov_b32_dpp v170, v166 row_shl:8 row_mask:0xf bank_mask:0x3
	v_mov_b32_dpp v171, v167 row_shl:8 row_mask:0xf bank_mask:0x3
	v_mov_b32_dpp v164, v212 row_shr:8 row_mask:0xf bank_mask:0xc
	v_mov_b32_dpp v165, v213 row_shr:8 row_mask:0xf bank_mask:0xc
	v_mov_b32_dpp v166, v214 row_shr:8 row_mask:0xf bank_mask:0xc
	v_mov_b32_dpp v167, v215 row_shr:8 row_mask:0xf bank_mask:0xc
	v_mov_b32_e32 v212, v176
	v_mov_b32_e32 v213, v177
	v_mov_b32_e32 v214, v178
	v_mov_b32_e32 v215, v179
	s_nop 0
	v_mov_b32_dpp v176, v172 row_shl:8 row_mask:0xf bank_mask:0x3
	v_mov_b32_dpp v177, v173 row_shl:8 row_mask:0xf bank_mask:0x3
	v_mov_b32_dpp v178, v174 row_shl:8 row_mask:0xf bank_mask:0x3
	v_mov_b32_dpp v179, v175 row_shl:8 row_mask:0xf bank_mask:0x3
	v_mov_b32_dpp v172, v212 row_shr:8 row_mask:0xf bank_mask:0xc
	v_mov_b32_dpp v173, v213 row_shr:8 row_mask:0xf bank_mask:0xc
	v_mov_b32_dpp v174, v214 row_shr:8 row_mask:0xf bank_mask:0xc
	v_mov_b32_dpp v175, v215 row_shr:8 row_mask:0xf bank_mask:0xc
	v_pk_add_f32 v[60:61], v[60:61], v[140:141]
	v_pk_add_f32 v[62:63], v[62:63], v[142:143]
	v_pk_add_f32 v[56:57], v[56:57], v[152:153]
	v_pk_add_f32 v[58:59], v[58:59], v[154:155]
	v_pk_add_f32 v[52:53], v[52:53], v[156:157]
	v_pk_add_f32 v[54:55], v[54:55], v[158:159]
	v_pk_add_f32 v[44:45], v[44:45], v[160:161]
	v_pk_add_f32 v[46:47], v[46:47], v[162:163]
	v_pk_add_f32 v[48:49], v[48:49], v[164:165]
	v_pk_add_f32 v[50:51], v[50:51], v[166:167]
	v_pk_add_f32 v[40:41], v[40:41], v[168:169]
	v_pk_add_f32 v[42:43], v[42:43], v[170:171]
	v_pk_add_f32 v[36:37], v[36:37], v[172:173]
	v_pk_add_f32 v[38:39], v[38:39], v[174:175]
	v_pk_add_f32 v[32:33], v[32:33], v[176:177]
	v_pk_add_f32 v[34:35], v[34:35], v[178:179]
	global_store_dwordx4 v220, v[60:63], s[52:53]
	global_store_dwordx4 v220, v[56:59], s[52:53] offset:64
	global_store_dwordx4 v220, v[52:55], s[52:53] offset:512
	global_store_dwordx4 v220, v[44:47], s[52:53] offset:576
	global_store_dwordx4 v221, v[48:51], s[52:53]
	global_store_dwordx4 v221, v[40:43], s[52:53] offset:64
	global_store_dwordx4 v221, v[36:39], s[52:53] offset:512
	global_store_dwordx4 v221, v[32:35], s[52:53] offset:576
	s_waitcnt vmcnt(8)
;     __device__ __forceinline__ void operator()(AccRef acc, const Unit& u, int wr, int wc, int fr, int fq) const {
;     ...
;         for (int ai = 0; ai < 2; ++ai)
; #pragma unroll
;             for (int mh = 0; mh < 2; ++mh) {
;                 f32x4 bs[2][2][2];
; #pragma unroll
;                 for (int m = 0; m < 2; ++m)
; #pragma unroll
;                     for (int bj = 0; bj < 2; ++bj)
; #pragma unroll
;                         for (int n = 0; n < 2; ++n) bs[m][bj][n] = *(const f32x4*)(base + (size_t)(row0 + ai * 128 + (2 * mh + m) * 16) * D + col0 + bj * 128 + n * 16);
; #pragma unroll
;                 for (int m = 0; m < 2; ++m)
; #pragma unroll
;                     for (int bj = 0; bj < 2; ++bj)
; #pragma unroll
;                         for (int n = 0; n < 2; ++n) *(f32x4*)(out + (size_t)(row0 + ai * 128 + (2 * mh + m) * 16) * D + col0 + bj * 128 + n * 16) = bs[m][bj][n] + sv[bj][n] * (acc[ai][bj][2 * mh + m][n] + bv[bj][n]);
;                 asm volatile("" ::: "memory"); }
	v_mov_b32_e32 v212, v184
	v_mov_b32_e32 v213, v185
	v_mov_b32_e32 v214, v186
	v_mov_b32_e32 v215, v187
	s_nop 0
	v_mov_b32_dpp v184, v180 row_shl:8 row_mask:0xf bank_mask:0x3
	v_mov_b32_dpp v185, v181 row_shl:8 row_mask:0xf bank_mask:0x3
	v_mov_b32_dpp v186, v182 row_shl:8 row_mask:0xf bank_mask:0x3
	v_mov_b32_dpp v187, v183 row_shl:8 row_mask:0xf bank_mask:0x3
	v_mov_b32_dpp v180, v212 row_shr:8 row_mask:0xf bank_mask:0xc
	v_mov_b32_dpp v181, v213 row_shr:8 row_mask:0xf bank_mask:0xc
	v_mov_b32_dpp v182, v214 row_shr:8 row_mask:0xf bank_mask:0xc
	v_mov_b32_dpp v183, v215 row_shr:8 row_mask:0xf bank_mask:0xc
	v_mov_b32_e32 v212, v192
	v_mov_b32_e32 v213, v193
	v_mov_b32_e32 v214, v194
	v_mov_b32_e32 v215, v195
	s_nop 0
	v_mov_b32_dpp v192, v188 row_shl:8 row_mask:0xf bank_mask:0x3
	v_mov_b32_dpp v193, v189 row_shl:8 row_mask:0xf bank_mask:0x3
	v_mov_b32_dpp v194, v190 row_shl:8 row_mask:0xf bank_mask:0x3
	v_mov_b32_dpp v195, v191 row_shl:8 row_mask:0xf bank_mask:0x3
	v_mov_b32_dpp v188, v212 row_shr:8 row_mask:0xf bank_mask:0xc
	v_mov_b32_dpp v189, v213 row_shr:8 row_mask:0xf bank_mask:0xc
	v_mov_b32_dpp v190, v214 row_shr:8 row_mask:0xf bank_mask:0xc
	v_mov_b32_dpp v191, v215 row_shr:8 row_mask:0xf bank_mask:0xc
	v_mov_b32_e32 v212, v200
	v_mov_b32_e32 v213, v201
	v_mov_b32_e32 v214, v202
	v_mov_b32_e32 v215, v203
	s_nop 0
	v_mov_b32_dpp v200, v196 row_shl:8 row_mask:0xf bank_mask:0x3
	v_mov_b32_dpp v201, v197 row_shl:8 row_mask:0xf bank_mask:0x3
	v_mov_b32_dpp v202, v198 row_shl:8 row_mask:0xf bank_mask:0x3
	v_mov_b32_dpp v203, v199 row_shl:8 row_mask:0xf bank_mask:0x3
	v_mov_b32_dpp v196, v212 row_shr:8 row_mask:0xf bank_mask:0xc
	v_mov_b32_dpp v197, v213 row_shr:8 row_mask:0xf bank_mask:0xc
	v_mov_b32_dpp v198, v214 row_shr:8 row_mask:0xf bank_mask:0xc
	v_mov_b32_dpp v199, v215 row_shr:8 row_mask:0xf bank_mask:0xc
	v_mov_b32_e32 v212, v208
	v_mov_b32_e32 v213, v209
	v_mov_b32_e32 v214, v210
	v_mov_b32_e32 v215, v211
	s_nop 0
	v_mov_b32_dpp v208, v204 row_shl:8 row_mask:0xf bank_mask:0x3
	v_mov_b32_dpp v209, v205 row_shl:8 row_mask:0xf bank_mask:0x3
	v_mov_b32_dpp v210, v206 row_shl:8 row_mask:0xf bank_mask:0x3
	v_mov_b32_dpp v211, v207 row_shl:8 row_mask:0xf bank_mask:0x3
	v_mov_b32_dpp v204, v212 row_shr:8 row_mask:0xf bank_mask:0xc
	v_mov_b32_dpp v205, v213 row_shr:8 row_mask:0xf bank_mask:0xc
	v_mov_b32_dpp v206, v214 row_shr:8 row_mask:0xf bank_mask:0xc
	v_mov_b32_dpp v207, v215 row_shr:8 row_mask:0xf bank_mask:0xc
	v_pk_add_f32 v[28:29], v[28:29], v[180:181]
	v_pk_add_f32 v[30:31], v[30:31], v[182:183]
	v_pk_add_f32 v[24:25], v[24:25], v[184:185]
	v_pk_add_f32 v[26:27], v[26:27], v[186:187]
	v_pk_add_f32 v[20:21], v[20:21], v[188:189]
	v_pk_add_f32 v[22:23], v[22:23], v[190:191]
	v_pk_add_f32 v[12:13], v[12:13], v[192:193]
	v_pk_add_f32 v[14:15], v[14:15], v[194:195]
	v_pk_add_f32 v[16:17], v[16:17], v[196:197]
	v_pk_add_f32 v[18:19], v[18:19], v[198:199]
	v_pk_add_f32 v[8:9], v[8:9], v[200:201]
	v_pk_add_f32 v[10:11], v[10:11], v[202:203]
	v_pk_add_f32 v[4:5], v[4:5], v[204:205]
	v_pk_add_f32 v[6:7], v[6:7], v[206:207]
	v_pk_add_f32 v[0:1], v[0:1], v[208:209]
	v_pk_add_f32 v[2:3], v[2:3], v[210:211]
	global_store_dwordx4 v222, v[28:31], s[52:53]
	global_store_dwordx4 v222, v[24:27], s[52:53] offset:64
	global_store_dwordx4 v222, v[20:23], s[52:53] offset:512
	global_store_dwordx4 v222, v[12:15], s[52:53] offset:576
	global_store_dwordx4 v223, v[16:19], s[52:53]
	global_store_dwordx4 v223, v[8:11], s[52:53] offset:64
	global_store_dwordx4 v223, v[4:7], s[52:53] offset:512
	global_store_dwordx4 v223, v[0:3], s[52:53] offset:576
	s_cbranch_vccz .LBB0_400
	s_waitcnt vmcnt(0)
	s_cmpk_gt_u32 s4, 0xff
	s_cbranch_scc1 .LBB0_415
	s_barrier

; #define PG8_STAGE(bufoff, gbase, voff) do { _Pragma("unroll") for (int _i = 0; _i < 2; ++_i) \
;         __builtin_amdgcn_global_load_lds((const unsigned*)((const char*)(gbase) + (voff)[_i]), (LAS unsigned*)(lds + (bufoff) + ldsw + _i * 8192), 16, 0, 0); } while (0)
; #define PG8_LDA(dst, b, h) do { _Pragma("unroll") for (int m = 0; m < 4; ++m) _Pragma("unroll") for (int k = 0; k < 2; ++k) dst[m][k] = *(const LAS bf16x8*)(lds + PG8_SA(b, h) + aoff + m * 2048 + k * 1024); } while (0)
; #define PG8_LDB(dst, b, h) do { _Pragma("unroll") for (int n = 0; n < 2; ++n) _Pragma("unroll") for (int k = 0; k < 2; ++k) dst[n][k] = *(const LAS bf16x8*)(lds + PG8_SB(b, h) + boff + n * 2048 + k * 1024); } while (0)
; #define PG8_MMA(ai, bj, At, Bt) do { __builtin_amdgcn_s_setprio(1); _Pragma("unroll") for (int m = 0; m < 4; ++m) _Pragma("unroll") for (int n = 0; n < 2; ++n) _Pragma("unroll") for (int k = 0; k < 2; ++k) \
;         acc[ai][bj][m][n] = __builtin_amdgcn_mfma_f32_16x16x32_bf16(Bt[n][k], At[m][k], acc[ai][bj][m][n], 0, 0, 0); __builtin_amdgcn_s_setprio(0); } while (0)
; #define PG8_WAIT_V(n) asm volatile("s_waitcnt vmcnt(" #n ")" ::: "memory")
; #define PG8_WAIT_L(n) asm volatile("s_waitcnt lgkmcnt(" #n ")" ::: "memory")
; template <class Epi>
; __device__ __forceinline__ void gemm_phase(LAS unsigned char* lds, const Gemm g, const StaticOrder& S, const Epi& E) {
;     ...
;         for (int t = 0; t < nt; t += 2) {
;             const bool last = (t == nt - 2);
;             const char* a1 = cA + (size_t)(t + 1) * kstep;
;             const char* a2 = last ? nA : cA + (size_t)(t + 2) * kstep; const char* b2 = last ? nB : cB + (size_t)(t + 2) * kstep;
;             const char* a3 = a2 + kstep; const char* b3 = b2 + kstep;
;             PG8_LDB(B0, 0, 0); PG8_SCHED; PG8_LDA(At, 0, 0); PG8_STAGE(PG8_SA(1, 1), a1 + hstepA, voffA);
;             PG8_WAIT_L(8); PG8_BAR; PG8_WAIT_L(0); PG8_MMA(0, 0, At, B0); PG8_BAR; PG8_SCHED;
;             PG8_LDB(B1, 0, 1); PG8_STAGE(PG8_SB(0, 0), b2, voffB);
;             PG8_BAR; PG8_WAIT_L(0); PG8_MMA(0, 1, At, B1); PG8_BAR;
;             PG8_LDA(At, 0, 1); PG8_STAGE(PG8_SA(0, 0), a2, voffA);
;             PG8_BAR; PG8_WAIT_L(0); PG8_MMA(1, 0, At, B0); PG8_BAR; PG8_SCHED;
;             PG8_STAGE(PG8_SB(0, 1), b2 + hstepB, voffB);
;             PG8_WAIT_V(6); PG8_BAR; PG8_MMA(1, 1, At, B1); PG8_BAR;
.LBB0_860:
	ds_read_b128 v[140:143], v149
	ds_read_b128 v[152:155], v149 offset:1024
	ds_read_b128 v[156:159], v149 offset:2048
	ds_read_b128 v[160:163], v149 offset:3072
	s_add_u32 s30, s28, 0x100
	s_addc_u32 s31, s29, 0
	s_cmp_eq_u32 s68, 40
	s_cselect_b32 s37, s13, s31
	s_cselect_b32 s36, s12, s30
	s_cselect_b32 s35, s15, s63
	s_cselect_b32 s34, s14, s49
	v_lshl_add_u64 v[144:145], s[28:29], 0, v[132:133]
	s_add_i32 m0, s8, 0xc000
	ds_read_b128 v[164:167], v150
	ds_read_b128 v[168:171], v150 offset:1024
	ds_read_b128 v[172:175], v150 offset:2048
	ds_read_b128 v[176:179], v150 offset:3072
	ds_read_b128 v[180:183], v150 offset:4096
	ds_read_b128 v[184:187], v150 offset:5120
	ds_read_b128 v[188:191], v150 offset:6144
	ds_read_b128 v[192:195], v150 offset:7168
	global_load_lds_dwordx4 v[144:145], off
	v_lshl_add_u64 v[144:145], s[28:29], 0, v[134:135]
	s_add_i32 m0, s8, 0xe000
	s_nop 0
	global_load_lds_dwordx4 v[144:145], off
	ds_read_b128 v[196:199], v151
	ds_read_b128 v[200:203], v151 offset:1024
	ds_read_b128 v[204:207], v151 offset:2048
	ds_read_b128 v[208:211], v151 offset:3072
	s_waitcnt lgkmcnt(0)
	s_barrier
	s_setprio 1
	v_mfma_f32_16x16x32_bf16 v[124:127], v[140:143], v[164:167], v[124:127]
	v_mfma_f32_16x16x32_bf16 v[120:123], v[156:159], v[164:167], v[120:123]
	v_mfma_f32_16x16x32_bf16 v[112:115], v[140:143], v[172:175], v[112:115]
	v_mfma_f32_16x16x32_bf16 v[104:107], v[156:159], v[172:175], v[104:107]
	v_mfma_f32_16x16x32_bf16 v[92:95], v[140:143], v[180:183], v[92:95]
	v_mfma_f32_16x16x32_bf16 v[88:91], v[156:159], v[180:183], v[88:91]
	v_mfma_f32_16x16x32_bf16 v[80:83], v[140:143], v[188:191], v[80:83]
	v_mfma_f32_16x16x32_bf16 v[72:75], v[156:159], v[188:191], v[72:75]
	v_mfma_f32_16x16x32_bf16 v[124:127], v[152:155], v[168:171], v[124:127]
	v_mfma_f32_16x16x32_bf16 v[120:123], v[160:163], v[168:171], v[120:123]
	v_mfma_f32_16x16x32_bf16 v[112:115], v[152:155], v[176:179], v[112:115]
	v_mfma_f32_16x16x32_bf16 v[104:107], v[160:163], v[176:179], v[104:107]
	v_mfma_f32_16x16x32_bf16 v[92:95], v[152:155], v[184:187], v[92:95]
	v_mfma_f32_16x16x32_bf16 v[88:91], v[160:163], v[184:187], v[88:91]
	v_mfma_f32_16x16x32_bf16 v[80:83], v[152:155], v[192:195], v[80:83]
	v_mfma_f32_16x16x32_bf16 v[72:75], v[160:163], v[192:195], v[72:75]
	v_mfma_f32_16x16x32_bf16 v[116:119], v[196:199], v[164:167], v[116:119]
	v_mfma_f32_16x16x32_bf16 v[108:111], v[204:207], v[164:167], v[108:111]
	v_mfma_f32_16x16x32_bf16 v[100:103], v[196:199], v[172:175], v[100:103]
	v_mfma_f32_16x16x32_bf16 v[96:99], v[204:207], v[172:175], v[96:99]
	v_mfma_f32_16x16x32_bf16 v[84:87], v[196:199], v[180:183], v[84:87]
	v_mfma_f32_16x16x32_bf16 v[76:79], v[204:207], v[180:183], v[76:79]
	v_mfma_f32_16x16x32_bf16 v[68:71], v[196:199], v[188:191], v[68:71]
	v_mfma_f32_16x16x32_bf16 v[64:67], v[204:207], v[188:191], v[64:67]
	v_mfma_f32_16x16x32_bf16 v[116:119], v[200:203], v[168:171], v[116:119]
	v_mfma_f32_16x16x32_bf16 v[108:111], v[208:211], v[168:171], v[108:111]
	v_mfma_f32_16x16x32_bf16 v[100:103], v[200:203], v[176:179], v[100:103]
	v_mfma_f32_16x16x32_bf16 v[96:99], v[208:211], v[176:179], v[96:99]
	v_mfma_f32_16x16x32_bf16 v[84:87], v[200:203], v[184:187], v[84:87]
	v_mfma_f32_16x16x32_bf16 v[76:79], v[208:211], v[184:187], v[76:79]
	v_mfma_f32_16x16x32_bf16 v[68:71], v[200:203], v[192:195], v[68:71]
	v_mfma_f32_16x16x32_bf16 v[64:67], v[208:211], v[192:195], v[64:67]
	s_setprio 0
	s_barrier
	s_nop 1
	ds_read_b128 v[164:167], v150 offset:16384
	ds_read_b128 v[168:171], v150 offset:17408
	ds_read_b128 v[172:175], v150 offset:18432
	ds_read_b128 v[176:179], v150 offset:19456
	ds_read_b128 v[180:183], v150 offset:20480
	ds_read_b128 v[184:187], v150 offset:21504
	ds_read_b128 v[188:191], v150 offset:22528
	ds_read_b128 v[192:195], v150 offset:23552
	s_add_i32 s28, s43, s7
	v_lshl_add_u64 v[144:145], s[34:35], 0, v[128:129]
	s_mov_b32 m0, s28
	s_nop 0
	global_load_lds_dwordx4 v[144:145], off
	v_lshl_add_u64 v[212:213], s[34:35], 0, v[130:131]
	s_add_i32 m0, s28, 0x2000
	s_nop 0
	global_load_lds_dwordx4 v[212:213], off
	s_mov_b32 m0, s8
	v_lshl_add_u64 v[214:215], s[36:37], 0, v[128:129]
	global_load_lds_dwordx4 v[214:215], off
	v_lshl_add_u64 v[216:217], s[36:37], 0, v[130:131]
	s_mov_b32 m0, s9
	s_nop 0
	global_load_lds_dwordx4 v[216:217], off
	s_add_u32 s28, s34, 0xb0000
	s_addc_u32 s29, s35, 0
	s_add_i32 s69, s44, s7
	v_lshl_add_u64 v[254:255], s[28:29], 0, v[128:129]
	s_mov_b32 m0, s69
	s_nop 0
	global_load_lds_dwordx4 v[254:255], off
	v_lshl_add_u64 v[254:255], s[28:29], 0, v[130:131]
	s_add_i32 m0, s69, 0x2000
	s_nop 0
	global_load_lds_dwordx4 v[254:255], off
	s_waitcnt vmcnt(6)
	s_waitcnt lgkmcnt(0)
	s_barrier
; #define PG8_STAGE(bufoff, gbase, voff) do { _Pragma("unroll") for (int _i = 0; _i < 2; ++_i) \
;         __builtin_amdgcn_global_load_lds((const unsigned*)((const char*)(gbase) + (voff)[_i]), (LAS unsigned*)(lds + (bufoff) + ldsw + _i * 8192), 16, 0, 0); } while (0)
; #define PG8_LDA(dst, b, h) do { _Pragma("unroll") for (int m = 0; m < 4; ++m) _Pragma("unroll") for (int k = 0; k < 2; ++k) dst[m][k] = *(const LAS bf16x8*)(lds + PG8_SA(b, h) + aoff + m * 2048 + k * 1024); } while (0)
; #define PG8_LDB(dst, b, h) do { _Pragma("unroll") for (int n = 0; n < 2; ++n) _Pragma("unroll") for (int k = 0; k < 2; ++k) dst[n][k] = *(const LAS bf16x8*)(lds + PG8_SB(b, h) + boff + n * 2048 + k * 1024); } while (0)
; #define PG8_MMA(ai, bj, At, Bt) do { __builtin_amdgcn_s_setprio(1); _Pragma("unroll") for (int m = 0; m < 4; ++m) _Pragma("unroll") for (int n = 0; n < 2; ++n) _Pragma("unroll") for (int k = 0; k < 2; ++k) \
;         acc[ai][bj][m][n] = __builtin_amdgcn_mfma_f32_16x16x32_bf16(Bt[n][k], At[m][k], acc[ai][bj][m][n], 0, 0, 0); __builtin_amdgcn_s_setprio(0); } while (0)
; #define PG8_WAIT_V(n) asm volatile("s_waitcnt vmcnt(" #n ")" ::: "memory")
; #define PG8_WAIT_L(n) asm volatile("s_waitcnt lgkmcnt(" #n ")" ::: "memory")
; #define PG8_BAR __builtin_amdgcn_s_barrier()
; #define PG8_SCHED __builtin_amdgcn_sched_barrier(0)
; template <class Epi>
; __device__ __forceinline__ void gemm_phase(LAS unsigned char* lds, const Gemm g, const StaticOrder& S, const Epi& E) {
;     ...
;             PG8_WAIT_V(6); PG8_BAR; PG8_MMA(1, 1, At, B1); PG8_BAR;
;             PG8_LDB(B0, 1, 0); PG8_SCHED; PG8_LDA(At, 1, 0); PG8_STAGE(PG8_SA(0, 1), a2 + hstepA, voffA);
;             PG8_WAIT_L(8); PG8_BAR; PG8_WAIT_L(0); PG8_MMA(0, 0, At, B0); PG8_BAR; PG8_SCHED;
;             PG8_LDB(B1, 1, 1); PG8_STAGE(PG8_SB(1, 0), b3, voffB);
;             PG8_BAR; PG8_WAIT_L(0); PG8_MMA(0, 1, At, B1); PG8_BAR;
;             PG8_LDA(At, 1, 1); PG8_STAGE(PG8_SA(1, 0), a3, voffA);
;             PG8_BAR; PG8_WAIT_L(0); PG8_MMA(1, 0, At, B0); PG8_BAR; PG8_SCHED;
	s_setprio 1
	v_mfma_f32_16x16x32_bf16 v[60:63], v[140:143], v[164:167], v[60:63]
	v_mfma_f32_16x16x32_bf16 v[56:59], v[156:159], v[164:167], v[56:59]
	v_mfma_f32_16x16x32_bf16 v[48:51], v[140:143], v[172:175], v[48:51]
	v_mfma_f32_16x16x32_bf16 v[40:43], v[156:159], v[172:175], v[40:43]
	v_mfma_f32_16x16x32_bf16 v[28:31], v[140:143], v[180:183], v[28:31]
	v_mfma_f32_16x16x32_bf16 v[24:27], v[156:159], v[180:183], v[24:27]
	v_mfma_f32_16x16x32_bf16 v[16:19], v[140:143], v[188:191], v[16:19]
	v_mfma_f32_16x16x32_bf16 v[8:11], v[156:159], v[188:191], v[8:11]
	v_mfma_f32_16x16x32_bf16 v[60:63], v[152:155], v[168:171], v[60:63]
	v_mfma_f32_16x16x32_bf16 v[56:59], v[160:163], v[168:171], v[56:59]
	v_mfma_f32_16x16x32_bf16 v[48:51], v[152:155], v[176:179], v[48:51]
	v_mfma_f32_16x16x32_bf16 v[40:43], v[160:163], v[176:179], v[40:43]
	v_mfma_f32_16x16x32_bf16 v[28:31], v[152:155], v[184:187], v[28:31]
	v_mfma_f32_16x16x32_bf16 v[24:27], v[160:163], v[184:187], v[24:27]
	v_mfma_f32_16x16x32_bf16 v[16:19], v[152:155], v[192:195], v[16:19]
	v_mfma_f32_16x16x32_bf16 v[8:11], v[160:163], v[192:195], v[8:11]
	v_mfma_f32_16x16x32_bf16 v[52:55], v[196:199], v[164:167], v[52:55]
	v_mfma_f32_16x16x32_bf16 v[44:47], v[204:207], v[164:167], v[44:47]
	v_mfma_f32_16x16x32_bf16 v[36:39], v[196:199], v[172:175], v[36:39]
	v_mfma_f32_16x16x32_bf16 v[32:35], v[204:207], v[172:175], v[32:35]
	v_mfma_f32_16x16x32_bf16 v[20:23], v[196:199], v[180:183], v[20:23]
	v_mfma_f32_16x16x32_bf16 v[12:15], v[204:207], v[180:183], v[12:15]
	v_mfma_f32_16x16x32_bf16 v[4:7], v[196:199], v[188:191], v[4:7]
	v_mfma_f32_16x16x32_bf16 v[0:3], v[204:207], v[188:191], v[0:3]
	v_mfma_f32_16x16x32_bf16 v[52:55], v[200:203], v[168:171], v[52:55]
	v_mfma_f32_16x16x32_bf16 v[44:47], v[208:211], v[168:171], v[44:47]
	v_mfma_f32_16x16x32_bf16 v[36:39], v[200:203], v[176:179], v[36:39]
	v_mfma_f32_16x16x32_bf16 v[32:35], v[208:211], v[176:179], v[32:35]
	v_mfma_f32_16x16x32_bf16 v[20:23], v[200:203], v[184:187], v[20:23]
	v_mfma_f32_16x16x32_bf16 v[12:15], v[208:211], v[184:187], v[12:15]
	v_mfma_f32_16x16x32_bf16 v[4:7], v[200:203], v[192:195], v[4:7]
	v_mfma_f32_16x16x32_bf16 v[0:3], v[208:211], v[192:195], v[0:3]
	s_setprio 0
	s_add_i32 s69, 0, 0x18000
	v_add_u32_e32 v160, s69, v147
	s_barrier
	ds_read_b128 v[140:143], v160
	ds_read_b128 v[152:155], v160 offset:1024
	ds_read_b128 v[156:159], v160 offset:2048
	ds_read_b128 v[160:163], v160 offset:3072
	s_add_u32 s28, s36, 0xb0000
	s_addc_u32 s29, s37, 0
	s_mov_b32 m0, s38
	v_lshl_add_u64 v[196:197], s[28:29], 0, v[128:129]
	ds_read_b128 v[164:167], v150 offset:32768
	ds_read_b128 v[168:171], v150 offset:33792
	ds_read_b128 v[172:175], v150 offset:34816
	ds_read_b128 v[176:179], v150 offset:35840
	ds_read_b128 v[180:183], v150 offset:36864
	ds_read_b128 v[184:187], v150 offset:37888
	ds_read_b128 v[188:191], v150 offset:38912
	ds_read_b128 v[192:195], v150 offset:39936
	global_load_lds_dwordx4 v[196:197], off
	v_lshl_add_u64 v[196:197], s[28:29], 0, v[130:131]
	s_mov_b32 m0, s39
	s_nop 0
	global_load_lds_dwordx4 v[196:197], off
	s_add_i32 s36, 0, 0x1c000
	v_add_u32_e32 v208, s36, v147
	ds_read_b128 v[196:199], v208
	ds_read_b128 v[200:203], v208 offset:1024
	ds_read_b128 v[204:207], v208 offset:2048
	ds_read_b128 v[208:211], v208 offset:3072
	s_waitcnt lgkmcnt(0)
	s_barrier
	s_setprio 1
	v_mfma_f32_16x16x32_bf16 v[124:127], v[140:143], v[164:167], v[124:127]
	v_mfma_f32_16x16x32_bf16 v[120:123], v[156:159], v[164:167], v[120:123]
	v_mfma_f32_16x16x32_bf16 v[112:115], v[140:143], v[172:175], v[112:115]
	v_mfma_f32_16x16x32_bf16 v[104:107], v[156:159], v[172:175], v[104:107]
	v_mfma_f32_16x16x32_bf16 v[92:95], v[140:143], v[180:183], v[92:95]
	v_mfma_f32_16x16x32_bf16 v[88:91], v[156:159], v[180:183], v[88:91]
	v_mfma_f32_16x16x32_bf16 v[80:83], v[140:143], v[188:191], v[80:83]
	v_mfma_f32_16x16x32_bf16 v[72:75], v[156:159], v[188:191], v[72:75]
	v_mfma_f32_16x16x32_bf16 v[124:127], v[152:155], v[168:171], v[124:127]
	v_mfma_f32_16x16x32_bf16 v[120:123], v[160:163], v[168:171], v[120:123]
	v_mfma_f32_16x16x32_bf16 v[112:115], v[152:155], v[176:179], v[112:115]
	v_mfma_f32_16x16x32_bf16 v[104:107], v[160:163], v[176:179], v[104:107]
	v_mfma_f32_16x16x32_bf16 v[92:95], v[152:155], v[184:187], v[92:95]
	v_mfma_f32_16x16x32_bf16 v[88:91], v[160:163], v[184:187], v[88:91]
	v_mfma_f32_16x16x32_bf16 v[80:83], v[152:155], v[192:195], v[80:83]
	v_mfma_f32_16x16x32_bf16 v[72:75], v[160:163], v[192:195], v[72:75]
	v_mfma_f32_16x16x32_bf16 v[116:119], v[196:199], v[164:167], v[116:119]
	v_mfma_f32_16x16x32_bf16 v[108:111], v[204:207], v[164:167], v[108:111]
	v_mfma_f32_16x16x32_bf16 v[100:103], v[196:199], v[172:175], v[100:103]
	v_mfma_f32_16x16x32_bf16 v[96:99], v[204:207], v[172:175], v[96:99]
	v_mfma_f32_16x16x32_bf16 v[84:87], v[196:199], v[180:183], v[84:87]
	v_mfma_f32_16x16x32_bf16 v[76:79], v[204:207], v[180:183], v[76:79]
	v_mfma_f32_16x16x32_bf16 v[68:71], v[196:199], v[188:191], v[68:71]
	v_mfma_f32_16x16x32_bf16 v[64:67], v[204:207], v[188:191], v[64:67]
	v_mfma_f32_16x16x32_bf16 v[116:119], v[200:203], v[168:171], v[116:119]
	v_mfma_f32_16x16x32_bf16 v[108:111], v[208:211], v[168:171], v[108:111]
	v_mfma_f32_16x16x32_bf16 v[100:103], v[200:203], v[176:179], v[100:103]
	v_mfma_f32_16x16x32_bf16 v[96:99], v[208:211], v[176:179], v[96:99]
	v_mfma_f32_16x16x32_bf16 v[84:87], v[200:203], v[184:187], v[84:87]
	v_mfma_f32_16x16x32_bf16 v[76:79], v[208:211], v[184:187], v[76:79]
	v_mfma_f32_16x16x32_bf16 v[68:71], v[200:203], v[192:195], v[68:71]
	v_mfma_f32_16x16x32_bf16 v[64:67], v[208:211], v[192:195], v[64:67]
	s_setprio 0
	s_barrier
; #define PG8_STAGE(bufoff, gbase, voff) do { _Pragma("unroll") for (int _i = 0; _i < 2; ++_i) \
;         __builtin_amdgcn_global_load_lds((const unsigned*)((const char*)(gbase) + (voff)[_i]), (LAS unsigned*)(lds + (bufoff) + ldsw + _i * 8192), 16, 0, 0); } while (0)
; #define PG8_WAIT_V(n) asm volatile("s_waitcnt vmcnt(" #n ")" ::: "memory")
; template <class Epi>
; __device__ __forceinline__ void gemm_phase(LAS unsigned char* lds, const Gemm g, const StaticOrder& S, const Epi& E) {
;     ...
;             PG8_LDB(B1, 1, 1); PG8_STAGE(PG8_SB(1, 0), b3, voffB);
;             PG8_BAR; PG8_WAIT_L(0); PG8_MMA(0, 1, At, B1); PG8_BAR;
;             PG8_LDA(At, 1, 1); PG8_STAGE(PG8_SA(1, 0), a3, voffA);
;             PG8_BAR; PG8_WAIT_L(0); PG8_MMA(1, 0, At, B0); PG8_BAR; PG8_SCHED;
;             PG8_STAGE(PG8_SB(1, 1), b3 + hstepB, voffB);
;             PG8_WAIT_V(6); PG8_BAR; PG8_MMA(1, 1, At, B1); PG8_BAR;
;         }
;     __device__ __forceinline__ void operator()(AccRef acc, const Unit& u, int wr, int wc, int fr, int fq) const {
;         const int row0 = u.pm * 256 + wr * 64 + fr, col0 = u.pn * 256 + wc * 32 + 4 * fq;
;         f32x4 sv[2][2], bv[2][2];
; #pragma unroll
;         for (int bj = 0; bj < 2; ++bj)
; #pragma unroll
;             for (int n = 0; n < 2; ++n) {
;                 sv[bj][n] = scale ? *(const f32x4*)(scale + col0 + bj * 128 + n * 16) : (f32x4){1.f, 1.f, 1.f, 1.f};
;                 bv[bj][n] = bias ? *(const f32x4*)(bias + col0 + bj * 128 + n * 16) : (f32x4){0.f, 0.f, 0.f, 0.f}; }
; #pragma unroll
;         for (int ai = 0; ai < 2; ++ai)
; #pragma unroll
;             for (int mh = 0; mh < 2; ++mh) {
;                 f32x4 bs[2][2][2];
; #pragma unroll
;                 for (int m = 0; m < 2; ++m)
; #pragma unroll
;                     for (int bj = 0; bj < 2; ++bj)
; #pragma unroll
;                         for (int n = 0; n < 2; ++n) bs[m][bj][n] = *(const f32x4*)(base + (size_t)(row0 + ai * 128 + (2 * mh + m) * 16) * D + col0 + bj * 128 + n * 16);
; #pragma unroll
;                 for (int m = 0; m < 2; ++m)
; #pragma unroll
;                     for (int bj = 0; bj < 2; ++bj)
; #pragma unroll
;                         for (int n = 0; n < 2; ++n) *(f32x4*)(out + (size_t)(row0 + ai * 128 + (2 * mh + m) * 16) * D + col0 + bj * 128 + n * 16) = bs[m][bj][n] + sv[bj][n] * (acc[ai][bj][2 * mh + m][n] + bv[bj][n]);
	s_nop 1
	ds_read_b128 v[164:167], v150 offset:49152
	ds_read_b128 v[168:171], v150 offset:50176
	ds_read_b128 v[172:175], v150 offset:51200
	ds_read_b128 v[176:179], v150 offset:52224
	ds_read_b128 v[180:183], v150 offset:53248
	ds_read_b128 v[184:187], v150 offset:54272
	ds_read_b128 v[188:191], v150 offset:55296
	ds_read_b128 v[192:195], v150 offset:56320
	s_add_i32 s28, s69, s7
	v_lshl_add_u64 v[254:255], v[144:145], 0, s[20:21]
	s_mov_b32 m0, s28
	s_nop 0
	global_load_lds_dwordx4 v[254:255], off
	v_lshl_add_u64 v[254:255], v[212:213], 0, s[20:21]
	s_add_i32 m0, s28, 0x2000
	s_nop 0
	global_load_lds_dwordx4 v[254:255], off
	s_mov_b32 m0, s41
	v_lshl_add_u64 v[254:255], v[214:215], 0, s[20:21]
	global_load_lds_dwordx4 v[254:255], off
	v_lshl_add_u64 v[144:145], v[216:217], 0, s[20:21]
	s_mov_b32 m0, s42
	s_nop 0
	global_load_lds_dwordx4 v[144:145], off
	s_add_u32 s28, s34, 0xb0080
	s_addc_u32 s29, s35, 0
	s_add_i32 s34, s36, s7
	v_lshl_add_u64 v[254:255], s[28:29], 0, v[128:129]
	s_mov_b32 m0, s34
	s_nop 0
	global_load_lds_dwordx4 v[254:255], off
	v_lshl_add_u64 v[254:255], s[28:29], 0, v[130:131]
	s_add_i32 m0, s34, 0x2000
	s_nop 0
	global_load_lds_dwordx4 v[254:255], off
	s_waitcnt vmcnt(6)
	s_waitcnt lgkmcnt(0)
	s_barrier
	s_setprio 1
	v_mfma_f32_16x16x32_bf16 v[60:63], v[140:143], v[164:167], v[60:63]
	v_mfma_f32_16x16x32_bf16 v[56:59], v[156:159], v[164:167], v[56:59]
	v_mfma_f32_16x16x32_bf16 v[48:51], v[140:143], v[172:175], v[48:51]
	v_mfma_f32_16x16x32_bf16 v[40:43], v[156:159], v[172:175], v[40:43]
	v_mfma_f32_16x16x32_bf16 v[28:31], v[140:143], v[180:183], v[28:31]
	v_mfma_f32_16x16x32_bf16 v[24:27], v[156:159], v[180:183], v[24:27]
	v_mfma_f32_16x16x32_bf16 v[16:19], v[140:143], v[188:191], v[16:19]
	v_mfma_f32_16x16x32_bf16 v[8:11], v[156:159], v[188:191], v[8:11]
	v_mfma_f32_16x16x32_bf16 v[60:63], v[152:155], v[168:171], v[60:63]
	v_mfma_f32_16x16x32_bf16 v[56:59], v[160:163], v[168:171], v[56:59]
	v_mfma_f32_16x16x32_bf16 v[48:51], v[152:155], v[176:179], v[48:51]
	v_mfma_f32_16x16x32_bf16 v[40:43], v[160:163], v[176:179], v[40:43]
	v_mfma_f32_16x16x32_bf16 v[28:31], v[152:155], v[184:187], v[28:31]
	v_mfma_f32_16x16x32_bf16 v[24:27], v[160:163], v[184:187], v[24:27]
	v_mfma_f32_16x16x32_bf16 v[16:19], v[152:155], v[192:195], v[16:19]
	v_mfma_f32_16x16x32_bf16 v[8:11], v[160:163], v[192:195], v[8:11]
	v_mfma_f32_16x16x32_bf16 v[52:55], v[196:199], v[164:167], v[52:55]
	v_mfma_f32_16x16x32_bf16 v[44:47], v[204:207], v[164:167], v[44:47]
	v_mfma_f32_16x16x32_bf16 v[36:39], v[196:199], v[172:175], v[36:39]
	v_mfma_f32_16x16x32_bf16 v[32:35], v[204:207], v[172:175], v[32:35]
	v_mfma_f32_16x16x32_bf16 v[20:23], v[196:199], v[180:183], v[20:23]
	v_mfma_f32_16x16x32_bf16 v[12:15], v[204:207], v[180:183], v[12:15]
	v_mfma_f32_16x16x32_bf16 v[4:7], v[196:199], v[188:191], v[4:7]
	v_mfma_f32_16x16x32_bf16 v[0:3], v[204:207], v[188:191], v[0:3]
	v_mfma_f32_16x16x32_bf16 v[52:55], v[200:203], v[168:171], v[52:55]
	v_mfma_f32_16x16x32_bf16 v[44:47], v[208:211], v[168:171], v[44:47]
	v_mfma_f32_16x16x32_bf16 v[36:39], v[200:203], v[176:179], v[36:39]
	v_mfma_f32_16x16x32_bf16 v[32:35], v[208:211], v[176:179], v[32:35]
	v_mfma_f32_16x16x32_bf16 v[20:23], v[200:203], v[184:187], v[20:23]
	v_mfma_f32_16x16x32_bf16 v[12:15], v[208:211], v[184:187], v[12:15]
	v_mfma_f32_16x16x32_bf16 v[4:7], v[200:203], v[192:195], v[4:7]
	v_mfma_f32_16x16x32_bf16 v[0:3], v[208:211], v[192:195], v[0:3]
	s_setprio 0
	s_add_i32 s68, s68, 2
	s_add_u32 s49, s49, 0x100
	s_addc_u32 s63, s63, 0
	s_cmp_gt_u32 s68, 41
	s_mov_b64 s[28:29], s[30:31]
	s_barrier
	s_cbranch_scc0 .LBB0_860
	v_lshl_or_b32 v144, s47, 8, v148
	v_lshl_add_u32 v145, s48, 8, v146
	v_lshlrev_b32_e32 v144, 2, v144
	v_lshl_add_u32 v145, v145, 12, v144
	v_add_u32_e32 v216, 0x10000, v145
	v_add_u32_e32 v217, 0x20000, v145
	v_add_u32_e32 v218, 0x30000, v145
	v_add_u32_e32 v220, 0x80000, v145
	v_add_u32_e32 v221, 0x90000, v145
	v_add_u32_e32 v222, 0xa0000, v145
	v_add_u32_e32 v223, 0xb0000, v145
	v_and_b32_e32 v235, 8, v146
	v_cmp_ne_u32_e32 vcc, 0, v235
	v_mov_b32_e32 v232, 0xffff8040
	s_nop 0
	v_cndmask_b32_e32 v232, 0, v232, vcc
	v_mov_b32_e32 v233, 64
	v_mov_b32_e32 v235, 0x8000
	v_cndmask_b32_e32 v233, v235, v233, vcc
	v_add_u32_e32 v224, v145, v232
	v_add_u32_e32 v225, v216, v232
	v_add_u32_e32 v226, v217, v232
	v_add_u32_e32 v227, v218, v232
	v_add_u32_e32 v228, v220, v232
	v_add_u32_e32 v229, v221, v232
	v_add_u32_e32 v230, v222, v232
	v_add_u32_e32 v231, v223, v232
	s_and_b64 vcc, exec, s[10:11]
	s_mov_b32 s47, s45
	s_mov_b32 s48, s46
	s_mov_b64 s[30:31], s[14:15]
	s_mov_b64 s[28:29], s[12:13]
	global_load_dwordx4 v[140:143], v224, s[52:53]
	v_add_u32_e32 v144, v145, v233
	global_load_dwordx4 v[152:155], v144, s[52:53]
	global_load_dwordx4 v[156:159], v224, s[52:53] offset:512
	v_add_u32_e32 v144, v145, v233
	global_load_dwordx4 v[160:163], v144, s[52:53] offset:512
	global_load_dwordx4 v[164:167], v225, s[52:53]
	v_add_u32_e32 v144, v216, v233
	global_load_dwordx4 v[168:171], v144, s[52:53]
	global_load_dwordx4 v[172:175], v225, s[52:53] offset:512
	v_add_u32_e32 v144, v216, v233
	global_load_dwordx4 v[176:179], v144, s[52:53] offset:512
	global_load_dwordx4 v[180:183], v226, s[52:53]
	v_add_u32_e32 v144, v217, v233
	global_load_dwordx4 v[184:187], v144, s[52:53]
	global_load_dwordx4 v[188:191], v226, s[52:53] offset:512
	v_add_u32_e32 v144, v217, v233
	global_load_dwordx4 v[192:195], v144, s[52:53] offset:512
	global_load_dwordx4 v[196:199], v227, s[52:53]
	v_add_u32_e32 v144, v218, v233
	global_load_dwordx4 v[200:203], v144, s[52:53]
	global_load_dwordx4 v[204:207], v227, s[52:53] offset:512
;     __device__ __forceinline__ void operator()(AccRef acc, const Unit& u, int wr, int wc, int fr, int fq) const {
;     ...
;                 sv[bj][n] = scale ? *(const f32x4*)(scale + col0 + bj * 128 + n * 16) : (f32x4){1.f, 1.f, 1.f, 1.f};
;                 bv[bj][n] = bias ? *(const f32x4*)(bias + col0 + bj * 128 + n * 16) : (f32x4){0.f, 0.f, 0.f, 0.f}; }
; #pragma unroll
;         for (int ai = 0; ai < 2; ++ai)
; #pragma unroll
;             for (int mh = 0; mh < 2; ++mh) {
;                 f32x4 bs[2][2][2];
; #pragma unroll
;                 for (int m = 0; m < 2; ++m)
; #pragma unroll
;                     for (int bj = 0; bj < 2; ++bj)
; #pragma unroll
;                         for (int n = 0; n < 2; ++n) bs[m][bj][n] = *(const f32x4*)(base + (size_t)(row0 + ai * 128 + (2 * mh + m) * 16) * D + col0 + bj * 128 + n * 16);
; #pragma unroll
;                 for (int m = 0; m < 2; ++m)
; #pragma unroll
;                     for (int bj = 0; bj < 2; ++bj)
; #pragma unroll
;                         for (int n = 0; n < 2; ++n) *(f32x4*)(out + (size_t)(row0 + ai * 128 + (2 * mh + m) * 16) * D + col0 + bj * 128 + n * 16) = bs[m][bj][n] + sv[bj][n] * (acc[ai][bj][2 * mh + m][n] + bv[bj][n]);
	v_add_u32_e32 v144, v218, v233
	global_load_dwordx4 v[208:211], v144, s[52:53] offset:512
	v_pk_add_f32 v[124:125], v[124:125], 0 op_sel_hi:[1,0]
	v_pk_add_f32 v[126:127], v[126:127], 0 op_sel_hi:[1,0]
	v_pk_add_f32 v[120:121], v[120:121], 0 op_sel_hi:[1,0]
	v_pk_add_f32 v[122:123], v[122:123], 0 op_sel_hi:[1,0]
	v_pk_add_f32 v[116:117], v[116:117], 0 op_sel_hi:[1,0]
	v_pk_add_f32 v[118:119], v[118:119], 0 op_sel_hi:[1,0]
	v_pk_add_f32 v[108:109], v[108:109], 0 op_sel_hi:[1,0]
	v_pk_add_f32 v[110:111], v[110:111], 0 op_sel_hi:[1,0]
	v_pk_add_f32 v[112:113], v[112:113], 0 op_sel_hi:[1,0]
	v_pk_add_f32 v[114:115], v[114:115], 0 op_sel_hi:[1,0]
	v_pk_add_f32 v[104:105], v[104:105], 0 op_sel_hi:[1,0]
	v_pk_add_f32 v[106:107], v[106:107], 0 op_sel_hi:[1,0]
	v_pk_add_f32 v[100:101], v[100:101], 0 op_sel_hi:[1,0]
	v_pk_add_f32 v[102:103], v[102:103], 0 op_sel_hi:[1,0]
	v_pk_add_f32 v[96:97], v[96:97], 0 op_sel_hi:[1,0]
	v_pk_add_f32 v[98:99], v[98:99], 0 op_sel_hi:[1,0]
	v_pk_add_f32 v[92:93], v[92:93], 0 op_sel_hi:[1,0]
	v_pk_add_f32 v[94:95], v[94:95], 0 op_sel_hi:[1,0]
	v_pk_add_f32 v[88:89], v[88:89], 0 op_sel_hi:[1,0]
	v_pk_add_f32 v[90:91], v[90:91], 0 op_sel_hi:[1,0]
	v_pk_add_f32 v[84:85], v[84:85], 0 op_sel_hi:[1,0]
	v_pk_add_f32 v[86:87], v[86:87], 0 op_sel_hi:[1,0]
	v_pk_add_f32 v[76:77], v[76:77], 0 op_sel_hi:[1,0]
	v_pk_add_f32 v[78:79], v[78:79], 0 op_sel_hi:[1,0]
	v_pk_add_f32 v[80:81], v[80:81], 0 op_sel_hi:[1,0]
	v_pk_add_f32 v[82:83], v[82:83], 0 op_sel_hi:[1,0]
	v_pk_add_f32 v[72:73], v[72:73], 0 op_sel_hi:[1,0]
	v_pk_add_f32 v[74:75], v[74:75], 0 op_sel_hi:[1,0]
	v_pk_add_f32 v[68:69], v[68:69], 0 op_sel_hi:[1,0]
	v_pk_add_f32 v[70:71], v[70:71], 0 op_sel_hi:[1,0]
	v_pk_add_f32 v[64:65], v[64:65], 0 op_sel_hi:[1,0]
	v_pk_add_f32 v[66:67], v[66:67], 0 op_sel_hi:[1,0]
	v_pk_add_f32 v[60:61], v[60:61], 0 op_sel_hi:[1,0]
	v_pk_add_f32 v[62:63], v[62:63], 0 op_sel_hi:[1,0]
	v_pk_add_f32 v[56:57], v[56:57], 0 op_sel_hi:[1,0]
	v_pk_add_f32 v[58:59], v[58:59], 0 op_sel_hi:[1,0]
	v_pk_add_f32 v[52:53], v[52:53], 0 op_sel_hi:[1,0]
	v_pk_add_f32 v[54:55], v[54:55], 0 op_sel_hi:[1,0]
	v_pk_add_f32 v[44:45], v[44:45], 0 op_sel_hi:[1,0]
	v_pk_add_f32 v[46:47], v[46:47], 0 op_sel_hi:[1,0]
	v_pk_add_f32 v[48:49], v[48:49], 0 op_sel_hi:[1,0]
	v_pk_add_f32 v[50:51], v[50:51], 0 op_sel_hi:[1,0]
	v_pk_add_f32 v[40:41], v[40:41], 0 op_sel_hi:[1,0]
	v_pk_add_f32 v[42:43], v[42:43], 0 op_sel_hi:[1,0]
	v_pk_add_f32 v[36:37], v[36:37], 0 op_sel_hi:[1,0]
	v_pk_add_f32 v[38:39], v[38:39], 0 op_sel_hi:[1,0]
	v_pk_add_f32 v[32:33], v[32:33], 0 op_sel_hi:[1,0]
	v_pk_add_f32 v[34:35], v[34:35], 0 op_sel_hi:[1,0]
	v_pk_add_f32 v[28:29], v[28:29], 0 op_sel_hi:[1,0]
	v_pk_add_f32 v[30:31], v[30:31], 0 op_sel_hi:[1,0]
	v_pk_add_f32 v[24:25], v[24:25], 0 op_sel_hi:[1,0]
	v_pk_add_f32 v[26:27], v[26:27], 0 op_sel_hi:[1,0]
	v_pk_add_f32 v[20:21], v[20:21], 0 op_sel_hi:[1,0]
	v_pk_add_f32 v[22:23], v[22:23], 0 op_sel_hi:[1,0]
	v_pk_add_f32 v[12:13], v[12:13], 0 op_sel_hi:[1,0]
	v_pk_add_f32 v[14:15], v[14:15], 0 op_sel_hi:[1,0]
	v_pk_add_f32 v[16:17], v[16:17], 0 op_sel_hi:[1,0]
	v_pk_add_f32 v[18:19], v[18:19], 0 op_sel_hi:[1,0]
	v_pk_add_f32 v[8:9], v[8:9], 0 op_sel_hi:[1,0]
	v_pk_add_f32 v[10:11], v[10:11], 0 op_sel_hi:[1,0]
	v_pk_add_f32 v[4:5], v[4:5], 0 op_sel_hi:[1,0]
	v_pk_add_f32 v[6:7], v[6:7], 0 op_sel_hi:[1,0]
	v_pk_add_f32 v[0:1], v[0:1], 0 op_sel_hi:[1,0]
	v_pk_add_f32 v[2:3], v[2:3], 0 op_sel_hi:[1,0]
	s_waitcnt vmcnt(8)
	v_mov_b32_e32 v212, v152
	v_mov_b32_e32 v213, v153
	v_mov_b32_e32 v214, v154
	v_mov_b32_e32 v215, v155
	s_nop 0
	v_mov_b32_dpp v152, v140 row_shl:8 row_mask:0xf bank_mask:0x3
	v_mov_b32_dpp v153, v141 row_shl:8 row_mask:0xf bank_mask:0x3
	v_mov_b32_dpp v154, v142 row_shl:8 row_mask:0xf bank_mask:0x3
	v_mov_b32_dpp v155, v143 row_shl:8 row_mask:0xf bank_mask:0x3
	v_mov_b32_dpp v140, v212 row_shr:8 row_mask:0xf bank_mask:0xc
	v_mov_b32_dpp v141, v213 row_shr:8 row_mask:0xf bank_mask:0xc
	v_mov_b32_dpp v142, v214 row_shr:8 row_mask:0xf bank_mask:0xc
	v_mov_b32_dpp v143, v215 row_shr:8 row_mask:0xf bank_mask:0xc
	v_mov_b32_e32 v212, v160
	v_mov_b32_e32 v213, v161
	v_mov_b32_e32 v214, v162
	v_mov_b32_e32 v215, v163
	s_nop 0
	v_mov_b32_dpp v160, v156 row_shl:8 row_mask:0xf bank_mask:0x3
	v_mov_b32_dpp v161, v157 row_shl:8 row_mask:0xf bank_mask:0x3
	v_mov_b32_dpp v162, v158 row_shl:8 row_mask:0xf bank_mask:0x3
	v_mov_b32_dpp v163, v159 row_shl:8 row_mask:0xf bank_mask:0x3
	v_mov_b32_dpp v156, v212 row_shr:8 row_mask:0xf bank_mask:0xc
	v_mov_b32_dpp v157, v213 row_shr:8 row_mask:0xf bank_mask:0xc
	v_mov_b32_dpp v158, v214 row_shr:8 row_mask:0xf bank_mask:0xc
	v_mov_b32_dpp v159, v215 row_shr:8 row_mask:0xf bank_mask:0xc
	v_mov_b32_e32 v212, v168
	v_mov_b32_e32 v213, v169
	v_mov_b32_e32 v214, v170
	v_mov_b32_e32 v215, v171
	s_nop 0
	v_mov_b32_dpp v168, v164 row_shl:8 row_mask:0xf bank_mask:0x3
	v_mov_b32_dpp v169, v165 row_shl:8 row_mask:0xf bank_mask:0x3
	v_mov_b32_dpp v170, v166 row_shl:8 row_mask:0xf bank_mask:0x3
	v_mov_b32_dpp v171, v167 row_shl:8 row_mask:0xf bank_mask:0x3
	v_mov_b32_dpp v164, v212 row_shr:8 row_mask:0xf bank_mask:0xc
	v_mov_b32_dpp v165, v213 row_shr:8 row_mask:0xf bank_mask:0xc
	v_mov_b32_dpp v166, v214 row_shr:8 row_mask:0xf bank_mask:0xc
	v_mov_b32_dpp v167, v215 row_shr:8 row_mask:0xf bank_mask:0xc
	v_mov_b32_e32 v212, v176
	v_mov_b32_e32 v213, v177
	v_mov_b32_e32 v214, v178
	v_mov_b32_e32 v215, v179
	s_nop 0
	v_mov_b32_dpp v176, v172 row_shl:8 row_mask:0xf bank_mask:0x3
	v_mov_b32_dpp v177, v173 row_shl:8 row_mask:0xf bank_mask:0x3
	v_mov_b32_dpp v178, v174 row_shl:8 row_mask:0xf bank_mask:0x3
;     __device__ __forceinline__ void operator()(AccRef acc, const Unit& u, int wr, int wc, int fr, int fq) const {
;     ...
;                         for (int n = 0; n < 2; ++n) bs[m][bj][n] = *(const f32x4*)(base + (size_t)(row0 + ai * 128 + (2 * mh + m) * 16) * D + col0 + bj * 128 + n * 16);
; #pragma unroll
;                 for (int m = 0; m < 2; ++m)
; #pragma unroll
;                     for (int bj = 0; bj < 2; ++bj)
; #pragma unroll
;                         for (int n = 0; n < 2; ++n) *(f32x4*)(out + (size_t)(row0 + ai * 128 + (2 * mh + m) * 16) * D + col0 + bj * 128 + n * 16) = bs[m][bj][n] + sv[bj][n] * (acc[ai][bj][2 * mh + m][n] + bv[bj][n]);
;                 asm volatile("" ::: "memory"); }
	v_mov_b32_dpp v179, v175 row_shl:8 row_mask:0xf bank_mask:0x3
	v_mov_b32_dpp v172, v212 row_shr:8 row_mask:0xf bank_mask:0xc
	v_mov_b32_dpp v173, v213 row_shr:8 row_mask:0xf bank_mask:0xc
	v_mov_b32_dpp v174, v214 row_shr:8 row_mask:0xf bank_mask:0xc
	v_mov_b32_dpp v175, v215 row_shr:8 row_mask:0xf bank_mask:0xc
	v_pk_add_f32 v[124:125], v[124:125], v[140:141]
	v_pk_add_f32 v[126:127], v[126:127], v[142:143]
	v_pk_add_f32 v[120:121], v[120:121], v[152:153]
	v_pk_add_f32 v[122:123], v[122:123], v[154:155]
	v_pk_add_f32 v[116:117], v[116:117], v[156:157]
	v_pk_add_f32 v[118:119], v[118:119], v[158:159]
	v_pk_add_f32 v[108:109], v[108:109], v[160:161]
	v_pk_add_f32 v[110:111], v[110:111], v[162:163]
	v_pk_add_f32 v[112:113], v[112:113], v[164:165]
	v_pk_add_f32 v[114:115], v[114:115], v[166:167]
	v_pk_add_f32 v[104:105], v[104:105], v[168:169]
	v_pk_add_f32 v[106:107], v[106:107], v[170:171]
	v_pk_add_f32 v[100:101], v[100:101], v[172:173]
	v_pk_add_f32 v[102:103], v[102:103], v[174:175]
	v_pk_add_f32 v[96:97], v[96:97], v[176:177]
	v_pk_add_f32 v[98:99], v[98:99], v[178:179]
	global_store_dwordx4 v145, v[124:127], s[52:53]
	global_store_dwordx4 v145, v[120:123], s[52:53] offset:64
	global_store_dwordx4 v145, v[116:119], s[52:53] offset:512
	global_store_dwordx4 v145, v[108:111], s[52:53] offset:576
	global_store_dwordx4 v216, v[112:115], s[52:53]
	global_store_dwordx4 v216, v[104:107], s[52:53] offset:64
	global_store_dwordx4 v216, v[100:103], s[52:53] offset:512
	global_store_dwordx4 v216, v[96:99], s[52:53] offset:576
	global_load_dwordx4 v[140:143], v228, s[52:53]
	v_add_u32_e32 v144, v220, v233
	global_load_dwordx4 v[152:155], v144, s[52:53]
	global_load_dwordx4 v[156:159], v228, s[52:53] offset:512
	v_add_u32_e32 v144, v220, v233
	global_load_dwordx4 v[160:163], v144, s[52:53] offset:512
	global_load_dwordx4 v[164:167], v229, s[52:53]
	v_add_u32_e32 v144, v221, v233
	global_load_dwordx4 v[168:171], v144, s[52:53]
	global_load_dwordx4 v[172:175], v229, s[52:53] offset:512
	v_add_u32_e32 v144, v221, v233
	global_load_dwordx4 v[176:179], v144, s[52:53] offset:512
	s_waitcnt vmcnt(16)
	v_mov_b32_e32 v212, v184
	v_mov_b32_e32 v213, v185
	v_mov_b32_e32 v214, v186
	v_mov_b32_e32 v215, v187
	s_nop 0
	v_mov_b32_dpp v184, v180 row_shl:8 row_mask:0xf bank_mask:0x3
	v_mov_b32_dpp v185, v181 row_shl:8 row_mask:0xf bank_mask:0x3
	v_mov_b32_dpp v186, v182 row_shl:8 row_mask:0xf bank_mask:0x3
	v_mov_b32_dpp v187, v183 row_shl:8 row_mask:0xf bank_mask:0x3
	v_mov_b32_dpp v180, v212 row_shr:8 row_mask:0xf bank_mask:0xc
	v_mov_b32_dpp v181, v213 row_shr:8 row_mask:0xf bank_mask:0xc
	v_mov_b32_dpp v182, v214 row_shr:8 row_mask:0xf bank_mask:0xc
	v_mov_b32_dpp v183, v215 row_shr:8 row_mask:0xf bank_mask:0xc
	v_mov_b32_e32 v212, v192
	v_mov_b32_e32 v213, v193
	v_mov_b32_e32 v214, v194
	v_mov_b32_e32 v215, v195
	s_nop 0
	v_mov_b32_dpp v192, v188 row_shl:8 row_mask:0xf bank_mask:0x3
	v_mov_b32_dpp v193, v189 row_shl:8 row_mask:0xf bank_mask:0x3
	v_mov_b32_dpp v194, v190 row_shl:8 row_mask:0xf bank_mask:0x3
	v_mov_b32_dpp v195, v191 row_shl:8 row_mask:0xf bank_mask:0x3
	v_mov_b32_dpp v188, v212 row_shr:8 row_mask:0xf bank_mask:0xc
	v_mov_b32_dpp v189, v213 row_shr:8 row_mask:0xf bank_mask:0xc
	v_mov_b32_dpp v190, v214 row_shr:8 row_mask:0xf bank_mask:0xc
	v_mov_b32_dpp v191, v215 row_shr:8 row_mask:0xf bank_mask:0xc
	v_mov_b32_e32 v212, v200
	v_mov_b32_e32 v213, v201
	v_mov_b32_e32 v214, v202
	v_mov_b32_e32 v215, v203
	s_nop 0
	v_mov_b32_dpp v200, v196 row_shl:8 row_mask:0xf bank_mask:0x3
	v_mov_b32_dpp v201, v197 row_shl:8 row_mask:0xf bank_mask:0x3
	v_mov_b32_dpp v202, v198 row_shl:8 row_mask:0xf bank_mask:0x3
	v_mov_b32_dpp v203, v199 row_shl:8 row_mask:0xf bank_mask:0x3
	v_mov_b32_dpp v196, v212 row_shr:8 row_mask:0xf bank_mask:0xc
	v_mov_b32_dpp v197, v213 row_shr:8 row_mask:0xf bank_mask:0xc
	v_mov_b32_dpp v198, v214 row_shr:8 row_mask:0xf bank_mask:0xc
	v_mov_b32_dpp v199, v215 row_shr:8 row_mask:0xf bank_mask:0xc
	v_mov_b32_e32 v212, v208
	v_mov_b32_e32 v213, v209
	v_mov_b32_e32 v214, v210
	v_mov_b32_e32 v215, v211
	s_nop 0
	v_mov_b32_dpp v208, v204 row_shl:8 row_mask:0xf bank_mask:0x3
	v_mov_b32_dpp v209, v205 row_shl:8 row_mask:0xf bank_mask:0x3
	v_mov_b32_dpp v210, v206 row_shl:8 row_mask:0xf bank_mask:0x3
	v_mov_b32_dpp v211, v207 row_shl:8 row_mask:0xf bank_mask:0x3
	v_mov_b32_dpp v204, v212 row_shr:8 row_mask:0xf bank_mask:0xc
	v_mov_b32_dpp v205, v213 row_shr:8 row_mask:0xf bank_mask:0xc
	v_mov_b32_dpp v206, v214 row_shr:8 row_mask:0xf bank_mask:0xc
	v_mov_b32_dpp v207, v215 row_shr:8 row_mask:0xf bank_mask:0xc
	v_pk_add_f32 v[92:93], v[92:93], v[180:181]
	v_pk_add_f32 v[94:95], v[94:95], v[182:183]
	v_pk_add_f32 v[88:89], v[88:89], v[184:185]
	v_pk_add_f32 v[90:91], v[90:91], v[186:187]
	v_pk_add_f32 v[84:85], v[84:85], v[188:189]
	v_pk_add_f32 v[86:87], v[86:87], v[190:191]
	v_pk_add_f32 v[76:77], v[76:77], v[192:193]
	v_pk_add_f32 v[78:79], v[78:79], v[194:195]
	v_pk_add_f32 v[80:81], v[80:81], v[196:197]
	v_pk_add_f32 v[82:83], v[82:83], v[198:199]
	v_pk_add_f32 v[72:73], v[72:73], v[200:201]
	v_pk_add_f32 v[74:75], v[74:75], v[202:203]
	v_pk_add_f32 v[68:69], v[68:69], v[204:205]
	v_pk_add_f32 v[70:71], v[70:71], v[206:207]
	v_pk_add_f32 v[64:65], v[64:65], v[208:209]
	v_pk_add_f32 v[66:67], v[66:67], v[210:211]
	global_store_dwordx4 v217, v[92:95], s[52:53]
	global_store_dwordx4 v217, v[88:91], s[52:53] offset:64
	global_store_dwordx4 v217, v[84:87], s[52:53] offset:512
	global_store_dwordx4 v217, v[76:79], s[52:53] offset:576
	global_store_dwordx4 v218, v[80:83], s[52:53]
	global_store_dwordx4 v218, v[72:75], s[52:53] offset:64
	global_store_dwordx4 v218, v[68:71], s[52:53] offset:512
	global_store_dwordx4 v218, v[64:67], s[52:53] offset:576
	global_load_dwordx4 v[180:183], v230, s[52:53]
	v_add_u32_e32 v144, v222, v233
	global_load_dwordx4 v[184:187], v144, s[52:53]
	global_load_dwordx4 v[188:191], v230, s[52:53] offset:512
	v_add_u32_e32 v144, v222, v233
	global_load_dwordx4 v[192:195], v144, s[52:53] offset:512
	global_load_dwordx4 v[196:199], v231, s[52:53]
	v_add_u32_e32 v144, v223, v233
	global_load_dwordx4 v[200:203], v144, s[52:53]
	global_load_dwordx4 v[204:207], v231, s[52:53] offset:512
	v_add_u32_e32 v144, v223, v233
	global_load_dwordx4 v[208:211], v144, s[52:53] offset:512
	s_waitcnt vmcnt(16)
;     __device__ __forceinline__ void operator()(AccRef acc, const Unit& u, int wr, int wc, int fr, int fq) const {
;     ...
;                         for (int n = 0; n < 2; ++n) bs[m][bj][n] = *(const f32x4*)(base + (size_t)(row0 + ai * 128 + (2 * mh + m) * 16) * D + col0 + bj * 128 + n * 16);
; #pragma unroll
;                 for (int m = 0; m < 2; ++m)
; #pragma unroll
;                     for (int bj = 0; bj < 2; ++bj)
; #pragma unroll
;                         for (int n = 0; n < 2; ++n) *(f32x4*)(out + (size_t)(row0 + ai * 128 + (2 * mh + m) * 16) * D + col0 + bj * 128 + n * 16) = bs[m][bj][n] + sv[bj][n] * (acc[ai][bj][2 * mh + m][n] + bv[bj][n]);
	v_mov_b32_e32 v212, v152
	v_mov_b32_e32 v213, v153
	v_mov_b32_e32 v214, v154
	v_mov_b32_e32 v215, v155
	s_nop 0
	v_mov_b32_dpp v152, v140 row_shl:8 row_mask:0xf bank_mask:0x3
	v_mov_b32_dpp v153, v141 row_shl:8 row_mask:0xf bank_mask:0x3
	v_mov_b32_dpp v154, v142 row_shl:8 row_mask:0xf bank_mask:0x3
	v_mov_b32_dpp v155, v143 row_shl:8 row_mask:0xf bank_mask:0x3
	v_mov_b32_dpp v140, v212 row_shr:8 row_mask:0xf bank_mask:0xc
	v_mov_b32_dpp v141, v213 row_shr:8 row_mask:0xf bank_mask:0xc
	v_mov_b32_dpp v142, v214 row_shr:8 row_mask:0xf bank_mask:0xc
	v_mov_b32_dpp v143, v215 row_shr:8 row_mask:0xf bank_mask:0xc
	v_mov_b32_e32 v212, v160
	v_mov_b32_e32 v213, v161
	v_mov_b32_e32 v214, v162
	v_mov_b32_e32 v215, v163
	s_nop 0
	v_mov_b32_dpp v160, v156 row_shl:8 row_mask:0xf bank_mask:0x3
	v_mov_b32_dpp v161, v157 row_shl:8 row_mask:0xf bank_mask:0x3
	v_mov_b32_dpp v162, v158 row_shl:8 row_mask:0xf bank_mask:0x3
	v_mov_b32_dpp v163, v159 row_shl:8 row_mask:0xf bank_mask:0x3
	v_mov_b32_dpp v156, v212 row_shr:8 row_mask:0xf bank_mask:0xc
	v_mov_b32_dpp v157, v213 row_shr:8 row_mask:0xf bank_mask:0xc
	v_mov_b32_dpp v158, v214 row_shr:8 row_mask:0xf bank_mask:0xc
	v_mov_b32_dpp v159, v215 row_shr:8 row_mask:0xf bank_mask:0xc
	v_mov_b32_e32 v212, v168
	v_mov_b32_e32 v213, v169
	v_mov_b32_e32 v214, v170
	v_mov_b32_e32 v215, v171
	s_nop 0
	v_mov_b32_dpp v168, v164 row_shl:8 row_mask:0xf bank_mask:0x3
	v_mov_b32_dpp v169, v165 row_shl:8 row_mask:0xf bank_mask:0x3
	v_mov_b32_dpp v170, v166 row_shl:8 row_mask:0xf bank_mask:0x3
	v_mov_b32_dpp v171, v167 row_shl:8 row_mask:0xf bank_mask:0x3
	v_mov_b32_dpp v164, v212 row_shr:8 row_mask:0xf bank_mask:0xc
	v_mov_b32_dpp v165, v213 row_shr:8 row_mask:0xf bank_mask:0xc
	v_mov_b32_dpp v166, v214 row_shr:8 row_mask:0xf bank_mask:0xc
	v_mov_b32_dpp v167, v215 row_shr:8 row_mask:0xf bank_mask:0xc
	v_mov_b32_e32 v212, v176
	v_mov_b32_e32 v213, v177
	v_mov_b32_e32 v214, v178
	v_mov_b32_e32 v215, v179
	s_nop 0
	v_mov_b32_dpp v176, v172 row_shl:8 row_mask:0xf bank_mask:0x3
	v_mov_b32_dpp v177, v173 row_shl:8 row_mask:0xf bank_mask:0x3
	v_mov_b32_dpp v178, v174 row_shl:8 row_mask:0xf bank_mask:0x3
	v_mov_b32_dpp v179, v175 row_shl:8 row_mask:0xf bank_mask:0x3
	v_mov_b32_dpp v172, v212 row_shr:8 row_mask:0xf bank_mask:0xc
	v_mov_b32_dpp v173, v213 row_shr:8 row_mask:0xf bank_mask:0xc
	v_mov_b32_dpp v174, v214 row_shr:8 row_mask:0xf bank_mask:0xc
	v_mov_b32_dpp v175, v215 row_shr:8 row_mask:0xf bank_mask:0xc
	v_pk_add_f32 v[60:61], v[60:61], v[140:141]
	v_pk_add_f32 v[62:63], v[62:63], v[142:143]
	v_pk_add_f32 v[56:57], v[56:57], v[152:153]
	v_pk_add_f32 v[58:59], v[58:59], v[154:155]
	v_pk_add_f32 v[52:53], v[52:53], v[156:157]
	v_pk_add_f32 v[54:55], v[54:55], v[158:159]
	v_pk_add_f32 v[44:45], v[44:45], v[160:161]
	v_pk_add_f32 v[46:47], v[46:47], v[162:163]
	v_pk_add_f32 v[48:49], v[48:49], v[164:165]
	v_pk_add_f32 v[50:51], v[50:51], v[166:167]
	v_pk_add_f32 v[40:41], v[40:41], v[168:169]
	v_pk_add_f32 v[42:43], v[42:43], v[170:171]
	v_pk_add_f32 v[36:37], v[36:37], v[172:173]
	v_pk_add_f32 v[38:39], v[38:39], v[174:175]
	v_pk_add_f32 v[32:33], v[32:33], v[176:177]
	v_pk_add_f32 v[34:35], v[34:35], v[178:179]
	global_store_dwordx4 v220, v[60:63], s[52:53]
	global_store_dwordx4 v220, v[56:59], s[52:53] offset:64
	global_store_dwordx4 v220, v[52:55], s[52:53] offset:512
	global_store_dwordx4 v220, v[44:47], s[52:53] offset:576
	global_store_dwordx4 v221, v[48:51], s[52:53]
	global_store_dwordx4 v221, v[40:43], s[52:53] offset:64
	global_store_dwordx4 v221, v[36:39], s[52:53] offset:512
	global_store_dwordx4 v221, v[32:35], s[52:53] offset:576
	s_waitcnt vmcnt(8)
; #define PG8_WAIT_V(n) asm volatile("s_waitcnt vmcnt(" #n ")" ::: "memory")
; #define PG8_BAR __builtin_amdgcn_s_barrier()
; template <class Epi>
; __device__ __forceinline__ void gemm_phase(LAS unsigned char* lds, const Gemm g, const StaticOrder& S, const Epi& E) {
;     ...
;         if (!has_next) break;
;         {
; #pragma unroll
;         for (int a = 0; a < 2; ++a)
; #pragma unroll
;             for (int b = 0; b < 2; ++b)
; #pragma unroll
;                 for (int m = 0; m < 4; ++m)
; #pragma unroll
;                     for (int n = 0; n < 2; ++n) acc[a][b][m][n] = (f32x4){0.f, 0.f, 0.f, 0.f};
;         }
;         cur = nxt; cA = nA; cB = nB; ++ui;
;     }
;     PG8_WAIT_V(0);
;     if (wr == 0) PG8_BAR;
;     PG8_BAR;
;     __device__ __forceinline__ void operator()(AccRef acc, const Unit& u, int wr, int wc, int fr, int fq) const {
;     ...
;                         for (int n = 0; n < 2; ++n) bs[m][bj][n] = *(const f32x4*)(base + (size_t)(row0 + ai * 128 + (2 * mh + m) * 16) * D + col0 + bj * 128 + n * 16);
; #pragma unroll
;                 for (int m = 0; m < 2; ++m)
; #pragma unroll
;                     for (int bj = 0; bj < 2; ++bj)
; #pragma unroll
;                         for (int n = 0; n < 2; ++n) *(f32x4*)(out + (size_t)(row0 + ai * 128 + (2 * mh + m) * 16) * D + col0 + bj * 128 + n * 16) = bs[m][bj][n] + sv[bj][n] * (acc[ai][bj][2 * mh + m][n] + bv[bj][n]);
;                 asm volatile("" ::: "memory"); }
	v_mov_b32_e32 v212, v184
	v_mov_b32_e32 v213, v185
	v_mov_b32_e32 v214, v186
	v_mov_b32_e32 v215, v187
	s_nop 0
	v_mov_b32_dpp v184, v180 row_shl:8 row_mask:0xf bank_mask:0x3
	v_mov_b32_dpp v185, v181 row_shl:8 row_mask:0xf bank_mask:0x3
	v_mov_b32_dpp v186, v182 row_shl:8 row_mask:0xf bank_mask:0x3
	v_mov_b32_dpp v187, v183 row_shl:8 row_mask:0xf bank_mask:0x3
	v_mov_b32_dpp v180, v212 row_shr:8 row_mask:0xf bank_mask:0xc
	v_mov_b32_dpp v181, v213 row_shr:8 row_mask:0xf bank_mask:0xc
	v_mov_b32_dpp v182, v214 row_shr:8 row_mask:0xf bank_mask:0xc
	v_mov_b32_dpp v183, v215 row_shr:8 row_mask:0xf bank_mask:0xc
	v_mov_b32_e32 v212, v192
	v_mov_b32_e32 v213, v193
	v_mov_b32_e32 v214, v194
	v_mov_b32_e32 v215, v195
	s_nop 0
	v_mov_b32_dpp v192, v188 row_shl:8 row_mask:0xf bank_mask:0x3
	v_mov_b32_dpp v193, v189 row_shl:8 row_mask:0xf bank_mask:0x3
	v_mov_b32_dpp v194, v190 row_shl:8 row_mask:0xf bank_mask:0x3
	v_mov_b32_dpp v195, v191 row_shl:8 row_mask:0xf bank_mask:0x3
	v_mov_b32_dpp v188, v212 row_shr:8 row_mask:0xf bank_mask:0xc
	v_mov_b32_dpp v189, v213 row_shr:8 row_mask:0xf bank_mask:0xc
	v_mov_b32_dpp v190, v214 row_shr:8 row_mask:0xf bank_mask:0xc
	v_mov_b32_dpp v191, v215 row_shr:8 row_mask:0xf bank_mask:0xc
	v_mov_b32_e32 v212, v200
	v_mov_b32_e32 v213, v201
	v_mov_b32_e32 v214, v202
	v_mov_b32_e32 v215, v203
	s_nop 0
	v_mov_b32_dpp v200, v196 row_shl:8 row_mask:0xf bank_mask:0x3
	v_mov_b32_dpp v201, v197 row_shl:8 row_mask:0xf bank_mask:0x3
	v_mov_b32_dpp v202, v198 row_shl:8 row_mask:0xf bank_mask:0x3
	v_mov_b32_dpp v203, v199 row_shl:8 row_mask:0xf bank_mask:0x3
	v_mov_b32_dpp v196, v212 row_shr:8 row_mask:0xf bank_mask:0xc
	v_mov_b32_dpp v197, v213 row_shr:8 row_mask:0xf bank_mask:0xc
	v_mov_b32_dpp v198, v214 row_shr:8 row_mask:0xf bank_mask:0xc
	v_mov_b32_dpp v199, v215 row_shr:8 row_mask:0xf bank_mask:0xc
	v_mov_b32_e32 v212, v208
	v_mov_b32_e32 v213, v209
	v_mov_b32_e32 v214, v210
	v_mov_b32_e32 v215, v211
	s_nop 0
	v_mov_b32_dpp v208, v204 row_shl:8 row_mask:0xf bank_mask:0x3
	v_mov_b32_dpp v209, v205 row_shl:8 row_mask:0xf bank_mask:0x3
	v_mov_b32_dpp v210, v206 row_shl:8 row_mask:0xf bank_mask:0x3
	v_mov_b32_dpp v211, v207 row_shl:8 row_mask:0xf bank_mask:0x3
	v_mov_b32_dpp v204, v212 row_shr:8 row_mask:0xf bank_mask:0xc
	v_mov_b32_dpp v205, v213 row_shr:8 row_mask:0xf bank_mask:0xc
	v_mov_b32_dpp v206, v214 row_shr:8 row_mask:0xf bank_mask:0xc
	v_mov_b32_dpp v207, v215 row_shr:8 row_mask:0xf bank_mask:0xc
	v_pk_add_f32 v[28:29], v[28:29], v[180:181]
	v_pk_add_f32 v[30:31], v[30:31], v[182:183]
	v_pk_add_f32 v[24:25], v[24:25], v[184:185]
	v_pk_add_f32 v[26:27], v[26:27], v[186:187]
	v_pk_add_f32 v[20:21], v[20:21], v[188:189]
	v_pk_add_f32 v[22:23], v[22:23], v[190:191]
	v_pk_add_f32 v[12:13], v[12:13], v[192:193]
	v_pk_add_f32 v[14:15], v[14:15], v[194:195]
	v_pk_add_f32 v[16:17], v[16:17], v[196:197]
	v_pk_add_f32 v[18:19], v[18:19], v[198:199]
	v_pk_add_f32 v[8:9], v[8:9], v[200:201]
	v_pk_add_f32 v[10:11], v[10:11], v[202:203]
	v_pk_add_f32 v[4:5], v[4:5], v[204:205]
	v_pk_add_f32 v[6:7], v[6:7], v[206:207]
	v_pk_add_f32 v[0:1], v[0:1], v[208:209]
	v_pk_add_f32 v[2:3], v[2:3], v[210:211]
	global_store_dwordx4 v222, v[28:31], s[52:53]
	global_store_dwordx4 v222, v[24:27], s[52:53] offset:64
	global_store_dwordx4 v222, v[20:23], s[52:53] offset:512
	global_store_dwordx4 v222, v[12:15], s[52:53] offset:576
	global_store_dwordx4 v223, v[16:19], s[52:53]
	global_store_dwordx4 v223, v[8:11], s[52:53] offset:64
	global_store_dwordx4 v223, v[4:7], s[52:53] offset:512
	global_store_dwordx4 v223, v[0:3], s[52:53] offset:576
	s_cbranch_vccz .LBB0_849
	s_waitcnt vmcnt(0)
	s_cmpk_gt_u32 s4, 0xff
	s_cbranch_scc1 .LBB0_864
	s_barrier

; #define PG8_STAGE(bufoff, gbase, voff) do { _Pragma("unroll") for (int _i = 0; _i < 2; ++_i) \
;         __builtin_amdgcn_global_load_lds((const unsigned*)((const char*)(gbase) + (voff)[_i]), (LAS unsigned*)(lds + (bufoff) + ldsw + _i * 8192), 16, 0, 0); } while (0)
; #define PG8_LDA(dst, b, h) do { _Pragma("unroll") for (int m = 0; m < 4; ++m) _Pragma("unroll") for (int k = 0; k < 2; ++k) dst[m][k] = *(const LAS bf16x8*)(lds + PG8_SA(b, h) + aoff + m * 2048 + k * 1024); } while (0)
; #define PG8_LDB(dst, b, h) do { _Pragma("unroll") for (int n = 0; n < 2; ++n) _Pragma("unroll") for (int k = 0; k < 2; ++k) dst[n][k] = *(const LAS bf16x8*)(lds + PG8_SB(b, h) + boff + n * 2048 + k * 1024); } while (0)
; #define PG8_MMA(ai, bj, At, Bt) do { __builtin_amdgcn_s_setprio(1); _Pragma("unroll") for (int m = 0; m < 4; ++m) _Pragma("unroll") for (int n = 0; n < 2; ++n) _Pragma("unroll") for (int k = 0; k < 2; ++k) \
;         acc[ai][bj][m][n] = __builtin_amdgcn_mfma_f32_16x16x32_bf16(Bt[n][k], At[m][k], acc[ai][bj][m][n], 0, 0, 0); __builtin_amdgcn_s_setprio(0); } while (0)
; #define PG8_WAIT_V(n) asm volatile("s_waitcnt vmcnt(" #n ")" ::: "memory")
; #define PG8_WAIT_L(n) asm volatile("s_waitcnt lgkmcnt(" #n ")" ::: "memory")
; template <class Epi>
; __device__ __forceinline__ void gemm_phase(LAS unsigned char* lds, const Gemm g, const StaticOrder& S, const Epi& E) {
;     ...
;         for (int t = 0; t < nt; t += 2) {
;             const bool last = (t == nt - 2);
;             const char* a1 = cA + (size_t)(t + 1) * kstep;
;             const char* a2 = last ? nA : cA + (size_t)(t + 2) * kstep; const char* b2 = last ? nB : cB + (size_t)(t + 2) * kstep;
;             const char* a3 = a2 + kstep; const char* b3 = b2 + kstep;
;             PG8_LDB(B0, 0, 0); PG8_SCHED; PG8_LDA(At, 0, 0); PG8_STAGE(PG8_SA(1, 1), a1 + hstepA, voffA);
;             PG8_WAIT_L(8); PG8_BAR; PG8_WAIT_L(0); PG8_MMA(0, 0, At, B0); PG8_BAR; PG8_SCHED;
;             PG8_LDB(B1, 0, 1); PG8_STAGE(PG8_SB(0, 0), b2, voffB);
;             PG8_BAR; PG8_WAIT_L(0); PG8_MMA(0, 1, At, B1); PG8_BAR;
;             PG8_LDA(At, 0, 1); PG8_STAGE(PG8_SA(0, 0), a2, voffA);
;             PG8_BAR; PG8_WAIT_L(0); PG8_MMA(1, 0, At, B0); PG8_BAR; PG8_SCHED;
;             PG8_STAGE(PG8_SB(0, 1), b2 + hstepB, voffB);
;             PG8_WAIT_V(6); PG8_BAR; PG8_MMA(1, 1, At, B1); PG8_BAR;
.LBB0_1239:
	ds_read_b128 v[140:143], v149
	ds_read_b128 v[152:155], v149 offset:1024
	ds_read_b128 v[156:159], v149 offset:2048
	ds_read_b128 v[160:163], v149 offset:3072
	s_add_u32 s40, s38, 0xfffc0080
	s_addc_u32 s41, s39, -1
	s_cmp_eq_u32 s76, 12
	s_cselect_b32 s43, s29, s41
	s_cselect_b32 s42, s72, s40
	s_cselect_b32 s41, s27, s75
	s_cselect_b32 s40, s73, s74
	v_lshl_add_u64 v[144:145], s[38:39], 0, v[132:133]
	s_add_i32 m0, s8, 0xc000
	ds_read_b128 v[164:167], v150
	ds_read_b128 v[168:171], v150 offset:1024
	ds_read_b128 v[172:175], v150 offset:2048
	ds_read_b128 v[176:179], v150 offset:3072
	ds_read_b128 v[180:183], v150 offset:4096
	ds_read_b128 v[184:187], v150 offset:5120
	ds_read_b128 v[188:191], v150 offset:6144
	ds_read_b128 v[192:195], v150 offset:7168
	global_load_lds_dwordx4 v[144:145], off
	v_lshl_add_u64 v[144:145], s[38:39], 0, v[134:135]
	s_add_i32 m0, s8, 0xe000
	s_nop 0
	global_load_lds_dwordx4 v[144:145], off
	ds_read_b128 v[196:199], v151
	ds_read_b128 v[200:203], v151 offset:1024
	ds_read_b128 v[204:207], v151 offset:2048
	ds_read_b128 v[208:211], v151 offset:3072
	s_waitcnt lgkmcnt(0)
	s_barrier
	s_setprio 1
	v_mfma_f32_16x16x32_bf16 v[124:127], v[140:143], v[164:167], v[124:127]
	v_mfma_f32_16x16x32_bf16 v[120:123], v[156:159], v[164:167], v[120:123]
	v_mfma_f32_16x16x32_bf16 v[112:115], v[140:143], v[172:175], v[112:115]
	v_mfma_f32_16x16x32_bf16 v[104:107], v[156:159], v[172:175], v[104:107]
	v_mfma_f32_16x16x32_bf16 v[92:95], v[140:143], v[180:183], v[92:95]
	v_mfma_f32_16x16x32_bf16 v[88:91], v[156:159], v[180:183], v[88:91]
	v_mfma_f32_16x16x32_bf16 v[80:83], v[140:143], v[188:191], v[80:83]
	v_mfma_f32_16x16x32_bf16 v[72:75], v[156:159], v[188:191], v[72:75]
	v_mfma_f32_16x16x32_bf16 v[124:127], v[152:155], v[168:171], v[124:127]
	v_mfma_f32_16x16x32_bf16 v[120:123], v[160:163], v[168:171], v[120:123]
	v_mfma_f32_16x16x32_bf16 v[112:115], v[152:155], v[176:179], v[112:115]
	v_mfma_f32_16x16x32_bf16 v[104:107], v[160:163], v[176:179], v[104:107]
	v_mfma_f32_16x16x32_bf16 v[92:95], v[152:155], v[184:187], v[92:95]
	v_mfma_f32_16x16x32_bf16 v[88:91], v[160:163], v[184:187], v[88:91]
	v_mfma_f32_16x16x32_bf16 v[80:83], v[152:155], v[192:195], v[80:83]
	v_mfma_f32_16x16x32_bf16 v[72:75], v[160:163], v[192:195], v[72:75]
	v_mfma_f32_16x16x32_bf16 v[116:119], v[196:199], v[164:167], v[116:119]
	v_mfma_f32_16x16x32_bf16 v[108:111], v[204:207], v[164:167], v[108:111]
	v_mfma_f32_16x16x32_bf16 v[100:103], v[196:199], v[172:175], v[100:103]
	v_mfma_f32_16x16x32_bf16 v[96:99], v[204:207], v[172:175], v[96:99]
	v_mfma_f32_16x16x32_bf16 v[84:87], v[196:199], v[180:183], v[84:87]
	v_mfma_f32_16x16x32_bf16 v[76:79], v[204:207], v[180:183], v[76:79]
	v_mfma_f32_16x16x32_bf16 v[68:71], v[196:199], v[188:191], v[68:71]
	v_mfma_f32_16x16x32_bf16 v[64:67], v[204:207], v[188:191], v[64:67]
	v_mfma_f32_16x16x32_bf16 v[116:119], v[200:203], v[168:171], v[116:119]
	v_mfma_f32_16x16x32_bf16 v[108:111], v[208:211], v[168:171], v[108:111]
	v_mfma_f32_16x16x32_bf16 v[100:103], v[200:203], v[176:179], v[100:103]
	v_mfma_f32_16x16x32_bf16 v[96:99], v[208:211], v[176:179], v[96:99]
	v_mfma_f32_16x16x32_bf16 v[84:87], v[200:203], v[184:187], v[84:87]
	v_mfma_f32_16x16x32_bf16 v[76:79], v[208:211], v[184:187], v[76:79]
	v_mfma_f32_16x16x32_bf16 v[68:71], v[200:203], v[192:195], v[68:71]
	v_mfma_f32_16x16x32_bf16 v[64:67], v[208:211], v[192:195], v[64:67]
	s_setprio 0
	s_barrier
	s_nop 1
	ds_read_b128 v[164:167], v150 offset:16384
	ds_read_b128 v[168:171], v150 offset:17408
	ds_read_b128 v[172:175], v150 offset:18432
	ds_read_b128 v[176:179], v150 offset:19456
	ds_read_b128 v[180:183], v150 offset:20480
	ds_read_b128 v[184:187], v150 offset:21504
	ds_read_b128 v[188:191], v150 offset:22528
	ds_read_b128 v[192:195], v150 offset:23552
	s_add_i32 s77, s48, s7
	v_lshl_add_u64 v[144:145], s[40:41], 0, v[128:129]
	s_mov_b32 m0, s77
	s_nop 0
	global_load_lds_dwordx4 v[144:145], off
	v_lshl_add_u64 v[212:213], s[40:41], 0, v[130:131]
	s_add_i32 m0, s77, 0x2000
	s_nop 0
	global_load_lds_dwordx4 v[212:213], off
	s_mov_b32 m0, s8
	v_lshl_add_u64 v[214:215], s[42:43], 0, v[128:129]
	global_load_lds_dwordx4 v[214:215], off
	v_lshl_add_u64 v[216:217], s[42:43], 0, v[130:131]
	s_mov_b32 m0, s9
	s_nop 0
	global_load_lds_dwordx4 v[216:217], off
	s_add_u32 s78, s40, 0x40000
	s_addc_u32 s79, s41, 0
	s_add_i32 s77, s49, s7
	v_lshl_add_u64 v[254:255], s[78:79], 0, v[128:129]
	s_mov_b32 m0, s77
	s_nop 0
	global_load_lds_dwordx4 v[254:255], off
	v_lshl_add_u64 v[254:255], s[78:79], 0, v[130:131]
	s_add_i32 m0, s77, 0x2000
	s_nop 0
	global_load_lds_dwordx4 v[254:255], off
	s_waitcnt vmcnt(6)
	s_waitcnt lgkmcnt(0)
	s_barrier
; #define PG8_STAGE(bufoff, gbase, voff) do { _Pragma("unroll") for (int _i = 0; _i < 2; ++_i) \
;         __builtin_amdgcn_global_load_lds((const unsigned*)((const char*)(gbase) + (voff)[_i]), (LAS unsigned*)(lds + (bufoff) + ldsw + _i * 8192), 16, 0, 0); } while (0)
; #define PG8_LDA(dst, b, h) do { _Pragma("unroll") for (int m = 0; m < 4; ++m) _Pragma("unroll") for (int k = 0; k < 2; ++k) dst[m][k] = *(const LAS bf16x8*)(lds + PG8_SA(b, h) + aoff + m * 2048 + k * 1024); } while (0)
; #define PG8_LDB(dst, b, h) do { _Pragma("unroll") for (int n = 0; n < 2; ++n) _Pragma("unroll") for (int k = 0; k < 2; ++k) dst[n][k] = *(const LAS bf16x8*)(lds + PG8_SB(b, h) + boff + n * 2048 + k * 1024); } while (0)
; #define PG8_MMA(ai, bj, At, Bt) do { __builtin_amdgcn_s_setprio(1); _Pragma("unroll") for (int m = 0; m < 4; ++m) _Pragma("unroll") for (int n = 0; n < 2; ++n) _Pragma("unroll") for (int k = 0; k < 2; ++k) \
;         acc[ai][bj][m][n] = __builtin_amdgcn_mfma_f32_16x16x32_bf16(Bt[n][k], At[m][k], acc[ai][bj][m][n], 0, 0, 0); __builtin_amdgcn_s_setprio(0); } while (0)
; #define PG8_WAIT_V(n) asm volatile("s_waitcnt vmcnt(" #n ")" ::: "memory")
; #define PG8_WAIT_L(n) asm volatile("s_waitcnt lgkmcnt(" #n ")" ::: "memory")
; #define PG8_BAR __builtin_amdgcn_s_barrier()
; #define PG8_SCHED __builtin_amdgcn_sched_barrier(0)
; template <class Epi>
; __device__ __forceinline__ void gemm_phase(LAS unsigned char* lds, const Gemm g, const StaticOrder& S, const Epi& E) {
;     ...
;             PG8_WAIT_V(6); PG8_BAR; PG8_MMA(1, 1, At, B1); PG8_BAR;
;             PG8_LDB(B0, 1, 0); PG8_SCHED; PG8_LDA(At, 1, 0); PG8_STAGE(PG8_SA(0, 1), a2 + hstepA, voffA);
;             PG8_WAIT_L(8); PG8_BAR; PG8_WAIT_L(0); PG8_MMA(0, 0, At, B0); PG8_BAR; PG8_SCHED;
;             PG8_LDB(B1, 1, 1); PG8_STAGE(PG8_SB(1, 0), b3, voffB);
;             PG8_BAR; PG8_WAIT_L(0); PG8_MMA(0, 1, At, B1); PG8_BAR;
;             PG8_LDA(At, 1, 1); PG8_STAGE(PG8_SA(1, 0), a3, voffA);
;             PG8_BAR; PG8_WAIT_L(0); PG8_MMA(1, 0, At, B0); PG8_BAR; PG8_SCHED;
	s_setprio 1
	v_mfma_f32_16x16x32_bf16 v[60:63], v[140:143], v[164:167], v[60:63]
	v_mfma_f32_16x16x32_bf16 v[56:59], v[156:159], v[164:167], v[56:59]
	v_mfma_f32_16x16x32_bf16 v[48:51], v[140:143], v[172:175], v[48:51]
	v_mfma_f32_16x16x32_bf16 v[40:43], v[156:159], v[172:175], v[40:43]
	v_mfma_f32_16x16x32_bf16 v[28:31], v[140:143], v[180:183], v[28:31]
	v_mfma_f32_16x16x32_bf16 v[24:27], v[156:159], v[180:183], v[24:27]
	v_mfma_f32_16x16x32_bf16 v[16:19], v[140:143], v[188:191], v[16:19]
	v_mfma_f32_16x16x32_bf16 v[8:11], v[156:159], v[188:191], v[8:11]
	v_mfma_f32_16x16x32_bf16 v[60:63], v[152:155], v[168:171], v[60:63]
	v_mfma_f32_16x16x32_bf16 v[56:59], v[160:163], v[168:171], v[56:59]
	v_mfma_f32_16x16x32_bf16 v[48:51], v[152:155], v[176:179], v[48:51]
	v_mfma_f32_16x16x32_bf16 v[40:43], v[160:163], v[176:179], v[40:43]
	v_mfma_f32_16x16x32_bf16 v[28:31], v[152:155], v[184:187], v[28:31]
	v_mfma_f32_16x16x32_bf16 v[24:27], v[160:163], v[184:187], v[24:27]
	v_mfma_f32_16x16x32_bf16 v[16:19], v[152:155], v[192:195], v[16:19]
	v_mfma_f32_16x16x32_bf16 v[8:11], v[160:163], v[192:195], v[8:11]
	v_mfma_f32_16x16x32_bf16 v[52:55], v[196:199], v[164:167], v[52:55]
	v_mfma_f32_16x16x32_bf16 v[44:47], v[204:207], v[164:167], v[44:47]
	v_mfma_f32_16x16x32_bf16 v[36:39], v[196:199], v[172:175], v[36:39]
	v_mfma_f32_16x16x32_bf16 v[32:35], v[204:207], v[172:175], v[32:35]
	v_mfma_f32_16x16x32_bf16 v[20:23], v[196:199], v[180:183], v[20:23]
	v_mfma_f32_16x16x32_bf16 v[12:15], v[204:207], v[180:183], v[12:15]
	v_mfma_f32_16x16x32_bf16 v[4:7], v[196:199], v[188:191], v[4:7]
	v_mfma_f32_16x16x32_bf16 v[0:3], v[204:207], v[188:191], v[0:3]
	v_mfma_f32_16x16x32_bf16 v[52:55], v[200:203], v[168:171], v[52:55]
	v_mfma_f32_16x16x32_bf16 v[44:47], v[208:211], v[168:171], v[44:47]
	v_mfma_f32_16x16x32_bf16 v[36:39], v[200:203], v[176:179], v[36:39]
	v_mfma_f32_16x16x32_bf16 v[32:35], v[208:211], v[176:179], v[32:35]
	v_mfma_f32_16x16x32_bf16 v[20:23], v[200:203], v[184:187], v[20:23]
	v_mfma_f32_16x16x32_bf16 v[12:15], v[208:211], v[184:187], v[12:15]
	v_mfma_f32_16x16x32_bf16 v[4:7], v[200:203], v[192:195], v[4:7]
	v_mfma_f32_16x16x32_bf16 v[0:3], v[208:211], v[192:195], v[0:3]
	s_setprio 0
	s_add_i32 s77, 0, 0x18000
	v_add_u32_e32 v160, s77, v147
	s_barrier
	ds_read_b128 v[140:143], v160
	ds_read_b128 v[152:155], v160 offset:1024
	ds_read_b128 v[156:159], v160 offset:2048
	ds_read_b128 v[160:163], v160 offset:3072
	s_add_u32 s42, s42, 0x40000
	s_addc_u32 s43, s43, 0
	s_mov_b32 m0, s37
	v_lshl_add_u64 v[196:197], s[42:43], 0, v[128:129]
	ds_read_b128 v[164:167], v150 offset:32768
	ds_read_b128 v[168:171], v150 offset:33792
	ds_read_b128 v[172:175], v150 offset:34816
	ds_read_b128 v[176:179], v150 offset:35840
	ds_read_b128 v[180:183], v150 offset:36864
	ds_read_b128 v[184:187], v150 offset:37888
	ds_read_b128 v[188:191], v150 offset:38912
	ds_read_b128 v[192:195], v150 offset:39936
	global_load_lds_dwordx4 v[196:197], off
	v_lshl_add_u64 v[196:197], s[42:43], 0, v[130:131]
	s_mov_b32 m0, s44
	s_nop 0
	global_load_lds_dwordx4 v[196:197], off
	s_add_i32 s42, 0, 0x1c000
	v_add_u32_e32 v208, s42, v147
	ds_read_b128 v[196:199], v208
	ds_read_b128 v[200:203], v208 offset:1024
	ds_read_b128 v[204:207], v208 offset:2048
	ds_read_b128 v[208:211], v208 offset:3072
	s_waitcnt lgkmcnt(0)
	s_barrier
	s_setprio 1
	v_mfma_f32_16x16x32_bf16 v[124:127], v[140:143], v[164:167], v[124:127]
	v_mfma_f32_16x16x32_bf16 v[120:123], v[156:159], v[164:167], v[120:123]
	v_mfma_f32_16x16x32_bf16 v[112:115], v[140:143], v[172:175], v[112:115]
	v_mfma_f32_16x16x32_bf16 v[104:107], v[156:159], v[172:175], v[104:107]
	v_mfma_f32_16x16x32_bf16 v[92:95], v[140:143], v[180:183], v[92:95]
	v_mfma_f32_16x16x32_bf16 v[88:91], v[156:159], v[180:183], v[88:91]
	v_mfma_f32_16x16x32_bf16 v[80:83], v[140:143], v[188:191], v[80:83]
	v_mfma_f32_16x16x32_bf16 v[72:75], v[156:159], v[188:191], v[72:75]
	v_mfma_f32_16x16x32_bf16 v[124:127], v[152:155], v[168:171], v[124:127]
	v_mfma_f32_16x16x32_bf16 v[120:123], v[160:163], v[168:171], v[120:123]
	v_mfma_f32_16x16x32_bf16 v[112:115], v[152:155], v[176:179], v[112:115]
	v_mfma_f32_16x16x32_bf16 v[104:107], v[160:163], v[176:179], v[104:107]
	v_mfma_f32_16x16x32_bf16 v[92:95], v[152:155], v[184:187], v[92:95]
	v_mfma_f32_16x16x32_bf16 v[88:91], v[160:163], v[184:187], v[88:91]
	v_mfma_f32_16x16x32_bf16 v[80:83], v[152:155], v[192:195], v[80:83]
	v_mfma_f32_16x16x32_bf16 v[72:75], v[160:163], v[192:195], v[72:75]
	v_mfma_f32_16x16x32_bf16 v[116:119], v[196:199], v[164:167], v[116:119]
	v_mfma_f32_16x16x32_bf16 v[108:111], v[204:207], v[164:167], v[108:111]
	v_mfma_f32_16x16x32_bf16 v[100:103], v[196:199], v[172:175], v[100:103]
	v_mfma_f32_16x16x32_bf16 v[96:99], v[204:207], v[172:175], v[96:99]
	v_mfma_f32_16x16x32_bf16 v[84:87], v[196:199], v[180:183], v[84:87]
	v_mfma_f32_16x16x32_bf16 v[76:79], v[204:207], v[180:183], v[76:79]
	v_mfma_f32_16x16x32_bf16 v[68:71], v[196:199], v[188:191], v[68:71]
	v_mfma_f32_16x16x32_bf16 v[64:67], v[204:207], v[188:191], v[64:67]
	v_mfma_f32_16x16x32_bf16 v[116:119], v[200:203], v[168:171], v[116:119]
	v_mfma_f32_16x16x32_bf16 v[108:111], v[208:211], v[168:171], v[108:111]
	v_mfma_f32_16x16x32_bf16 v[100:103], v[200:203], v[176:179], v[100:103]
	v_mfma_f32_16x16x32_bf16 v[96:99], v[208:211], v[176:179], v[96:99]
	v_mfma_f32_16x16x32_bf16 v[84:87], v[200:203], v[184:187], v[84:87]
	v_mfma_f32_16x16x32_bf16 v[76:79], v[208:211], v[184:187], v[76:79]
	v_mfma_f32_16x16x32_bf16 v[68:71], v[200:203], v[192:195], v[68:71]
	v_mfma_f32_16x16x32_bf16 v[64:67], v[208:211], v[192:195], v[64:67]
	s_setprio 0
	s_barrier
; #define PG8_STAGE(bufoff, gbase, voff) do { _Pragma("unroll") for (int _i = 0; _i < 2; ++_i) \
;         __builtin_amdgcn_global_load_lds((const unsigned*)((const char*)(gbase) + (voff)[_i]), (LAS unsigned*)(lds + (bufoff) + ldsw + _i * 8192), 16, 0, 0); } while (0)
; #define PG8_WAIT_V(n) asm volatile("s_waitcnt vmcnt(" #n ")" ::: "memory")
; template <class Epi>
; __device__ __forceinline__ void gemm_phase(LAS unsigned char* lds, const Gemm g, const StaticOrder& S, const Epi& E) {
;     ...
;             PG8_LDB(B1, 1, 1); PG8_STAGE(PG8_SB(1, 0), b3, voffB);
;             PG8_BAR; PG8_WAIT_L(0); PG8_MMA(0, 1, At, B1); PG8_BAR;
;             PG8_LDA(At, 1, 1); PG8_STAGE(PG8_SA(1, 0), a3, voffA);
;             PG8_BAR; PG8_WAIT_L(0); PG8_MMA(1, 0, At, B0); PG8_BAR; PG8_SCHED;
;             PG8_STAGE(PG8_SB(1, 1), b3 + hstepB, voffB);
;             PG8_WAIT_V(6); PG8_BAR; PG8_MMA(1, 1, At, B1); PG8_BAR;
;         }
;     __device__ __forceinline__ void operator()(AccRef acc, const Unit& u, int wr, int wc, int fr, int fq) const {
;         const int row0 = u.pm * 256 + wr * 64 + fr, col0 = u.pn * 256 + wc * 32 + 4 * fq;
;         f32x4 sv[2][2], bv[2][2];
; #pragma unroll
;         for (int bj = 0; bj < 2; ++bj)
; #pragma unroll
;             for (int n = 0; n < 2; ++n) {
;                 sv[bj][n] = scale ? *(const f32x4*)(scale + col0 + bj * 128 + n * 16) : (f32x4){1.f, 1.f, 1.f, 1.f};
;                 bv[bj][n] = bias ? *(const f32x4*)(bias + col0 + bj * 128 + n * 16) : (f32x4){0.f, 0.f, 0.f, 0.f}; }
; #pragma unroll
;         for (int ai = 0; ai < 2; ++ai)
; #pragma unroll
;             for (int mh = 0; mh < 2; ++mh) {
;                 f32x4 bs[2][2][2];
; #pragma unroll
;                 for (int m = 0; m < 2; ++m)
; #pragma unroll
;                     for (int bj = 0; bj < 2; ++bj)
; #pragma unroll
;                         for (int n = 0; n < 2; ++n) bs[m][bj][n] = *(const f32x4*)(base + (size_t)(row0 + ai * 128 + (2 * mh + m) * 16) * D + col0 + bj * 128 + n * 16);
; #pragma unroll
;                 for (int m = 0; m < 2; ++m)
; #pragma unroll
;                     for (int bj = 0; bj < 2; ++bj)
; #pragma unroll
;                         for (int n = 0; n < 2; ++n) *(f32x4*)(out + (size_t)(row0 + ai * 128 + (2 * mh + m) * 16) * D + col0 + bj * 128 + n * 16) = bs[m][bj][n] + sv[bj][n] * (acc[ai][bj][2 * mh + m][n] + bv[bj][n]);
	s_nop 1
	ds_read_b128 v[164:167], v150 offset:49152
	ds_read_b128 v[168:171], v150 offset:50176
	ds_read_b128 v[172:175], v150 offset:51200
	ds_read_b128 v[176:179], v150 offset:52224
	ds_read_b128 v[180:183], v150 offset:53248
	ds_read_b128 v[184:187], v150 offset:54272
	ds_read_b128 v[188:191], v150 offset:55296
	ds_read_b128 v[192:195], v150 offset:56320
	s_add_i32 s43, s77, s7
	v_lshl_add_u64 v[254:255], v[144:145], 0, s[12:13]
	s_mov_b32 m0, s43
	s_nop 0
	global_load_lds_dwordx4 v[254:255], off
	v_lshl_add_u64 v[254:255], v[212:213], 0, s[12:13]
	s_add_i32 m0, s43, 0x2000
	s_nop 0
	global_load_lds_dwordx4 v[254:255], off
	s_mov_b32 m0, s46
	v_lshl_add_u64 v[254:255], v[214:215], 0, s[12:13]
	global_load_lds_dwordx4 v[254:255], off
	v_lshl_add_u64 v[144:145], v[216:217], 0, s[12:13]
	s_mov_b32 m0, s47
	s_nop 0
	global_load_lds_dwordx4 v[144:145], off
	s_add_u32 s40, s40, 0x40080
	s_addc_u32 s41, s41, 0
	s_add_i32 s42, s42, s7
	v_lshl_add_u64 v[254:255], s[40:41], 0, v[128:129]
	s_mov_b32 m0, s42
	s_nop 0
	global_load_lds_dwordx4 v[254:255], off
	v_lshl_add_u64 v[254:255], s[40:41], 0, v[130:131]
	s_add_i32 m0, s42, 0x2000
	s_nop 0
	global_load_lds_dwordx4 v[254:255], off
	s_waitcnt vmcnt(6)
	s_waitcnt lgkmcnt(0)
	s_barrier
	s_setprio 1
	v_mfma_f32_16x16x32_bf16 v[60:63], v[140:143], v[164:167], v[60:63]
	v_mfma_f32_16x16x32_bf16 v[56:59], v[156:159], v[164:167], v[56:59]
	v_mfma_f32_16x16x32_bf16 v[48:51], v[140:143], v[172:175], v[48:51]
	v_mfma_f32_16x16x32_bf16 v[40:43], v[156:159], v[172:175], v[40:43]
	v_mfma_f32_16x16x32_bf16 v[28:31], v[140:143], v[180:183], v[28:31]
	v_mfma_f32_16x16x32_bf16 v[24:27], v[156:159], v[180:183], v[24:27]
	v_mfma_f32_16x16x32_bf16 v[16:19], v[140:143], v[188:191], v[16:19]
	v_mfma_f32_16x16x32_bf16 v[8:11], v[156:159], v[188:191], v[8:11]
	v_mfma_f32_16x16x32_bf16 v[60:63], v[152:155], v[168:171], v[60:63]
	v_mfma_f32_16x16x32_bf16 v[56:59], v[160:163], v[168:171], v[56:59]
	v_mfma_f32_16x16x32_bf16 v[48:51], v[152:155], v[176:179], v[48:51]
	v_mfma_f32_16x16x32_bf16 v[40:43], v[160:163], v[176:179], v[40:43]
	v_mfma_f32_16x16x32_bf16 v[28:31], v[152:155], v[184:187], v[28:31]
	v_mfma_f32_16x16x32_bf16 v[24:27], v[160:163], v[184:187], v[24:27]
	v_mfma_f32_16x16x32_bf16 v[16:19], v[152:155], v[192:195], v[16:19]
	v_mfma_f32_16x16x32_bf16 v[8:11], v[160:163], v[192:195], v[8:11]
	v_mfma_f32_16x16x32_bf16 v[52:55], v[196:199], v[164:167], v[52:55]
	v_mfma_f32_16x16x32_bf16 v[44:47], v[204:207], v[164:167], v[44:47]
	v_mfma_f32_16x16x32_bf16 v[36:39], v[196:199], v[172:175], v[36:39]
	v_mfma_f32_16x16x32_bf16 v[32:35], v[204:207], v[172:175], v[32:35]
	v_mfma_f32_16x16x32_bf16 v[20:23], v[196:199], v[180:183], v[20:23]
	v_mfma_f32_16x16x32_bf16 v[12:15], v[204:207], v[180:183], v[12:15]
	v_mfma_f32_16x16x32_bf16 v[4:7], v[196:199], v[188:191], v[4:7]
	v_mfma_f32_16x16x32_bf16 v[0:3], v[204:207], v[188:191], v[0:3]
	v_mfma_f32_16x16x32_bf16 v[52:55], v[200:203], v[168:171], v[52:55]
	v_mfma_f32_16x16x32_bf16 v[44:47], v[208:211], v[168:171], v[44:47]
	v_mfma_f32_16x16x32_bf16 v[36:39], v[200:203], v[176:179], v[36:39]
	v_mfma_f32_16x16x32_bf16 v[32:35], v[208:211], v[176:179], v[32:35]
	v_mfma_f32_16x16x32_bf16 v[20:23], v[200:203], v[184:187], v[20:23]
	v_mfma_f32_16x16x32_bf16 v[12:15], v[208:211], v[184:187], v[12:15]
	v_mfma_f32_16x16x32_bf16 v[4:7], v[200:203], v[192:195], v[4:7]
	v_mfma_f32_16x16x32_bf16 v[0:3], v[208:211], v[192:195], v[0:3]
	s_setprio 0
	s_add_i32 s76, s76, 2
	s_add_u32 s38, s38, 0x100
	s_addc_u32 s39, s39, 0
	s_add_u32 s74, s74, 0x100
	s_addc_u32 s75, s75, 0
	s_cmp_gt_u32 s76, 13
	s_barrier
	s_cbranch_scc0 .LBB0_1239
	v_lshl_or_b32 v144, s63, 8, v148
	v_lshl_add_u32 v145, s36, 8, v146
	v_lshlrev_b32_e32 v144, 2, v144
	v_lshl_add_u32 v145, v145, 12, v144
	v_add_u32_e32 v216, 0x10000, v145
	v_add_u32_e32 v217, 0x20000, v145
	v_add_u32_e32 v218, 0x30000, v145
	v_add_u32_e32 v220, 0x80000, v145
	v_add_u32_e32 v221, 0x90000, v145
	v_add_u32_e32 v222, 0xa0000, v145
	v_add_u32_e32 v223, 0xb0000, v145
	v_and_b32_e32 v235, 8, v146
	v_cmp_ne_u32_e32 vcc, 0, v235
	v_mov_b32_e32 v232, 0xffff8040
	s_nop 0
	v_cndmask_b32_e32 v232, 0, v232, vcc
	v_mov_b32_e32 v233, 64
	v_mov_b32_e32 v235, 0x8000
	v_cndmask_b32_e32 v233, v235, v233, vcc
	v_add_u32_e32 v224, v145, v232
	v_add_u32_e32 v225, v216, v232
	v_add_u32_e32 v226, v217, v232
	v_add_u32_e32 v227, v218, v232
	v_add_u32_e32 v228, v220, v232
	v_add_u32_e32 v229, v221, v232
	v_add_u32_e32 v230, v222, v232
	v_add_u32_e32 v231, v223, v232
	s_and_b64 vcc, exec, s[10:11]
	s_mov_b32 s63, s26
	s_mov_b32 s36, s28
	s_mov_b64 s[40:41], s[34:35]
	s_mov_b64 s[38:39], s[30:31]
	global_load_dwordx4 v[140:143], v224, s[52:53]
	v_add_u32_e32 v144, v145, v233
	global_load_dwordx4 v[152:155], v144, s[52:53]
	global_load_dwordx4 v[156:159], v224, s[52:53] offset:512
	v_add_u32_e32 v144, v145, v233
	global_load_dwordx4 v[160:163], v144, s[52:53] offset:512
	global_load_dwordx4 v[164:167], v225, s[52:53]
	v_add_u32_e32 v144, v216, v233
	global_load_dwordx4 v[168:171], v144, s[52:53]
	global_load_dwordx4 v[172:175], v225, s[52:53] offset:512
	v_add_u32_e32 v144, v216, v233
	global_load_dwordx4 v[176:179], v144, s[52:53] offset:512
	global_load_dwordx4 v[180:183], v226, s[52:53]
	v_add_u32_e32 v144, v217, v233
	global_load_dwordx4 v[184:187], v144, s[52:53]
	global_load_dwordx4 v[188:191], v226, s[52:53] offset:512
	v_add_u32_e32 v144, v217, v233
	global_load_dwordx4 v[192:195], v144, s[52:53] offset:512
	global_load_dwordx4 v[196:199], v227, s[52:53]
	v_add_u32_e32 v144, v218, v233
	global_load_dwordx4 v[200:203], v144, s[52:53]
;     __device__ __forceinline__ void operator()(AccRef acc, const Unit& u, int wr, int wc, int fr, int fq) const {
;     ...
;                 sv[bj][n] = scale ? *(const f32x4*)(scale + col0 + bj * 128 + n * 16) : (f32x4){1.f, 1.f, 1.f, 1.f};
;                 bv[bj][n] = bias ? *(const f32x4*)(bias + col0 + bj * 128 + n * 16) : (f32x4){0.f, 0.f, 0.f, 0.f}; }
; #pragma unroll
;         for (int ai = 0; ai < 2; ++ai)
; #pragma unroll
;             for (int mh = 0; mh < 2; ++mh) {
;                 f32x4 bs[2][2][2];
; #pragma unroll
;                 for (int m = 0; m < 2; ++m)
; #pragma unroll
;                     for (int bj = 0; bj < 2; ++bj)
; #pragma unroll
;                         for (int n = 0; n < 2; ++n) bs[m][bj][n] = *(const f32x4*)(base + (size_t)(row0 + ai * 128 + (2 * mh + m) * 16) * D + col0 + bj * 128 + n * 16);
; #pragma unroll
;                 for (int m = 0; m < 2; ++m)
; #pragma unroll
;                     for (int bj = 0; bj < 2; ++bj)
; #pragma unroll
;                         for (int n = 0; n < 2; ++n) *(f32x4*)(out + (size_t)(row0 + ai * 128 + (2 * mh + m) * 16) * D + col0 + bj * 128 + n * 16) = bs[m][bj][n] + sv[bj][n] * (acc[ai][bj][2 * mh + m][n] + bv[bj][n]);
	global_load_dwordx4 v[204:207], v227, s[52:53] offset:512
	v_add_u32_e32 v144, v218, v233
	global_load_dwordx4 v[208:211], v144, s[52:53] offset:512
	v_pk_add_f32 v[124:125], v[124:125], 0 op_sel_hi:[1,0]
	v_pk_add_f32 v[126:127], v[126:127], 0 op_sel_hi:[1,0]
	v_pk_add_f32 v[120:121], v[120:121], 0 op_sel_hi:[1,0]
	v_pk_add_f32 v[122:123], v[122:123], 0 op_sel_hi:[1,0]
	v_pk_add_f32 v[116:117], v[116:117], 0 op_sel_hi:[1,0]
	v_pk_add_f32 v[118:119], v[118:119], 0 op_sel_hi:[1,0]
	v_pk_add_f32 v[108:109], v[108:109], 0 op_sel_hi:[1,0]
	v_pk_add_f32 v[110:111], v[110:111], 0 op_sel_hi:[1,0]
	v_pk_add_f32 v[112:113], v[112:113], 0 op_sel_hi:[1,0]
	v_pk_add_f32 v[114:115], v[114:115], 0 op_sel_hi:[1,0]
	v_pk_add_f32 v[104:105], v[104:105], 0 op_sel_hi:[1,0]
	v_pk_add_f32 v[106:107], v[106:107], 0 op_sel_hi:[1,0]
	v_pk_add_f32 v[100:101], v[100:101], 0 op_sel_hi:[1,0]
	v_pk_add_f32 v[102:103], v[102:103], 0 op_sel_hi:[1,0]
	v_pk_add_f32 v[96:97], v[96:97], 0 op_sel_hi:[1,0]
	v_pk_add_f32 v[98:99], v[98:99], 0 op_sel_hi:[1,0]
	v_pk_add_f32 v[92:93], v[92:93], 0 op_sel_hi:[1,0]
	v_pk_add_f32 v[94:95], v[94:95], 0 op_sel_hi:[1,0]
	v_pk_add_f32 v[88:89], v[88:89], 0 op_sel_hi:[1,0]
	v_pk_add_f32 v[90:91], v[90:91], 0 op_sel_hi:[1,0]
	v_pk_add_f32 v[84:85], v[84:85], 0 op_sel_hi:[1,0]
	v_pk_add_f32 v[86:87], v[86:87], 0 op_sel_hi:[1,0]
	v_pk_add_f32 v[76:77], v[76:77], 0 op_sel_hi:[1,0]
	v_pk_add_f32 v[78:79], v[78:79], 0 op_sel_hi:[1,0]
	v_pk_add_f32 v[80:81], v[80:81], 0 op_sel_hi:[1,0]
	v_pk_add_f32 v[82:83], v[82:83], 0 op_sel_hi:[1,0]
	v_pk_add_f32 v[72:73], v[72:73], 0 op_sel_hi:[1,0]
	v_pk_add_f32 v[74:75], v[74:75], 0 op_sel_hi:[1,0]
	v_pk_add_f32 v[68:69], v[68:69], 0 op_sel_hi:[1,0]
	v_pk_add_f32 v[70:71], v[70:71], 0 op_sel_hi:[1,0]
	v_pk_add_f32 v[64:65], v[64:65], 0 op_sel_hi:[1,0]
	v_pk_add_f32 v[66:67], v[66:67], 0 op_sel_hi:[1,0]
	v_pk_add_f32 v[60:61], v[60:61], 0 op_sel_hi:[1,0]
	v_pk_add_f32 v[62:63], v[62:63], 0 op_sel_hi:[1,0]
	v_pk_add_f32 v[56:57], v[56:57], 0 op_sel_hi:[1,0]
	v_pk_add_f32 v[58:59], v[58:59], 0 op_sel_hi:[1,0]
	v_pk_add_f32 v[52:53], v[52:53], 0 op_sel_hi:[1,0]
	v_pk_add_f32 v[54:55], v[54:55], 0 op_sel_hi:[1,0]
	v_pk_add_f32 v[44:45], v[44:45], 0 op_sel_hi:[1,0]
	v_pk_add_f32 v[46:47], v[46:47], 0 op_sel_hi:[1,0]
	v_pk_add_f32 v[48:49], v[48:49], 0 op_sel_hi:[1,0]
	v_pk_add_f32 v[50:51], v[50:51], 0 op_sel_hi:[1,0]
	v_pk_add_f32 v[40:41], v[40:41], 0 op_sel_hi:[1,0]
	v_pk_add_f32 v[42:43], v[42:43], 0 op_sel_hi:[1,0]
	v_pk_add_f32 v[36:37], v[36:37], 0 op_sel_hi:[1,0]
	v_pk_add_f32 v[38:39], v[38:39], 0 op_sel_hi:[1,0]
	v_pk_add_f32 v[32:33], v[32:33], 0 op_sel_hi:[1,0]
	v_pk_add_f32 v[34:35], v[34:35], 0 op_sel_hi:[1,0]
	v_pk_add_f32 v[28:29], v[28:29], 0 op_sel_hi:[1,0]
	v_pk_add_f32 v[30:31], v[30:31], 0 op_sel_hi:[1,0]
	v_pk_add_f32 v[24:25], v[24:25], 0 op_sel_hi:[1,0]
	v_pk_add_f32 v[26:27], v[26:27], 0 op_sel_hi:[1,0]
	v_pk_add_f32 v[20:21], v[20:21], 0 op_sel_hi:[1,0]
	v_pk_add_f32 v[22:23], v[22:23], 0 op_sel_hi:[1,0]
	v_pk_add_f32 v[12:13], v[12:13], 0 op_sel_hi:[1,0]
	v_pk_add_f32 v[14:15], v[14:15], 0 op_sel_hi:[1,0]
	v_pk_add_f32 v[16:17], v[16:17], 0 op_sel_hi:[1,0]
	v_pk_add_f32 v[18:19], v[18:19], 0 op_sel_hi:[1,0]
	v_pk_add_f32 v[8:9], v[8:9], 0 op_sel_hi:[1,0]
	v_pk_add_f32 v[10:11], v[10:11], 0 op_sel_hi:[1,0]
	v_pk_add_f32 v[4:5], v[4:5], 0 op_sel_hi:[1,0]
	v_pk_add_f32 v[6:7], v[6:7], 0 op_sel_hi:[1,0]
	v_pk_add_f32 v[0:1], v[0:1], 0 op_sel_hi:[1,0]
	v_pk_add_f32 v[2:3], v[2:3], 0 op_sel_hi:[1,0]
	s_waitcnt vmcnt(8)
	v_mov_b32_e32 v212, v152
	v_mov_b32_e32 v213, v153
	v_mov_b32_e32 v214, v154
	v_mov_b32_e32 v215, v155
	s_nop 0
	v_mov_b32_dpp v152, v140 row_shl:8 row_mask:0xf bank_mask:0x3
	v_mov_b32_dpp v153, v141 row_shl:8 row_mask:0xf bank_mask:0x3
	v_mov_b32_dpp v154, v142 row_shl:8 row_mask:0xf bank_mask:0x3
	v_mov_b32_dpp v155, v143 row_shl:8 row_mask:0xf bank_mask:0x3
	v_mov_b32_dpp v140, v212 row_shr:8 row_mask:0xf bank_mask:0xc
	v_mov_b32_dpp v141, v213 row_shr:8 row_mask:0xf bank_mask:0xc
	v_mov_b32_dpp v142, v214 row_shr:8 row_mask:0xf bank_mask:0xc
	v_mov_b32_dpp v143, v215 row_shr:8 row_mask:0xf bank_mask:0xc
	v_mov_b32_e32 v212, v160
	v_mov_b32_e32 v213, v161
	v_mov_b32_e32 v214, v162
	v_mov_b32_e32 v215, v163
	s_nop 0
	v_mov_b32_dpp v160, v156 row_shl:8 row_mask:0xf bank_mask:0x3
	v_mov_b32_dpp v161, v157 row_shl:8 row_mask:0xf bank_mask:0x3
	v_mov_b32_dpp v162, v158 row_shl:8 row_mask:0xf bank_mask:0x3
	v_mov_b32_dpp v163, v159 row_shl:8 row_mask:0xf bank_mask:0x3
	v_mov_b32_dpp v156, v212 row_shr:8 row_mask:0xf bank_mask:0xc
	v_mov_b32_dpp v157, v213 row_shr:8 row_mask:0xf bank_mask:0xc
	v_mov_b32_dpp v158, v214 row_shr:8 row_mask:0xf bank_mask:0xc
	v_mov_b32_dpp v159, v215 row_shr:8 row_mask:0xf bank_mask:0xc
	v_mov_b32_e32 v212, v168
	v_mov_b32_e32 v213, v169
	v_mov_b32_e32 v214, v170
	v_mov_b32_e32 v215, v171
	s_nop 0
	v_mov_b32_dpp v168, v164 row_shl:8 row_mask:0xf bank_mask:0x3
	v_mov_b32_dpp v169, v165 row_shl:8 row_mask:0xf bank_mask:0x3
	v_mov_b32_dpp v170, v166 row_shl:8 row_mask:0xf bank_mask:0x3
	v_mov_b32_dpp v171, v167 row_shl:8 row_mask:0xf bank_mask:0x3
	v_mov_b32_dpp v164, v212 row_shr:8 row_mask:0xf bank_mask:0xc
	v_mov_b32_dpp v165, v213 row_shr:8 row_mask:0xf bank_mask:0xc
	v_mov_b32_dpp v166, v214 row_shr:8 row_mask:0xf bank_mask:0xc
	v_mov_b32_dpp v167, v215 row_shr:8 row_mask:0xf bank_mask:0xc
	v_mov_b32_e32 v212, v176
	v_mov_b32_e32 v213, v177
	v_mov_b32_e32 v214, v178
	v_mov_b32_e32 v215, v179
	s_nop 0
	v_mov_b32_dpp v176, v172 row_shl:8 row_mask:0xf bank_mask:0x3
	v_mov_b32_dpp v177, v173 row_shl:8 row_mask:0xf bank_mask:0x3
;     __device__ __forceinline__ void operator()(AccRef acc, const Unit& u, int wr, int wc, int fr, int fq) const {
;     ...
;                         for (int n = 0; n < 2; ++n) bs[m][bj][n] = *(const f32x4*)(base + (size_t)(row0 + ai * 128 + (2 * mh + m) * 16) * D + col0 + bj * 128 + n * 16);
; #pragma unroll
;                 for (int m = 0; m < 2; ++m)
; #pragma unroll
;                     for (int bj = 0; bj < 2; ++bj)
; #pragma unroll
;                         for (int n = 0; n < 2; ++n) *(f32x4*)(out + (size_t)(row0 + ai * 128 + (2 * mh + m) * 16) * D + col0 + bj * 128 + n * 16) = bs[m][bj][n] + sv[bj][n] * (acc[ai][bj][2 * mh + m][n] + bv[bj][n]);
;                 asm volatile("" ::: "memory"); }
	v_mov_b32_dpp v178, v174 row_shl:8 row_mask:0xf bank_mask:0x3
	v_mov_b32_dpp v179, v175 row_shl:8 row_mask:0xf bank_mask:0x3
	v_mov_b32_dpp v172, v212 row_shr:8 row_mask:0xf bank_mask:0xc
	v_mov_b32_dpp v173, v213 row_shr:8 row_mask:0xf bank_mask:0xc
	v_mov_b32_dpp v174, v214 row_shr:8 row_mask:0xf bank_mask:0xc
	v_mov_b32_dpp v175, v215 row_shr:8 row_mask:0xf bank_mask:0xc
	v_pk_add_f32 v[124:125], v[124:125], v[140:141]
	v_pk_add_f32 v[126:127], v[126:127], v[142:143]
	v_pk_add_f32 v[120:121], v[120:121], v[152:153]
	v_pk_add_f32 v[122:123], v[122:123], v[154:155]
	v_pk_add_f32 v[116:117], v[116:117], v[156:157]
	v_pk_add_f32 v[118:119], v[118:119], v[158:159]
	v_pk_add_f32 v[108:109], v[108:109], v[160:161]
	v_pk_add_f32 v[110:111], v[110:111], v[162:163]
	v_pk_add_f32 v[112:113], v[112:113], v[164:165]
	v_pk_add_f32 v[114:115], v[114:115], v[166:167]
	v_pk_add_f32 v[104:105], v[104:105], v[168:169]
	v_pk_add_f32 v[106:107], v[106:107], v[170:171]
	v_pk_add_f32 v[100:101], v[100:101], v[172:173]
	v_pk_add_f32 v[102:103], v[102:103], v[174:175]
	v_pk_add_f32 v[96:97], v[96:97], v[176:177]
	v_pk_add_f32 v[98:99], v[98:99], v[178:179]
	global_store_dwordx4 v145, v[124:127], s[52:53]
	global_store_dwordx4 v145, v[120:123], s[52:53] offset:64
	global_store_dwordx4 v145, v[116:119], s[52:53] offset:512
	global_store_dwordx4 v145, v[108:111], s[52:53] offset:576
	global_store_dwordx4 v216, v[112:115], s[52:53]
	global_store_dwordx4 v216, v[104:107], s[52:53] offset:64
	global_store_dwordx4 v216, v[100:103], s[52:53] offset:512
	global_store_dwordx4 v216, v[96:99], s[52:53] offset:576
	global_load_dwordx4 v[140:143], v228, s[52:53]
	v_add_u32_e32 v144, v220, v233
	global_load_dwordx4 v[152:155], v144, s[52:53]
	global_load_dwordx4 v[156:159], v228, s[52:53] offset:512
	v_add_u32_e32 v144, v220, v233
	global_load_dwordx4 v[160:163], v144, s[52:53] offset:512
	global_load_dwordx4 v[164:167], v229, s[52:53]
	v_add_u32_e32 v144, v221, v233
	global_load_dwordx4 v[168:171], v144, s[52:53]
	global_load_dwordx4 v[172:175], v229, s[52:53] offset:512
	v_add_u32_e32 v144, v221, v233
	global_load_dwordx4 v[176:179], v144, s[52:53] offset:512
	s_waitcnt vmcnt(16)
	v_mov_b32_e32 v212, v184
	v_mov_b32_e32 v213, v185
	v_mov_b32_e32 v214, v186
	v_mov_b32_e32 v215, v187
	s_nop 0
	v_mov_b32_dpp v184, v180 row_shl:8 row_mask:0xf bank_mask:0x3
	v_mov_b32_dpp v185, v181 row_shl:8 row_mask:0xf bank_mask:0x3
	v_mov_b32_dpp v186, v182 row_shl:8 row_mask:0xf bank_mask:0x3
	v_mov_b32_dpp v187, v183 row_shl:8 row_mask:0xf bank_mask:0x3
	v_mov_b32_dpp v180, v212 row_shr:8 row_mask:0xf bank_mask:0xc
	v_mov_b32_dpp v181, v213 row_shr:8 row_mask:0xf bank_mask:0xc
	v_mov_b32_dpp v182, v214 row_shr:8 row_mask:0xf bank_mask:0xc
	v_mov_b32_dpp v183, v215 row_shr:8 row_mask:0xf bank_mask:0xc
	v_mov_b32_e32 v212, v192
	v_mov_b32_e32 v213, v193
	v_mov_b32_e32 v214, v194
	v_mov_b32_e32 v215, v195
	s_nop 0
	v_mov_b32_dpp v192, v188 row_shl:8 row_mask:0xf bank_mask:0x3
	v_mov_b32_dpp v193, v189 row_shl:8 row_mask:0xf bank_mask:0x3
	v_mov_b32_dpp v194, v190 row_shl:8 row_mask:0xf bank_mask:0x3
	v_mov_b32_dpp v195, v191 row_shl:8 row_mask:0xf bank_mask:0x3
	v_mov_b32_dpp v188, v212 row_shr:8 row_mask:0xf bank_mask:0xc
	v_mov_b32_dpp v189, v213 row_shr:8 row_mask:0xf bank_mask:0xc
	v_mov_b32_dpp v190, v214 row_shr:8 row_mask:0xf bank_mask:0xc
	v_mov_b32_dpp v191, v215 row_shr:8 row_mask:0xf bank_mask:0xc
	v_mov_b32_e32 v212, v200
	v_mov_b32_e32 v213, v201
	v_mov_b32_e32 v214, v202
	v_mov_b32_e32 v215, v203
	s_nop 0
	v_mov_b32_dpp v200, v196 row_shl:8 row_mask:0xf bank_mask:0x3
	v_mov_b32_dpp v201, v197 row_shl:8 row_mask:0xf bank_mask:0x3
	v_mov_b32_dpp v202, v198 row_shl:8 row_mask:0xf bank_mask:0x3
	v_mov_b32_dpp v203, v199 row_shl:8 row_mask:0xf bank_mask:0x3
	v_mov_b32_dpp v196, v212 row_shr:8 row_mask:0xf bank_mask:0xc
	v_mov_b32_dpp v197, v213 row_shr:8 row_mask:0xf bank_mask:0xc
	v_mov_b32_dpp v198, v214 row_shr:8 row_mask:0xf bank_mask:0xc
	v_mov_b32_dpp v199, v215 row_shr:8 row_mask:0xf bank_mask:0xc
	v_mov_b32_e32 v212, v208
	v_mov_b32_e32 v213, v209
	v_mov_b32_e32 v214, v210
	v_mov_b32_e32 v215, v211
	s_nop 0
	v_mov_b32_dpp v208, v204 row_shl:8 row_mask:0xf bank_mask:0x3
	v_mov_b32_dpp v209, v205 row_shl:8 row_mask:0xf bank_mask:0x3
	v_mov_b32_dpp v210, v206 row_shl:8 row_mask:0xf bank_mask:0x3
	v_mov_b32_dpp v211, v207 row_shl:8 row_mask:0xf bank_mask:0x3
	v_mov_b32_dpp v204, v212 row_shr:8 row_mask:0xf bank_mask:0xc
	v_mov_b32_dpp v205, v213 row_shr:8 row_mask:0xf bank_mask:0xc
	v_mov_b32_dpp v206, v214 row_shr:8 row_mask:0xf bank_mask:0xc
	v_mov_b32_dpp v207, v215 row_shr:8 row_mask:0xf bank_mask:0xc
	v_pk_add_f32 v[92:93], v[92:93], v[180:181]
	v_pk_add_f32 v[94:95], v[94:95], v[182:183]
	v_pk_add_f32 v[88:89], v[88:89], v[184:185]
	v_pk_add_f32 v[90:91], v[90:91], v[186:187]
	v_pk_add_f32 v[84:85], v[84:85], v[188:189]
	v_pk_add_f32 v[86:87], v[86:87], v[190:191]
	v_pk_add_f32 v[76:77], v[76:77], v[192:193]
	v_pk_add_f32 v[78:79], v[78:79], v[194:195]
	v_pk_add_f32 v[80:81], v[80:81], v[196:197]
	v_pk_add_f32 v[82:83], v[82:83], v[198:199]
	v_pk_add_f32 v[72:73], v[72:73], v[200:201]
	v_pk_add_f32 v[74:75], v[74:75], v[202:203]
	v_pk_add_f32 v[68:69], v[68:69], v[204:205]
	v_pk_add_f32 v[70:71], v[70:71], v[206:207]
	v_pk_add_f32 v[64:65], v[64:65], v[208:209]
	v_pk_add_f32 v[66:67], v[66:67], v[210:211]
	global_store_dwordx4 v217, v[92:95], s[52:53]
	global_store_dwordx4 v217, v[88:91], s[52:53] offset:64
	global_store_dwordx4 v217, v[84:87], s[52:53] offset:512
	global_store_dwordx4 v217, v[76:79], s[52:53] offset:576
	global_store_dwordx4 v218, v[80:83], s[52:53]
	global_store_dwordx4 v218, v[72:75], s[52:53] offset:64
	global_store_dwordx4 v218, v[68:71], s[52:53] offset:512
	global_store_dwordx4 v218, v[64:67], s[52:53] offset:576
	global_load_dwordx4 v[180:183], v230, s[52:53]
	v_add_u32_e32 v144, v222, v233
	global_load_dwordx4 v[184:187], v144, s[52:53]
	global_load_dwordx4 v[188:191], v230, s[52:53] offset:512
	v_add_u32_e32 v144, v222, v233
	global_load_dwordx4 v[192:195], v144, s[52:53] offset:512
	global_load_dwordx4 v[196:199], v231, s[52:53]
	v_add_u32_e32 v144, v223, v233
	global_load_dwordx4 v[200:203], v144, s[52:53]
	global_load_dwordx4 v[204:207], v231, s[52:53] offset:512
	v_add_u32_e32 v144, v223, v233
	global_load_dwordx4 v[208:211], v144, s[52:53] offset:512
	s_waitcnt vmcnt(16)
;     __device__ __forceinline__ void operator()(AccRef acc, const Unit& u, int wr, int wc, int fr, int fq) const {
;     ...
;                         for (int n = 0; n < 2; ++n) bs[m][bj][n] = *(const f32x4*)(base + (size_t)(row0 + ai * 128 + (2 * mh + m) * 16) * D + col0 + bj * 128 + n * 16);
; #pragma unroll
;                 for (int m = 0; m < 2; ++m)
; #pragma unroll
;                     for (int bj = 0; bj < 2; ++bj)
; #pragma unroll
;                         for (int n = 0; n < 2; ++n) *(f32x4*)(out + (size_t)(row0 + ai * 128 + (2 * mh + m) * 16) * D + col0 + bj * 128 + n * 16) = bs[m][bj][n] + sv[bj][n] * (acc[ai][bj][2 * mh + m][n] + bv[bj][n]);
	v_mov_b32_e32 v212, v152
	v_mov_b32_e32 v213, v153
	v_mov_b32_e32 v214, v154
	v_mov_b32_e32 v215, v155
	s_nop 0
	v_mov_b32_dpp v152, v140 row_shl:8 row_mask:0xf bank_mask:0x3
	v_mov_b32_dpp v153, v141 row_shl:8 row_mask:0xf bank_mask:0x3
	v_mov_b32_dpp v154, v142 row_shl:8 row_mask:0xf bank_mask:0x3
	v_mov_b32_dpp v155, v143 row_shl:8 row_mask:0xf bank_mask:0x3
	v_mov_b32_dpp v140, v212 row_shr:8 row_mask:0xf bank_mask:0xc
	v_mov_b32_dpp v141, v213 row_shr:8 row_mask:0xf bank_mask:0xc
	v_mov_b32_dpp v142, v214 row_shr:8 row_mask:0xf bank_mask:0xc
	v_mov_b32_dpp v143, v215 row_shr:8 row_mask:0xf bank_mask:0xc
	v_mov_b32_e32 v212, v160
	v_mov_b32_e32 v213, v161
	v_mov_b32_e32 v214, v162
	v_mov_b32_e32 v215, v163
	s_nop 0
	v_mov_b32_dpp v160, v156 row_shl:8 row_mask:0xf bank_mask:0x3
	v_mov_b32_dpp v161, v157 row_shl:8 row_mask:0xf bank_mask:0x3
	v_mov_b32_dpp v162, v158 row_shl:8 row_mask:0xf bank_mask:0x3
	v_mov_b32_dpp v163, v159 row_shl:8 row_mask:0xf bank_mask:0x3
	v_mov_b32_dpp v156, v212 row_shr:8 row_mask:0xf bank_mask:0xc
	v_mov_b32_dpp v157, v213 row_shr:8 row_mask:0xf bank_mask:0xc
	v_mov_b32_dpp v158, v214 row_shr:8 row_mask:0xf bank_mask:0xc
	v_mov_b32_dpp v159, v215 row_shr:8 row_mask:0xf bank_mask:0xc
	v_mov_b32_e32 v212, v168
	v_mov_b32_e32 v213, v169
	v_mov_b32_e32 v214, v170
	v_mov_b32_e32 v215, v171
	s_nop 0
	v_mov_b32_dpp v168, v164 row_shl:8 row_mask:0xf bank_mask:0x3
	v_mov_b32_dpp v169, v165 row_shl:8 row_mask:0xf bank_mask:0x3
	v_mov_b32_dpp v170, v166 row_shl:8 row_mask:0xf bank_mask:0x3
	v_mov_b32_dpp v171, v167 row_shl:8 row_mask:0xf bank_mask:0x3
	v_mov_b32_dpp v164, v212 row_shr:8 row_mask:0xf bank_mask:0xc
	v_mov_b32_dpp v165, v213 row_shr:8 row_mask:0xf bank_mask:0xc
	v_mov_b32_dpp v166, v214 row_shr:8 row_mask:0xf bank_mask:0xc
	v_mov_b32_dpp v167, v215 row_shr:8 row_mask:0xf bank_mask:0xc
	v_mov_b32_e32 v212, v176
	v_mov_b32_e32 v213, v177
	v_mov_b32_e32 v214, v178
	v_mov_b32_e32 v215, v179
	s_nop 0
	v_mov_b32_dpp v176, v172 row_shl:8 row_mask:0xf bank_mask:0x3
	v_mov_b32_dpp v177, v173 row_shl:8 row_mask:0xf bank_mask:0x3
	v_mov_b32_dpp v178, v174 row_shl:8 row_mask:0xf bank_mask:0x3
	v_mov_b32_dpp v179, v175 row_shl:8 row_mask:0xf bank_mask:0x3
	v_mov_b32_dpp v172, v212 row_shr:8 row_mask:0xf bank_mask:0xc
	v_mov_b32_dpp v173, v213 row_shr:8 row_mask:0xf bank_mask:0xc
	v_mov_b32_dpp v174, v214 row_shr:8 row_mask:0xf bank_mask:0xc
	v_mov_b32_dpp v175, v215 row_shr:8 row_mask:0xf bank_mask:0xc
	v_pk_add_f32 v[60:61], v[60:61], v[140:141]
	v_pk_add_f32 v[62:63], v[62:63], v[142:143]
	v_pk_add_f32 v[56:57], v[56:57], v[152:153]
	v_pk_add_f32 v[58:59], v[58:59], v[154:155]
	v_pk_add_f32 v[52:53], v[52:53], v[156:157]
	v_pk_add_f32 v[54:55], v[54:55], v[158:159]
	v_pk_add_f32 v[44:45], v[44:45], v[160:161]
	v_pk_add_f32 v[46:47], v[46:47], v[162:163]
	v_pk_add_f32 v[48:49], v[48:49], v[164:165]
	v_pk_add_f32 v[50:51], v[50:51], v[166:167]
	v_pk_add_f32 v[40:41], v[40:41], v[168:169]
	v_pk_add_f32 v[42:43], v[42:43], v[170:171]
	v_pk_add_f32 v[36:37], v[36:37], v[172:173]
	v_pk_add_f32 v[38:39], v[38:39], v[174:175]
	v_pk_add_f32 v[32:33], v[32:33], v[176:177]
	v_pk_add_f32 v[34:35], v[34:35], v[178:179]
	global_store_dwordx4 v220, v[60:63], s[52:53]
	global_store_dwordx4 v220, v[56:59], s[52:53] offset:64
	global_store_dwordx4 v220, v[52:55], s[52:53] offset:512
	global_store_dwordx4 v220, v[44:47], s[52:53] offset:576
	global_store_dwordx4 v221, v[48:51], s[52:53]
	global_store_dwordx4 v221, v[40:43], s[52:53] offset:64
	global_store_dwordx4 v221, v[36:39], s[52:53] offset:512
	global_store_dwordx4 v221, v[32:35], s[52:53] offset:576
	s_waitcnt vmcnt(8)
; #define PG8_WAIT_V(n) asm volatile("s_waitcnt vmcnt(" #n ")" ::: "memory")
; #define PG8_BAR __builtin_amdgcn_s_barrier()
; template <class Epi>
; __device__ __forceinline__ void gemm_phase(LAS unsigned char* lds, const Gemm g, const StaticOrder& S, const Epi& E) {
;     ...
;         if (!has_next) break;
;         {
; #pragma unroll
;         for (int a = 0; a < 2; ++a)
; #pragma unroll
;             for (int b = 0; b < 2; ++b)
; #pragma unroll
;                 for (int m = 0; m < 4; ++m)
; #pragma unroll
;                     for (int n = 0; n < 2; ++n) acc[a][b][m][n] = (f32x4){0.f, 0.f, 0.f, 0.f};
;         }
;         cur = nxt; cA = nA; cB = nB; ++ui;
;     }
;     PG8_WAIT_V(0);
;     if (wr == 0) PG8_BAR;
;     PG8_BAR;
;     __device__ __forceinline__ void operator()(AccRef acc, const Unit& u, int wr, int wc, int fr, int fq) const {
;     ...
;                         for (int n = 0; n < 2; ++n) bs[m][bj][n] = *(const f32x4*)(base + (size_t)(row0 + ai * 128 + (2 * mh + m) * 16) * D + col0 + bj * 128 + n * 16);
; #pragma unroll
;                 for (int m = 0; m < 2; ++m)
; #pragma unroll
;                     for (int bj = 0; bj < 2; ++bj)
; #pragma unroll
;                         for (int n = 0; n < 2; ++n) *(f32x4*)(out + (size_t)(row0 + ai * 128 + (2 * mh + m) * 16) * D + col0 + bj * 128 + n * 16) = bs[m][bj][n] + sv[bj][n] * (acc[ai][bj][2 * mh + m][n] + bv[bj][n]);
;                 asm volatile("" ::: "memory"); }
	v_mov_b32_e32 v212, v184
	v_mov_b32_e32 v213, v185
	v_mov_b32_e32 v214, v186
	v_mov_b32_e32 v215, v187
	s_nop 0
	v_mov_b32_dpp v184, v180 row_shl:8 row_mask:0xf bank_mask:0x3
	v_mov_b32_dpp v185, v181 row_shl:8 row_mask:0xf bank_mask:0x3
	v_mov_b32_dpp v186, v182 row_shl:8 row_mask:0xf bank_mask:0x3
	v_mov_b32_dpp v187, v183 row_shl:8 row_mask:0xf bank_mask:0x3
	v_mov_b32_dpp v180, v212 row_shr:8 row_mask:0xf bank_mask:0xc
	v_mov_b32_dpp v181, v213 row_shr:8 row_mask:0xf bank_mask:0xc
	v_mov_b32_dpp v182, v214 row_shr:8 row_mask:0xf bank_mask:0xc
	v_mov_b32_dpp v183, v215 row_shr:8 row_mask:0xf bank_mask:0xc
	v_mov_b32_e32 v212, v192
	v_mov_b32_e32 v213, v193
	v_mov_b32_e32 v214, v194
	v_mov_b32_e32 v215, v195
	s_nop 0
	v_mov_b32_dpp v192, v188 row_shl:8 row_mask:0xf bank_mask:0x3
	v_mov_b32_dpp v193, v189 row_shl:8 row_mask:0xf bank_mask:0x3
	v_mov_b32_dpp v194, v190 row_shl:8 row_mask:0xf bank_mask:0x3
	v_mov_b32_dpp v195, v191 row_shl:8 row_mask:0xf bank_mask:0x3
	v_mov_b32_dpp v188, v212 row_shr:8 row_mask:0xf bank_mask:0xc
	v_mov_b32_dpp v189, v213 row_shr:8 row_mask:0xf bank_mask:0xc
	v_mov_b32_dpp v190, v214 row_shr:8 row_mask:0xf bank_mask:0xc
	v_mov_b32_dpp v191, v215 row_shr:8 row_mask:0xf bank_mask:0xc
	v_mov_b32_e32 v212, v200
	v_mov_b32_e32 v213, v201
	v_mov_b32_e32 v214, v202
	v_mov_b32_e32 v215, v203
	s_nop 0
	v_mov_b32_dpp v200, v196 row_shl:8 row_mask:0xf bank_mask:0x3
	v_mov_b32_dpp v201, v197 row_shl:8 row_mask:0xf bank_mask:0x3
	v_mov_b32_dpp v202, v198 row_shl:8 row_mask:0xf bank_mask:0x3
	v_mov_b32_dpp v203, v199 row_shl:8 row_mask:0xf bank_mask:0x3
	v_mov_b32_dpp v196, v212 row_shr:8 row_mask:0xf bank_mask:0xc
	v_mov_b32_dpp v197, v213 row_shr:8 row_mask:0xf bank_mask:0xc
	v_mov_b32_dpp v198, v214 row_shr:8 row_mask:0xf bank_mask:0xc
	v_mov_b32_dpp v199, v215 row_shr:8 row_mask:0xf bank_mask:0xc
	v_mov_b32_e32 v212, v208
	v_mov_b32_e32 v213, v209
	v_mov_b32_e32 v214, v210
	v_mov_b32_e32 v215, v211
	s_nop 0
	v_mov_b32_dpp v208, v204 row_shl:8 row_mask:0xf bank_mask:0x3
	v_mov_b32_dpp v209, v205 row_shl:8 row_mask:0xf bank_mask:0x3
	v_mov_b32_dpp v210, v206 row_shl:8 row_mask:0xf bank_mask:0x3
	v_mov_b32_dpp v211, v207 row_shl:8 row_mask:0xf bank_mask:0x3
	v_mov_b32_dpp v204, v212 row_shr:8 row_mask:0xf bank_mask:0xc
	v_mov_b32_dpp v205, v213 row_shr:8 row_mask:0xf bank_mask:0xc
	v_mov_b32_dpp v206, v214 row_shr:8 row_mask:0xf bank_mask:0xc
	v_mov_b32_dpp v207, v215 row_shr:8 row_mask:0xf bank_mask:0xc
	v_pk_add_f32 v[28:29], v[28:29], v[180:181]
	v_pk_add_f32 v[30:31], v[30:31], v[182:183]
	v_pk_add_f32 v[24:25], v[24:25], v[184:185]
	v_pk_add_f32 v[26:27], v[26:27], v[186:187]
	v_pk_add_f32 v[20:21], v[20:21], v[188:189]
	v_pk_add_f32 v[22:23], v[22:23], v[190:191]
	v_pk_add_f32 v[12:13], v[12:13], v[192:193]
	v_pk_add_f32 v[14:15], v[14:15], v[194:195]
	v_pk_add_f32 v[16:17], v[16:17], v[196:197]
	v_pk_add_f32 v[18:19], v[18:19], v[198:199]
	v_pk_add_f32 v[8:9], v[8:9], v[200:201]
	v_pk_add_f32 v[10:11], v[10:11], v[202:203]
	v_pk_add_f32 v[4:5], v[4:5], v[204:205]
	v_pk_add_f32 v[6:7], v[6:7], v[206:207]
	v_pk_add_f32 v[0:1], v[0:1], v[208:209]
	v_pk_add_f32 v[2:3], v[2:3], v[210:211]
	global_store_dwordx4 v222, v[28:31], s[52:53]
	global_store_dwordx4 v222, v[24:27], s[52:53] offset:64
	global_store_dwordx4 v222, v[20:23], s[52:53] offset:512
	global_store_dwordx4 v222, v[12:15], s[52:53] offset:576
	global_store_dwordx4 v223, v[16:19], s[52:53]
	global_store_dwordx4 v223, v[8:11], s[52:53] offset:64
	global_store_dwordx4 v223, v[4:7], s[52:53] offset:512
	global_store_dwordx4 v223, v[0:3], s[52:53] offset:576
	s_cbranch_vccz .LBB0_1232
	s_waitcnt vmcnt(0)
	s_cmpk_gt_u32 s4, 0xff
	s_cbranch_scc1 .LBB0_1243
	s_barrier

; #define PG8_STAGE(bufoff, gbase, voff) do { _Pragma("unroll") for (int _i = 0; _i < 2; ++_i) \
;         __builtin_amdgcn_global_load_lds((const unsigned*)((const char*)(gbase) + (voff)[_i]), (LAS unsigned*)(lds + (bufoff) + ldsw + _i * 8192), 16, 0, 0); } while (0)
; #define PG8_LDA(dst, b, h) do { _Pragma("unroll") for (int m = 0; m < 4; ++m) _Pragma("unroll") for (int k = 0; k < 2; ++k) dst[m][k] = *(const LAS bf16x8*)(lds + PG8_SA(b, h) + aoff + m * 2048 + k * 1024); } while (0)
; #define PG8_LDB(dst, b, h) do { _Pragma("unroll") for (int n = 0; n < 2; ++n) _Pragma("unroll") for (int k = 0; k < 2; ++k) dst[n][k] = *(const LAS bf16x8*)(lds + PG8_SB(b, h) + boff + n * 2048 + k * 1024); } while (0)
; #define PG8_MMA(ai, bj, At, Bt) do { __builtin_amdgcn_s_setprio(1); _Pragma("unroll") for (int m = 0; m < 4; ++m) _Pragma("unroll") for (int n = 0; n < 2; ++n) _Pragma("unroll") for (int k = 0; k < 2; ++k) \
;         acc[ai][bj][m][n] = __builtin_amdgcn_mfma_f32_16x16x32_bf16(Bt[n][k], At[m][k], acc[ai][bj][m][n], 0, 0, 0); __builtin_amdgcn_s_setprio(0); } while (0)
; #define PG8_WAIT_V(n) asm volatile("s_waitcnt vmcnt(" #n ")" ::: "memory")
; #define PG8_WAIT_L(n) asm volatile("s_waitcnt lgkmcnt(" #n ")" ::: "memory")
; template <class Epi>
; __device__ __forceinline__ void gemm_phase(LAS unsigned char* lds, const Gemm g, const StaticOrder& S, const Epi& E) {
;     ...
;         for (int t = 0; t < nt; t += 2) {
;             const bool last = (t == nt - 2);
;             const char* a1 = cA + (size_t)(t + 1) * kstep;
;             const char* a2 = last ? nA : cA + (size_t)(t + 2) * kstep; const char* b2 = last ? nB : cB + (size_t)(t + 2) * kstep;
;             const char* a3 = a2 + kstep; const char* b3 = b2 + kstep;
;             PG8_LDB(B0, 0, 0); PG8_SCHED; PG8_LDA(At, 0, 0); PG8_STAGE(PG8_SA(1, 1), a1 + hstepA, voffA);
;             PG8_WAIT_L(8); PG8_BAR; PG8_WAIT_L(0); PG8_MMA(0, 0, At, B0); PG8_BAR; PG8_SCHED;
;             PG8_LDB(B1, 0, 1); PG8_STAGE(PG8_SB(0, 0), b2, voffB);
;             PG8_BAR; PG8_WAIT_L(0); PG8_MMA(0, 1, At, B1); PG8_BAR;
;             PG8_LDA(At, 0, 1); PG8_STAGE(PG8_SA(0, 0), a2, voffA);
;             PG8_BAR; PG8_WAIT_L(0); PG8_MMA(1, 0, At, B0); PG8_BAR; PG8_SCHED;
;             PG8_STAGE(PG8_SB(0, 1), b2 + hstepB, voffB);
;             PG8_WAIT_V(6); PG8_BAR; PG8_MMA(1, 1, At, B1); PG8_BAR;
.LBB0_1461:
	ds_read_b128 v[140:143], v149
	ds_read_b128 v[152:155], v149 offset:1024
	ds_read_b128 v[156:159], v149 offset:2048
	ds_read_b128 v[160:163], v149 offset:3072
	s_add_u32 s34, s30, 0x100
	s_addc_u32 s35, s31, 0
	s_cmp_eq_u32 s74, 40
	s_cselect_b32 s39, s13, s35
	s_cselect_b32 s38, s12, s34
	s_cselect_b32 s37, s15, s73
	s_cselect_b32 s36, s14, s72
	v_lshl_add_u64 v[144:145], s[30:31], 0, v[132:133]
	s_add_i32 m0, s8, 0xc000
	ds_read_b128 v[164:167], v150
	ds_read_b128 v[168:171], v150 offset:1024
	ds_read_b128 v[172:175], v150 offset:2048
	ds_read_b128 v[176:179], v150 offset:3072
	ds_read_b128 v[180:183], v150 offset:4096
	ds_read_b128 v[184:187], v150 offset:5120
	ds_read_b128 v[188:191], v150 offset:6144
	ds_read_b128 v[192:195], v150 offset:7168
	global_load_lds_dwordx4 v[144:145], off
	v_lshl_add_u64 v[144:145], s[30:31], 0, v[134:135]
	s_add_i32 m0, s8, 0xe000
	s_nop 0
	global_load_lds_dwordx4 v[144:145], off
	ds_read_b128 v[196:199], v151
	ds_read_b128 v[200:203], v151 offset:1024
	ds_read_b128 v[204:207], v151 offset:2048
	ds_read_b128 v[208:211], v151 offset:3072
	s_waitcnt lgkmcnt(0)
	s_barrier
	s_setprio 1
	v_mfma_f32_16x16x32_bf16 v[124:127], v[140:143], v[164:167], v[124:127]
	v_mfma_f32_16x16x32_bf16 v[120:123], v[156:159], v[164:167], v[120:123]
	v_mfma_f32_16x16x32_bf16 v[112:115], v[140:143], v[172:175], v[112:115]
	v_mfma_f32_16x16x32_bf16 v[104:107], v[156:159], v[172:175], v[104:107]
	v_mfma_f32_16x16x32_bf16 v[92:95], v[140:143], v[180:183], v[92:95]
	v_mfma_f32_16x16x32_bf16 v[88:91], v[156:159], v[180:183], v[88:91]
	v_mfma_f32_16x16x32_bf16 v[80:83], v[140:143], v[188:191], v[80:83]
	v_mfma_f32_16x16x32_bf16 v[72:75], v[156:159], v[188:191], v[72:75]
	v_mfma_f32_16x16x32_bf16 v[124:127], v[152:155], v[168:171], v[124:127]
	v_mfma_f32_16x16x32_bf16 v[120:123], v[160:163], v[168:171], v[120:123]
	v_mfma_f32_16x16x32_bf16 v[112:115], v[152:155], v[176:179], v[112:115]
	v_mfma_f32_16x16x32_bf16 v[104:107], v[160:163], v[176:179], v[104:107]
	v_mfma_f32_16x16x32_bf16 v[92:95], v[152:155], v[184:187], v[92:95]
	v_mfma_f32_16x16x32_bf16 v[88:91], v[160:163], v[184:187], v[88:91]
	v_mfma_f32_16x16x32_bf16 v[80:83], v[152:155], v[192:195], v[80:83]
	v_mfma_f32_16x16x32_bf16 v[72:75], v[160:163], v[192:195], v[72:75]
	v_mfma_f32_16x16x32_bf16 v[116:119], v[196:199], v[164:167], v[116:119]
	v_mfma_f32_16x16x32_bf16 v[108:111], v[204:207], v[164:167], v[108:111]
	v_mfma_f32_16x16x32_bf16 v[100:103], v[196:199], v[172:175], v[100:103]
	v_mfma_f32_16x16x32_bf16 v[96:99], v[204:207], v[172:175], v[96:99]
	v_mfma_f32_16x16x32_bf16 v[84:87], v[196:199], v[180:183], v[84:87]
	v_mfma_f32_16x16x32_bf16 v[76:79], v[204:207], v[180:183], v[76:79]
	v_mfma_f32_16x16x32_bf16 v[68:71], v[196:199], v[188:191], v[68:71]
	v_mfma_f32_16x16x32_bf16 v[64:67], v[204:207], v[188:191], v[64:67]
	v_mfma_f32_16x16x32_bf16 v[116:119], v[200:203], v[168:171], v[116:119]
	v_mfma_f32_16x16x32_bf16 v[108:111], v[208:211], v[168:171], v[108:111]
	v_mfma_f32_16x16x32_bf16 v[100:103], v[200:203], v[176:179], v[100:103]
	v_mfma_f32_16x16x32_bf16 v[96:99], v[208:211], v[176:179], v[96:99]
	v_mfma_f32_16x16x32_bf16 v[84:87], v[200:203], v[184:187], v[84:87]
	v_mfma_f32_16x16x32_bf16 v[76:79], v[208:211], v[184:187], v[76:79]
	v_mfma_f32_16x16x32_bf16 v[68:71], v[200:203], v[192:195], v[68:71]
	v_mfma_f32_16x16x32_bf16 v[64:67], v[208:211], v[192:195], v[64:67]
	s_setprio 0
	s_barrier
	s_nop 1
	ds_read_b128 v[164:167], v150 offset:16384
	ds_read_b128 v[168:171], v150 offset:17408
	ds_read_b128 v[172:175], v150 offset:18432
	ds_read_b128 v[176:179], v150 offset:19456
	ds_read_b128 v[180:183], v150 offset:20480
	ds_read_b128 v[184:187], v150 offset:21504
	ds_read_b128 v[188:191], v150 offset:22528
	ds_read_b128 v[192:195], v150 offset:23552
	s_add_i32 s30, s45, s7
	v_lshl_add_u64 v[144:145], s[36:37], 0, v[128:129]
	s_mov_b32 m0, s30
	s_nop 0
	global_load_lds_dwordx4 v[144:145], off
	v_lshl_add_u64 v[212:213], s[36:37], 0, v[130:131]
	s_add_i32 m0, s30, 0x2000
	s_nop 0
	global_load_lds_dwordx4 v[212:213], off
	s_mov_b32 m0, s8
	v_lshl_add_u64 v[214:215], s[38:39], 0, v[128:129]
	global_load_lds_dwordx4 v[214:215], off
	v_lshl_add_u64 v[216:217], s[38:39], 0, v[130:131]
	s_mov_b32 m0, s9
	s_nop 0
	global_load_lds_dwordx4 v[216:217], off
	s_add_u32 s30, s36, 0xb0000
	s_addc_u32 s31, s37, 0
	s_add_i32 s75, s46, s7
	v_lshl_add_u64 v[254:255], s[30:31], 0, v[128:129]
	s_mov_b32 m0, s75
	s_nop 0
	global_load_lds_dwordx4 v[254:255], off
	v_lshl_add_u64 v[254:255], s[30:31], 0, v[130:131]
	s_add_i32 m0, s75, 0x2000
	s_nop 0
	global_load_lds_dwordx4 v[254:255], off
	s_waitcnt vmcnt(6)
	s_waitcnt lgkmcnt(0)
	s_barrier
; #define PG8_STAGE(bufoff, gbase, voff) do { _Pragma("unroll") for (int _i = 0; _i < 2; ++_i) \
;         __builtin_amdgcn_global_load_lds((const unsigned*)((const char*)(gbase) + (voff)[_i]), (LAS unsigned*)(lds + (bufoff) + ldsw + _i * 8192), 16, 0, 0); } while (0)
; #define PG8_LDA(dst, b, h) do { _Pragma("unroll") for (int m = 0; m < 4; ++m) _Pragma("unroll") for (int k = 0; k < 2; ++k) dst[m][k] = *(const LAS bf16x8*)(lds + PG8_SA(b, h) + aoff + m * 2048 + k * 1024); } while (0)
; #define PG8_LDB(dst, b, h) do { _Pragma("unroll") for (int n = 0; n < 2; ++n) _Pragma("unroll") for (int k = 0; k < 2; ++k) dst[n][k] = *(const LAS bf16x8*)(lds + PG8_SB(b, h) + boff + n * 2048 + k * 1024); } while (0)
; #define PG8_MMA(ai, bj, At, Bt) do { __builtin_amdgcn_s_setprio(1); _Pragma("unroll") for (int m = 0; m < 4; ++m) _Pragma("unroll") for (int n = 0; n < 2; ++n) _Pragma("unroll") for (int k = 0; k < 2; ++k) \
;         acc[ai][bj][m][n] = __builtin_amdgcn_mfma_f32_16x16x32_bf16(Bt[n][k], At[m][k], acc[ai][bj][m][n], 0, 0, 0); __builtin_amdgcn_s_setprio(0); } while (0)
; #define PG8_WAIT_V(n) asm volatile("s_waitcnt vmcnt(" #n ")" ::: "memory")
; #define PG8_WAIT_L(n) asm volatile("s_waitcnt lgkmcnt(" #n ")" ::: "memory")
; #define PG8_BAR __builtin_amdgcn_s_barrier()
; #define PG8_SCHED __builtin_amdgcn_sched_barrier(0)
; template <class Epi>
; __device__ __forceinline__ void gemm_phase(LAS unsigned char* lds, const Gemm g, const StaticOrder& S, const Epi& E) {
;     ...
;             PG8_WAIT_V(6); PG8_BAR; PG8_MMA(1, 1, At, B1); PG8_BAR;
;             PG8_LDB(B0, 1, 0); PG8_SCHED; PG8_LDA(At, 1, 0); PG8_STAGE(PG8_SA(0, 1), a2 + hstepA, voffA);
;             PG8_WAIT_L(8); PG8_BAR; PG8_WAIT_L(0); PG8_MMA(0, 0, At, B0); PG8_BAR; PG8_SCHED;
;             PG8_LDB(B1, 1, 1); PG8_STAGE(PG8_SB(1, 0), b3, voffB);
;             PG8_BAR; PG8_WAIT_L(0); PG8_MMA(0, 1, At, B1); PG8_BAR;
;             PG8_LDA(At, 1, 1); PG8_STAGE(PG8_SA(1, 0), a3, voffA);
;             PG8_BAR; PG8_WAIT_L(0); PG8_MMA(1, 0, At, B0); PG8_BAR; PG8_SCHED;
	s_setprio 1
	v_mfma_f32_16x16x32_bf16 v[60:63], v[140:143], v[164:167], v[60:63]
	v_mfma_f32_16x16x32_bf16 v[56:59], v[156:159], v[164:167], v[56:59]
	v_mfma_f32_16x16x32_bf16 v[48:51], v[140:143], v[172:175], v[48:51]
	v_mfma_f32_16x16x32_bf16 v[40:43], v[156:159], v[172:175], v[40:43]
	v_mfma_f32_16x16x32_bf16 v[28:31], v[140:143], v[180:183], v[28:31]
	v_mfma_f32_16x16x32_bf16 v[24:27], v[156:159], v[180:183], v[24:27]
	v_mfma_f32_16x16x32_bf16 v[16:19], v[140:143], v[188:191], v[16:19]
	v_mfma_f32_16x16x32_bf16 v[8:11], v[156:159], v[188:191], v[8:11]
	v_mfma_f32_16x16x32_bf16 v[60:63], v[152:155], v[168:171], v[60:63]
	v_mfma_f32_16x16x32_bf16 v[56:59], v[160:163], v[168:171], v[56:59]
	v_mfma_f32_16x16x32_bf16 v[48:51], v[152:155], v[176:179], v[48:51]
	v_mfma_f32_16x16x32_bf16 v[40:43], v[160:163], v[176:179], v[40:43]
	v_mfma_f32_16x16x32_bf16 v[28:31], v[152:155], v[184:187], v[28:31]
	v_mfma_f32_16x16x32_bf16 v[24:27], v[160:163], v[184:187], v[24:27]
	v_mfma_f32_16x16x32_bf16 v[16:19], v[152:155], v[192:195], v[16:19]
	v_mfma_f32_16x16x32_bf16 v[8:11], v[160:163], v[192:195], v[8:11]
	v_mfma_f32_16x16x32_bf16 v[52:55], v[196:199], v[164:167], v[52:55]
	v_mfma_f32_16x16x32_bf16 v[44:47], v[204:207], v[164:167], v[44:47]
	v_mfma_f32_16x16x32_bf16 v[36:39], v[196:199], v[172:175], v[36:39]
	v_mfma_f32_16x16x32_bf16 v[32:35], v[204:207], v[172:175], v[32:35]
	v_mfma_f32_16x16x32_bf16 v[20:23], v[196:199], v[180:183], v[20:23]
	v_mfma_f32_16x16x32_bf16 v[12:15], v[204:207], v[180:183], v[12:15]
	v_mfma_f32_16x16x32_bf16 v[4:7], v[196:199], v[188:191], v[4:7]
	v_mfma_f32_16x16x32_bf16 v[0:3], v[204:207], v[188:191], v[0:3]
	v_mfma_f32_16x16x32_bf16 v[52:55], v[200:203], v[168:171], v[52:55]
	v_mfma_f32_16x16x32_bf16 v[44:47], v[208:211], v[168:171], v[44:47]
	v_mfma_f32_16x16x32_bf16 v[36:39], v[200:203], v[176:179], v[36:39]
	v_mfma_f32_16x16x32_bf16 v[32:35], v[208:211], v[176:179], v[32:35]
	v_mfma_f32_16x16x32_bf16 v[20:23], v[200:203], v[184:187], v[20:23]
	v_mfma_f32_16x16x32_bf16 v[12:15], v[208:211], v[184:187], v[12:15]
	v_mfma_f32_16x16x32_bf16 v[4:7], v[200:203], v[192:195], v[4:7]
	v_mfma_f32_16x16x32_bf16 v[0:3], v[208:211], v[192:195], v[0:3]
	s_setprio 0
	s_add_i32 s75, 0, 0x18000
	v_add_u32_e32 v160, s75, v147
	s_barrier
	ds_read_b128 v[140:143], v160
	ds_read_b128 v[152:155], v160 offset:1024
	ds_read_b128 v[156:159], v160 offset:2048
	ds_read_b128 v[160:163], v160 offset:3072
	s_add_u32 s30, s38, 0xb0000
	s_addc_u32 s31, s39, 0
	s_mov_b32 m0, s40
	v_lshl_add_u64 v[196:197], s[30:31], 0, v[128:129]
	ds_read_b128 v[164:167], v150 offset:32768
	ds_read_b128 v[168:171], v150 offset:33792
	ds_read_b128 v[172:175], v150 offset:34816
	ds_read_b128 v[176:179], v150 offset:35840
	ds_read_b128 v[180:183], v150 offset:36864
	ds_read_b128 v[184:187], v150 offset:37888
	ds_read_b128 v[188:191], v150 offset:38912
	ds_read_b128 v[192:195], v150 offset:39936
	global_load_lds_dwordx4 v[196:197], off
	v_lshl_add_u64 v[196:197], s[30:31], 0, v[130:131]
	s_mov_b32 m0, s41
	s_nop 0
	global_load_lds_dwordx4 v[196:197], off
	s_add_i32 s38, 0, 0x1c000
	v_add_u32_e32 v208, s38, v147
	ds_read_b128 v[196:199], v208
	ds_read_b128 v[200:203], v208 offset:1024
	ds_read_b128 v[204:207], v208 offset:2048
	ds_read_b128 v[208:211], v208 offset:3072
	s_waitcnt lgkmcnt(0)
	s_barrier
	s_setprio 1
	v_mfma_f32_16x16x32_bf16 v[124:127], v[140:143], v[164:167], v[124:127]
	v_mfma_f32_16x16x32_bf16 v[120:123], v[156:159], v[164:167], v[120:123]
	v_mfma_f32_16x16x32_bf16 v[112:115], v[140:143], v[172:175], v[112:115]
	v_mfma_f32_16x16x32_bf16 v[104:107], v[156:159], v[172:175], v[104:107]
	v_mfma_f32_16x16x32_bf16 v[92:95], v[140:143], v[180:183], v[92:95]
	v_mfma_f32_16x16x32_bf16 v[88:91], v[156:159], v[180:183], v[88:91]
	v_mfma_f32_16x16x32_bf16 v[80:83], v[140:143], v[188:191], v[80:83]
	v_mfma_f32_16x16x32_bf16 v[72:75], v[156:159], v[188:191], v[72:75]
	v_mfma_f32_16x16x32_bf16 v[124:127], v[152:155], v[168:171], v[124:127]
	v_mfma_f32_16x16x32_bf16 v[120:123], v[160:163], v[168:171], v[120:123]
	v_mfma_f32_16x16x32_bf16 v[112:115], v[152:155], v[176:179], v[112:115]
	v_mfma_f32_16x16x32_bf16 v[104:107], v[160:163], v[176:179], v[104:107]
	v_mfma_f32_16x16x32_bf16 v[92:95], v[152:155], v[184:187], v[92:95]
	v_mfma_f32_16x16x32_bf16 v[88:91], v[160:163], v[184:187], v[88:91]
	v_mfma_f32_16x16x32_bf16 v[80:83], v[152:155], v[192:195], v[80:83]
	v_mfma_f32_16x16x32_bf16 v[72:75], v[160:163], v[192:195], v[72:75]
	v_mfma_f32_16x16x32_bf16 v[116:119], v[196:199], v[164:167], v[116:119]
	v_mfma_f32_16x16x32_bf16 v[108:111], v[204:207], v[164:167], v[108:111]
	v_mfma_f32_16x16x32_bf16 v[100:103], v[196:199], v[172:175], v[100:103]
	v_mfma_f32_16x16x32_bf16 v[96:99], v[204:207], v[172:175], v[96:99]
	v_mfma_f32_16x16x32_bf16 v[84:87], v[196:199], v[180:183], v[84:87]
	v_mfma_f32_16x16x32_bf16 v[76:79], v[204:207], v[180:183], v[76:79]
	v_mfma_f32_16x16x32_bf16 v[68:71], v[196:199], v[188:191], v[68:71]
	v_mfma_f32_16x16x32_bf16 v[64:67], v[204:207], v[188:191], v[64:67]
	v_mfma_f32_16x16x32_bf16 v[116:119], v[200:203], v[168:171], v[116:119]
	v_mfma_f32_16x16x32_bf16 v[108:111], v[208:211], v[168:171], v[108:111]
	v_mfma_f32_16x16x32_bf16 v[100:103], v[200:203], v[176:179], v[100:103]
	v_mfma_f32_16x16x32_bf16 v[96:99], v[208:211], v[176:179], v[96:99]
	v_mfma_f32_16x16x32_bf16 v[84:87], v[200:203], v[184:187], v[84:87]
	v_mfma_f32_16x16x32_bf16 v[76:79], v[208:211], v[184:187], v[76:79]
	v_mfma_f32_16x16x32_bf16 v[68:71], v[200:203], v[192:195], v[68:71]
	v_mfma_f32_16x16x32_bf16 v[64:67], v[208:211], v[192:195], v[64:67]
	s_setprio 0
	s_barrier
; #define PG8_STAGE(bufoff, gbase, voff) do { _Pragma("unroll") for (int _i = 0; _i < 2; ++_i) \
;         __builtin_amdgcn_global_load_lds((const unsigned*)((const char*)(gbase) + (voff)[_i]), (LAS unsigned*)(lds + (bufoff) + ldsw + _i * 8192), 16, 0, 0); } while (0)
; #define PG8_WAIT_V(n) asm volatile("s_waitcnt vmcnt(" #n ")" ::: "memory")
; template <class Epi>
; __device__ __forceinline__ void gemm_phase(LAS unsigned char* lds, const Gemm g, const StaticOrder& S, const Epi& E) {
;     ...
;             PG8_LDB(B1, 1, 1); PG8_STAGE(PG8_SB(1, 0), b3, voffB);
;             PG8_BAR; PG8_WAIT_L(0); PG8_MMA(0, 1, At, B1); PG8_BAR;
;             PG8_LDA(At, 1, 1); PG8_STAGE(PG8_SA(1, 0), a3, voffA);
;             PG8_BAR; PG8_WAIT_L(0); PG8_MMA(1, 0, At, B0); PG8_BAR; PG8_SCHED;
;             PG8_STAGE(PG8_SB(1, 1), b3 + hstepB, voffB);
;             PG8_WAIT_V(6); PG8_BAR; PG8_MMA(1, 1, At, B1); PG8_BAR;
;         }
;     __device__ __forceinline__ void operator()(AccRef acc, const Unit& u, int wr, int wc, int fr, int fq) const {
;         const int row0 = u.pm * 256 + wr * 64 + fr, col0 = u.pn * 256 + wc * 32 + 4 * fq;
;         f32x4 sv[2][2], bv[2][2];
; #pragma unroll
;         for (int bj = 0; bj < 2; ++bj)
; #pragma unroll
;             for (int n = 0; n < 2; ++n) {
;                 sv[bj][n] = scale ? *(const f32x4*)(scale + col0 + bj * 128 + n * 16) : (f32x4){1.f, 1.f, 1.f, 1.f};
;                 bv[bj][n] = bias ? *(const f32x4*)(bias + col0 + bj * 128 + n * 16) : (f32x4){0.f, 0.f, 0.f, 0.f}; }
; #pragma unroll
;         for (int ai = 0; ai < 2; ++ai)
; #pragma unroll
;             for (int mh = 0; mh < 2; ++mh) {
;                 f32x4 bs[2][2][2];
; #pragma unroll
;                 for (int m = 0; m < 2; ++m)
; #pragma unroll
;                     for (int bj = 0; bj < 2; ++bj)
; #pragma unroll
;                         for (int n = 0; n < 2; ++n) bs[m][bj][n] = *(const f32x4*)(base + (size_t)(row0 + ai * 128 + (2 * mh + m) * 16) * D + col0 + bj * 128 + n * 16);
; #pragma unroll
;                 for (int m = 0; m < 2; ++m)
; #pragma unroll
;                     for (int bj = 0; bj < 2; ++bj)
; #pragma unroll
;                         for (int n = 0; n < 2; ++n) *(f32x4*)(out + (size_t)(row0 + ai * 128 + (2 * mh + m) * 16) * D + col0 + bj * 128 + n * 16) = bs[m][bj][n] + sv[bj][n] * (acc[ai][bj][2 * mh + m][n] + bv[bj][n]);
	s_nop 1
	ds_read_b128 v[164:167], v150 offset:49152
	ds_read_b128 v[168:171], v150 offset:50176
	ds_read_b128 v[172:175], v150 offset:51200
	ds_read_b128 v[176:179], v150 offset:52224
	ds_read_b128 v[180:183], v150 offset:53248
	ds_read_b128 v[184:187], v150 offset:54272
	ds_read_b128 v[188:191], v150 offset:55296
	ds_read_b128 v[192:195], v150 offset:56320
	s_add_i32 s30, s75, s7
	v_lshl_add_u64 v[254:255], v[144:145], 0, s[22:23]
	s_mov_b32 m0, s30
	s_nop 0
	global_load_lds_dwordx4 v[254:255], off
	v_lshl_add_u64 v[254:255], v[212:213], 0, s[22:23]
	s_add_i32 m0, s30, 0x2000
	s_nop 0
	global_load_lds_dwordx4 v[254:255], off
	s_mov_b32 m0, s43
	v_lshl_add_u64 v[254:255], v[214:215], 0, s[22:23]
	global_load_lds_dwordx4 v[254:255], off
	v_lshl_add_u64 v[144:145], v[216:217], 0, s[22:23]
	s_mov_b32 m0, s44
	s_nop 0
	global_load_lds_dwordx4 v[144:145], off
	s_add_u32 s30, s36, 0xb0080
	s_addc_u32 s31, s37, 0
	s_add_i32 s36, s38, s7
	v_lshl_add_u64 v[254:255], s[30:31], 0, v[128:129]
	s_mov_b32 m0, s36
	s_nop 0
	global_load_lds_dwordx4 v[254:255], off
	v_lshl_add_u64 v[254:255], s[30:31], 0, v[130:131]
	s_add_i32 m0, s36, 0x2000
	s_nop 0
	global_load_lds_dwordx4 v[254:255], off
	s_waitcnt vmcnt(6)
	s_waitcnt lgkmcnt(0)
	s_barrier
	s_setprio 1
	v_mfma_f32_16x16x32_bf16 v[60:63], v[140:143], v[164:167], v[60:63]
	v_mfma_f32_16x16x32_bf16 v[56:59], v[156:159], v[164:167], v[56:59]
	v_mfma_f32_16x16x32_bf16 v[48:51], v[140:143], v[172:175], v[48:51]
	v_mfma_f32_16x16x32_bf16 v[40:43], v[156:159], v[172:175], v[40:43]
	v_mfma_f32_16x16x32_bf16 v[28:31], v[140:143], v[180:183], v[28:31]
	v_mfma_f32_16x16x32_bf16 v[24:27], v[156:159], v[180:183], v[24:27]
	v_mfma_f32_16x16x32_bf16 v[16:19], v[140:143], v[188:191], v[16:19]
	v_mfma_f32_16x16x32_bf16 v[8:11], v[156:159], v[188:191], v[8:11]
	v_mfma_f32_16x16x32_bf16 v[60:63], v[152:155], v[168:171], v[60:63]
	v_mfma_f32_16x16x32_bf16 v[56:59], v[160:163], v[168:171], v[56:59]
	v_mfma_f32_16x16x32_bf16 v[48:51], v[152:155], v[176:179], v[48:51]
	v_mfma_f32_16x16x32_bf16 v[40:43], v[160:163], v[176:179], v[40:43]
	v_mfma_f32_16x16x32_bf16 v[28:31], v[152:155], v[184:187], v[28:31]
	v_mfma_f32_16x16x32_bf16 v[24:27], v[160:163], v[184:187], v[24:27]
	v_mfma_f32_16x16x32_bf16 v[16:19], v[152:155], v[192:195], v[16:19]
	v_mfma_f32_16x16x32_bf16 v[8:11], v[160:163], v[192:195], v[8:11]
	v_mfma_f32_16x16x32_bf16 v[52:55], v[196:199], v[164:167], v[52:55]
	v_mfma_f32_16x16x32_bf16 v[44:47], v[204:207], v[164:167], v[44:47]
	v_mfma_f32_16x16x32_bf16 v[36:39], v[196:199], v[172:175], v[36:39]
	v_mfma_f32_16x16x32_bf16 v[32:35], v[204:207], v[172:175], v[32:35]
	v_mfma_f32_16x16x32_bf16 v[20:23], v[196:199], v[180:183], v[20:23]
	v_mfma_f32_16x16x32_bf16 v[12:15], v[204:207], v[180:183], v[12:15]
	v_mfma_f32_16x16x32_bf16 v[4:7], v[196:199], v[188:191], v[4:7]
	v_mfma_f32_16x16x32_bf16 v[0:3], v[204:207], v[188:191], v[0:3]
	v_mfma_f32_16x16x32_bf16 v[52:55], v[200:203], v[168:171], v[52:55]
	v_mfma_f32_16x16x32_bf16 v[44:47], v[208:211], v[168:171], v[44:47]
	v_mfma_f32_16x16x32_bf16 v[36:39], v[200:203], v[176:179], v[36:39]
	v_mfma_f32_16x16x32_bf16 v[32:35], v[208:211], v[176:179], v[32:35]
	v_mfma_f32_16x16x32_bf16 v[20:23], v[200:203], v[184:187], v[20:23]
	v_mfma_f32_16x16x32_bf16 v[12:15], v[208:211], v[184:187], v[12:15]
	v_mfma_f32_16x16x32_bf16 v[4:7], v[200:203], v[192:195], v[4:7]
	v_mfma_f32_16x16x32_bf16 v[0:3], v[208:211], v[192:195], v[0:3]
	s_setprio 0
	s_add_i32 s74, s74, 2
	s_add_u32 s72, s72, 0x100
	s_addc_u32 s73, s73, 0
	s_cmp_gt_u32 s74, 41
	s_mov_b64 s[30:31], s[34:35]
	s_barrier
	s_cbranch_scc0 .LBB0_1461
	v_lshl_or_b32 v144, s49, 8, v148
	v_lshl_add_u32 v145, s63, 8, v146
	v_lshlrev_b32_e32 v144, 2, v144
	v_lshl_add_u32 v145, v145, 12, v144
	v_add_u32_e32 v216, 0x10000, v145
	v_add_u32_e32 v217, 0x20000, v145
	v_add_u32_e32 v218, 0x30000, v145
	v_add_u32_e32 v220, 0x80000, v145
	v_add_u32_e32 v221, 0x90000, v145
	v_add_u32_e32 v222, 0xa0000, v145
	v_add_u32_e32 v223, 0xb0000, v145
	v_and_b32_e32 v235, 8, v146
	v_cmp_ne_u32_e32 vcc, 0, v235
	v_mov_b32_e32 v232, 0xffff8040
	s_nop 0
	v_cndmask_b32_e32 v232, 0, v232, vcc
	v_mov_b32_e32 v233, 64
	v_mov_b32_e32 v235, 0x8000
	v_cndmask_b32_e32 v233, v235, v233, vcc
	v_add_u32_e32 v224, v145, v232
	v_add_u32_e32 v225, v216, v232
	v_add_u32_e32 v226, v217, v232
	v_add_u32_e32 v227, v218, v232
	v_add_u32_e32 v228, v220, v232
	v_add_u32_e32 v229, v221, v232
	v_add_u32_e32 v230, v222, v232
	v_add_u32_e32 v231, v223, v232
	s_and_b64 vcc, exec, s[10:11]
	s_mov_b32 s49, s47
	s_mov_b32 s63, s48
	s_mov_b64 s[34:35], s[14:15]
	s_mov_b64 s[30:31], s[12:13]
	global_load_dwordx4 v[140:143], v224, s[52:53]
	v_add_u32_e32 v144, v145, v233
	global_load_dwordx4 v[152:155], v144, s[52:53]
	global_load_dwordx4 v[156:159], v224, s[52:53] offset:512
	v_add_u32_e32 v144, v145, v233
	global_load_dwordx4 v[160:163], v144, s[52:53] offset:512
	global_load_dwordx4 v[164:167], v225, s[52:53]
	v_add_u32_e32 v144, v216, v233
	global_load_dwordx4 v[168:171], v144, s[52:53]
	global_load_dwordx4 v[172:175], v225, s[52:53] offset:512
	v_add_u32_e32 v144, v216, v233
	global_load_dwordx4 v[176:179], v144, s[52:53] offset:512
	global_load_dwordx4 v[180:183], v226, s[52:53]
	v_add_u32_e32 v144, v217, v233
	global_load_dwordx4 v[184:187], v144, s[52:53]
	global_load_dwordx4 v[188:191], v226, s[52:53] offset:512
	v_add_u32_e32 v144, v217, v233
	global_load_dwordx4 v[192:195], v144, s[52:53] offset:512
	global_load_dwordx4 v[196:199], v227, s[52:53]
	v_add_u32_e32 v144, v218, v233
	global_load_dwordx4 v[200:203], v144, s[52:53]
	global_load_dwordx4 v[204:207], v227, s[52:53] offset:512
;     __device__ __forceinline__ void operator()(AccRef acc, const Unit& u, int wr, int wc, int fr, int fq) const {
;     ...
;                 sv[bj][n] = scale ? *(const f32x4*)(scale + col0 + bj * 128 + n * 16) : (f32x4){1.f, 1.f, 1.f, 1.f};
;                 bv[bj][n] = bias ? *(const f32x4*)(bias + col0 + bj * 128 + n * 16) : (f32x4){0.f, 0.f, 0.f, 0.f}; }
; #pragma unroll
;         for (int ai = 0; ai < 2; ++ai)
; #pragma unroll
;             for (int mh = 0; mh < 2; ++mh) {
;                 f32x4 bs[2][2][2];
; #pragma unroll
;                 for (int m = 0; m < 2; ++m)
; #pragma unroll
;                     for (int bj = 0; bj < 2; ++bj)
; #pragma unroll
;                         for (int n = 0; n < 2; ++n) bs[m][bj][n] = *(const f32x4*)(base + (size_t)(row0 + ai * 128 + (2 * mh + m) * 16) * D + col0 + bj * 128 + n * 16);
; #pragma unroll
;                 for (int m = 0; m < 2; ++m)
; #pragma unroll
;                     for (int bj = 0; bj < 2; ++bj)
; #pragma unroll
;                         for (int n = 0; n < 2; ++n) *(f32x4*)(out + (size_t)(row0 + ai * 128 + (2 * mh + m) * 16) * D + col0 + bj * 128 + n * 16) = bs[m][bj][n] + sv[bj][n] * (acc[ai][bj][2 * mh + m][n] + bv[bj][n]);
	v_add_u32_e32 v144, v218, v233
	global_load_dwordx4 v[208:211], v144, s[52:53] offset:512
	v_pk_add_f32 v[124:125], v[124:125], 0 op_sel_hi:[1,0]
	v_pk_add_f32 v[126:127], v[126:127], 0 op_sel_hi:[1,0]
	v_pk_add_f32 v[120:121], v[120:121], 0 op_sel_hi:[1,0]
	v_pk_add_f32 v[122:123], v[122:123], 0 op_sel_hi:[1,0]
	v_pk_add_f32 v[116:117], v[116:117], 0 op_sel_hi:[1,0]
	v_pk_add_f32 v[118:119], v[118:119], 0 op_sel_hi:[1,0]
	v_pk_add_f32 v[108:109], v[108:109], 0 op_sel_hi:[1,0]
	v_pk_add_f32 v[110:111], v[110:111], 0 op_sel_hi:[1,0]
	v_pk_add_f32 v[112:113], v[112:113], 0 op_sel_hi:[1,0]
	v_pk_add_f32 v[114:115], v[114:115], 0 op_sel_hi:[1,0]
	v_pk_add_f32 v[104:105], v[104:105], 0 op_sel_hi:[1,0]
	v_pk_add_f32 v[106:107], v[106:107], 0 op_sel_hi:[1,0]
	v_pk_add_f32 v[100:101], v[100:101], 0 op_sel_hi:[1,0]
	v_pk_add_f32 v[102:103], v[102:103], 0 op_sel_hi:[1,0]
	v_pk_add_f32 v[96:97], v[96:97], 0 op_sel_hi:[1,0]
	v_pk_add_f32 v[98:99], v[98:99], 0 op_sel_hi:[1,0]
	v_pk_add_f32 v[92:93], v[92:93], 0 op_sel_hi:[1,0]
	v_pk_add_f32 v[94:95], v[94:95], 0 op_sel_hi:[1,0]
	v_pk_add_f32 v[88:89], v[88:89], 0 op_sel_hi:[1,0]
	v_pk_add_f32 v[90:91], v[90:91], 0 op_sel_hi:[1,0]
	v_pk_add_f32 v[84:85], v[84:85], 0 op_sel_hi:[1,0]
	v_pk_add_f32 v[86:87], v[86:87], 0 op_sel_hi:[1,0]
	v_pk_add_f32 v[76:77], v[76:77], 0 op_sel_hi:[1,0]
	v_pk_add_f32 v[78:79], v[78:79], 0 op_sel_hi:[1,0]
	v_pk_add_f32 v[80:81], v[80:81], 0 op_sel_hi:[1,0]
	v_pk_add_f32 v[82:83], v[82:83], 0 op_sel_hi:[1,0]
	v_pk_add_f32 v[72:73], v[72:73], 0 op_sel_hi:[1,0]
	v_pk_add_f32 v[74:75], v[74:75], 0 op_sel_hi:[1,0]
	v_pk_add_f32 v[68:69], v[68:69], 0 op_sel_hi:[1,0]
	v_pk_add_f32 v[70:71], v[70:71], 0 op_sel_hi:[1,0]
	v_pk_add_f32 v[64:65], v[64:65], 0 op_sel_hi:[1,0]
	v_pk_add_f32 v[66:67], v[66:67], 0 op_sel_hi:[1,0]
	v_pk_add_f32 v[60:61], v[60:61], 0 op_sel_hi:[1,0]
	v_pk_add_f32 v[62:63], v[62:63], 0 op_sel_hi:[1,0]
	v_pk_add_f32 v[56:57], v[56:57], 0 op_sel_hi:[1,0]
	v_pk_add_f32 v[58:59], v[58:59], 0 op_sel_hi:[1,0]
	v_pk_add_f32 v[52:53], v[52:53], 0 op_sel_hi:[1,0]
	v_pk_add_f32 v[54:55], v[54:55], 0 op_sel_hi:[1,0]
	v_pk_add_f32 v[44:45], v[44:45], 0 op_sel_hi:[1,0]
	v_pk_add_f32 v[46:47], v[46:47], 0 op_sel_hi:[1,0]
	v_pk_add_f32 v[48:49], v[48:49], 0 op_sel_hi:[1,0]
	v_pk_add_f32 v[50:51], v[50:51], 0 op_sel_hi:[1,0]
	v_pk_add_f32 v[40:41], v[40:41], 0 op_sel_hi:[1,0]
	v_pk_add_f32 v[42:43], v[42:43], 0 op_sel_hi:[1,0]
	v_pk_add_f32 v[36:37], v[36:37], 0 op_sel_hi:[1,0]
	v_pk_add_f32 v[38:39], v[38:39], 0 op_sel_hi:[1,0]
	v_pk_add_f32 v[32:33], v[32:33], 0 op_sel_hi:[1,0]
	v_pk_add_f32 v[34:35], v[34:35], 0 op_sel_hi:[1,0]
	v_pk_add_f32 v[28:29], v[28:29], 0 op_sel_hi:[1,0]
	v_pk_add_f32 v[30:31], v[30:31], 0 op_sel_hi:[1,0]
	v_pk_add_f32 v[24:25], v[24:25], 0 op_sel_hi:[1,0]
	v_pk_add_f32 v[26:27], v[26:27], 0 op_sel_hi:[1,0]
	v_pk_add_f32 v[20:21], v[20:21], 0 op_sel_hi:[1,0]
	v_pk_add_f32 v[22:23], v[22:23], 0 op_sel_hi:[1,0]
	v_pk_add_f32 v[12:13], v[12:13], 0 op_sel_hi:[1,0]
	v_pk_add_f32 v[14:15], v[14:15], 0 op_sel_hi:[1,0]
	v_pk_add_f32 v[16:17], v[16:17], 0 op_sel_hi:[1,0]
	v_pk_add_f32 v[18:19], v[18:19], 0 op_sel_hi:[1,0]
	v_pk_add_f32 v[8:9], v[8:9], 0 op_sel_hi:[1,0]
	v_pk_add_f32 v[10:11], v[10:11], 0 op_sel_hi:[1,0]
	v_pk_add_f32 v[4:5], v[4:5], 0 op_sel_hi:[1,0]
	v_pk_add_f32 v[6:7], v[6:7], 0 op_sel_hi:[1,0]
	v_pk_add_f32 v[0:1], v[0:1], 0 op_sel_hi:[1,0]
	v_pk_add_f32 v[2:3], v[2:3], 0 op_sel_hi:[1,0]
	s_waitcnt vmcnt(8)
	v_mov_b32_e32 v212, v152
	v_mov_b32_e32 v213, v153
	v_mov_b32_e32 v214, v154
	v_mov_b32_e32 v215, v155
	s_nop 0
	v_mov_b32_dpp v152, v140 row_shl:8 row_mask:0xf bank_mask:0x3
	v_mov_b32_dpp v153, v141 row_shl:8 row_mask:0xf bank_mask:0x3
	v_mov_b32_dpp v154, v142 row_shl:8 row_mask:0xf bank_mask:0x3
	v_mov_b32_dpp v155, v143 row_shl:8 row_mask:0xf bank_mask:0x3
	v_mov_b32_dpp v140, v212 row_shr:8 row_mask:0xf bank_mask:0xc
	v_mov_b32_dpp v141, v213 row_shr:8 row_mask:0xf bank_mask:0xc
	v_mov_b32_dpp v142, v214 row_shr:8 row_mask:0xf bank_mask:0xc
	v_mov_b32_dpp v143, v215 row_shr:8 row_mask:0xf bank_mask:0xc
	v_mov_b32_e32 v212, v160
	v_mov_b32_e32 v213, v161
	v_mov_b32_e32 v214, v162
	v_mov_b32_e32 v215, v163
	s_nop 0
	v_mov_b32_dpp v160, v156 row_shl:8 row_mask:0xf bank_mask:0x3
	v_mov_b32_dpp v161, v157 row_shl:8 row_mask:0xf bank_mask:0x3
	v_mov_b32_dpp v162, v158 row_shl:8 row_mask:0xf bank_mask:0x3
	v_mov_b32_dpp v163, v159 row_shl:8 row_mask:0xf bank_mask:0x3
	v_mov_b32_dpp v156, v212 row_shr:8 row_mask:0xf bank_mask:0xc
	v_mov_b32_dpp v157, v213 row_shr:8 row_mask:0xf bank_mask:0xc
	v_mov_b32_dpp v158, v214 row_shr:8 row_mask:0xf bank_mask:0xc
	v_mov_b32_dpp v159, v215 row_shr:8 row_mask:0xf bank_mask:0xc
	v_mov_b32_e32 v212, v168
	v_mov_b32_e32 v213, v169
	v_mov_b32_e32 v214, v170
	v_mov_b32_e32 v215, v171
	s_nop 0
	v_mov_b32_dpp v168, v164 row_shl:8 row_mask:0xf bank_mask:0x3
	v_mov_b32_dpp v169, v165 row_shl:8 row_mask:0xf bank_mask:0x3
	v_mov_b32_dpp v170, v166 row_shl:8 row_mask:0xf bank_mask:0x3
	v_mov_b32_dpp v171, v167 row_shl:8 row_mask:0xf bank_mask:0x3
	v_mov_b32_dpp v164, v212 row_shr:8 row_mask:0xf bank_mask:0xc
	v_mov_b32_dpp v165, v213 row_shr:8 row_mask:0xf bank_mask:0xc
	v_mov_b32_dpp v166, v214 row_shr:8 row_mask:0xf bank_mask:0xc
	v_mov_b32_dpp v167, v215 row_shr:8 row_mask:0xf bank_mask:0xc
	v_mov_b32_e32 v212, v176
	v_mov_b32_e32 v213, v177
	v_mov_b32_e32 v214, v178
	v_mov_b32_e32 v215, v179
	s_nop 0
	v_mov_b32_dpp v176, v172 row_shl:8 row_mask:0xf bank_mask:0x3
	v_mov_b32_dpp v177, v173 row_shl:8 row_mask:0xf bank_mask:0x3
	v_mov_b32_dpp v178, v174 row_shl:8 row_mask:0xf bank_mask:0x3
;     __device__ __forceinline__ void operator()(AccRef acc, const Unit& u, int wr, int wc, int fr, int fq) const {
;     ...
;                         for (int n = 0; n < 2; ++n) bs[m][bj][n] = *(const f32x4*)(base + (size_t)(row0 + ai * 128 + (2 * mh + m) * 16) * D + col0 + bj * 128 + n * 16);
; #pragma unroll
;                 for (int m = 0; m < 2; ++m)
; #pragma unroll
;                     for (int bj = 0; bj < 2; ++bj)
; #pragma unroll
;                         for (int n = 0; n < 2; ++n) *(f32x4*)(out + (size_t)(row0 + ai * 128 + (2 * mh + m) * 16) * D + col0 + bj * 128 + n * 16) = bs[m][bj][n] + sv[bj][n] * (acc[ai][bj][2 * mh + m][n] + bv[bj][n]);
;                 asm volatile("" ::: "memory"); }
	v_mov_b32_dpp v179, v175 row_shl:8 row_mask:0xf bank_mask:0x3
	v_mov_b32_dpp v172, v212 row_shr:8 row_mask:0xf bank_mask:0xc
	v_mov_b32_dpp v173, v213 row_shr:8 row_mask:0xf bank_mask:0xc
	v_mov_b32_dpp v174, v214 row_shr:8 row_mask:0xf bank_mask:0xc
	v_mov_b32_dpp v175, v215 row_shr:8 row_mask:0xf bank_mask:0xc
	v_pk_add_f32 v[124:125], v[124:125], v[140:141]
	v_pk_add_f32 v[126:127], v[126:127], v[142:143]
	v_pk_add_f32 v[120:121], v[120:121], v[152:153]
	v_pk_add_f32 v[122:123], v[122:123], v[154:155]
	v_pk_add_f32 v[116:117], v[116:117], v[156:157]
	v_pk_add_f32 v[118:119], v[118:119], v[158:159]
	v_pk_add_f32 v[108:109], v[108:109], v[160:161]
	v_pk_add_f32 v[110:111], v[110:111], v[162:163]
	v_pk_add_f32 v[112:113], v[112:113], v[164:165]
	v_pk_add_f32 v[114:115], v[114:115], v[166:167]
	v_pk_add_f32 v[104:105], v[104:105], v[168:169]
	v_pk_add_f32 v[106:107], v[106:107], v[170:171]
	v_pk_add_f32 v[100:101], v[100:101], v[172:173]
	v_pk_add_f32 v[102:103], v[102:103], v[174:175]
	v_pk_add_f32 v[96:97], v[96:97], v[176:177]
	v_pk_add_f32 v[98:99], v[98:99], v[178:179]
	global_store_dwordx4 v145, v[124:127], s[52:53]
	global_store_dwordx4 v145, v[120:123], s[52:53] offset:64
	global_store_dwordx4 v145, v[116:119], s[52:53] offset:512
	global_store_dwordx4 v145, v[108:111], s[52:53] offset:576
	global_store_dwordx4 v216, v[112:115], s[52:53]
	global_store_dwordx4 v216, v[104:107], s[52:53] offset:64
	global_store_dwordx4 v216, v[100:103], s[52:53] offset:512
	global_store_dwordx4 v216, v[96:99], s[52:53] offset:576
	global_load_dwordx4 v[140:143], v228, s[52:53]
	v_add_u32_e32 v144, v220, v233
	global_load_dwordx4 v[152:155], v144, s[52:53]
	global_load_dwordx4 v[156:159], v228, s[52:53] offset:512
	v_add_u32_e32 v144, v220, v233
	global_load_dwordx4 v[160:163], v144, s[52:53] offset:512
	global_load_dwordx4 v[164:167], v229, s[52:53]
	v_add_u32_e32 v144, v221, v233
	global_load_dwordx4 v[168:171], v144, s[52:53]
	global_load_dwordx4 v[172:175], v229, s[52:53] offset:512
	v_add_u32_e32 v144, v221, v233
	global_load_dwordx4 v[176:179], v144, s[52:53] offset:512
	s_waitcnt vmcnt(16)
	v_mov_b32_e32 v212, v184
	v_mov_b32_e32 v213, v185
	v_mov_b32_e32 v214, v186
	v_mov_b32_e32 v215, v187
	s_nop 0
	v_mov_b32_dpp v184, v180 row_shl:8 row_mask:0xf bank_mask:0x3
	v_mov_b32_dpp v185, v181 row_shl:8 row_mask:0xf bank_mask:0x3
	v_mov_b32_dpp v186, v182 row_shl:8 row_mask:0xf bank_mask:0x3
	v_mov_b32_dpp v187, v183 row_shl:8 row_mask:0xf bank_mask:0x3
	v_mov_b32_dpp v180, v212 row_shr:8 row_mask:0xf bank_mask:0xc
	v_mov_b32_dpp v181, v213 row_shr:8 row_mask:0xf bank_mask:0xc
	v_mov_b32_dpp v182, v214 row_shr:8 row_mask:0xf bank_mask:0xc
	v_mov_b32_dpp v183, v215 row_shr:8 row_mask:0xf bank_mask:0xc
	v_mov_b32_e32 v212, v192
	v_mov_b32_e32 v213, v193
	v_mov_b32_e32 v214, v194
	v_mov_b32_e32 v215, v195
	s_nop 0
	v_mov_b32_dpp v192, v188 row_shl:8 row_mask:0xf bank_mask:0x3
	v_mov_b32_dpp v193, v189 row_shl:8 row_mask:0xf bank_mask:0x3
	v_mov_b32_dpp v194, v190 row_shl:8 row_mask:0xf bank_mask:0x3
	v_mov_b32_dpp v195, v191 row_shl:8 row_mask:0xf bank_mask:0x3
	v_mov_b32_dpp v188, v212 row_shr:8 row_mask:0xf bank_mask:0xc
	v_mov_b32_dpp v189, v213 row_shr:8 row_mask:0xf bank_mask:0xc
	v_mov_b32_dpp v190, v214 row_shr:8 row_mask:0xf bank_mask:0xc
	v_mov_b32_dpp v191, v215 row_shr:8 row_mask:0xf bank_mask:0xc
	v_mov_b32_e32 v212, v200
	v_mov_b32_e32 v213, v201
	v_mov_b32_e32 v214, v202
	v_mov_b32_e32 v215, v203
	s_nop 0
	v_mov_b32_dpp v200, v196 row_shl:8 row_mask:0xf bank_mask:0x3
	v_mov_b32_dpp v201, v197 row_shl:8 row_mask:0xf bank_mask:0x3
	v_mov_b32_dpp v202, v198 row_shl:8 row_mask:0xf bank_mask:0x3
	v_mov_b32_dpp v203, v199 row_shl:8 row_mask:0xf bank_mask:0x3
	v_mov_b32_dpp v196, v212 row_shr:8 row_mask:0xf bank_mask:0xc
	v_mov_b32_dpp v197, v213 row_shr:8 row_mask:0xf bank_mask:0xc
	v_mov_b32_dpp v198, v214 row_shr:8 row_mask:0xf bank_mask:0xc
	v_mov_b32_dpp v199, v215 row_shr:8 row_mask:0xf bank_mask:0xc
	v_mov_b32_e32 v212, v208
	v_mov_b32_e32 v213, v209
	v_mov_b32_e32 v214, v210
	v_mov_b32_e32 v215, v211
	s_nop 0
	v_mov_b32_dpp v208, v204 row_shl:8 row_mask:0xf bank_mask:0x3
	v_mov_b32_dpp v209, v205 row_shl:8 row_mask:0xf bank_mask:0x3
	v_mov_b32_dpp v210, v206 row_shl:8 row_mask:0xf bank_mask:0x3
	v_mov_b32_dpp v211, v207 row_shl:8 row_mask:0xf bank_mask:0x3
	v_mov_b32_dpp v204, v212 row_shr:8 row_mask:0xf bank_mask:0xc
	v_mov_b32_dpp v205, v213 row_shr:8 row_mask:0xf bank_mask:0xc
	v_mov_b32_dpp v206, v214 row_shr:8 row_mask:0xf bank_mask:0xc
	v_mov_b32_dpp v207, v215 row_shr:8 row_mask:0xf bank_mask:0xc
	v_pk_add_f32 v[92:93], v[92:93], v[180:181]
	v_pk_add_f32 v[94:95], v[94:95], v[182:183]
	v_pk_add_f32 v[88:89], v[88:89], v[184:185]
	v_pk_add_f32 v[90:91], v[90:91], v[186:187]
	v_pk_add_f32 v[84:85], v[84:85], v[188:189]
	v_pk_add_f32 v[86:87], v[86:87], v[190:191]
	v_pk_add_f32 v[76:77], v[76:77], v[192:193]
	v_pk_add_f32 v[78:79], v[78:79], v[194:195]
	v_pk_add_f32 v[80:81], v[80:81], v[196:197]
	v_pk_add_f32 v[82:83], v[82:83], v[198:199]
	v_pk_add_f32 v[72:73], v[72:73], v[200:201]
	v_pk_add_f32 v[74:75], v[74:75], v[202:203]
	v_pk_add_f32 v[68:69], v[68:69], v[204:205]
	v_pk_add_f32 v[70:71], v[70:71], v[206:207]
	v_pk_add_f32 v[64:65], v[64:65], v[208:209]
	v_pk_add_f32 v[66:67], v[66:67], v[210:211]
	global_store_dwordx4 v217, v[92:95], s[52:53]
	global_store_dwordx4 v217, v[88:91], s[52:53] offset:64
	global_store_dwordx4 v217, v[84:87], s[52:53] offset:512
	global_store_dwordx4 v217, v[76:79], s[52:53] offset:576
	global_store_dwordx4 v218, v[80:83], s[52:53]
	global_store_dwordx4 v218, v[72:75], s[52:53] offset:64
	global_store_dwordx4 v218, v[68:71], s[52:53] offset:512
	global_store_dwordx4 v218, v[64:67], s[52:53] offset:576
	global_load_dwordx4 v[180:183], v230, s[52:53]
	v_add_u32_e32 v144, v222, v233
	global_load_dwordx4 v[184:187], v144, s[52:53]
	global_load_dwordx4 v[188:191], v230, s[52:53] offset:512
	v_add_u32_e32 v144, v222, v233
	global_load_dwordx4 v[192:195], v144, s[52:53] offset:512
	global_load_dwordx4 v[196:199], v231, s[52:53]
	v_add_u32_e32 v144, v223, v233
	global_load_dwordx4 v[200:203], v144, s[52:53]
	global_load_dwordx4 v[204:207], v231, s[52:53] offset:512
	v_add_u32_e32 v144, v223, v233
	global_load_dwordx4 v[208:211], v144, s[52:53] offset:512
	s_waitcnt vmcnt(16)
;     __device__ __forceinline__ void operator()(AccRef acc, const Unit& u, int wr, int wc, int fr, int fq) const {
;     ...
;                         for (int n = 0; n < 2; ++n) bs[m][bj][n] = *(const f32x4*)(base + (size_t)(row0 + ai * 128 + (2 * mh + m) * 16) * D + col0 + bj * 128 + n * 16);
; #pragma unroll
;                 for (int m = 0; m < 2; ++m)
; #pragma unroll
;                     for (int bj = 0; bj < 2; ++bj)
; #pragma unroll
;                         for (int n = 0; n < 2; ++n) *(f32x4*)(out + (size_t)(row0 + ai * 128 + (2 * mh + m) * 16) * D + col0 + bj * 128 + n * 16) = bs[m][bj][n] + sv[bj][n] * (acc[ai][bj][2 * mh + m][n] + bv[bj][n]);
	v_mov_b32_e32 v212, v152
	v_mov_b32_e32 v213, v153
	v_mov_b32_e32 v214, v154
	v_mov_b32_e32 v215, v155
	s_nop 0
	v_mov_b32_dpp v152, v140 row_shl:8 row_mask:0xf bank_mask:0x3
	v_mov_b32_dpp v153, v141 row_shl:8 row_mask:0xf bank_mask:0x3
	v_mov_b32_dpp v154, v142 row_shl:8 row_mask:0xf bank_mask:0x3
	v_mov_b32_dpp v155, v143 row_shl:8 row_mask:0xf bank_mask:0x3
	v_mov_b32_dpp v140, v212 row_shr:8 row_mask:0xf bank_mask:0xc
	v_mov_b32_dpp v141, v213 row_shr:8 row_mask:0xf bank_mask:0xc
	v_mov_b32_dpp v142, v214 row_shr:8 row_mask:0xf bank_mask:0xc
	v_mov_b32_dpp v143, v215 row_shr:8 row_mask:0xf bank_mask:0xc
	v_mov_b32_e32 v212, v160
	v_mov_b32_e32 v213, v161
	v_mov_b32_e32 v214, v162
	v_mov_b32_e32 v215, v163
	s_nop 0
	v_mov_b32_dpp v160, v156 row_shl:8 row_mask:0xf bank_mask:0x3
	v_mov_b32_dpp v161, v157 row_shl:8 row_mask:0xf bank_mask:0x3
	v_mov_b32_dpp v162, v158 row_shl:8 row_mask:0xf bank_mask:0x3
	v_mov_b32_dpp v163, v159 row_shl:8 row_mask:0xf bank_mask:0x3
	v_mov_b32_dpp v156, v212 row_shr:8 row_mask:0xf bank_mask:0xc
	v_mov_b32_dpp v157, v213 row_shr:8 row_mask:0xf bank_mask:0xc
	v_mov_b32_dpp v158, v214 row_shr:8 row_mask:0xf bank_mask:0xc
	v_mov_b32_dpp v159, v215 row_shr:8 row_mask:0xf bank_mask:0xc
	v_mov_b32_e32 v212, v168
	v_mov_b32_e32 v213, v169
	v_mov_b32_e32 v214, v170
	v_mov_b32_e32 v215, v171
	s_nop 0
	v_mov_b32_dpp v168, v164 row_shl:8 row_mask:0xf bank_mask:0x3
	v_mov_b32_dpp v169, v165 row_shl:8 row_mask:0xf bank_mask:0x3
	v_mov_b32_dpp v170, v166 row_shl:8 row_mask:0xf bank_mask:0x3
	v_mov_b32_dpp v171, v167 row_shl:8 row_mask:0xf bank_mask:0x3
	v_mov_b32_dpp v164, v212 row_shr:8 row_mask:0xf bank_mask:0xc
	v_mov_b32_dpp v165, v213 row_shr:8 row_mask:0xf bank_mask:0xc
	v_mov_b32_dpp v166, v214 row_shr:8 row_mask:0xf bank_mask:0xc
	v_mov_b32_dpp v167, v215 row_shr:8 row_mask:0xf bank_mask:0xc
	v_mov_b32_e32 v212, v176
	v_mov_b32_e32 v213, v177
	v_mov_b32_e32 v214, v178
	v_mov_b32_e32 v215, v179
	s_nop 0
	v_mov_b32_dpp v176, v172 row_shl:8 row_mask:0xf bank_mask:0x3
	v_mov_b32_dpp v177, v173 row_shl:8 row_mask:0xf bank_mask:0x3
	v_mov_b32_dpp v178, v174 row_shl:8 row_mask:0xf bank_mask:0x3
	v_mov_b32_dpp v179, v175 row_shl:8 row_mask:0xf bank_mask:0x3
	v_mov_b32_dpp v172, v212 row_shr:8 row_mask:0xf bank_mask:0xc
	v_mov_b32_dpp v173, v213 row_shr:8 row_mask:0xf bank_mask:0xc
	v_mov_b32_dpp v174, v214 row_shr:8 row_mask:0xf bank_mask:0xc
	v_mov_b32_dpp v175, v215 row_shr:8 row_mask:0xf bank_mask:0xc
	v_pk_add_f32 v[60:61], v[60:61], v[140:141]
	v_pk_add_f32 v[62:63], v[62:63], v[142:143]
	v_pk_add_f32 v[56:57], v[56:57], v[152:153]
	v_pk_add_f32 v[58:59], v[58:59], v[154:155]
	v_pk_add_f32 v[52:53], v[52:53], v[156:157]
	v_pk_add_f32 v[54:55], v[54:55], v[158:159]
	v_pk_add_f32 v[44:45], v[44:45], v[160:161]
	v_pk_add_f32 v[46:47], v[46:47], v[162:163]
	v_pk_add_f32 v[48:49], v[48:49], v[164:165]
	v_pk_add_f32 v[50:51], v[50:51], v[166:167]
	v_pk_add_f32 v[40:41], v[40:41], v[168:169]
	v_pk_add_f32 v[42:43], v[42:43], v[170:171]
	v_pk_add_f32 v[36:37], v[36:37], v[172:173]
	v_pk_add_f32 v[38:39], v[38:39], v[174:175]
	v_pk_add_f32 v[32:33], v[32:33], v[176:177]
	v_pk_add_f32 v[34:35], v[34:35], v[178:179]
	global_store_dwordx4 v220, v[60:63], s[52:53]
	global_store_dwordx4 v220, v[56:59], s[52:53] offset:64
	global_store_dwordx4 v220, v[52:55], s[52:53] offset:512
	global_store_dwordx4 v220, v[44:47], s[52:53] offset:576
	global_store_dwordx4 v221, v[48:51], s[52:53]
	global_store_dwordx4 v221, v[40:43], s[52:53] offset:64
	global_store_dwordx4 v221, v[36:39], s[52:53] offset:512
	global_store_dwordx4 v221, v[32:35], s[52:53] offset:576
	s_waitcnt vmcnt(8)
; #define PG8_WAIT_V(n) asm volatile("s_waitcnt vmcnt(" #n ")" ::: "memory")
; #define PG8_BAR __builtin_amdgcn_s_barrier()
; template <class Epi>
; __device__ __forceinline__ void gemm_phase(LAS unsigned char* lds, const Gemm g, const StaticOrder& S, const Epi& E) {
;     ...
;         if (!has_next) break;
;         {
; #pragma unroll
;         for (int a = 0; a < 2; ++a)
; #pragma unroll
;             for (int b = 0; b < 2; ++b)
; #pragma unroll
;                 for (int m = 0; m < 4; ++m)
; #pragma unroll
;                     for (int n = 0; n < 2; ++n) acc[a][b][m][n] = (f32x4){0.f, 0.f, 0.f, 0.f};
;         }
;         cur = nxt; cA = nA; cB = nB; ++ui;
;     }
;     PG8_WAIT_V(0);
;     if (wr == 0) PG8_BAR;
;     PG8_BAR;
;     __device__ __forceinline__ void operator()(AccRef acc, const Unit& u, int wr, int wc, int fr, int fq) const {
;     ...
;                         for (int n = 0; n < 2; ++n) bs[m][bj][n] = *(const f32x4*)(base + (size_t)(row0 + ai * 128 + (2 * mh + m) * 16) * D + col0 + bj * 128 + n * 16);
; #pragma unroll
;                 for (int m = 0; m < 2; ++m)
; #pragma unroll
;                     for (int bj = 0; bj < 2; ++bj)
; #pragma unroll
;                         for (int n = 0; n < 2; ++n) *(f32x4*)(out + (size_t)(row0 + ai * 128 + (2 * mh + m) * 16) * D + col0 + bj * 128 + n * 16) = bs[m][bj][n] + sv[bj][n] * (acc[ai][bj][2 * mh + m][n] + bv[bj][n]);
;                 asm volatile("" ::: "memory"); }
	v_mov_b32_e32 v212, v184
	v_mov_b32_e32 v213, v185
	v_mov_b32_e32 v214, v186
	v_mov_b32_e32 v215, v187
	s_nop 0
	v_mov_b32_dpp v184, v180 row_shl:8 row_mask:0xf bank_mask:0x3
	v_mov_b32_dpp v185, v181 row_shl:8 row_mask:0xf bank_mask:0x3
	v_mov_b32_dpp v186, v182 row_shl:8 row_mask:0xf bank_mask:0x3
	v_mov_b32_dpp v187, v183 row_shl:8 row_mask:0xf bank_mask:0x3
	v_mov_b32_dpp v180, v212 row_shr:8 row_mask:0xf bank_mask:0xc
	v_mov_b32_dpp v181, v213 row_shr:8 row_mask:0xf bank_mask:0xc
	v_mov_b32_dpp v182, v214 row_shr:8 row_mask:0xf bank_mask:0xc
	v_mov_b32_dpp v183, v215 row_shr:8 row_mask:0xf bank_mask:0xc
	v_mov_b32_e32 v212, v192
	v_mov_b32_e32 v213, v193
	v_mov_b32_e32 v214, v194
	v_mov_b32_e32 v215, v195
	s_nop 0
	v_mov_b32_dpp v192, v188 row_shl:8 row_mask:0xf bank_mask:0x3
	v_mov_b32_dpp v193, v189 row_shl:8 row_mask:0xf bank_mask:0x3
	v_mov_b32_dpp v194, v190 row_shl:8 row_mask:0xf bank_mask:0x3
	v_mov_b32_dpp v195, v191 row_shl:8 row_mask:0xf bank_mask:0x3
	v_mov_b32_dpp v188, v212 row_shr:8 row_mask:0xf bank_mask:0xc
	v_mov_b32_dpp v189, v213 row_shr:8 row_mask:0xf bank_mask:0xc
	v_mov_b32_dpp v190, v214 row_shr:8 row_mask:0xf bank_mask:0xc
	v_mov_b32_dpp v191, v215 row_shr:8 row_mask:0xf bank_mask:0xc
	v_mov_b32_e32 v212, v200
	v_mov_b32_e32 v213, v201
	v_mov_b32_e32 v214, v202
	v_mov_b32_e32 v215, v203
	s_nop 0
	v_mov_b32_dpp v200, v196 row_shl:8 row_mask:0xf bank_mask:0x3
	v_mov_b32_dpp v201, v197 row_shl:8 row_mask:0xf bank_mask:0x3
	v_mov_b32_dpp v202, v198 row_shl:8 row_mask:0xf bank_mask:0x3
	v_mov_b32_dpp v203, v199 row_shl:8 row_mask:0xf bank_mask:0x3
	v_mov_b32_dpp v196, v212 row_shr:8 row_mask:0xf bank_mask:0xc
	v_mov_b32_dpp v197, v213 row_shr:8 row_mask:0xf bank_mask:0xc
	v_mov_b32_dpp v198, v214 row_shr:8 row_mask:0xf bank_mask:0xc
	v_mov_b32_dpp v199, v215 row_shr:8 row_mask:0xf bank_mask:0xc
	v_mov_b32_e32 v212, v208
	v_mov_b32_e32 v213, v209
	v_mov_b32_e32 v214, v210
	v_mov_b32_e32 v215, v211
	s_nop 0
	v_mov_b32_dpp v208, v204 row_shl:8 row_mask:0xf bank_mask:0x3
	v_mov_b32_dpp v209, v205 row_shl:8 row_mask:0xf bank_mask:0x3
	v_mov_b32_dpp v210, v206 row_shl:8 row_mask:0xf bank_mask:0x3
	v_mov_b32_dpp v211, v207 row_shl:8 row_mask:0xf bank_mask:0x3
	v_mov_b32_dpp v204, v212 row_shr:8 row_mask:0xf bank_mask:0xc
	v_mov_b32_dpp v205, v213 row_shr:8 row_mask:0xf bank_mask:0xc
	v_mov_b32_dpp v206, v214 row_shr:8 row_mask:0xf bank_mask:0xc
	v_mov_b32_dpp v207, v215 row_shr:8 row_mask:0xf bank_mask:0xc
	v_pk_add_f32 v[28:29], v[28:29], v[180:181]
	v_pk_add_f32 v[30:31], v[30:31], v[182:183]
	v_pk_add_f32 v[24:25], v[24:25], v[184:185]
	v_pk_add_f32 v[26:27], v[26:27], v[186:187]
	v_pk_add_f32 v[20:21], v[20:21], v[188:189]
	v_pk_add_f32 v[22:23], v[22:23], v[190:191]
	v_pk_add_f32 v[12:13], v[12:13], v[192:193]
	v_pk_add_f32 v[14:15], v[14:15], v[194:195]
	v_pk_add_f32 v[16:17], v[16:17], v[196:197]
	v_pk_add_f32 v[18:19], v[18:19], v[198:199]
	v_pk_add_f32 v[8:9], v[8:9], v[200:201]
	v_pk_add_f32 v[10:11], v[10:11], v[202:203]
	v_pk_add_f32 v[4:5], v[4:5], v[204:205]
	v_pk_add_f32 v[6:7], v[6:7], v[206:207]
	v_pk_add_f32 v[0:1], v[0:1], v[208:209]
	v_pk_add_f32 v[2:3], v[2:3], v[210:211]
	global_store_dwordx4 v222, v[28:31], s[52:53]
	global_store_dwordx4 v222, v[24:27], s[52:53] offset:64
	global_store_dwordx4 v222, v[20:23], s[52:53] offset:512
	global_store_dwordx4 v222, v[12:15], s[52:53] offset:576
	global_store_dwordx4 v223, v[16:19], s[52:53]
	global_store_dwordx4 v223, v[8:11], s[52:53] offset:64
	global_store_dwordx4 v223, v[4:7], s[52:53] offset:512
	global_store_dwordx4 v223, v[0:3], s[52:53] offset:576
	s_cbranch_vccz .LBB0_1450
	s_waitcnt vmcnt(0)
	s_cmpk_gt_u32 s4, 0xff
	s_cbranch_scc1 .LBB0_1465
	s_barrier

; #define PG8_STAGE(bufoff, gbase, voff) do { _Pragma("unroll") for (int _i = 0; _i < 2; ++_i) \
;         __builtin_amdgcn_global_load_lds((const unsigned*)((const char*)(gbase) + (voff)[_i]), (LAS unsigned*)(lds + (bufoff) + ldsw + _i * 8192), 16, 0, 0); } while (0)
; #define PG8_LDA(dst, b, h) do { _Pragma("unroll") for (int m = 0; m < 4; ++m) _Pragma("unroll") for (int k = 0; k < 2; ++k) dst[m][k] = *(const LAS bf16x8*)(lds + PG8_SA(b, h) + aoff + m * 2048 + k * 1024); } while (0)
; #define PG8_LDB(dst, b, h) do { _Pragma("unroll") for (int n = 0; n < 2; ++n) _Pragma("unroll") for (int k = 0; k < 2; ++k) dst[n][k] = *(const LAS bf16x8*)(lds + PG8_SB(b, h) + boff + n * 2048 + k * 1024); } while (0)
; #define PG8_MMA(ai, bj, At, Bt) do { __builtin_amdgcn_s_setprio(1); _Pragma("unroll") for (int m = 0; m < 4; ++m) _Pragma("unroll") for (int n = 0; n < 2; ++n) _Pragma("unroll") for (int k = 0; k < 2; ++k) \
;         acc[ai][bj][m][n] = __builtin_amdgcn_mfma_f32_16x16x32_bf16(Bt[n][k], At[m][k], acc[ai][bj][m][n], 0, 0, 0); __builtin_amdgcn_s_setprio(0); } while (0)
; #define PG8_WAIT_V(n) asm volatile("s_waitcnt vmcnt(" #n ")" ::: "memory")
; #define PG8_WAIT_L(n) asm volatile("s_waitcnt lgkmcnt(" #n ")" ::: "memory")
; template <class Epi>
; __device__ __forceinline__ void gemm_phase(LAS unsigned char* lds, const Gemm g, const StaticOrder& S, const Epi& E) {
;     ...
;         for (int t = 0; t < nt; t += 2) {
;             const bool last = (t == nt - 2);
;             const char* a1 = cA + (size_t)(t + 1) * kstep;
;             const char* a2 = last ? nA : cA + (size_t)(t + 2) * kstep; const char* b2 = last ? nB : cB + (size_t)(t + 2) * kstep;
;             const char* a3 = a2 + kstep; const char* b3 = b2 + kstep;
;             PG8_LDB(B0, 0, 0); PG8_SCHED; PG8_LDA(At, 0, 0); PG8_STAGE(PG8_SA(1, 1), a1 + hstepA, voffA);
;             PG8_WAIT_L(8); PG8_BAR; PG8_WAIT_L(0); PG8_MMA(0, 0, At, B0); PG8_BAR; PG8_SCHED;
;             PG8_LDB(B1, 0, 1); PG8_STAGE(PG8_SB(0, 0), b2, voffB);
;             PG8_BAR; PG8_WAIT_L(0); PG8_MMA(0, 1, At, B1); PG8_BAR;
;             PG8_LDA(At, 0, 1); PG8_STAGE(PG8_SA(0, 0), a2, voffA);
;             PG8_BAR; PG8_WAIT_L(0); PG8_MMA(1, 0, At, B0); PG8_BAR; PG8_SCHED;
;             PG8_STAGE(PG8_SB(0, 1), b2 + hstepB, voffB);
;             PG8_WAIT_V(6); PG8_BAR; PG8_MMA(1, 1, At, B1); PG8_BAR;
.LBB0_1820:
	ds_read_b128 v[140:143], v149
	ds_read_b128 v[152:155], v149 offset:1024
	ds_read_b128 v[156:159], v149 offset:2048
	ds_read_b128 v[160:163], v149 offset:3072
	s_add_u32 s36, s34, 0xfffc0080
	s_addc_u32 s37, s35, -1
	s_cmp_eq_u32 s70, 12
	s_cselect_b32 s39, s25, s37
	s_cselect_b32 s38, s47, s36
	s_cselect_b32 s37, s23, s63
	s_cselect_b32 s36, s48, s49
	v_lshl_add_u64 v[144:145], s[34:35], 0, v[132:133]
	s_add_i32 m0, s8, 0xc000
	ds_read_b128 v[164:167], v150
	ds_read_b128 v[168:171], v150 offset:1024
	ds_read_b128 v[172:175], v150 offset:2048
	ds_read_b128 v[176:179], v150 offset:3072
	ds_read_b128 v[180:183], v150 offset:4096
	ds_read_b128 v[184:187], v150 offset:5120
	ds_read_b128 v[188:191], v150 offset:6144
	ds_read_b128 v[192:195], v150 offset:7168
	global_load_lds_dwordx4 v[144:145], off
	v_lshl_add_u64 v[144:145], s[34:35], 0, v[134:135]
	s_add_i32 m0, s8, 0xe000
	s_nop 0
	global_load_lds_dwordx4 v[144:145], off
	ds_read_b128 v[196:199], v151
	ds_read_b128 v[200:203], v151 offset:1024
	ds_read_b128 v[204:207], v151 offset:2048
	ds_read_b128 v[208:211], v151 offset:3072
	s_waitcnt lgkmcnt(0)
	s_barrier
	s_setprio 1
	v_mfma_f32_16x16x32_bf16 v[124:127], v[140:143], v[164:167], v[124:127]
	v_mfma_f32_16x16x32_bf16 v[120:123], v[156:159], v[164:167], v[120:123]
	v_mfma_f32_16x16x32_bf16 v[112:115], v[140:143], v[172:175], v[112:115]
	v_mfma_f32_16x16x32_bf16 v[104:107], v[156:159], v[172:175], v[104:107]
	v_mfma_f32_16x16x32_bf16 v[92:95], v[140:143], v[180:183], v[92:95]
	v_mfma_f32_16x16x32_bf16 v[88:91], v[156:159], v[180:183], v[88:91]
	v_mfma_f32_16x16x32_bf16 v[80:83], v[140:143], v[188:191], v[80:83]
	v_mfma_f32_16x16x32_bf16 v[72:75], v[156:159], v[188:191], v[72:75]
	v_mfma_f32_16x16x32_bf16 v[124:127], v[152:155], v[168:171], v[124:127]
	v_mfma_f32_16x16x32_bf16 v[120:123], v[160:163], v[168:171], v[120:123]
	v_mfma_f32_16x16x32_bf16 v[112:115], v[152:155], v[176:179], v[112:115]
	v_mfma_f32_16x16x32_bf16 v[104:107], v[160:163], v[176:179], v[104:107]
	v_mfma_f32_16x16x32_bf16 v[92:95], v[152:155], v[184:187], v[92:95]
	v_mfma_f32_16x16x32_bf16 v[88:91], v[160:163], v[184:187], v[88:91]
	v_mfma_f32_16x16x32_bf16 v[80:83], v[152:155], v[192:195], v[80:83]
	v_mfma_f32_16x16x32_bf16 v[72:75], v[160:163], v[192:195], v[72:75]
	v_mfma_f32_16x16x32_bf16 v[116:119], v[196:199], v[164:167], v[116:119]
	v_mfma_f32_16x16x32_bf16 v[108:111], v[204:207], v[164:167], v[108:111]
	v_mfma_f32_16x16x32_bf16 v[100:103], v[196:199], v[172:175], v[100:103]
	v_mfma_f32_16x16x32_bf16 v[96:99], v[204:207], v[172:175], v[96:99]
	v_mfma_f32_16x16x32_bf16 v[84:87], v[196:199], v[180:183], v[84:87]
	v_mfma_f32_16x16x32_bf16 v[76:79], v[204:207], v[180:183], v[76:79]
	v_mfma_f32_16x16x32_bf16 v[68:71], v[196:199], v[188:191], v[68:71]
	v_mfma_f32_16x16x32_bf16 v[64:67], v[204:207], v[188:191], v[64:67]
	v_mfma_f32_16x16x32_bf16 v[116:119], v[200:203], v[168:171], v[116:119]
	v_mfma_f32_16x16x32_bf16 v[108:111], v[208:211], v[168:171], v[108:111]
	v_mfma_f32_16x16x32_bf16 v[100:103], v[200:203], v[176:179], v[100:103]
	v_mfma_f32_16x16x32_bf16 v[96:99], v[208:211], v[176:179], v[96:99]
	v_mfma_f32_16x16x32_bf16 v[84:87], v[200:203], v[184:187], v[84:87]
	v_mfma_f32_16x16x32_bf16 v[76:79], v[208:211], v[184:187], v[76:79]
	v_mfma_f32_16x16x32_bf16 v[68:71], v[200:203], v[192:195], v[68:71]
	v_mfma_f32_16x16x32_bf16 v[64:67], v[208:211], v[192:195], v[64:67]
	s_setprio 0
	s_barrier
	s_nop 1
	ds_read_b128 v[164:167], v150 offset:16384
	ds_read_b128 v[168:171], v150 offset:17408
	ds_read_b128 v[172:175], v150 offset:18432
	ds_read_b128 v[176:179], v150 offset:19456
	ds_read_b128 v[180:183], v150 offset:20480
	ds_read_b128 v[184:187], v150 offset:21504
	ds_read_b128 v[188:191], v150 offset:22528
	ds_read_b128 v[192:195], v150 offset:23552
	s_add_i32 s71, s44, s7
	v_lshl_add_u64 v[144:145], s[36:37], 0, v[128:129]
	s_mov_b32 m0, s71
	s_nop 0
	global_load_lds_dwordx4 v[144:145], off
	v_lshl_add_u64 v[212:213], s[36:37], 0, v[130:131]
	s_add_i32 m0, s71, 0x2000
	s_nop 0
	global_load_lds_dwordx4 v[212:213], off
	s_mov_b32 m0, s8
	v_lshl_add_u64 v[214:215], s[38:39], 0, v[128:129]
	global_load_lds_dwordx4 v[214:215], off
	v_lshl_add_u64 v[216:217], s[38:39], 0, v[130:131]
	s_mov_b32 m0, s9
	s_nop 0
	global_load_lds_dwordx4 v[216:217], off
	s_add_u32 s72, s36, 0x40000
	s_addc_u32 s73, s37, 0
	s_add_i32 s71, s45, s7
	v_lshl_add_u64 v[254:255], s[72:73], 0, v[128:129]
	s_mov_b32 m0, s71
	s_nop 0
	global_load_lds_dwordx4 v[254:255], off
	v_lshl_add_u64 v[254:255], s[72:73], 0, v[130:131]
	s_add_i32 m0, s71, 0x2000
	s_nop 0
	global_load_lds_dwordx4 v[254:255], off
	s_waitcnt vmcnt(6)
	s_waitcnt lgkmcnt(0)
	s_barrier
; #define PG8_STAGE(bufoff, gbase, voff) do { _Pragma("unroll") for (int _i = 0; _i < 2; ++_i) \
;         __builtin_amdgcn_global_load_lds((const unsigned*)((const char*)(gbase) + (voff)[_i]), (LAS unsigned*)(lds + (bufoff) + ldsw + _i * 8192), 16, 0, 0); } while (0)
; #define PG8_LDA(dst, b, h) do { _Pragma("unroll") for (int m = 0; m < 4; ++m) _Pragma("unroll") for (int k = 0; k < 2; ++k) dst[m][k] = *(const LAS bf16x8*)(lds + PG8_SA(b, h) + aoff + m * 2048 + k * 1024); } while (0)
; #define PG8_LDB(dst, b, h) do { _Pragma("unroll") for (int n = 0; n < 2; ++n) _Pragma("unroll") for (int k = 0; k < 2; ++k) dst[n][k] = *(const LAS bf16x8*)(lds + PG8_SB(b, h) + boff + n * 2048 + k * 1024); } while (0)
; #define PG8_MMA(ai, bj, At, Bt) do { __builtin_amdgcn_s_setprio(1); _Pragma("unroll") for (int m = 0; m < 4; ++m) _Pragma("unroll") for (int n = 0; n < 2; ++n) _Pragma("unroll") for (int k = 0; k < 2; ++k) \
;         acc[ai][bj][m][n] = __builtin_amdgcn_mfma_f32_16x16x32_bf16(Bt[n][k], At[m][k], acc[ai][bj][m][n], 0, 0, 0); __builtin_amdgcn_s_setprio(0); } while (0)
; #define PG8_WAIT_V(n) asm volatile("s_waitcnt vmcnt(" #n ")" ::: "memory")
; #define PG8_WAIT_L(n) asm volatile("s_waitcnt lgkmcnt(" #n ")" ::: "memory")
; #define PG8_BAR __builtin_amdgcn_s_barrier()
; #define PG8_SCHED __builtin_amdgcn_sched_barrier(0)
; template <class Epi>
; __device__ __forceinline__ void gemm_phase(LAS unsigned char* lds, const Gemm g, const StaticOrder& S, const Epi& E) {
;     ...
;             PG8_WAIT_V(6); PG8_BAR; PG8_MMA(1, 1, At, B1); PG8_BAR;
;             PG8_LDB(B0, 1, 0); PG8_SCHED; PG8_LDA(At, 1, 0); PG8_STAGE(PG8_SA(0, 1), a2 + hstepA, voffA);
;             PG8_WAIT_L(8); PG8_BAR; PG8_WAIT_L(0); PG8_MMA(0, 0, At, B0); PG8_BAR; PG8_SCHED;
;             PG8_LDB(B1, 1, 1); PG8_STAGE(PG8_SB(1, 0), b3, voffB);
;             PG8_BAR; PG8_WAIT_L(0); PG8_MMA(0, 1, At, B1); PG8_BAR;
;             PG8_LDA(At, 1, 1); PG8_STAGE(PG8_SA(1, 0), a3, voffA);
;             PG8_BAR; PG8_WAIT_L(0); PG8_MMA(1, 0, At, B0); PG8_BAR; PG8_SCHED;
	s_setprio 1
	v_mfma_f32_16x16x32_bf16 v[60:63], v[140:143], v[164:167], v[60:63]
	v_mfma_f32_16x16x32_bf16 v[56:59], v[156:159], v[164:167], v[56:59]
	v_mfma_f32_16x16x32_bf16 v[48:51], v[140:143], v[172:175], v[48:51]
	v_mfma_f32_16x16x32_bf16 v[40:43], v[156:159], v[172:175], v[40:43]
	v_mfma_f32_16x16x32_bf16 v[28:31], v[140:143], v[180:183], v[28:31]
	v_mfma_f32_16x16x32_bf16 v[24:27], v[156:159], v[180:183], v[24:27]
	v_mfma_f32_16x16x32_bf16 v[16:19], v[140:143], v[188:191], v[16:19]
	v_mfma_f32_16x16x32_bf16 v[8:11], v[156:159], v[188:191], v[8:11]
	v_mfma_f32_16x16x32_bf16 v[60:63], v[152:155], v[168:171], v[60:63]
	v_mfma_f32_16x16x32_bf16 v[56:59], v[160:163], v[168:171], v[56:59]
	v_mfma_f32_16x16x32_bf16 v[48:51], v[152:155], v[176:179], v[48:51]
	v_mfma_f32_16x16x32_bf16 v[40:43], v[160:163], v[176:179], v[40:43]
	v_mfma_f32_16x16x32_bf16 v[28:31], v[152:155], v[184:187], v[28:31]
	v_mfma_f32_16x16x32_bf16 v[24:27], v[160:163], v[184:187], v[24:27]
	v_mfma_f32_16x16x32_bf16 v[16:19], v[152:155], v[192:195], v[16:19]
	v_mfma_f32_16x16x32_bf16 v[8:11], v[160:163], v[192:195], v[8:11]
	v_mfma_f32_16x16x32_bf16 v[52:55], v[196:199], v[164:167], v[52:55]
	v_mfma_f32_16x16x32_bf16 v[44:47], v[204:207], v[164:167], v[44:47]
	v_mfma_f32_16x16x32_bf16 v[36:39], v[196:199], v[172:175], v[36:39]
	v_mfma_f32_16x16x32_bf16 v[32:35], v[204:207], v[172:175], v[32:35]
	v_mfma_f32_16x16x32_bf16 v[20:23], v[196:199], v[180:183], v[20:23]
	v_mfma_f32_16x16x32_bf16 v[12:15], v[204:207], v[180:183], v[12:15]
	v_mfma_f32_16x16x32_bf16 v[4:7], v[196:199], v[188:191], v[4:7]
	v_mfma_f32_16x16x32_bf16 v[0:3], v[204:207], v[188:191], v[0:3]
	v_mfma_f32_16x16x32_bf16 v[52:55], v[200:203], v[168:171], v[52:55]
	v_mfma_f32_16x16x32_bf16 v[44:47], v[208:211], v[168:171], v[44:47]
	v_mfma_f32_16x16x32_bf16 v[36:39], v[200:203], v[176:179], v[36:39]
	v_mfma_f32_16x16x32_bf16 v[32:35], v[208:211], v[176:179], v[32:35]
	v_mfma_f32_16x16x32_bf16 v[20:23], v[200:203], v[184:187], v[20:23]
	v_mfma_f32_16x16x32_bf16 v[12:15], v[208:211], v[184:187], v[12:15]
	v_mfma_f32_16x16x32_bf16 v[4:7], v[200:203], v[192:195], v[4:7]
	v_mfma_f32_16x16x32_bf16 v[0:3], v[208:211], v[192:195], v[0:3]
	s_setprio 0
	s_add_i32 s71, 0, 0x18000
	v_add_u32_e32 v160, s71, v147
	s_barrier
	ds_read_b128 v[140:143], v160
	ds_read_b128 v[152:155], v160 offset:1024
	ds_read_b128 v[156:159], v160 offset:2048
	ds_read_b128 v[160:163], v160 offset:3072
	s_add_u32 s38, s38, 0x40000
	s_addc_u32 s39, s39, 0
	s_mov_b32 m0, s31
	v_lshl_add_u64 v[196:197], s[38:39], 0, v[128:129]
	ds_read_b128 v[164:167], v150 offset:32768
	ds_read_b128 v[168:171], v150 offset:33792
	ds_read_b128 v[172:175], v150 offset:34816
	ds_read_b128 v[176:179], v150 offset:35840
	ds_read_b128 v[180:183], v150 offset:36864
	ds_read_b128 v[184:187], v150 offset:37888
	ds_read_b128 v[188:191], v150 offset:38912
	ds_read_b128 v[192:195], v150 offset:39936
	global_load_lds_dwordx4 v[196:197], off
	v_lshl_add_u64 v[196:197], s[38:39], 0, v[130:131]
	s_mov_b32 m0, s40
	s_nop 0
	global_load_lds_dwordx4 v[196:197], off
	s_add_i32 s38, 0, 0x1c000
	v_add_u32_e32 v208, s38, v147
	ds_read_b128 v[196:199], v208
	ds_read_b128 v[200:203], v208 offset:1024
	ds_read_b128 v[204:207], v208 offset:2048
	ds_read_b128 v[208:211], v208 offset:3072
	s_waitcnt lgkmcnt(0)
	s_barrier
	s_setprio 1
	v_mfma_f32_16x16x32_bf16 v[124:127], v[140:143], v[164:167], v[124:127]
	v_mfma_f32_16x16x32_bf16 v[120:123], v[156:159], v[164:167], v[120:123]
	v_mfma_f32_16x16x32_bf16 v[112:115], v[140:143], v[172:175], v[112:115]
	v_mfma_f32_16x16x32_bf16 v[104:107], v[156:159], v[172:175], v[104:107]
	v_mfma_f32_16x16x32_bf16 v[92:95], v[140:143], v[180:183], v[92:95]
	v_mfma_f32_16x16x32_bf16 v[88:91], v[156:159], v[180:183], v[88:91]
	v_mfma_f32_16x16x32_bf16 v[80:83], v[140:143], v[188:191], v[80:83]
	v_mfma_f32_16x16x32_bf16 v[72:75], v[156:159], v[188:191], v[72:75]
	v_mfma_f32_16x16x32_bf16 v[124:127], v[152:155], v[168:171], v[124:127]
	v_mfma_f32_16x16x32_bf16 v[120:123], v[160:163], v[168:171], v[120:123]
	v_mfma_f32_16x16x32_bf16 v[112:115], v[152:155], v[176:179], v[112:115]
	v_mfma_f32_16x16x32_bf16 v[104:107], v[160:163], v[176:179], v[104:107]
	v_mfma_f32_16x16x32_bf16 v[92:95], v[152:155], v[184:187], v[92:95]
	v_mfma_f32_16x16x32_bf16 v[88:91], v[160:163], v[184:187], v[88:91]
	v_mfma_f32_16x16x32_bf16 v[80:83], v[152:155], v[192:195], v[80:83]
	v_mfma_f32_16x16x32_bf16 v[72:75], v[160:163], v[192:195], v[72:75]
	v_mfma_f32_16x16x32_bf16 v[116:119], v[196:199], v[164:167], v[116:119]
	v_mfma_f32_16x16x32_bf16 v[108:111], v[204:207], v[164:167], v[108:111]
	v_mfma_f32_16x16x32_bf16 v[100:103], v[196:199], v[172:175], v[100:103]
	v_mfma_f32_16x16x32_bf16 v[96:99], v[204:207], v[172:175], v[96:99]
	v_mfma_f32_16x16x32_bf16 v[84:87], v[196:199], v[180:183], v[84:87]
	v_mfma_f32_16x16x32_bf16 v[76:79], v[204:207], v[180:183], v[76:79]
	v_mfma_f32_16x16x32_bf16 v[68:71], v[196:199], v[188:191], v[68:71]
	v_mfma_f32_16x16x32_bf16 v[64:67], v[204:207], v[188:191], v[64:67]
	v_mfma_f32_16x16x32_bf16 v[116:119], v[200:203], v[168:171], v[116:119]
	v_mfma_f32_16x16x32_bf16 v[108:111], v[208:211], v[168:171], v[108:111]
	v_mfma_f32_16x16x32_bf16 v[100:103], v[200:203], v[176:179], v[100:103]
	v_mfma_f32_16x16x32_bf16 v[96:99], v[208:211], v[176:179], v[96:99]
	v_mfma_f32_16x16x32_bf16 v[84:87], v[200:203], v[184:187], v[84:87]
	v_mfma_f32_16x16x32_bf16 v[76:79], v[208:211], v[184:187], v[76:79]
	v_mfma_f32_16x16x32_bf16 v[68:71], v[200:203], v[192:195], v[68:71]
	v_mfma_f32_16x16x32_bf16 v[64:67], v[208:211], v[192:195], v[64:67]
	s_setprio 0
	s_barrier
; #define PG8_STAGE(bufoff, gbase, voff) do { _Pragma("unroll") for (int _i = 0; _i < 2; ++_i) \
;         __builtin_amdgcn_global_load_lds((const unsigned*)((const char*)(gbase) + (voff)[_i]), (LAS unsigned*)(lds + (bufoff) + ldsw + _i * 8192), 16, 0, 0); } while (0)
; #define PG8_MMA(ai, bj, At, Bt) do { __builtin_amdgcn_s_setprio(1); _Pragma("unroll") for (int m = 0; m < 4; ++m) _Pragma("unroll") for (int n = 0; n < 2; ++n) _Pragma("unroll") for (int k = 0; k < 2; ++k) \
;         acc[ai][bj][m][n] = __builtin_amdgcn_mfma_f32_16x16x32_bf16(Bt[n][k], At[m][k], acc[ai][bj][m][n], 0, 0, 0); __builtin_amdgcn_s_setprio(0); } while (0)
; #define PG8_WAIT_V(n) asm volatile("s_waitcnt vmcnt(" #n ")" ::: "memory")
; #define PG8_WAIT_L(n) asm volatile("s_waitcnt lgkmcnt(" #n ")" ::: "memory")
; #define PG8_BAR __builtin_amdgcn_s_barrier()
; #define PG8_SCHED __builtin_amdgcn_sched_barrier(0)
; template <class Epi>
; __device__ __forceinline__ void gemm_phase(LAS unsigned char* lds, const Gemm g, const StaticOrder& S, const Epi& E) {
;     ...
;             PG8_BAR; PG8_WAIT_L(0); PG8_MMA(1, 0, At, B0); PG8_BAR; PG8_SCHED;
;             PG8_STAGE(PG8_SB(1, 1), b3 + hstepB, voffB);
;             PG8_WAIT_V(6); PG8_BAR; PG8_MMA(1, 1, At, B1); PG8_BAR;
;     __device__ __forceinline__ void operator()(AccRef acc, const Unit& u, int wr, int wc, int fr, int fq) const {
;         const int row0 = u.pm * 256 + wr * 64 + fr, col0 = u.pn * 256 + wc * 32 + 4 * fq;
;         f32x4 sv[2][2], bv[2][2];
; #pragma unroll
;         for (int bj = 0; bj < 2; ++bj)
; #pragma unroll
;             for (int n = 0; n < 2; ++n) {
;                 sv[bj][n] = scale ? *(const f32x4*)(scale + col0 + bj * 128 + n * 16) : (f32x4){1.f, 1.f, 1.f, 1.f};
;                 bv[bj][n] = bias ? *(const f32x4*)(bias + col0 + bj * 128 + n * 16) : (f32x4){0.f, 0.f, 0.f, 0.f}; }
; #pragma unroll
;         for (int ai = 0; ai < 2; ++ai)
; #pragma unroll
;             for (int mh = 0; mh < 2; ++mh) {
;                 f32x4 bs[2][2][2];
; #pragma unroll
;                 for (int m = 0; m < 2; ++m)
; #pragma unroll
;                     for (int bj = 0; bj < 2; ++bj)
; #pragma unroll
;                         for (int n = 0; n < 2; ++n) bs[m][bj][n] = *(const f32x4*)(base + (size_t)(row0 + ai * 128 + (2 * mh + m) * 16) * D + col0 + bj * 128 + n * 16);
	s_nop 1
	ds_read_b128 v[164:167], v150 offset:49152
	ds_read_b128 v[168:171], v150 offset:50176
	ds_read_b128 v[172:175], v150 offset:51200
	ds_read_b128 v[176:179], v150 offset:52224
	ds_read_b128 v[180:183], v150 offset:53248
	ds_read_b128 v[184:187], v150 offset:54272
	ds_read_b128 v[188:191], v150 offset:55296
	ds_read_b128 v[192:195], v150 offset:56320
	s_add_i32 s39, s71, s7
	v_lshl_add_u64 v[254:255], v[144:145], 0, s[12:13]
	s_mov_b32 m0, s39
	s_nop 0
	global_load_lds_dwordx4 v[254:255], off
	v_lshl_add_u64 v[254:255], v[212:213], 0, s[12:13]
	s_add_i32 m0, s39, 0x2000
	s_nop 0
	global_load_lds_dwordx4 v[254:255], off
	s_mov_b32 m0, s42
	v_lshl_add_u64 v[254:255], v[214:215], 0, s[12:13]
	global_load_lds_dwordx4 v[254:255], off
	v_lshl_add_u64 v[144:145], v[216:217], 0, s[12:13]
	s_mov_b32 m0, s43
	s_nop 0
	global_load_lds_dwordx4 v[144:145], off
	s_add_u32 s36, s36, 0x40080
	s_addc_u32 s37, s37, 0
	s_add_i32 s38, s38, s7
	v_lshl_add_u64 v[254:255], s[36:37], 0, v[128:129]
	s_mov_b32 m0, s38
	s_nop 0
	global_load_lds_dwordx4 v[254:255], off
	v_lshl_add_u64 v[254:255], s[36:37], 0, v[130:131]
	s_add_i32 m0, s38, 0x2000
	s_nop 0
	global_load_lds_dwordx4 v[254:255], off
	s_waitcnt vmcnt(6)
	s_waitcnt lgkmcnt(0)
	s_barrier
	s_setprio 1
	v_mfma_f32_16x16x32_bf16 v[60:63], v[140:143], v[164:167], v[60:63]
	v_mfma_f32_16x16x32_bf16 v[56:59], v[156:159], v[164:167], v[56:59]
	v_mfma_f32_16x16x32_bf16 v[48:51], v[140:143], v[172:175], v[48:51]
	v_mfma_f32_16x16x32_bf16 v[40:43], v[156:159], v[172:175], v[40:43]
	v_mfma_f32_16x16x32_bf16 v[28:31], v[140:143], v[180:183], v[28:31]
	v_mfma_f32_16x16x32_bf16 v[24:27], v[156:159], v[180:183], v[24:27]
	v_mfma_f32_16x16x32_bf16 v[16:19], v[140:143], v[188:191], v[16:19]
	v_mfma_f32_16x16x32_bf16 v[8:11], v[156:159], v[188:191], v[8:11]
	v_mfma_f32_16x16x32_bf16 v[60:63], v[152:155], v[168:171], v[60:63]
	v_mfma_f32_16x16x32_bf16 v[56:59], v[160:163], v[168:171], v[56:59]
	v_mfma_f32_16x16x32_bf16 v[48:51], v[152:155], v[176:179], v[48:51]
	v_mfma_f32_16x16x32_bf16 v[40:43], v[160:163], v[176:179], v[40:43]
	v_mfma_f32_16x16x32_bf16 v[28:31], v[152:155], v[184:187], v[28:31]
	v_mfma_f32_16x16x32_bf16 v[24:27], v[160:163], v[184:187], v[24:27]
	v_mfma_f32_16x16x32_bf16 v[16:19], v[152:155], v[192:195], v[16:19]
	v_mfma_f32_16x16x32_bf16 v[8:11], v[160:163], v[192:195], v[8:11]
	v_mfma_f32_16x16x32_bf16 v[52:55], v[196:199], v[164:167], v[52:55]
	v_mfma_f32_16x16x32_bf16 v[44:47], v[204:207], v[164:167], v[44:47]
	v_mfma_f32_16x16x32_bf16 v[36:39], v[196:199], v[172:175], v[36:39]
	v_mfma_f32_16x16x32_bf16 v[32:35], v[204:207], v[172:175], v[32:35]
	v_mfma_f32_16x16x32_bf16 v[20:23], v[196:199], v[180:183], v[20:23]
	v_mfma_f32_16x16x32_bf16 v[12:15], v[204:207], v[180:183], v[12:15]
	v_mfma_f32_16x16x32_bf16 v[4:7], v[196:199], v[188:191], v[4:7]
	v_mfma_f32_16x16x32_bf16 v[0:3], v[204:207], v[188:191], v[0:3]
	v_mfma_f32_16x16x32_bf16 v[52:55], v[200:203], v[168:171], v[52:55]
	v_mfma_f32_16x16x32_bf16 v[44:47], v[208:211], v[168:171], v[44:47]
	v_mfma_f32_16x16x32_bf16 v[36:39], v[200:203], v[176:179], v[36:39]
	v_mfma_f32_16x16x32_bf16 v[32:35], v[208:211], v[176:179], v[32:35]
	v_mfma_f32_16x16x32_bf16 v[20:23], v[200:203], v[184:187], v[20:23]
	v_mfma_f32_16x16x32_bf16 v[12:15], v[208:211], v[184:187], v[12:15]
	v_mfma_f32_16x16x32_bf16 v[4:7], v[200:203], v[192:195], v[4:7]
	v_mfma_f32_16x16x32_bf16 v[0:3], v[208:211], v[192:195], v[0:3]
	s_setprio 0
	s_add_i32 s70, s70, 2
	s_add_u32 s34, s34, 0x100
	s_addc_u32 s35, s35, 0
	s_add_u32 s49, s49, 0x100
	s_addc_u32 s63, s63, 0
	s_cmp_gt_u32 s70, 13
	s_barrier
	s_cbranch_scc0 .LBB0_1820
	v_lshl_or_b32 v144, s46, 8, v148
	v_lshl_add_u32 v145, s30, 8, v146
	v_lshlrev_b32_e32 v144, 2, v144
	v_lshl_add_u32 v145, v145, 12, v144
	v_add_u32_e32 v216, 0x10000, v145
	v_add_u32_e32 v217, 0x20000, v145
	v_add_u32_e32 v218, 0x30000, v145
	v_add_u32_e32 v220, 0x80000, v145
	v_add_u32_e32 v221, 0x90000, v145
	v_add_u32_e32 v222, 0xa0000, v145
	v_add_u32_e32 v223, 0xb0000, v145
	v_and_b32_e32 v235, 8, v146
	v_cmp_ne_u32_e32 vcc, 0, v235
	v_mov_b32_e32 v232, 0xffff8040
	s_nop 0
	v_cndmask_b32_e32 v232, 0, v232, vcc
	v_mov_b32_e32 v233, 64
	v_mov_b32_e32 v235, 0x8000
	v_cndmask_b32_e32 v233, v235, v233, vcc
	v_add_u32_e32 v224, v145, v232
	v_add_u32_e32 v225, v216, v232
	v_add_u32_e32 v226, v217, v232
	v_add_u32_e32 v227, v218, v232
	v_add_u32_e32 v228, v220, v232
	v_add_u32_e32 v229, v221, v232
	v_add_u32_e32 v230, v222, v232
	v_add_u32_e32 v231, v223, v232
	s_and_b64 vcc, exec, s[10:11]
	s_mov_b32 s46, s22
	s_mov_b32 s30, s24
	s_mov_b64 s[36:37], s[28:29]
	s_mov_b64 s[34:35], s[26:27]
	global_load_dwordx4 v[140:143], v224, s[52:53]
	v_add_u32_e32 v144, v145, v233
	global_load_dwordx4 v[152:155], v144, s[52:53]
	global_load_dwordx4 v[156:159], v224, s[52:53] offset:512
	v_add_u32_e32 v144, v145, v233
	global_load_dwordx4 v[160:163], v144, s[52:53] offset:512
	global_load_dwordx4 v[164:167], v225, s[52:53]
	v_add_u32_e32 v144, v216, v233
	global_load_dwordx4 v[168:171], v144, s[52:53]
	global_load_dwordx4 v[172:175], v225, s[52:53] offset:512
	v_add_u32_e32 v144, v216, v233
	global_load_dwordx4 v[176:179], v144, s[52:53] offset:512
	global_load_dwordx4 v[180:183], v226, s[52:53]
	v_add_u32_e32 v144, v217, v233
	global_load_dwordx4 v[184:187], v144, s[52:53]
	global_load_dwordx4 v[188:191], v226, s[52:53] offset:512
	v_add_u32_e32 v144, v217, v233
	global_load_dwordx4 v[192:195], v144, s[52:53] offset:512
	global_load_dwordx4 v[196:199], v227, s[52:53]
	v_add_u32_e32 v144, v218, v233
	global_load_dwordx4 v[200:203], v144, s[52:53]
;     __device__ __forceinline__ void operator()(AccRef acc, const Unit& u, int wr, int wc, int fr, int fq) const {
;     ...
;                         for (int n = 0; n < 2; ++n) bs[m][bj][n] = *(const f32x4*)(base + (size_t)(row0 + ai * 128 + (2 * mh + m) * 16) * D + col0 + bj * 128 + n * 16);
; #pragma unroll
;                 for (int m = 0; m < 2; ++m)
; #pragma unroll
;                     for (int bj = 0; bj < 2; ++bj)
; #pragma unroll
;                         for (int n = 0; n < 2; ++n) *(f32x4*)(out + (size_t)(row0 + ai * 128 + (2 * mh + m) * 16) * D + col0 + bj * 128 + n * 16) = bs[m][bj][n] + sv[bj][n] * (acc[ai][bj][2 * mh + m][n] + bv[bj][n]);
	global_load_dwordx4 v[204:207], v227, s[52:53] offset:512
	v_add_u32_e32 v144, v218, v233
	global_load_dwordx4 v[208:211], v144, s[52:53] offset:512
	v_pk_add_f32 v[124:125], v[124:125], 0 op_sel_hi:[1,0]
	v_pk_add_f32 v[126:127], v[126:127], 0 op_sel_hi:[1,0]
	v_pk_add_f32 v[120:121], v[120:121], 0 op_sel_hi:[1,0]
	v_pk_add_f32 v[122:123], v[122:123], 0 op_sel_hi:[1,0]
	v_pk_add_f32 v[116:117], v[116:117], 0 op_sel_hi:[1,0]
	v_pk_add_f32 v[118:119], v[118:119], 0 op_sel_hi:[1,0]
	v_pk_add_f32 v[108:109], v[108:109], 0 op_sel_hi:[1,0]
	v_pk_add_f32 v[110:111], v[110:111], 0 op_sel_hi:[1,0]
	v_pk_add_f32 v[112:113], v[112:113], 0 op_sel_hi:[1,0]
	v_pk_add_f32 v[114:115], v[114:115], 0 op_sel_hi:[1,0]
	v_pk_add_f32 v[104:105], v[104:105], 0 op_sel_hi:[1,0]
	v_pk_add_f32 v[106:107], v[106:107], 0 op_sel_hi:[1,0]
	v_pk_add_f32 v[100:101], v[100:101], 0 op_sel_hi:[1,0]
	v_pk_add_f32 v[102:103], v[102:103], 0 op_sel_hi:[1,0]
	v_pk_add_f32 v[96:97], v[96:97], 0 op_sel_hi:[1,0]
	v_pk_add_f32 v[98:99], v[98:99], 0 op_sel_hi:[1,0]
	v_pk_add_f32 v[92:93], v[92:93], 0 op_sel_hi:[1,0]
	v_pk_add_f32 v[94:95], v[94:95], 0 op_sel_hi:[1,0]
	v_pk_add_f32 v[88:89], v[88:89], 0 op_sel_hi:[1,0]
	v_pk_add_f32 v[90:91], v[90:91], 0 op_sel_hi:[1,0]
	v_pk_add_f32 v[84:85], v[84:85], 0 op_sel_hi:[1,0]
	v_pk_add_f32 v[86:87], v[86:87], 0 op_sel_hi:[1,0]
	v_pk_add_f32 v[76:77], v[76:77], 0 op_sel_hi:[1,0]
	v_pk_add_f32 v[78:79], v[78:79], 0 op_sel_hi:[1,0]
	v_pk_add_f32 v[80:81], v[80:81], 0 op_sel_hi:[1,0]
	v_pk_add_f32 v[82:83], v[82:83], 0 op_sel_hi:[1,0]
	v_pk_add_f32 v[72:73], v[72:73], 0 op_sel_hi:[1,0]
	v_pk_add_f32 v[74:75], v[74:75], 0 op_sel_hi:[1,0]
	v_pk_add_f32 v[68:69], v[68:69], 0 op_sel_hi:[1,0]
	v_pk_add_f32 v[70:71], v[70:71], 0 op_sel_hi:[1,0]
	v_pk_add_f32 v[64:65], v[64:65], 0 op_sel_hi:[1,0]
	v_pk_add_f32 v[66:67], v[66:67], 0 op_sel_hi:[1,0]
	v_pk_add_f32 v[60:61], v[60:61], 0 op_sel_hi:[1,0]
	v_pk_add_f32 v[62:63], v[62:63], 0 op_sel_hi:[1,0]
	v_pk_add_f32 v[56:57], v[56:57], 0 op_sel_hi:[1,0]
	v_pk_add_f32 v[58:59], v[58:59], 0 op_sel_hi:[1,0]
	v_pk_add_f32 v[52:53], v[52:53], 0 op_sel_hi:[1,0]
	v_pk_add_f32 v[54:55], v[54:55], 0 op_sel_hi:[1,0]
	v_pk_add_f32 v[44:45], v[44:45], 0 op_sel_hi:[1,0]
	v_pk_add_f32 v[46:47], v[46:47], 0 op_sel_hi:[1,0]
	v_pk_add_f32 v[48:49], v[48:49], 0 op_sel_hi:[1,0]
	v_pk_add_f32 v[50:51], v[50:51], 0 op_sel_hi:[1,0]
	v_pk_add_f32 v[40:41], v[40:41], 0 op_sel_hi:[1,0]
	v_pk_add_f32 v[42:43], v[42:43], 0 op_sel_hi:[1,0]
	v_pk_add_f32 v[36:37], v[36:37], 0 op_sel_hi:[1,0]
	v_pk_add_f32 v[38:39], v[38:39], 0 op_sel_hi:[1,0]
	v_pk_add_f32 v[32:33], v[32:33], 0 op_sel_hi:[1,0]
	v_pk_add_f32 v[34:35], v[34:35], 0 op_sel_hi:[1,0]
	v_pk_add_f32 v[28:29], v[28:29], 0 op_sel_hi:[1,0]
	v_pk_add_f32 v[30:31], v[30:31], 0 op_sel_hi:[1,0]
	v_pk_add_f32 v[24:25], v[24:25], 0 op_sel_hi:[1,0]
	v_pk_add_f32 v[26:27], v[26:27], 0 op_sel_hi:[1,0]
	v_pk_add_f32 v[20:21], v[20:21], 0 op_sel_hi:[1,0]
	v_pk_add_f32 v[22:23], v[22:23], 0 op_sel_hi:[1,0]
	v_pk_add_f32 v[12:13], v[12:13], 0 op_sel_hi:[1,0]
	v_pk_add_f32 v[14:15], v[14:15], 0 op_sel_hi:[1,0]
	v_pk_add_f32 v[16:17], v[16:17], 0 op_sel_hi:[1,0]
	v_pk_add_f32 v[18:19], v[18:19], 0 op_sel_hi:[1,0]
	v_pk_add_f32 v[8:9], v[8:9], 0 op_sel_hi:[1,0]
	v_pk_add_f32 v[10:11], v[10:11], 0 op_sel_hi:[1,0]
	v_pk_add_f32 v[4:5], v[4:5], 0 op_sel_hi:[1,0]
	v_pk_add_f32 v[6:7], v[6:7], 0 op_sel_hi:[1,0]
	v_pk_add_f32 v[0:1], v[0:1], 0 op_sel_hi:[1,0]
	v_pk_add_f32 v[2:3], v[2:3], 0 op_sel_hi:[1,0]
	s_waitcnt vmcnt(8)
	v_mov_b32_e32 v212, v152
	v_mov_b32_e32 v213, v153
	v_mov_b32_e32 v214, v154
	v_mov_b32_e32 v215, v155
	s_nop 0
	v_mov_b32_dpp v152, v140 row_shl:8 row_mask:0xf bank_mask:0x3
	v_mov_b32_dpp v153, v141 row_shl:8 row_mask:0xf bank_mask:0x3
	v_mov_b32_dpp v154, v142 row_shl:8 row_mask:0xf bank_mask:0x3
	v_mov_b32_dpp v155, v143 row_shl:8 row_mask:0xf bank_mask:0x3
	v_mov_b32_dpp v140, v212 row_shr:8 row_mask:0xf bank_mask:0xc
	v_mov_b32_dpp v141, v213 row_shr:8 row_mask:0xf bank_mask:0xc
	v_mov_b32_dpp v142, v214 row_shr:8 row_mask:0xf bank_mask:0xc
	v_mov_b32_dpp v143, v215 row_shr:8 row_mask:0xf bank_mask:0xc
	v_mov_b32_e32 v212, v160
	v_mov_b32_e32 v213, v161
	v_mov_b32_e32 v214, v162
	v_mov_b32_e32 v215, v163
	s_nop 0
	v_mov_b32_dpp v160, v156 row_shl:8 row_mask:0xf bank_mask:0x3
	v_mov_b32_dpp v161, v157 row_shl:8 row_mask:0xf bank_mask:0x3
	v_mov_b32_dpp v162, v158 row_shl:8 row_mask:0xf bank_mask:0x3
	v_mov_b32_dpp v163, v159 row_shl:8 row_mask:0xf bank_mask:0x3
	v_mov_b32_dpp v156, v212 row_shr:8 row_mask:0xf bank_mask:0xc
	v_mov_b32_dpp v157, v213 row_shr:8 row_mask:0xf bank_mask:0xc
	v_mov_b32_dpp v158, v214 row_shr:8 row_mask:0xf bank_mask:0xc
	v_mov_b32_dpp v159, v215 row_shr:8 row_mask:0xf bank_mask:0xc
	v_mov_b32_e32 v212, v168
	v_mov_b32_e32 v213, v169
	v_mov_b32_e32 v214, v170
	v_mov_b32_e32 v215, v171
	s_nop 0
	v_mov_b32_dpp v168, v164 row_shl:8 row_mask:0xf bank_mask:0x3
	v_mov_b32_dpp v169, v165 row_shl:8 row_mask:0xf bank_mask:0x3
	v_mov_b32_dpp v170, v166 row_shl:8 row_mask:0xf bank_mask:0x3
	v_mov_b32_dpp v171, v167 row_shl:8 row_mask:0xf bank_mask:0x3
	v_mov_b32_dpp v164, v212 row_shr:8 row_mask:0xf bank_mask:0xc
	v_mov_b32_dpp v165, v213 row_shr:8 row_mask:0xf bank_mask:0xc
	v_mov_b32_dpp v166, v214 row_shr:8 row_mask:0xf bank_mask:0xc
	v_mov_b32_dpp v167, v215 row_shr:8 row_mask:0xf bank_mask:0xc
	v_mov_b32_e32 v212, v176
	v_mov_b32_e32 v213, v177
	v_mov_b32_e32 v214, v178
	v_mov_b32_e32 v215, v179
	s_nop 0
	v_mov_b32_dpp v176, v172 row_shl:8 row_mask:0xf bank_mask:0x3
	v_mov_b32_dpp v177, v173 row_shl:8 row_mask:0xf bank_mask:0x3
;     __device__ __forceinline__ void operator()(AccRef acc, const Unit& u, int wr, int wc, int fr, int fq) const {
;     ...
;                         for (int n = 0; n < 2; ++n) bs[m][bj][n] = *(const f32x4*)(base + (size_t)(row0 + ai * 128 + (2 * mh + m) * 16) * D + col0 + bj * 128 + n * 16);
; #pragma unroll
;                 for (int m = 0; m < 2; ++m)
; #pragma unroll
;                     for (int bj = 0; bj < 2; ++bj)
; #pragma unroll
;                         for (int n = 0; n < 2; ++n) *(f32x4*)(out + (size_t)(row0 + ai * 128 + (2 * mh + m) * 16) * D + col0 + bj * 128 + n * 16) = bs[m][bj][n] + sv[bj][n] * (acc[ai][bj][2 * mh + m][n] + bv[bj][n]);
;                 asm volatile("" ::: "memory"); }
	v_mov_b32_dpp v178, v174 row_shl:8 row_mask:0xf bank_mask:0x3
	v_mov_b32_dpp v179, v175 row_shl:8 row_mask:0xf bank_mask:0x3
	v_mov_b32_dpp v172, v212 row_shr:8 row_mask:0xf bank_mask:0xc
	v_mov_b32_dpp v173, v213 row_shr:8 row_mask:0xf bank_mask:0xc
	v_mov_b32_dpp v174, v214 row_shr:8 row_mask:0xf bank_mask:0xc
	v_mov_b32_dpp v175, v215 row_shr:8 row_mask:0xf bank_mask:0xc
	v_pk_add_f32 v[124:125], v[124:125], v[140:141]
	v_pk_add_f32 v[126:127], v[126:127], v[142:143]
	v_pk_add_f32 v[120:121], v[120:121], v[152:153]
	v_pk_add_f32 v[122:123], v[122:123], v[154:155]
	v_pk_add_f32 v[116:117], v[116:117], v[156:157]
	v_pk_add_f32 v[118:119], v[118:119], v[158:159]
	v_pk_add_f32 v[108:109], v[108:109], v[160:161]
	v_pk_add_f32 v[110:111], v[110:111], v[162:163]
	v_pk_add_f32 v[112:113], v[112:113], v[164:165]
	v_pk_add_f32 v[114:115], v[114:115], v[166:167]
	v_pk_add_f32 v[104:105], v[104:105], v[168:169]
	v_pk_add_f32 v[106:107], v[106:107], v[170:171]
	v_pk_add_f32 v[100:101], v[100:101], v[172:173]
	v_pk_add_f32 v[102:103], v[102:103], v[174:175]
	v_pk_add_f32 v[96:97], v[96:97], v[176:177]
	v_pk_add_f32 v[98:99], v[98:99], v[178:179]
	global_store_dwordx4 v145, v[124:127], s[52:53]
	global_store_dwordx4 v145, v[120:123], s[52:53] offset:64
	global_store_dwordx4 v145, v[116:119], s[52:53] offset:512
	global_store_dwordx4 v145, v[108:111], s[52:53] offset:576
	global_store_dwordx4 v216, v[112:115], s[52:53]
	global_store_dwordx4 v216, v[104:107], s[52:53] offset:64
	global_store_dwordx4 v216, v[100:103], s[52:53] offset:512
	global_store_dwordx4 v216, v[96:99], s[52:53] offset:576
	global_load_dwordx4 v[140:143], v228, s[52:53]
	v_add_u32_e32 v144, v220, v233
	global_load_dwordx4 v[152:155], v144, s[52:53]
	global_load_dwordx4 v[156:159], v228, s[52:53] offset:512
	v_add_u32_e32 v144, v220, v233
	global_load_dwordx4 v[160:163], v144, s[52:53] offset:512
	global_load_dwordx4 v[164:167], v229, s[52:53]
	v_add_u32_e32 v144, v221, v233
	global_load_dwordx4 v[168:171], v144, s[52:53]
	global_load_dwordx4 v[172:175], v229, s[52:53] offset:512
	v_add_u32_e32 v144, v221, v233
	global_load_dwordx4 v[176:179], v144, s[52:53] offset:512
	s_waitcnt vmcnt(16)
	v_mov_b32_e32 v212, v184
	v_mov_b32_e32 v213, v185
	v_mov_b32_e32 v214, v186
	v_mov_b32_e32 v215, v187
	s_nop 0
	v_mov_b32_dpp v184, v180 row_shl:8 row_mask:0xf bank_mask:0x3
	v_mov_b32_dpp v185, v181 row_shl:8 row_mask:0xf bank_mask:0x3
	v_mov_b32_dpp v186, v182 row_shl:8 row_mask:0xf bank_mask:0x3
	v_mov_b32_dpp v187, v183 row_shl:8 row_mask:0xf bank_mask:0x3
	v_mov_b32_dpp v180, v212 row_shr:8 row_mask:0xf bank_mask:0xc
	v_mov_b32_dpp v181, v213 row_shr:8 row_mask:0xf bank_mask:0xc
	v_mov_b32_dpp v182, v214 row_shr:8 row_mask:0xf bank_mask:0xc
	v_mov_b32_dpp v183, v215 row_shr:8 row_mask:0xf bank_mask:0xc
	v_mov_b32_e32 v212, v192
	v_mov_b32_e32 v213, v193
	v_mov_b32_e32 v214, v194
	v_mov_b32_e32 v215, v195
	s_nop 0
	v_mov_b32_dpp v192, v188 row_shl:8 row_mask:0xf bank_mask:0x3
	v_mov_b32_dpp v193, v189 row_shl:8 row_mask:0xf bank_mask:0x3
	v_mov_b32_dpp v194, v190 row_shl:8 row_mask:0xf bank_mask:0x3
	v_mov_b32_dpp v195, v191 row_shl:8 row_mask:0xf bank_mask:0x3
	v_mov_b32_dpp v188, v212 row_shr:8 row_mask:0xf bank_mask:0xc
	v_mov_b32_dpp v189, v213 row_shr:8 row_mask:0xf bank_mask:0xc
	v_mov_b32_dpp v190, v214 row_shr:8 row_mask:0xf bank_mask:0xc
	v_mov_b32_dpp v191, v215 row_shr:8 row_mask:0xf bank_mask:0xc
	v_mov_b32_e32 v212, v200
	v_mov_b32_e32 v213, v201
	v_mov_b32_e32 v214, v202
	v_mov_b32_e32 v215, v203
	s_nop 0
	v_mov_b32_dpp v200, v196 row_shl:8 row_mask:0xf bank_mask:0x3
	v_mov_b32_dpp v201, v197 row_shl:8 row_mask:0xf bank_mask:0x3
	v_mov_b32_dpp v202, v198 row_shl:8 row_mask:0xf bank_mask:0x3
	v_mov_b32_dpp v203, v199 row_shl:8 row_mask:0xf bank_mask:0x3
	v_mov_b32_dpp v196, v212 row_shr:8 row_mask:0xf bank_mask:0xc
	v_mov_b32_dpp v197, v213 row_shr:8 row_mask:0xf bank_mask:0xc
	v_mov_b32_dpp v198, v214 row_shr:8 row_mask:0xf bank_mask:0xc
	v_mov_b32_dpp v199, v215 row_shr:8 row_mask:0xf bank_mask:0xc
	v_mov_b32_e32 v212, v208
	v_mov_b32_e32 v213, v209
	v_mov_b32_e32 v214, v210
	v_mov_b32_e32 v215, v211
	s_nop 0
	v_mov_b32_dpp v208, v204 row_shl:8 row_mask:0xf bank_mask:0x3
	v_mov_b32_dpp v209, v205 row_shl:8 row_mask:0xf bank_mask:0x3
	v_mov_b32_dpp v210, v206 row_shl:8 row_mask:0xf bank_mask:0x3
	v_mov_b32_dpp v211, v207 row_shl:8 row_mask:0xf bank_mask:0x3
	v_mov_b32_dpp v204, v212 row_shr:8 row_mask:0xf bank_mask:0xc
	v_mov_b32_dpp v205, v213 row_shr:8 row_mask:0xf bank_mask:0xc
	v_mov_b32_dpp v206, v214 row_shr:8 row_mask:0xf bank_mask:0xc
	v_mov_b32_dpp v207, v215 row_shr:8 row_mask:0xf bank_mask:0xc
	v_pk_add_f32 v[92:93], v[92:93], v[180:181]
	v_pk_add_f32 v[94:95], v[94:95], v[182:183]
	v_pk_add_f32 v[88:89], v[88:89], v[184:185]
	v_pk_add_f32 v[90:91], v[90:91], v[186:187]
	v_pk_add_f32 v[84:85], v[84:85], v[188:189]
	v_pk_add_f32 v[86:87], v[86:87], v[190:191]
	v_pk_add_f32 v[76:77], v[76:77], v[192:193]
	v_pk_add_f32 v[78:79], v[78:79], v[194:195]
	v_pk_add_f32 v[80:81], v[80:81], v[196:197]
	v_pk_add_f32 v[82:83], v[82:83], v[198:199]
	v_pk_add_f32 v[72:73], v[72:73], v[200:201]
	v_pk_add_f32 v[74:75], v[74:75], v[202:203]
	v_pk_add_f32 v[68:69], v[68:69], v[204:205]
	v_pk_add_f32 v[70:71], v[70:71], v[206:207]
	v_pk_add_f32 v[64:65], v[64:65], v[208:209]
	v_pk_add_f32 v[66:67], v[66:67], v[210:211]
	global_store_dwordx4 v217, v[92:95], s[52:53]
	global_store_dwordx4 v217, v[88:91], s[52:53] offset:64
	global_store_dwordx4 v217, v[84:87], s[52:53] offset:512
	global_store_dwordx4 v217, v[76:79], s[52:53] offset:576
	global_store_dwordx4 v218, v[80:83], s[52:53]
	global_store_dwordx4 v218, v[72:75], s[52:53] offset:64
	global_store_dwordx4 v218, v[68:71], s[52:53] offset:512
	global_store_dwordx4 v218, v[64:67], s[52:53] offset:576
	global_load_dwordx4 v[180:183], v230, s[52:53]
	v_add_u32_e32 v144, v222, v233
	global_load_dwordx4 v[184:187], v144, s[52:53]
	global_load_dwordx4 v[188:191], v230, s[52:53] offset:512
	v_add_u32_e32 v144, v222, v233
	global_load_dwordx4 v[192:195], v144, s[52:53] offset:512
	global_load_dwordx4 v[196:199], v231, s[52:53]
	v_add_u32_e32 v144, v223, v233
	global_load_dwordx4 v[200:203], v144, s[52:53]
	global_load_dwordx4 v[204:207], v231, s[52:53] offset:512
	v_add_u32_e32 v144, v223, v233
	global_load_dwordx4 v[208:211], v144, s[52:53] offset:512
	s_waitcnt vmcnt(16)
;     __device__ __forceinline__ void operator()(AccRef acc, const Unit& u, int wr, int wc, int fr, int fq) const {
;     ...
;                         for (int n = 0; n < 2; ++n) bs[m][bj][n] = *(const f32x4*)(base + (size_t)(row0 + ai * 128 + (2 * mh + m) * 16) * D + col0 + bj * 128 + n * 16);
; #pragma unroll
;                 for (int m = 0; m < 2; ++m)
; #pragma unroll
;                     for (int bj = 0; bj < 2; ++bj)
; #pragma unroll
;                         for (int n = 0; n < 2; ++n) *(f32x4*)(out + (size_t)(row0 + ai * 128 + (2 * mh + m) * 16) * D + col0 + bj * 128 + n * 16) = bs[m][bj][n] + sv[bj][n] * (acc[ai][bj][2 * mh + m][n] + bv[bj][n]);
	v_mov_b32_e32 v212, v152
	v_mov_b32_e32 v213, v153
	v_mov_b32_e32 v214, v154
	v_mov_b32_e32 v215, v155
	s_nop 0
	v_mov_b32_dpp v152, v140 row_shl:8 row_mask:0xf bank_mask:0x3
	v_mov_b32_dpp v153, v141 row_shl:8 row_mask:0xf bank_mask:0x3
	v_mov_b32_dpp v154, v142 row_shl:8 row_mask:0xf bank_mask:0x3
	v_mov_b32_dpp v155, v143 row_shl:8 row_mask:0xf bank_mask:0x3
	v_mov_b32_dpp v140, v212 row_shr:8 row_mask:0xf bank_mask:0xc
	v_mov_b32_dpp v141, v213 row_shr:8 row_mask:0xf bank_mask:0xc
	v_mov_b32_dpp v142, v214 row_shr:8 row_mask:0xf bank_mask:0xc
	v_mov_b32_dpp v143, v215 row_shr:8 row_mask:0xf bank_mask:0xc
	v_mov_b32_e32 v212, v160
	v_mov_b32_e32 v213, v161
	v_mov_b32_e32 v214, v162
	v_mov_b32_e32 v215, v163
	s_nop 0
	v_mov_b32_dpp v160, v156 row_shl:8 row_mask:0xf bank_mask:0x3
	v_mov_b32_dpp v161, v157 row_shl:8 row_mask:0xf bank_mask:0x3
	v_mov_b32_dpp v162, v158 row_shl:8 row_mask:0xf bank_mask:0x3
	v_mov_b32_dpp v163, v159 row_shl:8 row_mask:0xf bank_mask:0x3
	v_mov_b32_dpp v156, v212 row_shr:8 row_mask:0xf bank_mask:0xc
	v_mov_b32_dpp v157, v213 row_shr:8 row_mask:0xf bank_mask:0xc
	v_mov_b32_dpp v158, v214 row_shr:8 row_mask:0xf bank_mask:0xc
	v_mov_b32_dpp v159, v215 row_shr:8 row_mask:0xf bank_mask:0xc
	v_mov_b32_e32 v212, v168
	v_mov_b32_e32 v213, v169
	v_mov_b32_e32 v214, v170
	v_mov_b32_e32 v215, v171
	s_nop 0
	v_mov_b32_dpp v168, v164 row_shl:8 row_mask:0xf bank_mask:0x3
	v_mov_b32_dpp v169, v165 row_shl:8 row_mask:0xf bank_mask:0x3
	v_mov_b32_dpp v170, v166 row_shl:8 row_mask:0xf bank_mask:0x3
	v_mov_b32_dpp v171, v167 row_shl:8 row_mask:0xf bank_mask:0x3
	v_mov_b32_dpp v164, v212 row_shr:8 row_mask:0xf bank_mask:0xc
	v_mov_b32_dpp v165, v213 row_shr:8 row_mask:0xf bank_mask:0xc
	v_mov_b32_dpp v166, v214 row_shr:8 row_mask:0xf bank_mask:0xc
	v_mov_b32_dpp v167, v215 row_shr:8 row_mask:0xf bank_mask:0xc
	v_mov_b32_e32 v212, v176
	v_mov_b32_e32 v213, v177
	v_mov_b32_e32 v214, v178
	v_mov_b32_e32 v215, v179
	s_nop 0
	v_mov_b32_dpp v176, v172 row_shl:8 row_mask:0xf bank_mask:0x3
	v_mov_b32_dpp v177, v173 row_shl:8 row_mask:0xf bank_mask:0x3
	v_mov_b32_dpp v178, v174 row_shl:8 row_mask:0xf bank_mask:0x3
	v_mov_b32_dpp v179, v175 row_shl:8 row_mask:0xf bank_mask:0x3
	v_mov_b32_dpp v172, v212 row_shr:8 row_mask:0xf bank_mask:0xc
	v_mov_b32_dpp v173, v213 row_shr:8 row_mask:0xf bank_mask:0xc
	v_mov_b32_dpp v174, v214 row_shr:8 row_mask:0xf bank_mask:0xc
	v_mov_b32_dpp v175, v215 row_shr:8 row_mask:0xf bank_mask:0xc
	v_pk_add_f32 v[60:61], v[60:61], v[140:141]
	v_pk_add_f32 v[62:63], v[62:63], v[142:143]
	v_pk_add_f32 v[56:57], v[56:57], v[152:153]
	v_pk_add_f32 v[58:59], v[58:59], v[154:155]
	v_pk_add_f32 v[52:53], v[52:53], v[156:157]
	v_pk_add_f32 v[54:55], v[54:55], v[158:159]
	v_pk_add_f32 v[44:45], v[44:45], v[160:161]
	v_pk_add_f32 v[46:47], v[46:47], v[162:163]
	v_pk_add_f32 v[48:49], v[48:49], v[164:165]
	v_pk_add_f32 v[50:51], v[50:51], v[166:167]
	v_pk_add_f32 v[40:41], v[40:41], v[168:169]
	v_pk_add_f32 v[42:43], v[42:43], v[170:171]
	v_pk_add_f32 v[36:37], v[36:37], v[172:173]
	v_pk_add_f32 v[38:39], v[38:39], v[174:175]
	v_pk_add_f32 v[32:33], v[32:33], v[176:177]
	v_pk_add_f32 v[34:35], v[34:35], v[178:179]
	global_store_dwordx4 v220, v[60:63], s[52:53]
	global_store_dwordx4 v220, v[56:59], s[52:53] offset:64
	global_store_dwordx4 v220, v[52:55], s[52:53] offset:512
	global_store_dwordx4 v220, v[44:47], s[52:53] offset:576
	global_store_dwordx4 v221, v[48:51], s[52:53]
	global_store_dwordx4 v221, v[40:43], s[52:53] offset:64
	global_store_dwordx4 v221, v[36:39], s[52:53] offset:512
	global_store_dwordx4 v221, v[32:35], s[52:53] offset:576
	s_waitcnt vmcnt(8)
; #define PG8_WAIT_V(n) asm volatile("s_waitcnt vmcnt(" #n ")" ::: "memory")
; #define PG8_BAR __builtin_amdgcn_s_barrier()
; template <class Epi>
; __device__ __forceinline__ void gemm_phase(LAS unsigned char* lds, const Gemm g, const StaticOrder& S, const Epi& E) {
;     ...
;         if (!has_next) break;
;         {
; #pragma unroll
;         for (int a = 0; a < 2; ++a)
; #pragma unroll
;             for (int b = 0; b < 2; ++b)
; #pragma unroll
;                 for (int m = 0; m < 4; ++m)
; #pragma unroll
;                     for (int n = 0; n < 2; ++n) acc[a][b][m][n] = (f32x4){0.f, 0.f, 0.f, 0.f};
;         }
;         cur = nxt; cA = nA; cB = nB; ++ui;
;     }
;     PG8_WAIT_V(0);
;     if (wr == 0) PG8_BAR;
;     PG8_BAR;
;     __device__ __forceinline__ void operator()(AccRef acc, const Unit& u, int wr, int wc, int fr, int fq) const {
;     ...
;                         for (int n = 0; n < 2; ++n) bs[m][bj][n] = *(const f32x4*)(base + (size_t)(row0 + ai * 128 + (2 * mh + m) * 16) * D + col0 + bj * 128 + n * 16);
; #pragma unroll
;                 for (int m = 0; m < 2; ++m)
; #pragma unroll
;                     for (int bj = 0; bj < 2; ++bj)
; #pragma unroll
;                         for (int n = 0; n < 2; ++n) *(f32x4*)(out + (size_t)(row0 + ai * 128 + (2 * mh + m) * 16) * D + col0 + bj * 128 + n * 16) = bs[m][bj][n] + sv[bj][n] * (acc[ai][bj][2 * mh + m][n] + bv[bj][n]);
;                 asm volatile("" ::: "memory"); }
	v_mov_b32_e32 v212, v184
	v_mov_b32_e32 v213, v185
	v_mov_b32_e32 v214, v186
	v_mov_b32_e32 v215, v187
	s_nop 0
	v_mov_b32_dpp v184, v180 row_shl:8 row_mask:0xf bank_mask:0x3
	v_mov_b32_dpp v185, v181 row_shl:8 row_mask:0xf bank_mask:0x3
	v_mov_b32_dpp v186, v182 row_shl:8 row_mask:0xf bank_mask:0x3
	v_mov_b32_dpp v187, v183 row_shl:8 row_mask:0xf bank_mask:0x3
	v_mov_b32_dpp v180, v212 row_shr:8 row_mask:0xf bank_mask:0xc
	v_mov_b32_dpp v181, v213 row_shr:8 row_mask:0xf bank_mask:0xc
	v_mov_b32_dpp v182, v214 row_shr:8 row_mask:0xf bank_mask:0xc
	v_mov_b32_dpp v183, v215 row_shr:8 row_mask:0xf bank_mask:0xc
	v_mov_b32_e32 v212, v192
	v_mov_b32_e32 v213, v193
	v_mov_b32_e32 v214, v194
	v_mov_b32_e32 v215, v195
	s_nop 0
	v_mov_b32_dpp v192, v188 row_shl:8 row_mask:0xf bank_mask:0x3
	v_mov_b32_dpp v193, v189 row_shl:8 row_mask:0xf bank_mask:0x3
	v_mov_b32_dpp v194, v190 row_shl:8 row_mask:0xf bank_mask:0x3
	v_mov_b32_dpp v195, v191 row_shl:8 row_mask:0xf bank_mask:0x3
	v_mov_b32_dpp v188, v212 row_shr:8 row_mask:0xf bank_mask:0xc
	v_mov_b32_dpp v189, v213 row_shr:8 row_mask:0xf bank_mask:0xc
	v_mov_b32_dpp v190, v214 row_shr:8 row_mask:0xf bank_mask:0xc
	v_mov_b32_dpp v191, v215 row_shr:8 row_mask:0xf bank_mask:0xc
	v_mov_b32_e32 v212, v200
	v_mov_b32_e32 v213, v201
	v_mov_b32_e32 v214, v202
	v_mov_b32_e32 v215, v203
	s_nop 0
	v_mov_b32_dpp v200, v196 row_shl:8 row_mask:0xf bank_mask:0x3
	v_mov_b32_dpp v201, v197 row_shl:8 row_mask:0xf bank_mask:0x3
	v_mov_b32_dpp v202, v198 row_shl:8 row_mask:0xf bank_mask:0x3
	v_mov_b32_dpp v203, v199 row_shl:8 row_mask:0xf bank_mask:0x3
	v_mov_b32_dpp v196, v212 row_shr:8 row_mask:0xf bank_mask:0xc
	v_mov_b32_dpp v197, v213 row_shr:8 row_mask:0xf bank_mask:0xc
	v_mov_b32_dpp v198, v214 row_shr:8 row_mask:0xf bank_mask:0xc
	v_mov_b32_dpp v199, v215 row_shr:8 row_mask:0xf bank_mask:0xc
	v_mov_b32_e32 v212, v208
	v_mov_b32_e32 v213, v209
	v_mov_b32_e32 v214, v210
	v_mov_b32_e32 v215, v211
	s_nop 0
	v_mov_b32_dpp v208, v204 row_shl:8 row_mask:0xf bank_mask:0x3
	v_mov_b32_dpp v209, v205 row_shl:8 row_mask:0xf bank_mask:0x3
	v_mov_b32_dpp v210, v206 row_shl:8 row_mask:0xf bank_mask:0x3
	v_mov_b32_dpp v211, v207 row_shl:8 row_mask:0xf bank_mask:0x3
	v_mov_b32_dpp v204, v212 row_shr:8 row_mask:0xf bank_mask:0xc
	v_mov_b32_dpp v205, v213 row_shr:8 row_mask:0xf bank_mask:0xc
	v_mov_b32_dpp v206, v214 row_shr:8 row_mask:0xf bank_mask:0xc
	v_mov_b32_dpp v207, v215 row_shr:8 row_mask:0xf bank_mask:0xc
	v_pk_add_f32 v[28:29], v[28:29], v[180:181]
	v_pk_add_f32 v[30:31], v[30:31], v[182:183]
	v_pk_add_f32 v[24:25], v[24:25], v[184:185]
	v_pk_add_f32 v[26:27], v[26:27], v[186:187]
	v_pk_add_f32 v[20:21], v[20:21], v[188:189]
	v_pk_add_f32 v[22:23], v[22:23], v[190:191]
	v_pk_add_f32 v[12:13], v[12:13], v[192:193]
	v_pk_add_f32 v[14:15], v[14:15], v[194:195]
	v_pk_add_f32 v[16:17], v[16:17], v[196:197]
	v_pk_add_f32 v[18:19], v[18:19], v[198:199]
	v_pk_add_f32 v[8:9], v[8:9], v[200:201]
	v_pk_add_f32 v[10:11], v[10:11], v[202:203]
	v_pk_add_f32 v[4:5], v[4:5], v[204:205]
	v_pk_add_f32 v[6:7], v[6:7], v[206:207]
	v_pk_add_f32 v[0:1], v[0:1], v[208:209]
	v_pk_add_f32 v[2:3], v[2:3], v[210:211]
	global_store_dwordx4 v222, v[28:31], s[52:53]
	global_store_dwordx4 v222, v[24:27], s[52:53] offset:64
	global_store_dwordx4 v222, v[20:23], s[52:53] offset:512
	global_store_dwordx4 v222, v[12:15], s[52:53] offset:576
	global_store_dwordx4 v223, v[16:19], s[52:53]
	global_store_dwordx4 v223, v[8:11], s[52:53] offset:64
	global_store_dwordx4 v223, v[4:7], s[52:53] offset:512
	global_store_dwordx4 v223, v[0:3], s[52:53] offset:576
	s_cbranch_vccz .LBB0_1813
	s_waitcnt vmcnt(0)
	s_cmpk_gt_u32 s4, 0xff
	s_cbranch_scc1 .LBB0_1824
	s_barrier

; #define PG8_STAGE(bufoff, gbase, voff) do { _Pragma("unroll") for (int _i = 0; _i < 2; ++_i) \
;         __builtin_amdgcn_global_load_lds((const unsigned*)((const char*)(gbase) + (voff)[_i]), (LAS unsigned*)(lds + (bufoff) + ldsw + _i * 8192), 16, 0, 0); } while (0)
; #define PG8_LDA(dst, b, h) do { _Pragma("unroll") for (int m = 0; m < 4; ++m) _Pragma("unroll") for (int k = 0; k < 2; ++k) dst[m][k] = *(const LAS bf16x8*)(lds + PG8_SA(b, h) + aoff + m * 2048 + k * 1024); } while (0)
; #define PG8_LDB(dst, b, h) do { _Pragma("unroll") for (int n = 0; n < 2; ++n) _Pragma("unroll") for (int k = 0; k < 2; ++k) dst[n][k] = *(const LAS bf16x8*)(lds + PG8_SB(b, h) + boff + n * 2048 + k * 1024); } while (0)
; #define PG8_MMA(ai, bj, At, Bt) do { __builtin_amdgcn_s_setprio(1); _Pragma("unroll") for (int m = 0; m < 4; ++m) _Pragma("unroll") for (int n = 0; n < 2; ++n) _Pragma("unroll") for (int k = 0; k < 2; ++k) \
;         acc[ai][bj][m][n] = __builtin_amdgcn_mfma_f32_16x16x32_bf16(Bt[n][k], At[m][k], acc[ai][bj][m][n], 0, 0, 0); __builtin_amdgcn_s_setprio(0); } while (0)
; #define PG8_WAIT_L(n) asm volatile("s_waitcnt lgkmcnt(" #n ")" ::: "memory")
; #define PG8_BAR __builtin_amdgcn_s_barrier()
; #define PG8_SCHED __builtin_amdgcn_sched_barrier(0)
; template <class Epi>
; __device__ __forceinline__ void gemm_phase(LAS unsigned char* lds, const Gemm g, const StaticOrder& S, const Epi& E) {
;     ...
;         for (int t = 0; t < nt; t += 2) {
;             const bool last = (t == nt - 2);
;             const char* a1 = cA + (size_t)(t + 1) * kstep;
;             const char* a2 = last ? nA : cA + (size_t)(t + 2) * kstep; const char* b2 = last ? nB : cB + (size_t)(t + 2) * kstep;
;             const char* a3 = a2 + kstep; const char* b3 = b2 + kstep;
;             PG8_LDB(B0, 0, 0); PG8_SCHED; PG8_LDA(At, 0, 0); PG8_STAGE(PG8_SA(1, 1), a1 + hstepA, voffA);
;             PG8_WAIT_L(8); PG8_BAR; PG8_WAIT_L(0); PG8_MMA(0, 0, At, B0); PG8_BAR; PG8_SCHED;
;             PG8_LDB(B1, 0, 1); PG8_STAGE(PG8_SB(0, 0), b2, voffB);
;             PG8_BAR; PG8_WAIT_L(0); PG8_MMA(0, 1, At, B1); PG8_BAR;
;             PG8_LDA(At, 0, 1); PG8_STAGE(PG8_SA(0, 0), a2, voffA);
;             PG8_BAR; PG8_WAIT_L(0); PG8_MMA(1, 0, At, B0); PG8_BAR; PG8_SCHED;
.LBB0_2042:
	ds_read_b128 v[140:143], v149
	ds_read_b128 v[152:155], v149 offset:1024
	ds_read_b128 v[156:159], v149 offset:2048
	ds_read_b128 v[160:163], v149 offset:3072
	s_add_u32 s20, s18, 0x100
	s_addc_u32 s21, s19, 0
	s_cmp_eq_u32 s46, 40
	s_cselect_b32 s25, s5, s21
	s_cselect_b32 s24, s4, s20
	s_cselect_b32 s23, s7, s45
	s_cselect_b32 s22, s6, s44
	v_lshl_add_u64 v[144:145], s[18:19], 0, v[132:133]
	s_add_i32 m0, s30, 0xc000
	ds_read_b128 v[164:167], v150
	ds_read_b128 v[168:171], v150 offset:1024
	ds_read_b128 v[172:175], v150 offset:2048
	ds_read_b128 v[176:179], v150 offset:3072
	ds_read_b128 v[180:183], v150 offset:4096
	ds_read_b128 v[184:187], v150 offset:5120
	ds_read_b128 v[188:191], v150 offset:6144
	ds_read_b128 v[192:195], v150 offset:7168
	global_load_lds_dwordx4 v[144:145], off
	v_lshl_add_u64 v[144:145], s[18:19], 0, v[134:135]
	s_add_i32 m0, s30, 0xe000
	s_nop 0
	global_load_lds_dwordx4 v[144:145], off
	ds_read_b128 v[196:199], v151
	ds_read_b128 v[200:203], v151 offset:1024
	ds_read_b128 v[204:207], v151 offset:2048
	ds_read_b128 v[208:211], v151 offset:3072
	s_waitcnt lgkmcnt(0)
	s_barrier
	s_setprio 1
	v_mfma_f32_16x16x32_bf16 v[124:127], v[140:143], v[164:167], v[124:127]
	v_mfma_f32_16x16x32_bf16 v[120:123], v[156:159], v[164:167], v[120:123]
	v_mfma_f32_16x16x32_bf16 v[112:115], v[140:143], v[172:175], v[112:115]
	v_mfma_f32_16x16x32_bf16 v[104:107], v[156:159], v[172:175], v[104:107]
	v_mfma_f32_16x16x32_bf16 v[92:95], v[140:143], v[180:183], v[92:95]
	v_mfma_f32_16x16x32_bf16 v[88:91], v[156:159], v[180:183], v[88:91]
	v_mfma_f32_16x16x32_bf16 v[80:83], v[140:143], v[188:191], v[80:83]
	v_mfma_f32_16x16x32_bf16 v[72:75], v[156:159], v[188:191], v[72:75]
	v_mfma_f32_16x16x32_bf16 v[124:127], v[152:155], v[168:171], v[124:127]
	v_mfma_f32_16x16x32_bf16 v[120:123], v[160:163], v[168:171], v[120:123]
	v_mfma_f32_16x16x32_bf16 v[112:115], v[152:155], v[176:179], v[112:115]
	v_mfma_f32_16x16x32_bf16 v[104:107], v[160:163], v[176:179], v[104:107]
	v_mfma_f32_16x16x32_bf16 v[92:95], v[152:155], v[184:187], v[92:95]
	v_mfma_f32_16x16x32_bf16 v[88:91], v[160:163], v[184:187], v[88:91]
	v_mfma_f32_16x16x32_bf16 v[80:83], v[152:155], v[192:195], v[80:83]
	v_mfma_f32_16x16x32_bf16 v[72:75], v[160:163], v[192:195], v[72:75]
	v_mfma_f32_16x16x32_bf16 v[116:119], v[196:199], v[164:167], v[116:119]
	v_mfma_f32_16x16x32_bf16 v[108:111], v[204:207], v[164:167], v[108:111]
	v_mfma_f32_16x16x32_bf16 v[100:103], v[196:199], v[172:175], v[100:103]
	v_mfma_f32_16x16x32_bf16 v[96:99], v[204:207], v[172:175], v[96:99]
	v_mfma_f32_16x16x32_bf16 v[84:87], v[196:199], v[180:183], v[84:87]
	v_mfma_f32_16x16x32_bf16 v[76:79], v[204:207], v[180:183], v[76:79]
	v_mfma_f32_16x16x32_bf16 v[68:71], v[196:199], v[188:191], v[68:71]
	v_mfma_f32_16x16x32_bf16 v[64:67], v[204:207], v[188:191], v[64:67]
	v_mfma_f32_16x16x32_bf16 v[116:119], v[200:203], v[168:171], v[116:119]
	v_mfma_f32_16x16x32_bf16 v[108:111], v[208:211], v[168:171], v[108:111]
	v_mfma_f32_16x16x32_bf16 v[100:103], v[200:203], v[176:179], v[100:103]
	v_mfma_f32_16x16x32_bf16 v[96:99], v[208:211], v[176:179], v[96:99]
	v_mfma_f32_16x16x32_bf16 v[84:87], v[200:203], v[184:187], v[84:87]
	v_mfma_f32_16x16x32_bf16 v[76:79], v[208:211], v[184:187], v[76:79]
	v_mfma_f32_16x16x32_bf16 v[68:71], v[200:203], v[192:195], v[68:71]
	v_mfma_f32_16x16x32_bf16 v[64:67], v[208:211], v[192:195], v[64:67]
	s_setprio 0
	s_barrier
	s_nop 1
	ds_read_b128 v[164:167], v150 offset:16384
	ds_read_b128 v[168:171], v150 offset:17408
	ds_read_b128 v[172:175], v150 offset:18432
	ds_read_b128 v[176:179], v150 offset:19456
	ds_read_b128 v[180:183], v150 offset:20480
	ds_read_b128 v[184:187], v150 offset:21504
	ds_read_b128 v[188:191], v150 offset:22528
	ds_read_b128 v[192:195], v150 offset:23552
	s_add_i32 s18, s38, s29
	v_lshl_add_u64 v[144:145], s[22:23], 0, v[128:129]
	s_mov_b32 m0, s18
	s_nop 0
	global_load_lds_dwordx4 v[144:145], off
	v_lshl_add_u64 v[212:213], s[22:23], 0, v[130:131]
	s_add_i32 m0, s18, 0x2000
	s_nop 0
	global_load_lds_dwordx4 v[212:213], off
	s_mov_b32 m0, s30
	v_lshl_add_u64 v[214:215], s[24:25], 0, v[128:129]
	global_load_lds_dwordx4 v[214:215], off
	v_lshl_add_u64 v[216:217], s[24:25], 0, v[130:131]
	s_mov_b32 m0, s31
	s_nop 0
	global_load_lds_dwordx4 v[216:217], off
	s_add_u32 s18, s22, 0xb0000
	s_addc_u32 s19, s23, 0
	s_add_i32 s47, s39, s29
	v_lshl_add_u64 v[254:255], s[18:19], 0, v[128:129]
	s_mov_b32 m0, s47
	s_nop 0
	global_load_lds_dwordx4 v[254:255], off
	v_lshl_add_u64 v[254:255], s[18:19], 0, v[130:131]
	s_add_i32 m0, s47, 0x2000
	s_nop 0
	global_load_lds_dwordx4 v[254:255], off
	s_waitcnt vmcnt(6)
	s_waitcnt lgkmcnt(0)
	s_barrier
; #define PG8_STAGE(bufoff, gbase, voff) do { _Pragma("unroll") for (int _i = 0; _i < 2; ++_i) \
;         __builtin_amdgcn_global_load_lds((const unsigned*)((const char*)(gbase) + (voff)[_i]), (LAS unsigned*)(lds + (bufoff) + ldsw + _i * 8192), 16, 0, 0); } while (0)
; #define PG8_LDA(dst, b, h) do { _Pragma("unroll") for (int m = 0; m < 4; ++m) _Pragma("unroll") for (int k = 0; k < 2; ++k) dst[m][k] = *(const LAS bf16x8*)(lds + PG8_SA(b, h) + aoff + m * 2048 + k * 1024); } while (0)
; #define PG8_LDB(dst, b, h) do { _Pragma("unroll") for (int n = 0; n < 2; ++n) _Pragma("unroll") for (int k = 0; k < 2; ++k) dst[n][k] = *(const LAS bf16x8*)(lds + PG8_SB(b, h) + boff + n * 2048 + k * 1024); } while (0)
; #define PG8_MMA(ai, bj, At, Bt) do { __builtin_amdgcn_s_setprio(1); _Pragma("unroll") for (int m = 0; m < 4; ++m) _Pragma("unroll") for (int n = 0; n < 2; ++n) _Pragma("unroll") for (int k = 0; k < 2; ++k) \
;         acc[ai][bj][m][n] = __builtin_amdgcn_mfma_f32_16x16x32_bf16(Bt[n][k], At[m][k], acc[ai][bj][m][n], 0, 0, 0); __builtin_amdgcn_s_setprio(0); } while (0)
; #define PG8_WAIT_V(n) asm volatile("s_waitcnt vmcnt(" #n ")" ::: "memory")
; #define PG8_WAIT_L(n) asm volatile("s_waitcnt lgkmcnt(" #n ")" ::: "memory")
; #define PG8_BAR __builtin_amdgcn_s_barrier()
; #define PG8_SCHED __builtin_amdgcn_sched_barrier(0)
; template <class Epi>
; __device__ __forceinline__ void gemm_phase(LAS unsigned char* lds, const Gemm g, const StaticOrder& S, const Epi& E) {
;     ...
;             PG8_BAR; PG8_WAIT_L(0); PG8_MMA(1, 0, At, B0); PG8_BAR; PG8_SCHED;
;             PG8_STAGE(PG8_SB(0, 1), b2 + hstepB, voffB);
;             PG8_WAIT_V(6); PG8_BAR; PG8_MMA(1, 1, At, B1); PG8_BAR;
;             PG8_LDB(B0, 1, 0); PG8_SCHED; PG8_LDA(At, 1, 0); PG8_STAGE(PG8_SA(0, 1), a2 + hstepA, voffA);
;             PG8_WAIT_L(8); PG8_BAR; PG8_WAIT_L(0); PG8_MMA(0, 0, At, B0); PG8_BAR; PG8_SCHED;
;             PG8_LDB(B1, 1, 1); PG8_STAGE(PG8_SB(1, 0), b3, voffB);
;             PG8_BAR; PG8_WAIT_L(0); PG8_MMA(0, 1, At, B1); PG8_BAR;
;             PG8_LDA(At, 1, 1); PG8_STAGE(PG8_SA(1, 0), a3, voffA);
	s_setprio 1
	v_mfma_f32_16x16x32_bf16 v[60:63], v[140:143], v[164:167], v[60:63]
	v_mfma_f32_16x16x32_bf16 v[56:59], v[156:159], v[164:167], v[56:59]
	v_mfma_f32_16x16x32_bf16 v[48:51], v[140:143], v[172:175], v[48:51]
	v_mfma_f32_16x16x32_bf16 v[40:43], v[156:159], v[172:175], v[40:43]
	v_mfma_f32_16x16x32_bf16 v[28:31], v[140:143], v[180:183], v[28:31]
	v_mfma_f32_16x16x32_bf16 v[24:27], v[156:159], v[180:183], v[24:27]
	v_mfma_f32_16x16x32_bf16 v[16:19], v[140:143], v[188:191], v[16:19]
	v_mfma_f32_16x16x32_bf16 v[8:11], v[156:159], v[188:191], v[8:11]
	v_mfma_f32_16x16x32_bf16 v[60:63], v[152:155], v[168:171], v[60:63]
	v_mfma_f32_16x16x32_bf16 v[56:59], v[160:163], v[168:171], v[56:59]
	v_mfma_f32_16x16x32_bf16 v[48:51], v[152:155], v[176:179], v[48:51]
	v_mfma_f32_16x16x32_bf16 v[40:43], v[160:163], v[176:179], v[40:43]
	v_mfma_f32_16x16x32_bf16 v[28:31], v[152:155], v[184:187], v[28:31]
	v_mfma_f32_16x16x32_bf16 v[24:27], v[160:163], v[184:187], v[24:27]
	v_mfma_f32_16x16x32_bf16 v[16:19], v[152:155], v[192:195], v[16:19]
	v_mfma_f32_16x16x32_bf16 v[8:11], v[160:163], v[192:195], v[8:11]
	v_mfma_f32_16x16x32_bf16 v[52:55], v[196:199], v[164:167], v[52:55]
	v_mfma_f32_16x16x32_bf16 v[44:47], v[204:207], v[164:167], v[44:47]
	v_mfma_f32_16x16x32_bf16 v[36:39], v[196:199], v[172:175], v[36:39]
	v_mfma_f32_16x16x32_bf16 v[32:35], v[204:207], v[172:175], v[32:35]
	v_mfma_f32_16x16x32_bf16 v[20:23], v[196:199], v[180:183], v[20:23]
	v_mfma_f32_16x16x32_bf16 v[12:15], v[204:207], v[180:183], v[12:15]
	v_mfma_f32_16x16x32_bf16 v[4:7], v[196:199], v[188:191], v[4:7]
	v_mfma_f32_16x16x32_bf16 v[0:3], v[204:207], v[188:191], v[0:3]
	v_mfma_f32_16x16x32_bf16 v[52:55], v[200:203], v[168:171], v[52:55]
	v_mfma_f32_16x16x32_bf16 v[44:47], v[208:211], v[168:171], v[44:47]
	v_mfma_f32_16x16x32_bf16 v[36:39], v[200:203], v[176:179], v[36:39]
	v_mfma_f32_16x16x32_bf16 v[32:35], v[208:211], v[176:179], v[32:35]
	v_mfma_f32_16x16x32_bf16 v[20:23], v[200:203], v[184:187], v[20:23]
	v_mfma_f32_16x16x32_bf16 v[12:15], v[208:211], v[184:187], v[12:15]
	v_mfma_f32_16x16x32_bf16 v[4:7], v[200:203], v[192:195], v[4:7]
	v_mfma_f32_16x16x32_bf16 v[0:3], v[208:211], v[192:195], v[0:3]
	s_setprio 0
	s_add_i32 s47, 0, 0x18000
	v_add_u32_e32 v160, s47, v147
	s_barrier
	ds_read_b128 v[140:143], v160
	ds_read_b128 v[152:155], v160 offset:1024
	ds_read_b128 v[156:159], v160 offset:2048
	ds_read_b128 v[160:163], v160 offset:3072
	s_add_u32 s18, s24, 0xb0000
	s_addc_u32 s19, s25, 0
	s_mov_b32 m0, s33
	v_lshl_add_u64 v[196:197], s[18:19], 0, v[128:129]
	ds_read_b128 v[164:167], v150 offset:32768
	ds_read_b128 v[168:171], v150 offset:33792
	ds_read_b128 v[172:175], v150 offset:34816
	ds_read_b128 v[176:179], v150 offset:35840
	ds_read_b128 v[180:183], v150 offset:36864
	ds_read_b128 v[184:187], v150 offset:37888
	ds_read_b128 v[188:191], v150 offset:38912
	ds_read_b128 v[192:195], v150 offset:39936
	global_load_lds_dwordx4 v[196:197], off
	v_lshl_add_u64 v[196:197], s[18:19], 0, v[130:131]
	s_mov_b32 m0, s34
	s_nop 0
	global_load_lds_dwordx4 v[196:197], off
	s_add_i32 s24, 0, 0x1c000
	v_add_u32_e32 v208, s24, v147
	ds_read_b128 v[196:199], v208
	ds_read_b128 v[200:203], v208 offset:1024
	ds_read_b128 v[204:207], v208 offset:2048
	ds_read_b128 v[208:211], v208 offset:3072
	s_waitcnt lgkmcnt(0)
	s_barrier
	s_setprio 1
	v_mfma_f32_16x16x32_bf16 v[124:127], v[140:143], v[164:167], v[124:127]
	v_mfma_f32_16x16x32_bf16 v[120:123], v[156:159], v[164:167], v[120:123]
	v_mfma_f32_16x16x32_bf16 v[112:115], v[140:143], v[172:175], v[112:115]
	v_mfma_f32_16x16x32_bf16 v[104:107], v[156:159], v[172:175], v[104:107]
	v_mfma_f32_16x16x32_bf16 v[92:95], v[140:143], v[180:183], v[92:95]
	v_mfma_f32_16x16x32_bf16 v[88:91], v[156:159], v[180:183], v[88:91]
	v_mfma_f32_16x16x32_bf16 v[80:83], v[140:143], v[188:191], v[80:83]
	v_mfma_f32_16x16x32_bf16 v[72:75], v[156:159], v[188:191], v[72:75]
	v_mfma_f32_16x16x32_bf16 v[124:127], v[152:155], v[168:171], v[124:127]
	v_mfma_f32_16x16x32_bf16 v[120:123], v[160:163], v[168:171], v[120:123]
	v_mfma_f32_16x16x32_bf16 v[112:115], v[152:155], v[176:179], v[112:115]
	v_mfma_f32_16x16x32_bf16 v[104:107], v[160:163], v[176:179], v[104:107]
	v_mfma_f32_16x16x32_bf16 v[92:95], v[152:155], v[184:187], v[92:95]
	v_mfma_f32_16x16x32_bf16 v[88:91], v[160:163], v[184:187], v[88:91]
	v_mfma_f32_16x16x32_bf16 v[80:83], v[152:155], v[192:195], v[80:83]
	v_mfma_f32_16x16x32_bf16 v[72:75], v[160:163], v[192:195], v[72:75]
	v_mfma_f32_16x16x32_bf16 v[116:119], v[196:199], v[164:167], v[116:119]
	v_mfma_f32_16x16x32_bf16 v[108:111], v[204:207], v[164:167], v[108:111]
	v_mfma_f32_16x16x32_bf16 v[100:103], v[196:199], v[172:175], v[100:103]
	v_mfma_f32_16x16x32_bf16 v[96:99], v[204:207], v[172:175], v[96:99]
	v_mfma_f32_16x16x32_bf16 v[84:87], v[196:199], v[180:183], v[84:87]
	v_mfma_f32_16x16x32_bf16 v[76:79], v[204:207], v[180:183], v[76:79]
	v_mfma_f32_16x16x32_bf16 v[68:71], v[196:199], v[188:191], v[68:71]
	v_mfma_f32_16x16x32_bf16 v[64:67], v[204:207], v[188:191], v[64:67]
	v_mfma_f32_16x16x32_bf16 v[116:119], v[200:203], v[168:171], v[116:119]
	v_mfma_f32_16x16x32_bf16 v[108:111], v[208:211], v[168:171], v[108:111]
	v_mfma_f32_16x16x32_bf16 v[100:103], v[200:203], v[176:179], v[100:103]
	v_mfma_f32_16x16x32_bf16 v[96:99], v[208:211], v[176:179], v[96:99]
	v_mfma_f32_16x16x32_bf16 v[84:87], v[200:203], v[184:187], v[84:87]
	v_mfma_f32_16x16x32_bf16 v[76:79], v[208:211], v[184:187], v[76:79]
	v_mfma_f32_16x16x32_bf16 v[68:71], v[200:203], v[192:195], v[68:71]
	v_mfma_f32_16x16x32_bf16 v[64:67], v[208:211], v[192:195], v[64:67]
	s_setprio 0
	s_barrier
; #define PG8_STAGE(bufoff, gbase, voff) do { _Pragma("unroll") for (int _i = 0; _i < 2; ++_i) \
;         __builtin_amdgcn_global_load_lds((const unsigned*)((const char*)(gbase) + (voff)[_i]), (LAS unsigned*)(lds + (bufoff) + ldsw + _i * 8192), 16, 0, 0); } while (0)
; #define PG8_LDA(dst, b, h) do { _Pragma("unroll") for (int m = 0; m < 4; ++m) _Pragma("unroll") for (int k = 0; k < 2; ++k) dst[m][k] = *(const LAS bf16x8*)(lds + PG8_SA(b, h) + aoff + m * 2048 + k * 1024); } while (0)
; #define PG8_MMA(ai, bj, At, Bt) do { __builtin_amdgcn_s_setprio(1); _Pragma("unroll") for (int m = 0; m < 4; ++m) _Pragma("unroll") for (int n = 0; n < 2; ++n) _Pragma("unroll") for (int k = 0; k < 2; ++k) \
;         acc[ai][bj][m][n] = __builtin_amdgcn_mfma_f32_16x16x32_bf16(Bt[n][k], At[m][k], acc[ai][bj][m][n], 0, 0, 0); __builtin_amdgcn_s_setprio(0); } while (0)
; template <class Epi>
; __device__ __forceinline__ void gemm_phase(LAS unsigned char* lds, const Gemm g, const StaticOrder& S, const Epi& E) {
;     ...
;             PG8_LDA(At, 1, 1); PG8_STAGE(PG8_SA(1, 0), a3, voffA);
;             PG8_BAR; PG8_WAIT_L(0); PG8_MMA(1, 0, At, B0); PG8_BAR; PG8_SCHED;
;             PG8_STAGE(PG8_SB(1, 1), b3 + hstepB, voffB);
;             PG8_WAIT_V(6); PG8_BAR; PG8_MMA(1, 1, At, B1); PG8_BAR;
;     __device__ __forceinline__ void operator()(AccRef acc, const Unit& u, int wr, int wc, int fr, int fq) const {
;         const int row0 = u.pm * 256 + wr * 64 + fr, col0 = u.pn * 256 + wc * 32 + 4 * fq;
;         f32x4 sv[2][2], bv[2][2];
; #pragma unroll
;         for (int bj = 0; bj < 2; ++bj)
; #pragma unroll
;             for (int n = 0; n < 2; ++n) {
;                 sv[bj][n] = scale ? *(const f32x4*)(scale + col0 + bj * 128 + n * 16) : (f32x4){1.f, 1.f, 1.f, 1.f};
;                 bv[bj][n] = bias ? *(const f32x4*)(bias + col0 + bj * 128 + n * 16) : (f32x4){0.f, 0.f, 0.f, 0.f}; }
; #pragma unroll
;         for (int ai = 0; ai < 2; ++ai)
; #pragma unroll
;             for (int mh = 0; mh < 2; ++mh) {
;                 f32x4 bs[2][2][2];
; #pragma unroll
;                 for (int m = 0; m < 2; ++m)
; #pragma unroll
;                     for (int bj = 0; bj < 2; ++bj)
; #pragma unroll
;                         for (int n = 0; n < 2; ++n) bs[m][bj][n] = *(const f32x4*)(base + (size_t)(row0 + ai * 128 + (2 * mh + m) * 16) * D + col0 + bj * 128 + n * 16);
	s_nop 1
	ds_read_b128 v[164:167], v150 offset:49152
	ds_read_b128 v[168:171], v150 offset:50176
	ds_read_b128 v[172:175], v150 offset:51200
	ds_read_b128 v[176:179], v150 offset:52224
	ds_read_b128 v[180:183], v150 offset:53248
	ds_read_b128 v[184:187], v150 offset:54272
	ds_read_b128 v[188:191], v150 offset:55296
	ds_read_b128 v[192:195], v150 offset:56320
	s_add_i32 s18, s47, s29
	v_lshl_add_u64 v[254:255], v[144:145], 0, s[10:11]
	s_mov_b32 m0, s18
	s_nop 0
	global_load_lds_dwordx4 v[254:255], off
	v_lshl_add_u64 v[254:255], v[212:213], 0, s[10:11]
	s_add_i32 m0, s18, 0x2000
	s_nop 0
	global_load_lds_dwordx4 v[254:255], off
	s_mov_b32 m0, s36
	v_lshl_add_u64 v[254:255], v[214:215], 0, s[10:11]
	global_load_lds_dwordx4 v[254:255], off
	v_lshl_add_u64 v[144:145], v[216:217], 0, s[10:11]
	s_mov_b32 m0, s37
	s_nop 0
	global_load_lds_dwordx4 v[144:145], off
	s_add_u32 s18, s22, 0xb0080
	s_addc_u32 s19, s23, 0
	s_add_i32 s22, s24, s29
	v_lshl_add_u64 v[254:255], s[18:19], 0, v[128:129]
	s_mov_b32 m0, s22
	s_nop 0
	global_load_lds_dwordx4 v[254:255], off
	v_lshl_add_u64 v[254:255], s[18:19], 0, v[130:131]
	s_add_i32 m0, s22, 0x2000
	s_nop 0
	global_load_lds_dwordx4 v[254:255], off
	s_waitcnt vmcnt(6)
	s_waitcnt lgkmcnt(0)
	s_barrier
	s_setprio 1
	v_mfma_f32_16x16x32_bf16 v[60:63], v[140:143], v[164:167], v[60:63]
	v_mfma_f32_16x16x32_bf16 v[56:59], v[156:159], v[164:167], v[56:59]
	v_mfma_f32_16x16x32_bf16 v[48:51], v[140:143], v[172:175], v[48:51]
	v_mfma_f32_16x16x32_bf16 v[40:43], v[156:159], v[172:175], v[40:43]
	v_mfma_f32_16x16x32_bf16 v[28:31], v[140:143], v[180:183], v[28:31]
	v_mfma_f32_16x16x32_bf16 v[24:27], v[156:159], v[180:183], v[24:27]
	v_mfma_f32_16x16x32_bf16 v[16:19], v[140:143], v[188:191], v[16:19]
	v_mfma_f32_16x16x32_bf16 v[8:11], v[156:159], v[188:191], v[8:11]
	v_mfma_f32_16x16x32_bf16 v[60:63], v[152:155], v[168:171], v[60:63]
	v_mfma_f32_16x16x32_bf16 v[56:59], v[160:163], v[168:171], v[56:59]
	v_mfma_f32_16x16x32_bf16 v[48:51], v[152:155], v[176:179], v[48:51]
	v_mfma_f32_16x16x32_bf16 v[40:43], v[160:163], v[176:179], v[40:43]
	v_mfma_f32_16x16x32_bf16 v[28:31], v[152:155], v[184:187], v[28:31]
	v_mfma_f32_16x16x32_bf16 v[24:27], v[160:163], v[184:187], v[24:27]
	v_mfma_f32_16x16x32_bf16 v[16:19], v[152:155], v[192:195], v[16:19]
	v_mfma_f32_16x16x32_bf16 v[8:11], v[160:163], v[192:195], v[8:11]
	v_mfma_f32_16x16x32_bf16 v[52:55], v[196:199], v[164:167], v[52:55]
	v_mfma_f32_16x16x32_bf16 v[44:47], v[204:207], v[164:167], v[44:47]
	v_mfma_f32_16x16x32_bf16 v[36:39], v[196:199], v[172:175], v[36:39]
	v_mfma_f32_16x16x32_bf16 v[32:35], v[204:207], v[172:175], v[32:35]
	v_mfma_f32_16x16x32_bf16 v[20:23], v[196:199], v[180:183], v[20:23]
	v_mfma_f32_16x16x32_bf16 v[12:15], v[204:207], v[180:183], v[12:15]
	v_mfma_f32_16x16x32_bf16 v[4:7], v[196:199], v[188:191], v[4:7]
	v_mfma_f32_16x16x32_bf16 v[0:3], v[204:207], v[188:191], v[0:3]
	v_mfma_f32_16x16x32_bf16 v[52:55], v[200:203], v[168:171], v[52:55]
	v_mfma_f32_16x16x32_bf16 v[44:47], v[208:211], v[168:171], v[44:47]
	v_mfma_f32_16x16x32_bf16 v[36:39], v[200:203], v[176:179], v[36:39]
	v_mfma_f32_16x16x32_bf16 v[32:35], v[208:211], v[176:179], v[32:35]
	v_mfma_f32_16x16x32_bf16 v[20:23], v[200:203], v[184:187], v[20:23]
	v_mfma_f32_16x16x32_bf16 v[12:15], v[208:211], v[184:187], v[12:15]
	v_mfma_f32_16x16x32_bf16 v[4:7], v[200:203], v[192:195], v[4:7]
	v_mfma_f32_16x16x32_bf16 v[0:3], v[208:211], v[192:195], v[0:3]
	s_setprio 0
	s_add_i32 s46, s46, 2
	s_add_u32 s44, s44, 0x100
	s_addc_u32 s45, s45, 0
	s_cmp_gt_u32 s46, 41
	s_mov_b64 s[18:19], s[20:21]
	s_barrier
	s_cbranch_scc0 .LBB0_2042
	v_lshl_or_b32 v144, s42, 8, v148
	v_lshl_add_u32 v145, s43, 8, v146
	v_lshlrev_b32_e32 v144, 2, v144
	v_lshl_add_u32 v145, v145, 12, v144
	v_add_u32_e32 v216, 0x10000, v145
	v_add_u32_e32 v217, 0x20000, v145
	v_add_u32_e32 v218, 0x30000, v145
	v_add_u32_e32 v220, 0x80000, v145
	v_add_u32_e32 v221, 0x90000, v145
	v_add_u32_e32 v222, 0xa0000, v145
	v_add_u32_e32 v223, 0xb0000, v145
	v_and_b32_e32 v235, 8, v146
	v_cmp_ne_u32_e32 vcc, 0, v235
	v_mov_b32_e32 v232, 0xffff8040
	s_nop 0
	v_cndmask_b32_e32 v232, 0, v232, vcc
	v_mov_b32_e32 v233, 64
	v_mov_b32_e32 v235, 0x8000
	v_cndmask_b32_e32 v233, v235, v233, vcc
	v_add_u32_e32 v224, v145, v232
	v_add_u32_e32 v225, v216, v232
	v_add_u32_e32 v226, v217, v232
	v_add_u32_e32 v227, v218, v232
	v_add_u32_e32 v228, v220, v232
	v_add_u32_e32 v229, v221, v232
	v_add_u32_e32 v230, v222, v232
	v_add_u32_e32 v231, v223, v232
	s_and_b64 vcc, exec, s[0:1]
	s_mov_b32 s42, s40
	s_mov_b32 s43, s41
	s_mov_b64 s[20:21], s[6:7]
	s_mov_b64 s[18:19], s[4:5]
	global_load_dwordx4 v[140:143], v224, s[52:53]
	v_add_u32_e32 v144, v145, v233
	global_load_dwordx4 v[152:155], v144, s[52:53]
	global_load_dwordx4 v[156:159], v224, s[52:53] offset:512
	v_add_u32_e32 v144, v145, v233
	global_load_dwordx4 v[160:163], v144, s[52:53] offset:512
	global_load_dwordx4 v[164:167], v225, s[52:53]
	v_add_u32_e32 v144, v216, v233
	global_load_dwordx4 v[168:171], v144, s[52:53]
	global_load_dwordx4 v[172:175], v225, s[52:53] offset:512
	v_add_u32_e32 v144, v216, v233
	global_load_dwordx4 v[176:179], v144, s[52:53] offset:512
	global_load_dwordx4 v[180:183], v226, s[52:53]
	v_add_u32_e32 v144, v217, v233
	global_load_dwordx4 v[184:187], v144, s[52:53]
	global_load_dwordx4 v[188:191], v226, s[52:53] offset:512
	v_add_u32_e32 v144, v217, v233
	global_load_dwordx4 v[192:195], v144, s[52:53] offset:512
	global_load_dwordx4 v[196:199], v227, s[52:53]
	v_add_u32_e32 v144, v218, v233
	global_load_dwordx4 v[200:203], v144, s[52:53]
	global_load_dwordx4 v[204:207], v227, s[52:53] offset:512
;     __device__ __forceinline__ void operator()(AccRef acc, const Unit& u, int wr, int wc, int fr, int fq) const {
;     ...
;                         for (int n = 0; n < 2; ++n) bs[m][bj][n] = *(const f32x4*)(base + (size_t)(row0 + ai * 128 + (2 * mh + m) * 16) * D + col0 + bj * 128 + n * 16);
; #pragma unroll
;                 for (int m = 0; m < 2; ++m)
; #pragma unroll
;                     for (int bj = 0; bj < 2; ++bj)
; #pragma unroll
;                         for (int n = 0; n < 2; ++n) *(f32x4*)(out + (size_t)(row0 + ai * 128 + (2 * mh + m) * 16) * D + col0 + bj * 128 + n * 16) = bs[m][bj][n] + sv[bj][n] * (acc[ai][bj][2 * mh + m][n] + bv[bj][n]);
	v_add_u32_e32 v144, v218, v233
	global_load_dwordx4 v[208:211], v144, s[52:53] offset:512
	v_pk_add_f32 v[124:125], v[124:125], 0 op_sel_hi:[1,0]
	v_pk_add_f32 v[126:127], v[126:127], 0 op_sel_hi:[1,0]
	v_pk_add_f32 v[120:121], v[120:121], 0 op_sel_hi:[1,0]
	v_pk_add_f32 v[122:123], v[122:123], 0 op_sel_hi:[1,0]
	v_pk_add_f32 v[116:117], v[116:117], 0 op_sel_hi:[1,0]
	v_pk_add_f32 v[118:119], v[118:119], 0 op_sel_hi:[1,0]
	v_pk_add_f32 v[108:109], v[108:109], 0 op_sel_hi:[1,0]
	v_pk_add_f32 v[110:111], v[110:111], 0 op_sel_hi:[1,0]
	v_pk_add_f32 v[112:113], v[112:113], 0 op_sel_hi:[1,0]
	v_pk_add_f32 v[114:115], v[114:115], 0 op_sel_hi:[1,0]
	v_pk_add_f32 v[104:105], v[104:105], 0 op_sel_hi:[1,0]
	v_pk_add_f32 v[106:107], v[106:107], 0 op_sel_hi:[1,0]
	v_pk_add_f32 v[100:101], v[100:101], 0 op_sel_hi:[1,0]
	v_pk_add_f32 v[102:103], v[102:103], 0 op_sel_hi:[1,0]
	v_pk_add_f32 v[96:97], v[96:97], 0 op_sel_hi:[1,0]
	v_pk_add_f32 v[98:99], v[98:99], 0 op_sel_hi:[1,0]
	v_pk_add_f32 v[92:93], v[92:93], 0 op_sel_hi:[1,0]
	v_pk_add_f32 v[94:95], v[94:95], 0 op_sel_hi:[1,0]
	v_pk_add_f32 v[88:89], v[88:89], 0 op_sel_hi:[1,0]
	v_pk_add_f32 v[90:91], v[90:91], 0 op_sel_hi:[1,0]
	v_pk_add_f32 v[84:85], v[84:85], 0 op_sel_hi:[1,0]
	v_pk_add_f32 v[86:87], v[86:87], 0 op_sel_hi:[1,0]
	v_pk_add_f32 v[76:77], v[76:77], 0 op_sel_hi:[1,0]
	v_pk_add_f32 v[78:79], v[78:79], 0 op_sel_hi:[1,0]
	v_pk_add_f32 v[80:81], v[80:81], 0 op_sel_hi:[1,0]
	v_pk_add_f32 v[82:83], v[82:83], 0 op_sel_hi:[1,0]
	v_pk_add_f32 v[72:73], v[72:73], 0 op_sel_hi:[1,0]
	v_pk_add_f32 v[74:75], v[74:75], 0 op_sel_hi:[1,0]
	v_pk_add_f32 v[68:69], v[68:69], 0 op_sel_hi:[1,0]
	v_pk_add_f32 v[70:71], v[70:71], 0 op_sel_hi:[1,0]
	v_pk_add_f32 v[64:65], v[64:65], 0 op_sel_hi:[1,0]
	v_pk_add_f32 v[66:67], v[66:67], 0 op_sel_hi:[1,0]
	v_pk_add_f32 v[60:61], v[60:61], 0 op_sel_hi:[1,0]
	v_pk_add_f32 v[62:63], v[62:63], 0 op_sel_hi:[1,0]
	v_pk_add_f32 v[56:57], v[56:57], 0 op_sel_hi:[1,0]
	v_pk_add_f32 v[58:59], v[58:59], 0 op_sel_hi:[1,0]
	v_pk_add_f32 v[52:53], v[52:53], 0 op_sel_hi:[1,0]
	v_pk_add_f32 v[54:55], v[54:55], 0 op_sel_hi:[1,0]
	v_pk_add_f32 v[44:45], v[44:45], 0 op_sel_hi:[1,0]
	v_pk_add_f32 v[46:47], v[46:47], 0 op_sel_hi:[1,0]
	v_pk_add_f32 v[48:49], v[48:49], 0 op_sel_hi:[1,0]
	v_pk_add_f32 v[50:51], v[50:51], 0 op_sel_hi:[1,0]
	v_pk_add_f32 v[40:41], v[40:41], 0 op_sel_hi:[1,0]
	v_pk_add_f32 v[42:43], v[42:43], 0 op_sel_hi:[1,0]
	v_pk_add_f32 v[36:37], v[36:37], 0 op_sel_hi:[1,0]
	v_pk_add_f32 v[38:39], v[38:39], 0 op_sel_hi:[1,0]
	v_pk_add_f32 v[32:33], v[32:33], 0 op_sel_hi:[1,0]
	v_pk_add_f32 v[34:35], v[34:35], 0 op_sel_hi:[1,0]
	v_pk_add_f32 v[28:29], v[28:29], 0 op_sel_hi:[1,0]
	v_pk_add_f32 v[30:31], v[30:31], 0 op_sel_hi:[1,0]
	v_pk_add_f32 v[24:25], v[24:25], 0 op_sel_hi:[1,0]
	v_pk_add_f32 v[26:27], v[26:27], 0 op_sel_hi:[1,0]
	v_pk_add_f32 v[20:21], v[20:21], 0 op_sel_hi:[1,0]
	v_pk_add_f32 v[22:23], v[22:23], 0 op_sel_hi:[1,0]
	v_pk_add_f32 v[12:13], v[12:13], 0 op_sel_hi:[1,0]
	v_pk_add_f32 v[14:15], v[14:15], 0 op_sel_hi:[1,0]
	v_pk_add_f32 v[16:17], v[16:17], 0 op_sel_hi:[1,0]
	v_pk_add_f32 v[18:19], v[18:19], 0 op_sel_hi:[1,0]
	v_pk_add_f32 v[8:9], v[8:9], 0 op_sel_hi:[1,0]
	v_pk_add_f32 v[10:11], v[10:11], 0 op_sel_hi:[1,0]
	v_pk_add_f32 v[4:5], v[4:5], 0 op_sel_hi:[1,0]
	v_pk_add_f32 v[6:7], v[6:7], 0 op_sel_hi:[1,0]
	v_pk_add_f32 v[0:1], v[0:1], 0 op_sel_hi:[1,0]
	v_pk_add_f32 v[2:3], v[2:3], 0 op_sel_hi:[1,0]
	s_waitcnt vmcnt(8)
	v_mov_b32_e32 v212, v152
	v_mov_b32_e32 v213, v153
	v_mov_b32_e32 v214, v154
	v_mov_b32_e32 v215, v155
	s_nop 0
	v_mov_b32_dpp v152, v140 row_shl:8 row_mask:0xf bank_mask:0x3
	v_mov_b32_dpp v153, v141 row_shl:8 row_mask:0xf bank_mask:0x3
	v_mov_b32_dpp v154, v142 row_shl:8 row_mask:0xf bank_mask:0x3
	v_mov_b32_dpp v155, v143 row_shl:8 row_mask:0xf bank_mask:0x3
	v_mov_b32_dpp v140, v212 row_shr:8 row_mask:0xf bank_mask:0xc
	v_mov_b32_dpp v141, v213 row_shr:8 row_mask:0xf bank_mask:0xc
	v_mov_b32_dpp v142, v214 row_shr:8 row_mask:0xf bank_mask:0xc
	v_mov_b32_dpp v143, v215 row_shr:8 row_mask:0xf bank_mask:0xc
	v_mov_b32_e32 v212, v160
	v_mov_b32_e32 v213, v161
	v_mov_b32_e32 v214, v162
	v_mov_b32_e32 v215, v163
	s_nop 0
	v_mov_b32_dpp v160, v156 row_shl:8 row_mask:0xf bank_mask:0x3
	v_mov_b32_dpp v161, v157 row_shl:8 row_mask:0xf bank_mask:0x3
	v_mov_b32_dpp v162, v158 row_shl:8 row_mask:0xf bank_mask:0x3
	v_mov_b32_dpp v163, v159 row_shl:8 row_mask:0xf bank_mask:0x3
	v_mov_b32_dpp v156, v212 row_shr:8 row_mask:0xf bank_mask:0xc
	v_mov_b32_dpp v157, v213 row_shr:8 row_mask:0xf bank_mask:0xc
	v_mov_b32_dpp v158, v214 row_shr:8 row_mask:0xf bank_mask:0xc
	v_mov_b32_dpp v159, v215 row_shr:8 row_mask:0xf bank_mask:0xc
	v_mov_b32_e32 v212, v168
	v_mov_b32_e32 v213, v169
	v_mov_b32_e32 v214, v170
	v_mov_b32_e32 v215, v171
	s_nop 0
	v_mov_b32_dpp v168, v164 row_shl:8 row_mask:0xf bank_mask:0x3
	v_mov_b32_dpp v169, v165 row_shl:8 row_mask:0xf bank_mask:0x3
	v_mov_b32_dpp v170, v166 row_shl:8 row_mask:0xf bank_mask:0x3
	v_mov_b32_dpp v171, v167 row_shl:8 row_mask:0xf bank_mask:0x3
	v_mov_b32_dpp v164, v212 row_shr:8 row_mask:0xf bank_mask:0xc
	v_mov_b32_dpp v165, v213 row_shr:8 row_mask:0xf bank_mask:0xc
	v_mov_b32_dpp v166, v214 row_shr:8 row_mask:0xf bank_mask:0xc
	v_mov_b32_dpp v167, v215 row_shr:8 row_mask:0xf bank_mask:0xc
	v_mov_b32_e32 v212, v176
	v_mov_b32_e32 v213, v177
	v_mov_b32_e32 v214, v178
	v_mov_b32_e32 v215, v179
	s_nop 0
	v_mov_b32_dpp v176, v172 row_shl:8 row_mask:0xf bank_mask:0x3
	v_mov_b32_dpp v177, v173 row_shl:8 row_mask:0xf bank_mask:0x3
	v_mov_b32_dpp v178, v174 row_shl:8 row_mask:0xf bank_mask:0x3
;     __device__ __forceinline__ void operator()(AccRef acc, const Unit& u, int wr, int wc, int fr, int fq) const {
;     ...
;                         for (int n = 0; n < 2; ++n) bs[m][bj][n] = *(const f32x4*)(base + (size_t)(row0 + ai * 128 + (2 * mh + m) * 16) * D + col0 + bj * 128 + n * 16);
; #pragma unroll
;                 for (int m = 0; m < 2; ++m)
; #pragma unroll
;                     for (int bj = 0; bj < 2; ++bj)
; #pragma unroll
;                         for (int n = 0; n < 2; ++n) *(f32x4*)(out + (size_t)(row0 + ai * 128 + (2 * mh + m) * 16) * D + col0 + bj * 128 + n * 16) = bs[m][bj][n] + sv[bj][n] * (acc[ai][bj][2 * mh + m][n] + bv[bj][n]);
;                 asm volatile("" ::: "memory"); }
	v_mov_b32_dpp v179, v175 row_shl:8 row_mask:0xf bank_mask:0x3
	v_mov_b32_dpp v172, v212 row_shr:8 row_mask:0xf bank_mask:0xc
	v_mov_b32_dpp v173, v213 row_shr:8 row_mask:0xf bank_mask:0xc
	v_mov_b32_dpp v174, v214 row_shr:8 row_mask:0xf bank_mask:0xc
	v_mov_b32_dpp v175, v215 row_shr:8 row_mask:0xf bank_mask:0xc
	v_pk_add_f32 v[124:125], v[124:125], v[140:141]
	v_pk_add_f32 v[126:127], v[126:127], v[142:143]
	v_pk_add_f32 v[120:121], v[120:121], v[152:153]
	v_pk_add_f32 v[122:123], v[122:123], v[154:155]
	v_pk_add_f32 v[116:117], v[116:117], v[156:157]
	v_pk_add_f32 v[118:119], v[118:119], v[158:159]
	v_pk_add_f32 v[108:109], v[108:109], v[160:161]
	v_pk_add_f32 v[110:111], v[110:111], v[162:163]
	v_pk_add_f32 v[112:113], v[112:113], v[164:165]
	v_pk_add_f32 v[114:115], v[114:115], v[166:167]
	v_pk_add_f32 v[104:105], v[104:105], v[168:169]
	v_pk_add_f32 v[106:107], v[106:107], v[170:171]
	v_pk_add_f32 v[100:101], v[100:101], v[172:173]
	v_pk_add_f32 v[102:103], v[102:103], v[174:175]
	v_pk_add_f32 v[96:97], v[96:97], v[176:177]
	v_pk_add_f32 v[98:99], v[98:99], v[178:179]
	global_store_dwordx4 v145, v[124:127], s[52:53]
	global_store_dwordx4 v145, v[120:123], s[52:53] offset:64
	global_store_dwordx4 v145, v[116:119], s[52:53] offset:512
	global_store_dwordx4 v145, v[108:111], s[52:53] offset:576
	global_store_dwordx4 v216, v[112:115], s[52:53]
	global_store_dwordx4 v216, v[104:107], s[52:53] offset:64
	global_store_dwordx4 v216, v[100:103], s[52:53] offset:512
	global_store_dwordx4 v216, v[96:99], s[52:53] offset:576
	global_load_dwordx4 v[140:143], v228, s[52:53]
	v_add_u32_e32 v144, v220, v233
	global_load_dwordx4 v[152:155], v144, s[52:53]
	global_load_dwordx4 v[156:159], v228, s[52:53] offset:512
	v_add_u32_e32 v144, v220, v233
	global_load_dwordx4 v[160:163], v144, s[52:53] offset:512
	global_load_dwordx4 v[164:167], v229, s[52:53]
	v_add_u32_e32 v144, v221, v233
	global_load_dwordx4 v[168:171], v144, s[52:53]
	global_load_dwordx4 v[172:175], v229, s[52:53] offset:512
	v_add_u32_e32 v144, v221, v233
	global_load_dwordx4 v[176:179], v144, s[52:53] offset:512
	s_waitcnt vmcnt(16)
	v_mov_b32_e32 v212, v184
	v_mov_b32_e32 v213, v185
	v_mov_b32_e32 v214, v186
	v_mov_b32_e32 v215, v187
	s_nop 0
	v_mov_b32_dpp v184, v180 row_shl:8 row_mask:0xf bank_mask:0x3
	v_mov_b32_dpp v185, v181 row_shl:8 row_mask:0xf bank_mask:0x3
	v_mov_b32_dpp v186, v182 row_shl:8 row_mask:0xf bank_mask:0x3
	v_mov_b32_dpp v187, v183 row_shl:8 row_mask:0xf bank_mask:0x3
	v_mov_b32_dpp v180, v212 row_shr:8 row_mask:0xf bank_mask:0xc
	v_mov_b32_dpp v181, v213 row_shr:8 row_mask:0xf bank_mask:0xc
	v_mov_b32_dpp v182, v214 row_shr:8 row_mask:0xf bank_mask:0xc
	v_mov_b32_dpp v183, v215 row_shr:8 row_mask:0xf bank_mask:0xc
	v_mov_b32_e32 v212, v192
	v_mov_b32_e32 v213, v193
	v_mov_b32_e32 v214, v194
	v_mov_b32_e32 v215, v195
	s_nop 0
	v_mov_b32_dpp v192, v188 row_shl:8 row_mask:0xf bank_mask:0x3
	v_mov_b32_dpp v193, v189 row_shl:8 row_mask:0xf bank_mask:0x3
	v_mov_b32_dpp v194, v190 row_shl:8 row_mask:0xf bank_mask:0x3
	v_mov_b32_dpp v195, v191 row_shl:8 row_mask:0xf bank_mask:0x3
	v_mov_b32_dpp v188, v212 row_shr:8 row_mask:0xf bank_mask:0xc
	v_mov_b32_dpp v189, v213 row_shr:8 row_mask:0xf bank_mask:0xc
	v_mov_b32_dpp v190, v214 row_shr:8 row_mask:0xf bank_mask:0xc
	v_mov_b32_dpp v191, v215 row_shr:8 row_mask:0xf bank_mask:0xc
	v_mov_b32_e32 v212, v200
	v_mov_b32_e32 v213, v201
	v_mov_b32_e32 v214, v202
	v_mov_b32_e32 v215, v203
	s_nop 0
	v_mov_b32_dpp v200, v196 row_shl:8 row_mask:0xf bank_mask:0x3
	v_mov_b32_dpp v201, v197 row_shl:8 row_mask:0xf bank_mask:0x3
	v_mov_b32_dpp v202, v198 row_shl:8 row_mask:0xf bank_mask:0x3
	v_mov_b32_dpp v203, v199 row_shl:8 row_mask:0xf bank_mask:0x3
	v_mov_b32_dpp v196, v212 row_shr:8 row_mask:0xf bank_mask:0xc
	v_mov_b32_dpp v197, v213 row_shr:8 row_mask:0xf bank_mask:0xc
	v_mov_b32_dpp v198, v214 row_shr:8 row_mask:0xf bank_mask:0xc
	v_mov_b32_dpp v199, v215 row_shr:8 row_mask:0xf bank_mask:0xc
	v_mov_b32_e32 v212, v208
	v_mov_b32_e32 v213, v209
	v_mov_b32_e32 v214, v210
	v_mov_b32_e32 v215, v211
	s_nop 0
	v_mov_b32_dpp v208, v204 row_shl:8 row_mask:0xf bank_mask:0x3
	v_mov_b32_dpp v209, v205 row_shl:8 row_mask:0xf bank_mask:0x3
	v_mov_b32_dpp v210, v206 row_shl:8 row_mask:0xf bank_mask:0x3
	v_mov_b32_dpp v211, v207 row_shl:8 row_mask:0xf bank_mask:0x3
	v_mov_b32_dpp v204, v212 row_shr:8 row_mask:0xf bank_mask:0xc
	v_mov_b32_dpp v205, v213 row_shr:8 row_mask:0xf bank_mask:0xc
	v_mov_b32_dpp v206, v214 row_shr:8 row_mask:0xf bank_mask:0xc
	v_mov_b32_dpp v207, v215 row_shr:8 row_mask:0xf bank_mask:0xc
	v_pk_add_f32 v[92:93], v[92:93], v[180:181]
	v_pk_add_f32 v[94:95], v[94:95], v[182:183]
	v_pk_add_f32 v[88:89], v[88:89], v[184:185]
	v_pk_add_f32 v[90:91], v[90:91], v[186:187]
	v_pk_add_f32 v[84:85], v[84:85], v[188:189]
	v_pk_add_f32 v[86:87], v[86:87], v[190:191]
	v_pk_add_f32 v[76:77], v[76:77], v[192:193]
	v_pk_add_f32 v[78:79], v[78:79], v[194:195]
	v_pk_add_f32 v[80:81], v[80:81], v[196:197]
	v_pk_add_f32 v[82:83], v[82:83], v[198:199]
	v_pk_add_f32 v[72:73], v[72:73], v[200:201]
	v_pk_add_f32 v[74:75], v[74:75], v[202:203]
	v_pk_add_f32 v[68:69], v[68:69], v[204:205]
	v_pk_add_f32 v[70:71], v[70:71], v[206:207]
	v_pk_add_f32 v[64:65], v[64:65], v[208:209]
	v_pk_add_f32 v[66:67], v[66:67], v[210:211]
	global_store_dwordx4 v217, v[92:95], s[52:53]
	global_store_dwordx4 v217, v[88:91], s[52:53] offset:64
	global_store_dwordx4 v217, v[84:87], s[52:53] offset:512
	global_store_dwordx4 v217, v[76:79], s[52:53] offset:576
	global_store_dwordx4 v218, v[80:83], s[52:53]
	global_store_dwordx4 v218, v[72:75], s[52:53] offset:64
	global_store_dwordx4 v218, v[68:71], s[52:53] offset:512
	global_store_dwordx4 v218, v[64:67], s[52:53] offset:576
	global_load_dwordx4 v[180:183], v230, s[52:53]
	v_add_u32_e32 v144, v222, v233
	global_load_dwordx4 v[184:187], v144, s[52:53]
	global_load_dwordx4 v[188:191], v230, s[52:53] offset:512
	v_add_u32_e32 v144, v222, v233
	global_load_dwordx4 v[192:195], v144, s[52:53] offset:512
	global_load_dwordx4 v[196:199], v231, s[52:53]
	v_add_u32_e32 v144, v223, v233
	global_load_dwordx4 v[200:203], v144, s[52:53]
	global_load_dwordx4 v[204:207], v231, s[52:53] offset:512
	v_add_u32_e32 v144, v223, v233
	global_load_dwordx4 v[208:211], v144, s[52:53] offset:512
	s_waitcnt vmcnt(16)
;     __device__ __forceinline__ void operator()(AccRef acc, const Unit& u, int wr, int wc, int fr, int fq) const {
;     ...
;                         for (int n = 0; n < 2; ++n) bs[m][bj][n] = *(const f32x4*)(base + (size_t)(row0 + ai * 128 + (2 * mh + m) * 16) * D + col0 + bj * 128 + n * 16);
; #pragma unroll
;                 for (int m = 0; m < 2; ++m)
; #pragma unroll
;                     for (int bj = 0; bj < 2; ++bj)
; #pragma unroll
;                         for (int n = 0; n < 2; ++n) *(f32x4*)(out + (size_t)(row0 + ai * 128 + (2 * mh + m) * 16) * D + col0 + bj * 128 + n * 16) = bs[m][bj][n] + sv[bj][n] * (acc[ai][bj][2 * mh + m][n] + bv[bj][n]);
	v_mov_b32_e32 v212, v152
	v_mov_b32_e32 v213, v153
	v_mov_b32_e32 v214, v154
	v_mov_b32_e32 v215, v155
	s_nop 0
	v_mov_b32_dpp v152, v140 row_shl:8 row_mask:0xf bank_mask:0x3
	v_mov_b32_dpp v153, v141 row_shl:8 row_mask:0xf bank_mask:0x3
	v_mov_b32_dpp v154, v142 row_shl:8 row_mask:0xf bank_mask:0x3
	v_mov_b32_dpp v155, v143 row_shl:8 row_mask:0xf bank_mask:0x3
	v_mov_b32_dpp v140, v212 row_shr:8 row_mask:0xf bank_mask:0xc
	v_mov_b32_dpp v141, v213 row_shr:8 row_mask:0xf bank_mask:0xc
	v_mov_b32_dpp v142, v214 row_shr:8 row_mask:0xf bank_mask:0xc
	v_mov_b32_dpp v143, v215 row_shr:8 row_mask:0xf bank_mask:0xc
	v_mov_b32_e32 v212, v160
	v_mov_b32_e32 v213, v161
	v_mov_b32_e32 v214, v162
	v_mov_b32_e32 v215, v163
	s_nop 0
	v_mov_b32_dpp v160, v156 row_shl:8 row_mask:0xf bank_mask:0x3
	v_mov_b32_dpp v161, v157 row_shl:8 row_mask:0xf bank_mask:0x3
	v_mov_b32_dpp v162, v158 row_shl:8 row_mask:0xf bank_mask:0x3
	v_mov_b32_dpp v163, v159 row_shl:8 row_mask:0xf bank_mask:0x3
	v_mov_b32_dpp v156, v212 row_shr:8 row_mask:0xf bank_mask:0xc
	v_mov_b32_dpp v157, v213 row_shr:8 row_mask:0xf bank_mask:0xc
	v_mov_b32_dpp v158, v214 row_shr:8 row_mask:0xf bank_mask:0xc
	v_mov_b32_dpp v159, v215 row_shr:8 row_mask:0xf bank_mask:0xc
	v_mov_b32_e32 v212, v168
	v_mov_b32_e32 v213, v169
	v_mov_b32_e32 v214, v170
	v_mov_b32_e32 v215, v171
	s_nop 0
	v_mov_b32_dpp v168, v164 row_shl:8 row_mask:0xf bank_mask:0x3
	v_mov_b32_dpp v169, v165 row_shl:8 row_mask:0xf bank_mask:0x3
	v_mov_b32_dpp v170, v166 row_shl:8 row_mask:0xf bank_mask:0x3
	v_mov_b32_dpp v171, v167 row_shl:8 row_mask:0xf bank_mask:0x3
	v_mov_b32_dpp v164, v212 row_shr:8 row_mask:0xf bank_mask:0xc
	v_mov_b32_dpp v165, v213 row_shr:8 row_mask:0xf bank_mask:0xc
	v_mov_b32_dpp v166, v214 row_shr:8 row_mask:0xf bank_mask:0xc
	v_mov_b32_dpp v167, v215 row_shr:8 row_mask:0xf bank_mask:0xc
	v_mov_b32_e32 v212, v176
	v_mov_b32_e32 v213, v177
	v_mov_b32_e32 v214, v178
	v_mov_b32_e32 v215, v179
	s_nop 0
	v_mov_b32_dpp v176, v172 row_shl:8 row_mask:0xf bank_mask:0x3
	v_mov_b32_dpp v177, v173 row_shl:8 row_mask:0xf bank_mask:0x3
	v_mov_b32_dpp v178, v174 row_shl:8 row_mask:0xf bank_mask:0x3
	v_mov_b32_dpp v179, v175 row_shl:8 row_mask:0xf bank_mask:0x3
	v_mov_b32_dpp v172, v212 row_shr:8 row_mask:0xf bank_mask:0xc
	v_mov_b32_dpp v173, v213 row_shr:8 row_mask:0xf bank_mask:0xc
	v_mov_b32_dpp v174, v214 row_shr:8 row_mask:0xf bank_mask:0xc
	v_mov_b32_dpp v175, v215 row_shr:8 row_mask:0xf bank_mask:0xc
	v_pk_add_f32 v[60:61], v[60:61], v[140:141]
	v_pk_add_f32 v[62:63], v[62:63], v[142:143]
	v_pk_add_f32 v[56:57], v[56:57], v[152:153]
	v_pk_add_f32 v[58:59], v[58:59], v[154:155]
	v_pk_add_f32 v[52:53], v[52:53], v[156:157]
	v_pk_add_f32 v[54:55], v[54:55], v[158:159]
	v_pk_add_f32 v[44:45], v[44:45], v[160:161]
	v_pk_add_f32 v[46:47], v[46:47], v[162:163]
	v_pk_add_f32 v[48:49], v[48:49], v[164:165]
	v_pk_add_f32 v[50:51], v[50:51], v[166:167]
	v_pk_add_f32 v[40:41], v[40:41], v[168:169]
	v_pk_add_f32 v[42:43], v[42:43], v[170:171]
	v_pk_add_f32 v[36:37], v[36:37], v[172:173]
	v_pk_add_f32 v[38:39], v[38:39], v[174:175]
	v_pk_add_f32 v[32:33], v[32:33], v[176:177]
	v_pk_add_f32 v[34:35], v[34:35], v[178:179]
	global_store_dwordx4 v220, v[60:63], s[52:53]
	global_store_dwordx4 v220, v[56:59], s[52:53] offset:64
	global_store_dwordx4 v220, v[52:55], s[52:53] offset:512
	global_store_dwordx4 v220, v[44:47], s[52:53] offset:576
	global_store_dwordx4 v221, v[48:51], s[52:53]
	global_store_dwordx4 v221, v[40:43], s[52:53] offset:64
	global_store_dwordx4 v221, v[36:39], s[52:53] offset:512
	global_store_dwordx4 v221, v[32:35], s[52:53] offset:576
	s_waitcnt vmcnt(8)
; #define PG8_WAIT_V(n) asm volatile("s_waitcnt vmcnt(" #n ")" ::: "memory")
; #define PG8_BAR __builtin_amdgcn_s_barrier()
; template <class Epi>
; __device__ __forceinline__ void gemm_phase(LAS unsigned char* lds, const Gemm g, const StaticOrder& S, const Epi& E) {
;     ...
;         if (!has_next) break;
;         {
; #pragma unroll
;         for (int a = 0; a < 2; ++a)
; #pragma unroll
;             for (int b = 0; b < 2; ++b)
; #pragma unroll
;                 for (int m = 0; m < 4; ++m)
; #pragma unroll
;                     for (int n = 0; n < 2; ++n) acc[a][b][m][n] = (f32x4){0.f, 0.f, 0.f, 0.f};
;         }
;         cur = nxt; cA = nA; cB = nB; ++ui;
;     }
;     PG8_WAIT_V(0);
;     if (wr == 0) PG8_BAR;
;     PG8_BAR;
;     __device__ __forceinline__ void operator()(AccRef acc, const Unit& u, int wr, int wc, int fr, int fq) const {
;     ...
;                         for (int n = 0; n < 2; ++n) bs[m][bj][n] = *(const f32x4*)(base + (size_t)(row0 + ai * 128 + (2 * mh + m) * 16) * D + col0 + bj * 128 + n * 16);
; #pragma unroll
;                 for (int m = 0; m < 2; ++m)
; #pragma unroll
;                     for (int bj = 0; bj < 2; ++bj)
; #pragma unroll
;                         for (int n = 0; n < 2; ++n) *(f32x4*)(out + (size_t)(row0 + ai * 128 + (2 * mh + m) * 16) * D + col0 + bj * 128 + n * 16) = bs[m][bj][n] + sv[bj][n] * (acc[ai][bj][2 * mh + m][n] + bv[bj][n]);
;                 asm volatile("" ::: "memory"); }
	v_mov_b32_e32 v212, v184
	v_mov_b32_e32 v213, v185
	v_mov_b32_e32 v214, v186
	v_mov_b32_e32 v215, v187
	s_nop 0
	v_mov_b32_dpp v184, v180 row_shl:8 row_mask:0xf bank_mask:0x3
	v_mov_b32_dpp v185, v181 row_shl:8 row_mask:0xf bank_mask:0x3
	v_mov_b32_dpp v186, v182 row_shl:8 row_mask:0xf bank_mask:0x3
	v_mov_b32_dpp v187, v183 row_shl:8 row_mask:0xf bank_mask:0x3
	v_mov_b32_dpp v180, v212 row_shr:8 row_mask:0xf bank_mask:0xc
	v_mov_b32_dpp v181, v213 row_shr:8 row_mask:0xf bank_mask:0xc
	v_mov_b32_dpp v182, v214 row_shr:8 row_mask:0xf bank_mask:0xc
	v_mov_b32_dpp v183, v215 row_shr:8 row_mask:0xf bank_mask:0xc
	v_mov_b32_e32 v212, v192
	v_mov_b32_e32 v213, v193
	v_mov_b32_e32 v214, v194
	v_mov_b32_e32 v215, v195
	s_nop 0
	v_mov_b32_dpp v192, v188 row_shl:8 row_mask:0xf bank_mask:0x3
	v_mov_b32_dpp v193, v189 row_shl:8 row_mask:0xf bank_mask:0x3
	v_mov_b32_dpp v194, v190 row_shl:8 row_mask:0xf bank_mask:0x3
	v_mov_b32_dpp v195, v191 row_shl:8 row_mask:0xf bank_mask:0x3
	v_mov_b32_dpp v188, v212 row_shr:8 row_mask:0xf bank_mask:0xc
	v_mov_b32_dpp v189, v213 row_shr:8 row_mask:0xf bank_mask:0xc
	v_mov_b32_dpp v190, v214 row_shr:8 row_mask:0xf bank_mask:0xc
	v_mov_b32_dpp v191, v215 row_shr:8 row_mask:0xf bank_mask:0xc
	v_mov_b32_e32 v212, v200
	v_mov_b32_e32 v213, v201
	v_mov_b32_e32 v214, v202
	v_mov_b32_e32 v215, v203
	s_nop 0
	v_mov_b32_dpp v200, v196 row_shl:8 row_mask:0xf bank_mask:0x3
	v_mov_b32_dpp v201, v197 row_shl:8 row_mask:0xf bank_mask:0x3
	v_mov_b32_dpp v202, v198 row_shl:8 row_mask:0xf bank_mask:0x3
	v_mov_b32_dpp v203, v199 row_shl:8 row_mask:0xf bank_mask:0x3
	v_mov_b32_dpp v196, v212 row_shr:8 row_mask:0xf bank_mask:0xc
	v_mov_b32_dpp v197, v213 row_shr:8 row_mask:0xf bank_mask:0xc
	v_mov_b32_dpp v198, v214 row_shr:8 row_mask:0xf bank_mask:0xc
	v_mov_b32_dpp v199, v215 row_shr:8 row_mask:0xf bank_mask:0xc
	v_mov_b32_e32 v212, v208
	v_mov_b32_e32 v213, v209
	v_mov_b32_e32 v214, v210
	v_mov_b32_e32 v215, v211
	s_nop 0
	v_mov_b32_dpp v208, v204 row_shl:8 row_mask:0xf bank_mask:0x3
	v_mov_b32_dpp v209, v205 row_shl:8 row_mask:0xf bank_mask:0x3
	v_mov_b32_dpp v210, v206 row_shl:8 row_mask:0xf bank_mask:0x3
	v_mov_b32_dpp v211, v207 row_shl:8 row_mask:0xf bank_mask:0x3
	v_mov_b32_dpp v204, v212 row_shr:8 row_mask:0xf bank_mask:0xc
	v_mov_b32_dpp v205, v213 row_shr:8 row_mask:0xf bank_mask:0xc
	v_mov_b32_dpp v206, v214 row_shr:8 row_mask:0xf bank_mask:0xc
	v_mov_b32_dpp v207, v215 row_shr:8 row_mask:0xf bank_mask:0xc
	v_pk_add_f32 v[28:29], v[28:29], v[180:181]
	v_pk_add_f32 v[30:31], v[30:31], v[182:183]
	v_pk_add_f32 v[24:25], v[24:25], v[184:185]
	v_pk_add_f32 v[26:27], v[26:27], v[186:187]
	v_pk_add_f32 v[20:21], v[20:21], v[188:189]
	v_pk_add_f32 v[22:23], v[22:23], v[190:191]
	v_pk_add_f32 v[12:13], v[12:13], v[192:193]
	v_pk_add_f32 v[14:15], v[14:15], v[194:195]
	v_pk_add_f32 v[16:17], v[16:17], v[196:197]
	v_pk_add_f32 v[18:19], v[18:19], v[198:199]
	v_pk_add_f32 v[8:9], v[8:9], v[200:201]
	v_pk_add_f32 v[10:11], v[10:11], v[202:203]
	v_pk_add_f32 v[4:5], v[4:5], v[204:205]
	v_pk_add_f32 v[6:7], v[6:7], v[206:207]
	v_pk_add_f32 v[0:1], v[0:1], v[208:209]
	v_pk_add_f32 v[2:3], v[2:3], v[210:211]
	global_store_dwordx4 v222, v[28:31], s[52:53]
	global_store_dwordx4 v222, v[24:27], s[52:53] offset:64
	global_store_dwordx4 v222, v[20:23], s[52:53] offset:512
	global_store_dwordx4 v222, v[12:15], s[52:53] offset:576
	global_store_dwordx4 v223, v[16:19], s[52:53]
	global_store_dwordx4 v223, v[8:11], s[52:53] offset:64
	global_store_dwordx4 v223, v[4:7], s[52:53] offset:512
	global_store_dwordx4 v223, v[0:3], s[52:53] offset:576
	s_cbranch_vccz .LBB0_2031
	s_waitcnt vmcnt(0)
	s_cmpk_gt_u32 s26, 0xff
	s_cbranch_scc1 .LBB0_2046
	s_barrier
